# load hoisting may cross stores (no aliasing inside a phase) with counted waits; swa V staging loads batched
# speedup vs baseline: 1.0031x; 1.0031x over previous
.LBB0_399:
	s_or_b64 exec, exec, s[4:5]
	s_and_b32 s2, s12, -2
	s_cmp_eq_u32 s13, 0
	s_cselect_b64 vcc, -1, 0
	s_lshl_b32 s4, s2, 4
	v_or_b32_e32 v47, s14, v75
	v_lshl_add_u32 v46, v79, 4, 0
	v_or_b32_e32 v48, s4, v75
	v_mad_u64_u32 v[100:101], s[6:7], v48, s88, v[46:47]
	s_or_b32 s6, s4, 16
	s_add_i32 s3, s2, 2
	v_or_b32_e32 v48, s6, v75
	s_lshl_b32 s12, s3, 4
	v_mad_u64_u32 v[98:99], s[8:9], v48, s88, v[46:47]
	v_or_b32_e32 v48, s12, v75
	s_add_i32 s20, s4, 48
	s_add_i32 s49, s2, 4
	v_mad_u64_u32 v[96:97], s[8:9], v48, s88, v[46:47]
	v_or_b32_e32 v48, s20, v75
	s_lshl_b32 s28, s49, 4
	v_mad_u64_u32 v[94:95], s[8:9], v48, s88, v[46:47]
	v_or_b32_e32 v48, s28, v75
	s_add_i32 s38, s4, 0x50
	v_mad_u64_u32 v[92:93], s[8:9], v48, s88, v[46:47]
	v_or_b32_e32 v48, s38, v75
	v_mad_u64_u32 v[90:91], s[8:9], v48, s88, v[46:47]
	s_add_i32 s88, s2, 6
	s_lshl_b32 s54, s88, 4
	s_movk_i32 s5, 0x90
	v_or_b32_e32 v48, s54, v75
	s_add_i32 s62, s4, 0x70
	s_add_i32 s89, s2, 8
	v_mad_u64_u32 v[88:89], s[8:9], v48, s5, v[46:47]
	v_or_b32_e32 v48, s62, v75
	s_lshl_b32 s70, s89, 4
	v_mad_u64_u32 v[86:87], s[8:9], v48, s5, v[46:47]
	v_or_b32_e32 v48, s70, v75
	s_add_i32 s78, s4, 0x90
	v_mad_u64_u32 v[84:85], s[8:9], v48, s5, v[46:47]
	v_or_b32_e32 v48, s78, v75
	v_mad_u64_u32 v[82:83], s[8:9], v48, s5, v[46:47]
	v_max_i32_e32 v46, 0x80, v47
	v_lshlrev_b32_e32 v48, 2, v79
	v_cndmask_b32_e32 v46, v47, v46, vcc
	v_add_u32_e32 v47, 0x80, v47
	v_or_b32_e32 v49, s4, v48
	v_cmp_lt_i32_e32 vcc, v49, v46
	v_cmp_gt_i32_e64 s[4:5], v49, v47
	v_or_b32_e32 v50, 1, v49
	s_or_b64 s[40:41], vcc, s[4:5]
	v_cmp_lt_i32_e32 vcc, v50, v46
	v_cmp_ge_i32_e64 s[4:5], v49, v47
	v_or_b32_e32 v50, 2, v49
	v_writelane_b32 v255, s40, 0
	s_or_b64 s[42:43], vcc, s[4:5]
	v_cmp_lt_i32_e32 vcc, v50, v46
	v_cmp_gt_i32_e64 s[4:5], v50, v47
	v_writelane_b32 v255, s41, 1
	s_or_b64 s[4:5], vcc, s[4:5]
	v_writelane_b32 v255, s4, 2
	v_or_b32_e32 v49, 3, v49
	v_cmp_lt_i32_e32 vcc, v49, v46
	v_writelane_b32 v255, s5, 3
	v_cmp_gt_i32_e64 s[4:5], v49, v47
	s_or_b64 s[4:5], vcc, s[4:5]
	v_or_b32_e32 v49, s6, v48
	v_writelane_b32 v255, s4, 4
	v_cmp_lt_i32_e32 vcc, v49, v46
	v_or_b32_e32 v50, 1, v49
	v_writelane_b32 v255, s5, 5
	v_cmp_gt_i32_e64 s[4:5], v49, v47
	s_or_b64 s[4:5], vcc, s[4:5]
	v_cmp_lt_i32_e32 vcc, v50, v46
	v_writelane_b32 v255, s4, 6
	v_cmp_ge_i32_e64 s[6:7], v49, v47
	v_or_b32_e32 v50, 2, v49
	v_writelane_b32 v255, s5, 7
	s_or_b64 s[6:7], vcc, s[6:7]
	v_cmp_lt_i32_e32 vcc, v50, v46
	v_cmp_gt_i32_e64 s[8:9], v50, v47
	v_or_b32_e32 v49, 3, v49
	v_writelane_b32 v255, s6, 8
	s_or_b64 s[4:5], vcc, s[8:9]
	v_cmp_lt_i32_e32 vcc, v49, v46
	v_cmp_gt_i32_e64 s[10:11], v49, v47
	v_or_b32_e32 v49, s12, v48
	v_writelane_b32 v255, s7, 9
	s_or_b64 s[44:45], vcc, s[10:11]
	v_cmp_lt_i32_e32 vcc, v49, v46
	v_cmp_gt_i32_e64 s[12:13], v49, v47
	v_or_b32_e32 v50, 1, v49
	v_writelane_b32 v255, s4, 10
	s_or_b64 s[8:9], vcc, s[12:13]
	v_cmp_lt_i32_e32 vcc, v50, v46
	v_cmp_ge_i32_e64 s[14:15], v49, v47
	v_or_b32_e32 v50, 2, v49
	v_writelane_b32 v255, s5, 11
	s_or_b64 s[12:13], vcc, s[14:15]
	v_cmp_lt_i32_e32 vcc, v50, v46
	v_cmp_gt_i32_e64 s[16:17], v50, v47
	v_or_b32_e32 v49, 3, v49
	v_writelane_b32 v255, s8, 12
	s_or_b64 s[10:11], vcc, s[16:17]
	v_cmp_lt_i32_e32 vcc, v49, v46
	v_cmp_gt_i32_e64 s[18:19], v49, v47
	v_or_b32_e32 v49, s20, v48
	v_writelane_b32 v255, s9, 13
	s_or_b64 s[8:9], vcc, s[18:19]
	v_cmp_lt_i32_e32 vcc, v49, v46
	v_cmp_gt_i32_e64 s[20:21], v49, v47
	v_or_b32_e32 v50, 1, v49
	s_or_b64 s[20:21], vcc, s[20:21]
	v_cmp_lt_i32_e32 vcc, v50, v46
	v_cmp_ge_i32_e64 s[22:23], v49, v47
	v_or_b32_e32 v50, 2, v49
	s_or_b64 s[18:19], vcc, s[22:23]
	v_cmp_lt_i32_e32 vcc, v50, v46
	v_cmp_gt_i32_e64 s[24:25], v50, v47
	v_or_b32_e32 v49, 3, v49
	s_or_b64 s[16:17], vcc, s[24:25]
	v_cmp_lt_i32_e32 vcc, v49, v46
	v_cmp_gt_i32_e64 s[26:27], v49, v47
	v_or_b32_e32 v49, s28, v48
	s_or_b64 s[14:15], vcc, s[26:27]
	v_cmp_lt_i32_e32 vcc, v49, v46
	v_cmp_gt_i32_e64 s[28:29], v49, v47
	v_or_b32_e32 v50, 1, v49
	s_or_b64 s[28:29], vcc, s[28:29]
	v_cmp_lt_i32_e32 vcc, v50, v46
	v_cmp_ge_i32_e64 s[30:31], v49, v47
	v_or_b32_e32 v50, 2, v49
	s_or_b64 s[24:25], vcc, s[30:31]
	v_cmp_lt_i32_e32 vcc, v50, v46
	v_cmp_gt_i32_e64 s[34:35], v50, v47
	v_or_b32_e32 v49, 3, v49
	s_or_b64 s[22:23], vcc, s[34:35]
	v_cmp_lt_i32_e32 vcc, v49, v46
	v_cmp_gt_i32_e64 s[36:37], v49, v47
	v_or_b32_e32 v49, s38, v48
	s_or_b64 s[26:27], vcc, s[36:37]
	v_cmp_lt_i32_e32 vcc, v49, v46
	v_cmp_gt_i32_e64 s[38:39], v49, v47
	v_or_b32_e32 v50, 1, v49
	s_or_b64 s[38:39], vcc, s[38:39]
	v_cmp_lt_i32_e32 vcc, v50, v46
	v_cmp_ge_i32_e64 s[46:47], v49, v47
	v_or_b32_e32 v50, 2, v49
	s_or_b64 s[30:31], vcc, s[46:47]
	v_cmp_lt_i32_e32 vcc, v50, v46
	v_cmp_gt_i32_e64 s[50:51], v50, v47
	v_or_b32_e32 v49, 3, v49
	s_or_b64 s[34:35], vcc, s[50:51]
	v_cmp_lt_i32_e32 vcc, v49, v46
	v_cmp_gt_i32_e64 s[52:53], v49, v47
	v_or_b32_e32 v49, s54, v48
	s_or_b64 s[36:37], vcc, s[52:53]
	v_cmp_lt_i32_e32 vcc, v49, v46
	v_cmp_gt_i32_e64 s[54:55], v49, v47
	v_or_b32_e32 v50, 1, v49
	s_or_b64 s[54:55], vcc, s[54:55]
	v_cmp_lt_i32_e32 vcc, v50, v46
	v_cmp_ge_i32_e64 s[56:57], v49, v47
	v_or_b32_e32 v50, 2, v49
	s_or_b64 s[46:47], vcc, s[56:57]
	v_cmp_lt_i32_e32 vcc, v50, v46
	v_cmp_gt_i32_e64 s[58:59], v50, v47
	v_or_b32_e32 v49, 3, v49
	s_or_b64 s[50:51], vcc, s[58:59]
	v_cmp_lt_i32_e32 vcc, v49, v46
	v_cmp_gt_i32_e64 s[60:61], v49, v47
	v_or_b32_e32 v49, s62, v48
	s_or_b64 s[52:53], vcc, s[60:61]
	v_cmp_lt_i32_e32 vcc, v49, v46
	v_cmp_gt_i32_e64 s[62:63], v49, v47
	v_or_b32_e32 v50, 1, v49
	s_or_b64 s[62:63], vcc, s[62:63]
	v_cmp_lt_i32_e32 vcc, v50, v46
	v_cmp_ge_i32_e64 s[64:65], v49, v47
	v_or_b32_e32 v50, 2, v49
	s_or_b64 s[56:57], vcc, s[64:65]
	v_cmp_lt_i32_e32 vcc, v50, v46
	v_cmp_gt_i32_e64 s[66:67], v50, v47
	v_or_b32_e32 v49, 3, v49
	s_or_b64 s[58:59], vcc, s[66:67]
	v_cmp_lt_i32_e32 vcc, v49, v46
	v_cmp_gt_i32_e64 s[68:69], v49, v47
	v_or_b32_e32 v49, s70, v48
	s_or_b64 s[60:61], vcc, s[68:69]
	v_cmp_lt_i32_e32 vcc, v49, v46
	v_cmp_gt_i32_e64 s[70:71], v49, v47
	v_or_b32_e32 v50, 1, v49
	v_ashrrev_i32_e32 v3, 31, v2
	s_or_b64 s[70:71], vcc, s[70:71]
	v_cmp_lt_i32_e32 vcc, v50, v46
	v_cmp_ge_i32_e64 s[72:73], v49, v47
	v_or_b32_e32 v50, 2, v49
	s_or_b64 s[64:65], vcc, s[72:73]
	v_cmp_lt_i32_e32 vcc, v50, v46
	v_cmp_gt_i32_e64 s[74:75], v50, v47
	v_or_b32_e32 v49, 3, v49
	v_lshlrev_b64 v[2:3], 11, v[2:3]
	v_lshlrev_b32_e32 v0, 3, v79
	s_or_b64 s[66:67], vcc, s[74:75]
	v_cmp_lt_i32_e32 vcc, v49, v46
	v_cmp_gt_i32_e64 s[76:77], v49, v47
	v_or_b32_e32 v48, s78, v48
	v_lshl_add_u64 v[2:3], s[0:1], 0, v[2:3]
	s_or_b64 s[68:69], vcc, s[76:77]
	v_cmp_lt_i32_e32 vcc, v48, v46
	v_cmp_gt_i32_e64 s[78:79], v48, v47
	v_or_b32_e32 v49, 1, v48
	v_lshl_add_u64 v[2:3], v[2:3], 0, v[0:1]
	s_mov_b64 s[0:1], 0xa000000
	s_or_b64 s[78:79], vcc, s[78:79]
	v_cmp_lt_i32_e32 vcc, v49, v46
	v_cmp_ge_i32_e64 s[80:81], v48, v47
	v_or_b32_e32 v49, 2, v48
	v_lshl_add_u64 v[80:81], v[2:3], 0, s[0:1]
	v_readlane_b32 s0, v254, 14
	s_or_b64 s[76:77], vcc, s[80:81]
	v_cmp_lt_i32_e32 vcc, v49, v46
	v_cmp_gt_i32_e64 s[82:83], v49, v47
	v_or_b32_e32 v48, 3, v48
	v_mov_b32_e32 v79, s0
	s_waitcnt lgkmcnt(0)
	s_barrier
	s_or_b64 s[72:73], vcc, s[82:83]
	v_cmp_lt_i32_e32 vcc, v48, v46
	v_cmp_gt_i32_e64 s[84:85], v48, v47
	v_add_u32_e32 v46, 0, v0
	v_mul_u32_u24_e32 v47, 0x210, v75
	s_lshl_b32 s2, s2, 5
	v_lshlrev_b32_e32 v64, 16, v38
	v_and_b32_e32 v66, 0xffff0000, v38
	v_lshlrev_b32_e32 v65, 16, v39
	v_and_b32_e32 v67, 0xffff0000, v39
	v_lshlrev_b32_e32 v68, 16, v40
	v_and_b32_e32 v70, 0xffff0000, v40
	v_lshlrev_b32_e32 v69, 16, v41
	v_and_b32_e32 v71, 0xffff0000, v41
	ds_read2_b64 v[38:41], v79 offset1:1
	v_add3_u32 v91, v46, s2, v47
	s_lshl_b32 s2, s3, 5
	v_add3_u32 v89, v46, s2, v47
	s_lshl_b32 s2, s49, 5
	v_add3_u32 v87, v46, s2, v47
	s_lshl_b32 s2, s88, 5
	v_readlane_b32 s0, v254, 51
	v_add3_u32 v85, v46, s2, v47
	s_lshl_b32 s2, s89, 5
	v_readlane_b32 s1, v254, 52
	s_or_b64 s[74:75], vcc, s[84:85]
	v_add3_u32 v83, v46, s2, v47
	s_waitcnt lgkmcnt(0)
	v_readfirstlane_b32 s2, v38
	s_lshl_b64 s[0:1], s[0:1], 2
	v_readfirstlane_b32 s3, v39
	s_add_u32 s2, s2, s0
	v_lshlrev_b32_e32 v3, 16, v43
	v_and_b32_e32 v59, 0xffff0000, v43
	v_lshlrev_b32_e32 v60, 16, v44
	v_and_b32_e32 v62, 0xffff0000, v44
	v_lshlrev_b32_e32 v61, 16, v45
	v_and_b32_e32 v63, 0xffff0000, v45
	s_addc_u32 s3, s3, s1
	v_lshlrev_b32_e32 v0, 2, v0
	v_mov_b32_e32 v44, v67
	v_mov_b32_e32 v45, v65
	v_lshlrev_b32_e32 v2, 16, v42
	v_and_b32_e32 v58, 0xffff0000, v42
	v_lshl_add_u64 v[38:39], s[2:3], 0, v[0:1]
	v_mov_b32_e32 v42, v59
	v_mov_b32_e32 v43, v3
	v_pk_mul_f32 v[44:45], v[44:45], v[44:45]
	global_load_dwordx4 v[46:49], v[38:39], off offset:128
	v_pk_fma_f32 v[72:73], v[42:43], v[42:43], v[44:45]
	global_load_dwordx4 v[42:45], v[38:39], off
	global_load_dwordx4 v[50:53], v[38:39], off offset:16
	global_load_dwordx4 v[54:57], v[38:39], off offset:144
	v_mul_f32_e32 v38, v58, v58
	v_mul_f32_e32 v39, v2, v2
	v_fmac_f32_e32 v38, v66, v66
	v_fmac_f32_e32 v39, v64, v64
	v_mov_b32_e32 v104, v18
	v_mov_b32_e32 v105, v20
	v_mov_b32_e32 v20, v19
	v_mov_b32_e32 v18, v70
	v_mov_b32_e32 v19, v68
	v_add_f32_e32 v38, v39, v38
	v_mov_b32_e32 v102, v10
	v_mov_b32_e32 v103, v12
	v_mov_b32_e32 v12, v11
	v_mov_b32_e32 v10, v62
	v_mov_b32_e32 v11, v60
	v_pk_mul_f32 v[18:19], v[18:19], v[18:19]
	v_add_f32_e32 v38, v73, v38
	v_pk_fma_f32 v[10:11], v[10:11], v[10:11], v[18:19]
	v_add_f32_e32 v38, v72, v38
	v_mov_b32_e32 v18, v63
	v_mov_b32_e32 v19, v61
	v_add_f32_e32 v11, v11, v38
	v_add_f32_e32 v10, v10, v11
	s_mov_b32 s2, 0xf800000
	v_readfirstlane_b32 s49, v40
	v_writelane_b32 v255, s12, 14
	s_mov_b32 s94, 0xf149f2ca
	s_mov_b64 s[84:85], s[8:9]
	v_writelane_b32 v255, s13, 15
	v_writelane_b32 v255, s18, 16
	s_mov_b64 s[82:83], s[10:11]
	s_waitcnt vmcnt(0) lgkmcnt(0)
	v_mov_b32_e32 v76, v46
	v_mov_b32_e32 v77, v48
	v_mov_b32_e32 v74, v42
	v_mov_b32_e32 v75, v44
	v_mov_b32_e32 v44, v43
	v_mov_b32_e32 v42, v71
	v_mov_b32_e32 v43, v69
	v_pk_mul_f32 v[42:43], v[42:43], v[42:43]
	v_mov_b32_e32 v48, v47
	v_pk_fma_f32 v[18:19], v[18:19], v[18:19], v[42:43]
	v_writelane_b32 v255, s19, 17
	v_add_f32_e32 v10, v19, v10
	v_add_f32_e32 v10, v18, v10
	ds_bpermute_b32 v11, v109, v10
	v_writelane_b32 v255, s16, 18
	s_waitcnt lgkmcnt(0)
	v_add_f32_e32 v10, v10, v11
	ds_bpermute_b32 v11, v110, v10
	v_writelane_b32 v255, s17, 19
	v_writelane_b32 v255, s70, 20
	s_waitcnt lgkmcnt(0)
	v_add_f32_e32 v10, v10, v11
	v_fmamk_f32 v10, v10, 0x3c800000, v219
	v_cmp_gt_f32_e32 vcc, s2, v10
	v_mul_f32_e32 v11, 0x4f800000, v10
	v_writelane_b32 v255, s71, 21
	v_cndmask_b32_e32 v10, v10, v11, vcc
	v_sqrt_f32_e32 v11, v10
	s_nop 0
	v_add_u32_e32 v18, -1, v11
	v_fma_f32 v19, -v18, v11, v10
	v_cmp_ge_f32_e64 s[88:89], 0, v19
	v_add_u32_e32 v19, 1, v11
	s_nop 0
	v_cndmask_b32_e64 v18, v11, v18, s[88:89]
	v_fma_f32 v11, -v19, v11, v10
	v_cmp_lt_f32_e64 s[88:89], 0, v11
	s_nop 1
	v_cndmask_b32_e64 v11, v18, v19, s[88:89]
	v_mul_f32_e32 v18, 0x37800000, v11
	v_cndmask_b32_e32 v11, v11, v18, vcc
	v_cmp_class_f32_e32 vcc, v10, v221
	v_readfirstlane_b32 s88, v41
	s_nop 0
	v_cndmask_b32_e32 v10, v11, v10, vcc
	v_div_scale_f32 v11, s[2:3], v10, v10, 1.0
	v_rcp_f32_e32 v18, v11
	s_add_i32 s2, s48, s93
	s_ashr_i32 s3, s2, 31
	s_lshl_b64 s[2:3], s[2:3], 2
	v_fma_f32 v19, -v11, v18, 1.0
	v_fmac_f32_e32 v18, v19, v18
	v_div_scale_f32 v19, vcc, 1.0, v10, 1.0
	v_mul_f32_e32 v38, v19, v18
	v_fma_f32 v39, -v11, v38, v19
	v_fmac_f32_e32 v38, v39, v18
	v_fma_f32 v11, -v11, v38, v19
	v_div_fmas_f32 v11, v11, v18, v38
	v_div_fixup_f32 v10, v11, v10, 1.0
	v_pk_mul_f32 v[18:19], v[10:11], v[64:65] op_sel_hi:[0,1]
	v_pk_mul_f32 v[38:39], v[76:77], v[18:19]
	v_pk_mul_f32 v[18:19], v[10:11], v[58:59] op_sel_hi:[0,1]
	v_pk_mul_f32 v[2:3], v[10:11], v[2:3] op_sel_hi:[0,1]
	v_pk_mul_f32 v[42:43], v[18:19], v[44:45]
	v_pk_mul_f32 v[18:19], v[10:11], v[66:67] op_sel_hi:[0,1]
	v_pk_mul_f32 v[2:3], v[74:75], v[2:3]
	v_pk_mul_f32 v[44:45], v[18:19], v[48:49]
	v_pk_mul_f32 v[18:19], v[102:103], v[38:39]
	v_mov_b32_e32 v58, v50
	v_pk_fma_f32 v[18:19], v[104:105], v[2:3], v[18:19]
	v_mov_b32_e32 v59, v52
	v_pk_mul_f32 v[46:47], v[18:19], s[86:87] op_sel_hi:[1,0]
	v_pk_mul_f32 v[18:19], v[12:13], v[44:45]
	v_mov_b32_e32 v52, v51
	v_pk_fma_f32 v[18:19], v[20:21], v[42:43], v[18:19]
	s_add_u32 s48, s49, s2
	v_pk_mul_f32 v[48:49], v[18:19], s[86:87] op_sel_hi:[1,0]
	v_pk_mul_f32 v[18:19], v[10:11], v[60:61] op_sel_hi:[0,1]
	v_pk_mul_f32 v[58:59], v[18:19], v[58:59]
	v_pk_mul_f32 v[18:19], v[10:11], v[68:69] op_sel_hi:[0,1]
	v_mov_b32_e32 v60, v54
	v_mov_b32_e32 v61, v56
	v_pk_mul_f32 v[60:61], v[18:19], v[60:61]
	v_pk_mul_f32 v[18:19], v[10:11], v[62:63] op_sel_hi:[0,1]
	v_pk_mul_f32 v[50:51], v[18:19], v[52:53]
	v_pk_mul_f32 v[10:11], v[10:11], v[70:71] op_sel_hi:[0,1]
	v_mov_b32_e32 v56, v55
	v_mov_b32_e32 v18, v14
	v_mov_b32_e32 v19, v16
	v_mov_b32_e32 v16, v15
	v_pk_mul_f32 v[14:15], v[104:105], v[38:39]
	v_pk_mul_f32 v[52:53], v[10:11], v[56:57]
	v_pk_fma_f32 v[2:3], v[102:103], v[2:3], v[14:15] neg_lo:[0,0,1] neg_hi:[0,0,1]
	v_pk_mul_f32 v[14:15], v[20:21], v[44:45]
	v_mov_b32_e32 v10, v6
	v_mov_b32_e32 v11, v8
	v_mov_b32_e32 v8, v7
	v_pk_fma_f32 v[14:15], v[12:13], v[42:43], v[14:15] neg_lo:[0,0,1] neg_hi:[0,0,1]
	v_pk_mul_f32 v[38:39], v[18:19], v[60:61]
	v_pk_mul_f32 v[42:43], v[16:17], v[52:53]
	v_pk_mul_f32 v[6:7], v[8:9], v[52:53]
	v_pk_mul_f32 v[14:15], v[14:15], s[86:87] op_sel_hi:[1,0]
	v_pk_fma_f32 v[38:39], v[10:11], v[58:59], v[38:39] neg_lo:[0,0,1] neg_hi:[0,0,1]
	v_pk_fma_f32 v[42:43], v[8:9], v[50:51], v[42:43] neg_lo:[0,0,1] neg_hi:[0,0,1]
	v_pk_fma_f32 v[6:7], v[16:17], v[50:51], v[6:7]
	v_pk_mul_f32 v[38:39], v[38:39], s[86:87] op_sel_hi:[1,0]
	v_pk_mul_f32 v[42:43], v[42:43], s[86:87] op_sel_hi:[1,0]
	v_bfe_u32 v50, v15, 16, 1
	v_bfe_u32 v51, v14, 16, 1
	v_pk_mul_f32 v[54:55], v[10:11], v[60:61]
	v_pk_mul_f32 v[2:3], v[2:3], s[86:87] op_sel_hi:[1,0]
	v_bfe_u32 v44, v43, 16, 1
	v_bfe_u32 v45, v42, 16, 1
	v_add3_u32 v14, v14, v51, s91
	v_add3_u32 v15, v15, v50, s91
	v_bfe_u32 v50, v38, 16, 1
	v_bfe_u32 v51, v39, 16, 1
	v_pk_fma_f32 v[54:55], v[18:19], v[58:59], v[54:55]
	v_add3_u32 v42, v42, v45, s91
	v_add3_u32 v43, v43, v44, s91
	v_bfe_u32 v44, v2, 16, 1
	v_bfe_u32 v45, v3, 16, 1
	v_add3_u32 v39, v39, v51, s91
	v_add3_u32 v38, v38, v50, s91
	v_pk_mul_f32 v[54:55], v[54:55], s[86:87] op_sel_hi:[1,0]
	v_add3_u32 v3, v3, v45, s91
	v_add3_u32 v2, v2, v44, s91
	v_lshrrev_b32_e32 v38, 16, v38
	v_lshrrev_b32_e32 v39, 16, v39
	v_pk_mul_f32 v[6:7], v[6:7], s[86:87] op_sel_hi:[1,0]
	v_lshrrev_b32_e32 v2, 16, v2
	v_lshrrev_b32_e32 v3, 16, v3
	v_and_or_b32 v115, v43, s33, v39
	v_and_or_b32 v114, v42, s33, v38
	v_bfe_u32 v38, v54, 16, 1
	v_bfe_u32 v39, v55, 16, 1
	v_and_or_b32 v113, v15, s33, v3
	v_and_or_b32 v112, v14, s33, v2
	v_bfe_u32 v2, v7, 16, 1
	v_bfe_u32 v3, v6, 16, 1
	v_add3_u32 v39, v55, v39, s91
	v_add3_u32 v38, v54, v38, s91
	v_add3_u32 v3, v6, v3, s91
	v_add3_u32 v2, v7, v2, s91
	v_lshrrev_b32_e32 v38, 16, v38
	v_lshrrev_b32_e32 v39, 16, v39
	v_and_or_b32 v119, v2, s33, v39
	v_and_or_b32 v118, v3, s33, v38
	ds_read_b128 v[38:41], v100
	ds_read_b128 v[42:45], v100 offset:64
	v_bfe_u32 v6, v46, 16, 1
	v_bfe_u32 v7, v47, 16, 1
	s_waitcnt lgkmcnt(1)
	v_mfma_f32_16x16x32_bf16 v[38:41], v[38:41], v[112:115], 0
	v_bfe_u32 v14, v49, 16, 1
	v_bfe_u32 v15, v48, 16, 1
	v_add3_u32 v7, v47, v7, s91
	v_add3_u32 v6, v46, v6, s91
	v_add3_u32 v15, v48, v15, s91
	v_add3_u32 v14, v49, v14, s91
	v_lshrrev_b32_e32 v6, 16, v6
	v_lshrrev_b32_e32 v7, 16, v7
	v_and_or_b32 v117, v14, s33, v7
	v_and_or_b32 v116, v15, s33, v6
	s_addc_u32 s49, s88, s3
	s_nop 1
	v_mov_b64_e32 v[148:149], s[48:49]
	global_load_dword v150, v[148:149], off
	v_mov_b64_e32 v[2:3], s[48:49]
	s_waitcnt lgkmcnt(0)
	v_mfma_f32_16x16x32_bf16 v[74:77], v[42:45], v[116:119], v[38:41]
	ds_read_b128 v[42:45], v98 offset:64
	s_waitcnt vmcnt(0)
	s_nop 0
	v_mov_b32_e32 v3, v150
	s_nop 1
	v_mov_b32_e32 v2, s94
	ds_read_b128 v[38:41], v98
	s_waitcnt lgkmcnt(0)
	v_mfma_f32_16x16x32_bf16 v[38:41], v[38:41], v[112:115], 0
	s_nop 1
	v_cndmask_b32_e64 v15, v74, v2, s[40:41]
	s_mov_b64 s[40:41], s[42:43]
	v_mfma_f32_16x16x32_bf16 v[70:73], v[42:45], v[116:119], v[38:41]
	ds_read_b128 v[42:45], v96 offset:64
	v_writelane_b32 v255, s40, 22
	v_cndmask_b32_e64 v14, v75, v227, s[42:43]
	ds_read_b128 v[38:41], v96
	s_waitcnt lgkmcnt(0)
	v_mfma_f32_16x16x32_bf16 v[38:41], v[38:41], v[112:115], 0
	v_writelane_b32 v255, s41, 23
	v_max3_f32 v2, v15, s94, v14
	v_readlane_b32 s80, v255, 2
	v_mfma_f32_16x16x32_bf16 v[66:69], v[42:45], v[116:119], v[38:41]
	ds_read_b128 v[42:45], v94 offset:64
	v_readlane_b32 s42, v255, 4
	v_readlane_b32 s81, v255, 3
	s_nop 0
	ds_read_b128 v[38:41], v94
	s_waitcnt lgkmcnt(0)
	v_mfma_f32_16x16x32_bf16 v[38:41], v[38:41], v[112:115], 0
	v_readlane_b32 s43, v255, 5
	v_cndmask_b32_e64 v7, v76, v227, s[80:81]
	v_mfma_f32_16x16x32_bf16 v[62:65], v[42:45], v[116:119], v[38:41]
	ds_read_b128 v[42:45], v92 offset:64
	v_cndmask_b32_e64 v6, v77, v227, s[42:43]
	v_readlane_b32 s48, v255, 6
	s_nop 1
	ds_read_b128 v[38:41], v92
	s_waitcnt lgkmcnt(0)
	v_mfma_f32_16x16x32_bf16 v[38:41], v[38:41], v[112:115], 0
	v_max3_f32 v76, v2, v7, v6
	v_mov_b32_e32 v2, s94
	v_readlane_b32 s49, v255, 7
	v_mfma_f32_16x16x32_bf16 v[58:61], v[42:45], v[116:119], v[38:41]
	ds_read_b128 v[42:45], v90 offset:64
	v_cndmask_b32_e64 v75, v70, v2, s[48:49]
	v_cndmask_b32_e64 v74, v71, v227, s[6:7]
	s_nop 0
	ds_read_b128 v[38:41], v90
	s_waitcnt lgkmcnt(0)
	v_mfma_f32_16x16x32_bf16 v[38:41], v[38:41], v[112:115], 0
	v_max3_f32 v2, v76, v75, v74
	v_cndmask_b32_e64 v71, v72, v227, s[4:5]
	v_mfma_f32_16x16x32_bf16 v[54:57], v[42:45], v[116:119], v[38:41]
	ds_read_b128 v[42:45], v88 offset:64
	v_cndmask_b32_e64 v70, v73, v227, s[44:45]
	v_readlane_b32 s4, v255, 12
	s_nop 1
	ds_read_b128 v[38:41], v88
	s_waitcnt lgkmcnt(0)
	v_mfma_f32_16x16x32_bf16 v[38:41], v[38:41], v[112:115], 0
	v_max3_f32 v76, v2, v71, v70
	v_mov_b32_e32 v2, s94
	v_readlane_b32 s5, v255, 13
	v_mfma_f32_16x16x32_bf16 v[50:53], v[42:45], v[116:119], v[38:41]
	ds_read_b128 v[42:45], v86 offset:64
	v_cndmask_b32_e64 v73, v66, v2, s[4:5]
	v_cndmask_b32_e64 v72, v67, v227, s[12:13]
	s_nop 0
	ds_read_b128 v[38:41], v86
	s_waitcnt lgkmcnt(0)
	v_mfma_f32_16x16x32_bf16 v[38:41], v[38:41], v[112:115], 0
	v_max3_f32 v2, v76, v73, v72
	v_cndmask_b32_e64 v67, v68, v227, s[10:11]
	v_mfma_f32_16x16x32_bf16 v[46:49], v[42:45], v[116:119], v[38:41]
	ds_read_b128 v[42:45], v84 offset:64
	v_cndmask_b32_e64 v66, v69, v227, s[8:9]
	v_max3_f32 v76, v2, v67, v66
	s_nop 1
	ds_read_b128 v[38:41], v84
	s_waitcnt lgkmcnt(0)
	v_mfma_f32_16x16x32_bf16 v[38:41], v[38:41], v[112:115], 0
	v_mov_b32_e32 v2, s94
	v_cndmask_b32_e64 v69, v62, v2, s[20:21]
	v_cndmask_b32_e64 v68, v63, v227, s[18:19]
	v_mfma_f32_16x16x32_bf16 v[42:45], v[42:45], v[116:119], v[38:41]
	v_max3_f32 v2, v76, v69, v68
	v_cndmask_b32_e64 v63, v64, v227, s[16:17]
	v_cndmask_b32_e64 v62, v65, v227, s[14:15]
	s_nop 0
	ds_read_b128 v[38:41], v82
	v_max3_f32 v76, v2, v63, v62
	v_mov_b32_e32 v2, s94
	v_cndmask_b32_e64 v65, v58, v2, s[28:29]
	v_cndmask_b32_e64 v64, v59, v227, s[24:25]
	v_max3_f32 v2, v76, v65, v64
	v_cndmask_b32_e64 v59, v60, v227, s[22:23]
	v_cndmask_b32_e64 v58, v61, v227, s[26:27]
	s_waitcnt lgkmcnt(0)
	v_mfma_f32_16x16x32_bf16 v[38:41], v[38:41], v[112:115], 0
	ds_read_b128 v[112:115], v82 offset:64
	v_max3_f32 v76, v2, v59, v58
	v_mov_b32_e32 v2, s94
	v_cndmask_b32_e64 v61, v54, v2, s[38:39]
	v_cndmask_b32_e64 v60, v55, v227, s[30:31]
	v_max3_f32 v2, v76, v61, v60
	v_cndmask_b32_e64 v55, v56, v227, s[34:35]
	v_cndmask_b32_e64 v54, v57, v227, s[36:37]
	v_max3_f32 v76, v2, v55, v54
	v_mov_b32_e32 v2, s94
	v_cndmask_b32_e64 v57, v50, v2, s[54:55]
	v_cndmask_b32_e64 v56, v51, v227, s[46:47]
	v_max3_f32 v2, v76, v57, v56
	v_cndmask_b32_e64 v51, v52, v227, s[50:51]
	v_cndmask_b32_e64 v50, v53, v227, s[52:53]
	v_max3_f32 v76, v2, v51, v50
	v_mov_b32_e32 v2, s94
	v_cndmask_b32_e64 v53, v46, v2, s[62:63]
	v_cndmask_b32_e64 v52, v47, v227, s[56:57]
	v_max3_f32 v2, v76, v53, v52
	v_cndmask_b32_e64 v47, v48, v227, s[58:59]
	v_cndmask_b32_e64 v46, v49, v227, s[60:61]
	s_waitcnt lgkmcnt(0)
	v_mfma_f32_16x16x32_bf16 v[38:41], v[112:115], v[116:119], v[38:41]
	v_max3_f32 v76, v2, v47, v46
	v_mov_b32_e32 v2, s94
	v_cndmask_b32_e64 v49, v42, v2, s[70:71]
	v_cndmask_b32_e64 v48, v43, v227, s[64:65]
	v_max3_f32 v2, v76, v49, v48
	v_cndmask_b32_e64 v43, v44, v227, s[66:67]
	v_cndmask_b32_e64 v42, v45, v227, s[68:69]
	s_mov_b64 s[4:5], s[24:25]
	v_max3_f32 v44, v2, v43, v42
	v_mov_b32_e32 v2, s94
	s_mov_b64 s[24:25], s[78:79]
	s_mov_b64 s[70:71], s[76:77]
	v_cndmask_b32_e64 v2, v38, v2, s[24:25]
	v_cndmask_b32_e64 v38, v39, v227, s[70:71]
	v_max3_f32 v39, v44, v2, v38
	v_cndmask_b32_e64 v40, v40, v227, s[72:73]
	v_cndmask_b32_e64 v41, v41, v227, s[74:75]
	v_max3_f32 v39, v39, v40, v41
	ds_bpermute_b32 v44, v109, v39
	s_mov_b32 s93, s95
	s_mov_b32 s6, 0xf800000
	v_readlane_b32 s8, v255, 0
	s_waitcnt lgkmcnt(0)
	v_max_f32_e32 v44, v44, v44
	v_max_f32_e32 v39, v39, v44
	ds_bpermute_b32 v44, v110, v39
	v_readlane_b32 s9, v255, 1
	v_readlane_b32 s18, v255, 6
	v_readlane_b32 s10, v255, 8
	v_readlane_b32 s19, v255, 7
	s_waitcnt vmcnt(0) lgkmcnt(0)
	v_max3_f32 v39, v39, v44, v3
	v_sub_f32_e32 v15, v15, v39
	v_mul_f32_e32 v15, 0x3fb8aa3b, v15
	v_sub_f32_e32 v14, v14, v39
	v_exp_f32_e32 v15, v15
	v_mul_f32_e32 v14, 0x3fb8aa3b, v14
	v_sub_f32_e32 v7, v7, v39
	v_exp_f32_e32 v14, v14
	v_mul_f32_e32 v7, 0x3fb8aa3b, v7
	v_sub_f32_e32 v6, v6, v39
	v_exp_f32_e32 v7, v7
	v_mul_f32_e32 v6, 0x3fb8aa3b, v6
	v_sub_f32_e32 v45, v75, v39
	v_exp_f32_e32 v6, v6
	v_mul_f32_e32 v45, 0x3fb8aa3b, v45
	v_sub_f32_e32 v74, v74, v39
	v_add_f32_e32 v44, 0, v15
	v_exp_f32_e32 v45, v45
	v_mul_f32_e32 v74, 0x3fb8aa3b, v74
	v_sub_f32_e32 v71, v71, v39
	v_add_f32_e32 v44, v14, v44
	v_exp_f32_e32 v74, v74
	v_mul_f32_e32 v71, 0x3fb8aa3b, v71
	v_sub_f32_e32 v70, v70, v39
	v_add_f32_e32 v44, v7, v44
	v_exp_f32_e32 v71, v71
	v_mul_f32_e32 v70, 0x3fb8aa3b, v70
	v_sub_f32_e32 v73, v73, v39
	v_add_f32_e32 v44, v6, v44
	v_exp_f32_e32 v70, v70
	v_mul_f32_e32 v73, 0x3fb8aa3b, v73
	v_sub_f32_e32 v72, v72, v39
	v_add_f32_e32 v44, v45, v44
	v_exp_f32_e32 v75, v73
	v_mul_f32_e32 v72, 0x3fb8aa3b, v72
	v_sub_f32_e32 v67, v67, v39
	v_add_f32_e32 v44, v74, v44
	v_exp_f32_e32 v76, v72
	v_mul_f32_e32 v67, 0x3fb8aa3b, v67
	v_sub_f32_e32 v66, v66, v39
	v_add_f32_e32 v44, v71, v44
	v_exp_f32_e32 v67, v67
	v_mul_f32_e32 v66, 0x3fb8aa3b, v66
	v_sub_f32_e32 v69, v69, v39
	v_add_f32_e32 v44, v70, v44
	v_exp_f32_e32 v66, v66
	v_mul_f32_e32 v69, 0x3fb8aa3b, v69
	v_sub_f32_e32 v68, v68, v39
	v_add_f32_e32 v44, v75, v44
	v_exp_f32_e32 v69, v69
	v_mul_f32_e32 v68, 0x3fb8aa3b, v68
	v_sub_f32_e32 v63, v63, v39
	v_add_f32_e32 v44, v76, v44
	v_exp_f32_e32 v68, v68
	v_mul_f32_e32 v63, 0x3fb8aa3b, v63
	v_sub_f32_e32 v62, v62, v39
	v_add_f32_e32 v44, v67, v44
	v_exp_f32_e32 v63, v63
	v_mul_f32_e32 v62, 0x3fb8aa3b, v62
	v_sub_f32_e32 v65, v65, v39
	v_add_f32_e32 v44, v66, v44
	v_exp_f32_e32 v62, v62
	v_mul_f32_e32 v65, 0x3fb8aa3b, v65
	v_sub_f32_e32 v64, v64, v39
	v_sub_f32_e32 v58, v58, v39
	v_add_f32_e32 v44, v69, v44
	v_exp_f32_e32 v65, v65
	v_mul_f32_e32 v64, 0x3fb8aa3b, v64
	v_sub_f32_e32 v59, v59, v39
	v_mul_f32_e32 v58, 0x3fb8aa3b, v58
	v_add_f32_e32 v44, v68, v44
	v_exp_f32_e32 v64, v64
	v_mul_f32_e32 v59, 0x3fb8aa3b, v59
	v_exp_f32_e32 v93, v58
	v_sub_f32_e32 v58, v61, v39
	v_add_f32_e32 v44, v63, v44
	v_exp_f32_e32 v77, v59
	v_mul_f32_e32 v58, 0x3fb8aa3b, v58
	v_add_f32_e32 v44, v62, v44
	v_exp_f32_e32 v95, v58
	v_sub_f32_e32 v58, v60, v39
	v_sub_f32_e32 v54, v54, v39
	v_add_f32_e32 v44, v65, v44
	v_mul_f32_e32 v58, 0x3fb8aa3b, v58
	v_sub_f32_e32 v55, v55, v39
	v_mul_f32_e32 v54, 0x3fb8aa3b, v54
	v_add_f32_e32 v44, v64, v44
	v_exp_f32_e32 v97, v58
	v_mul_f32_e32 v55, 0x3fb8aa3b, v55
	v_exp_f32_e32 v101, v54
	v_sub_f32_e32 v54, v57, v39
	v_add_f32_e32 v44, v77, v44
	v_exp_f32_e32 v99, v55
	v_mul_f32_e32 v54, 0x3fb8aa3b, v54
	v_add_f32_e32 v44, v93, v44
	v_exp_f32_e32 v111, v54
	v_sub_f32_e32 v54, v56, v39
	v_sub_f32_e32 v50, v50, v39
	v_add_f32_e32 v44, v95, v44
	v_mul_f32_e32 v54, 0x3fb8aa3b, v54
	v_sub_f32_e32 v51, v51, v39
	v_mul_f32_e32 v50, 0x3fb8aa3b, v50
	v_add_f32_e32 v44, v97, v44
	v_exp_f32_e32 v112, v54
	v_mul_f32_e32 v51, 0x3fb8aa3b, v51
	v_exp_f32_e32 v114, v50
	v_sub_f32_e32 v50, v53, v39
	v_add_f32_e32 v44, v99, v44
	v_exp_f32_e32 v113, v51
	v_mul_f32_e32 v50, 0x3fb8aa3b, v50
	v_add_f32_e32 v44, v101, v44
	v_exp_f32_e32 v115, v50
	v_sub_f32_e32 v50, v52, v39
	v_sub_f32_e32 v46, v46, v39
	v_add_f32_e32 v44, v111, v44
	v_mul_f32_e32 v50, 0x3fb8aa3b, v50
	v_sub_f32_e32 v47, v47, v39
	v_mul_f32_e32 v46, 0x3fb8aa3b, v46
	v_add_f32_e32 v44, v112, v44
	v_exp_f32_e32 v116, v50
	v_mul_f32_e32 v47, 0x3fb8aa3b, v47
	v_exp_f32_e32 v118, v46
	v_sub_f32_e32 v46, v49, v39
	v_add_f32_e32 v44, v113, v44
	v_exp_f32_e32 v117, v47
	v_mul_f32_e32 v46, 0x3fb8aa3b, v46
	v_add_f32_e32 v44, v114, v44
	v_exp_f32_e32 v119, v46
	v_sub_f32_e32 v46, v48, v39
	v_add_f32_e32 v44, v115, v44
	v_mul_f32_e32 v46, 0x3fb8aa3b, v46
	v_sub_f32_e32 v43, v43, v39
	v_add_f32_e32 v44, v116, v44
	v_exp_f32_e32 v120, v46
	v_mul_f32_e32 v43, 0x3fb8aa3b, v43
	v_sub_f32_e32 v42, v42, v39
	v_sub_f32_e32 v38, v38, v39
	v_add_f32_e32 v44, v117, v44
	v_exp_f32_e32 v121, v43
	v_mul_f32_e32 v42, 0x3fb8aa3b, v42
	v_sub_f32_e32 v2, v2, v39
	v_mul_f32_e32 v38, 0x3fb8aa3b, v38
	v_add_f32_e32 v44, v118, v44
	v_exp_f32_e32 v122, v42
	v_mul_f32_e32 v2, 0x3fb8aa3b, v2
	v_exp_f32_e32 v124, v38
	v_sub_f32_e32 v38, v40, v39
	v_add_f32_e32 v44, v119, v44
	v_exp_f32_e32 v123, v2
	v_mul_f32_e32 v38, 0x3fb8aa3b, v38
	v_add_f32_e32 v44, v120, v44
	v_exp_f32_e32 v125, v38
	v_sub_f32_e32 v38, v41, v39
	v_add_f32_e32 v43, v121, v44
	v_mul_f32_e32 v38, 0x3fb8aa3b, v38
	v_add_f32_e32 v42, v122, v43
	v_exp_f32_e32 v126, v38
	v_add_f32_e32 v2, v123, v42
	v_add_f32_e32 v2, v124, v2
	v_add_f32_e32 v2, v125, v2
	v_add_f32_e32 v2, v126, v2
	ds_bpermute_b32 v38, v109, v2
	v_sub_f32_e32 v3, v3, v39
	v_mul_f32_e32 v3, 0x3fb8aa3b, v3
	v_exp_f32_e32 v3, v3
	v_bfe_u32 v40, v14, 16, 1
	s_waitcnt lgkmcnt(0)
	v_add_f32_e32 v2, v2, v38
	ds_bpermute_b32 v38, v110, v2
	v_bfe_u32 v42, v71, 16, 1
	v_add3_u32 v14, v14, v40, s91
	v_bfe_u32 v40, v7, 16, 1
	v_bfe_u32 v41, v45, 16, 1
	s_waitcnt lgkmcnt(0)
	v_add_f32_e32 v2, v2, v38
	v_add_f32_e32 v2, v3, v2
	v_bfe_u32 v3, v70, 16, 1
	v_add3_u32 v3, v70, v3, s91
	v_add3_u32 v42, v71, v42, s91
	v_add_u32_e32 v73, 0x9000, v91
	v_add_u32_e32 v72, 0xb000, v91
	v_add_u32_e32 v71, 0xd000, v91
	v_add_u32_e32 v70, 0xf000, v91
	v_add3_u32 v41, v45, v41, s91
	v_add3_u32 v7, v7, v40, s91
	v_lshrrev_b32_e32 v40, 16, v42
	ds_read2_b64 v[42:45], v73 offset1:4
	ds_read2_b64 v[46:49], v72 offset0:32 offset1:36
	ds_read2_b64 v[50:53], v71 offset0:64 offset1:68
	ds_read2_b64 v[54:57], v70 offset0:96 offset1:100
	v_bfe_u32 v39, v6, 16, 1
	v_add3_u32 v6, v6, v39, s91
	v_bfe_u32 v39, v15, 16, 1
	v_bfe_u32 v38, v74, 16, 1
	v_add3_u32 v15, v15, v39, s91
	v_add3_u32 v38, v74, v38, s91
	v_lshrrev_b32_e32 v15, 16, v15
	v_lshrrev_b32_e32 v7, 16, v7
	v_lshrrev_b32_e32 v39, 16, v41
	v_and_or_b32 v41, v3, s33, v40
	v_and_or_b32 v40, v38, s33, v39
	v_and_or_b32 v39, v6, s33, v7
	v_and_or_b32 v38, v14, s33, v15
	v_bfe_u32 v15, v75, 16, 1
	v_bfe_u32 v3, v62, 16, 1
	s_waitcnt lgkmcnt(3)
	v_mfma_f32_16x16x32_bf16 v[42:45], v[42:45], v[38:41], 0
	v_bfe_u32 v6, v68, 16, 1
	v_bfe_u32 v7, v66, 16, 1
	v_bfe_u32 v14, v76, 16, 1
	s_waitcnt lgkmcnt(2)
	v_mfma_f32_16x16x32_bf16 v[46:49], v[46:49], v[38:41], 0
	v_add3_u32 v15, v75, v15, s91
	v_add3_u32 v14, v76, v14, s91
	v_add3_u32 v7, v66, v7, s91
	s_waitcnt lgkmcnt(1)
	v_mfma_f32_16x16x32_bf16 v[50:53], v[50:53], v[38:41], 0
	v_add3_u32 v6, v68, v6, s91
	v_add3_u32 v3, v62, v3, s91
	v_lshrrev_b32_e32 v15, 16, v15
	s_waitcnt lgkmcnt(0)
	v_mfma_f32_16x16x32_bf16 v[38:41], v[54:57], v[38:41], 0
	v_bfe_u32 v55, v69, 16, 1
	v_add3_u32 v55, v69, v55, s91
	v_add_u32_e32 v69, 0x9000, v89
	ds_read2_b64 v[58:61], v69 offset1:4
	v_bfe_u32 v54, v67, 16, 1
	v_bfe_u32 v56, v63, 16, 1
	v_add3_u32 v56, v63, v56, s91
	v_add3_u32 v54, v67, v54, s91
	v_lshrrev_b32_e32 v54, 16, v54
	v_lshrrev_b32_e32 v55, 16, v55
	v_lshrrev_b32_e32 v56, 16, v56
	v_and_or_b32 v57, v3, s33, v56
	v_and_or_b32 v56, v6, s33, v55
	v_and_or_b32 v55, v7, s33, v54
	v_and_or_b32 v54, v14, s33, v15
	v_add_u32_e32 v68, 0xb000, v89
	v_add_u32_e32 v67, 0xd000, v89
	s_waitcnt lgkmcnt(0)
	v_mfma_f32_16x16x32_bf16 v[42:45], v[58:61], v[54:57], v[42:45]
	ds_read2_b64 v[58:61], v68 offset0:32 offset1:36
	v_add_u32_e32 v66, 0xf000, v89
	v_bfe_u32 v15, v65, 16, 1
	s_waitcnt lgkmcnt(0)
	v_mfma_f32_16x16x32_bf16 v[46:49], v[58:61], v[54:57], v[46:49]
	ds_read2_b64 v[58:61], v67 offset0:64 offset1:68
	v_add3_u32 v15, v65, v15, s91
	v_add_u32_e32 v65, 0x9000, v87
	s_waitcnt lgkmcnt(0)
	v_mfma_f32_16x16x32_bf16 v[50:53], v[58:61], v[54:57], v[50:53]
	ds_read2_b64 v[58:61], v66 offset0:96 offset1:100
	v_bfe_u32 v3, v101, 16, 1
	s_waitcnt lgkmcnt(0)
	v_mfma_f32_16x16x32_bf16 v[38:41], v[58:61], v[54:57], v[38:41]
	ds_read2_b64 v[58:61], v65 offset1:4
	v_bfe_u32 v54, v77, 16, 1
	v_bfe_u32 v55, v95, 16, 1
	v_bfe_u32 v56, v99, 16, 1
	v_bfe_u32 v6, v97, 16, 1
	v_bfe_u32 v7, v93, 16, 1
	v_bfe_u32 v14, v64, 16, 1
	v_add3_u32 v56, v99, v56, s91
	v_add3_u32 v55, v95, v55, s91
	v_add3_u32 v54, v77, v54, s91
	v_add3_u32 v14, v64, v14, s91
	v_add3_u32 v7, v93, v7, s91
	v_add3_u32 v6, v97, v6, s91
	v_add3_u32 v3, v101, v3, s91
	v_lshrrev_b32_e32 v15, 16, v15
	v_lshrrev_b32_e32 v54, 16, v54
	v_lshrrev_b32_e32 v55, 16, v55
	v_lshrrev_b32_e32 v56, 16, v56
	v_and_or_b32 v57, v3, s33, v56
	v_and_or_b32 v56, v6, s33, v55
	v_and_or_b32 v55, v7, s33, v54
	v_and_or_b32 v54, v14, s33, v15
	v_add_u32_e32 v64, 0xb000, v87
	v_add_u32_e32 v63, 0xd000, v87
	s_waitcnt lgkmcnt(0)
	v_mfma_f32_16x16x32_bf16 v[42:45], v[58:61], v[54:57], v[42:45]
	ds_read2_b64 v[58:61], v64 offset0:32 offset1:36
	v_add_u32_e32 v62, 0xf000, v87
	v_bfe_u32 v15, v111, 16, 1
	s_waitcnt lgkmcnt(0)
	v_mfma_f32_16x16x32_bf16 v[46:49], v[58:61], v[54:57], v[46:49]
	ds_read2_b64 v[58:61], v63 offset0:64 offset1:68
	v_bfe_u32 v3, v118, 16, 1
	v_bfe_u32 v6, v116, 16, 1
	s_waitcnt lgkmcnt(0)
	v_mfma_f32_16x16x32_bf16 v[50:53], v[58:61], v[54:57], v[50:53]
	ds_read2_b64 v[58:61], v62 offset0:96 offset1:100
	v_bfe_u32 v7, v114, 16, 1
	s_waitcnt lgkmcnt(0)
	v_mfma_f32_16x16x32_bf16 v[38:41], v[58:61], v[54:57], v[38:41]
	v_add_u32_e32 v61, 0x9000, v85
	ds_read2_b64 v[74:77], v61 offset1:4
	v_bfe_u32 v54, v113, 16, 1
	v_bfe_u32 v55, v115, 16, 1
	v_bfe_u32 v56, v117, 16, 1
	v_bfe_u32 v14, v112, 16, 1
	v_add3_u32 v56, v117, v56, s91
	v_add3_u32 v55, v115, v55, s91
	v_add3_u32 v54, v113, v54, s91
	v_add3_u32 v15, v111, v15, s91
	v_add3_u32 v14, v112, v14, s91
	v_add3_u32 v7, v114, v7, s91
	v_add3_u32 v6, v116, v6, s91
	v_add3_u32 v3, v118, v3, s91
	v_lshrrev_b32_e32 v15, 16, v15
	v_lshrrev_b32_e32 v54, 16, v54
	v_lshrrev_b32_e32 v55, 16, v55
	v_lshrrev_b32_e32 v56, 16, v56
	v_and_or_b32 v57, v3, s33, v56
	v_and_or_b32 v56, v6, s33, v55
	v_and_or_b32 v55, v7, s33, v54
	v_and_or_b32 v54, v14, s33, v15
	v_add_u32_e32 v60, 0xb000, v85
	v_add_u32_e32 v59, 0xd000, v85
	s_waitcnt lgkmcnt(0)
	v_mfma_f32_16x16x32_bf16 v[42:45], v[74:77], v[54:57], v[42:45]
	ds_read2_b64 v[74:77], v60 offset0:32 offset1:36
	v_add_u32_e32 v58, 0xf000, v85
	v_bfe_u32 v3, v126, 16, 1
	s_waitcnt lgkmcnt(0)
	v_mfma_f32_16x16x32_bf16 v[46:49], v[74:77], v[54:57], v[46:49]
	ds_read2_b64 v[74:77], v59 offset0:64 offset1:68
	v_bfe_u32 v6, v124, 16, 1
	v_bfe_u32 v7, v122, 16, 1
	s_waitcnt lgkmcnt(0)
	v_mfma_f32_16x16x32_bf16 v[74:77], v[74:77], v[54:57], v[50:53]
	s_nop 2
	ds_read2_b64 v[50:53], v58 offset0:96 offset1:100
	v_add3_u32 v7, v122, v7, s91
	s_waitcnt lgkmcnt(0)
	v_mfma_f32_16x16x32_bf16 v[38:41], v[50:53], v[54:57], v[38:41]
	v_bfe_u32 v50, v121, 16, 1
	v_bfe_u32 v51, v123, 16, 1
	v_bfe_u32 v52, v125, 16, 1
	v_add3_u32 v52, v125, v52, s91
	v_add3_u32 v51, v123, v51, s91
	v_add3_u32 v50, v121, v50, s91
	v_add3_u32 v6, v124, v6, s91
	v_add3_u32 v3, v126, v3, s91
	v_lshrrev_b32_e32 v50, 16, v50
	v_lshrrev_b32_e32 v51, 16, v51
	v_lshrrev_b32_e32 v52, 16, v52
	v_add_u32_e32 v57, 0x9000, v83
	v_and_or_b32 v115, v3, s33, v52
	v_and_or_b32 v114, v6, s33, v51
	v_and_or_b32 v113, v7, s33, v50
	ds_read2_b64 v[50:53], v57 offset1:4
	v_bfe_u32 v15, v119, 16, 1
	v_bfe_u32 v14, v120, 16, 1
	v_add3_u32 v15, v119, v15, s91
	v_add3_u32 v14, v120, v14, s91
	v_lshrrev_b32_e32 v15, 16, v15
	v_and_or_b32 v112, v14, s33, v15
	v_add_u32_e32 v56, 0xb000, v83
	v_div_scale_f32 v3, s[48:49], v2, v2, 1.0
	s_waitcnt lgkmcnt(0)
	v_mfma_f32_16x16x32_bf16 v[50:53], v[50:53], v[112:115], v[42:45]
	v_rcp_f32_e32 v6, v3
	v_add_u32_e32 v55, 0xd000, v83
	v_add_u32_e32 v54, 0xf000, v83
	ds_read2_b64 v[42:45], v56 offset0:32 offset1:36
	v_fma_f32 v7, -v3, v6, 1.0
	v_fmac_f32_e32 v6, v7, v6
	v_div_scale_f32 v7, vcc, 1.0, v2, 1.0
	v_mul_f32_e32 v14, v7, v6
	v_fma_f32 v15, -v3, v14, v7
	v_fmac_f32_e32 v14, v15, v6
	s_waitcnt lgkmcnt(0)
	v_mfma_f32_16x16x32_bf16 v[46:49], v[42:45], v[112:115], v[46:49]
	ds_read2_b64 v[42:45], v55 offset0:64 offset1:68
	v_fma_f32 v3, -v3, v14, v7
	v_div_fmas_f32 v3, v3, v6, v14
	v_div_fixup_f32 v6, v3, v2, 1.0
	v_mov_b32_e32 v14, v50
	v_mov_b32_e32 v15, v52
	v_pk_mul_f32 v[14:15], v[6:7], v[14:15] op_sel_hi:[0,1]
	v_mov_b32_e32 v52, v51
	v_pk_mul_f32 v[50:51], v[6:7], v[52:53] op_sel_hi:[0,1]
	v_and_b32_sdwa v7, v15, v218 dst_sel:DWORD dst_unused:UNUSED_PAD src0_sel:WORD_1 src1_sel:DWORD
	v_and_b32_sdwa v52, v14, v218 dst_sel:DWORD dst_unused:UNUSED_PAD src0_sel:WORD_1 src1_sel:DWORD
	v_add3_u32 v14, v14, v52, s91
	v_add3_u32 v7, v15, v7, s91
	v_and_b32_sdwa v15, v51, v218 dst_sel:DWORD dst_unused:UNUSED_PAD src0_sel:WORD_1 src1_sel:DWORD
	v_and_b32_sdwa v52, v50, v218 dst_sel:DWORD dst_unused:UNUSED_PAD src0_sel:WORD_1 src1_sel:DWORD
	v_add3_u32 v15, v51, v15, s91
	v_add3_u32 v50, v50, v52, s91
	v_and_b32_e32 v15, 0xffff0000, v15
	v_and_b32_e32 v50, 0xffff0000, v50
	v_lshl_add_u64 v[2:3], v[80:81], 0, s[92:93]
	v_or_b32_sdwa v15, v15, v7 dst_sel:DWORD dst_unused:UNUSED_PAD src0_sel:DWORD src1_sel:WORD_1
	v_or_b32_sdwa v14, v50, v14 dst_sel:DWORD dst_unused:UNUSED_PAD src0_sel:DWORD src1_sel:WORD_1
	s_waitcnt lgkmcnt(0)
	v_mfma_f32_16x16x32_bf16 v[42:45], v[42:45], v[112:115], v[74:77]
	s_mov_b64 s[92:93], s[42:43]
	v_readlane_b32 s11, v255, 9
	v_readlane_b32 s12, v255, 10
	ds_read2_b64 v[74:77], v54 offset0:96 offset1:100
	global_store_dwordx2 v[2:3], v[14:15], off
	v_mov_b32_e32 v14, v46
	v_mov_b32_e32 v15, v48
	v_pk_mul_f32 v[14:15], v[6:7], v[14:15] op_sel_hi:[0,1]
	v_mov_b32_e32 v48, v47
	v_pk_mul_f32 v[46:47], v[6:7], v[48:49] op_sel_hi:[0,1]
	v_and_b32_sdwa v7, v15, v218 dst_sel:DWORD dst_unused:UNUSED_PAD src0_sel:WORD_1 src1_sel:DWORD
	v_and_b32_sdwa v48, v14, v218 dst_sel:DWORD dst_unused:UNUSED_PAD src0_sel:WORD_1 src1_sel:DWORD
	v_add3_u32 v14, v14, v48, s91
	v_add3_u32 v7, v15, v7, s91
	v_and_b32_sdwa v15, v47, v218 dst_sel:DWORD dst_unused:UNUSED_PAD src0_sel:WORD_1 src1_sel:DWORD
	v_and_b32_sdwa v48, v46, v218 dst_sel:DWORD dst_unused:UNUSED_PAD src0_sel:WORD_1 src1_sel:DWORD
	v_add3_u32 v15, v47, v15, s91
	v_add3_u32 v46, v46, v48, s91
	v_and_b32_e32 v15, 0xffff0000, v15
	v_and_b32_e32 v46, 0xffff0000, v46
	v_or_b32_sdwa v15, v15, v7 dst_sel:DWORD dst_unused:UNUSED_PAD src0_sel:DWORD src1_sel:WORD_1
	v_or_b32_sdwa v14, v46, v14 dst_sel:DWORD dst_unused:UNUSED_PAD src0_sel:DWORD src1_sel:WORD_1
	global_store_dwordx2 v[2:3], v[14:15], off offset:32
	v_mov_b32_e32 v14, v42
	v_mov_b32_e32 v15, v44
	v_pk_mul_f32 v[14:15], v[6:7], v[14:15] op_sel_hi:[0,1]
	v_mov_b32_e32 v44, v43
	v_pk_mul_f32 v[42:43], v[6:7], v[44:45] op_sel_hi:[0,1]
	v_and_b32_sdwa v7, v15, v218 dst_sel:DWORD dst_unused:UNUSED_PAD src0_sel:WORD_1 src1_sel:DWORD
	v_and_b32_sdwa v44, v14, v218 dst_sel:DWORD dst_unused:UNUSED_PAD src0_sel:WORD_1 src1_sel:DWORD
	s_waitcnt lgkmcnt(0)
	v_mfma_f32_16x16x32_bf16 v[38:41], v[74:77], v[112:115], v[38:41]
	v_add3_u32 v14, v14, v44, s91
	v_add3_u32 v7, v15, v7, s91
	v_and_b32_sdwa v15, v43, v218 dst_sel:DWORD dst_unused:UNUSED_PAD src0_sel:WORD_1 src1_sel:DWORD
	v_and_b32_sdwa v44, v42, v218 dst_sel:DWORD dst_unused:UNUSED_PAD src0_sel:WORD_1 src1_sel:DWORD
	v_add3_u32 v15, v43, v15, s91
	v_add3_u32 v42, v42, v44, s91
	v_and_b32_e32 v15, 0xffff0000, v15
	v_and_b32_e32 v42, 0xffff0000, v42
	v_or_b32_sdwa v15, v15, v7 dst_sel:DWORD dst_unused:UNUSED_PAD src0_sel:DWORD src1_sel:WORD_1
	v_or_b32_sdwa v14, v42, v14 dst_sel:DWORD dst_unused:UNUSED_PAD src0_sel:DWORD src1_sel:WORD_1
	global_store_dwordx2 v[2:3], v[14:15], off offset:64
	v_mov_b32_e32 v14, v38
	v_mov_b32_e32 v15, v40
	v_pk_mul_f32 v[14:15], v[6:7], v[14:15] op_sel_hi:[0,1]
	v_mov_b32_e32 v40, v39
	v_pk_mul_f32 v[6:7], v[6:7], v[40:41] op_sel_hi:[0,1]
	v_and_b32_sdwa v38, v15, v218 dst_sel:DWORD dst_unused:UNUSED_PAD src0_sel:WORD_1 src1_sel:DWORD
	v_and_b32_sdwa v39, v14, v218 dst_sel:DWORD dst_unused:UNUSED_PAD src0_sel:WORD_1 src1_sel:DWORD
	v_add3_u32 v14, v14, v39, s91
	v_add3_u32 v15, v15, v38, s91
	v_and_b32_sdwa v38, v7, v218 dst_sel:DWORD dst_unused:UNUSED_PAD src0_sel:WORD_1 src1_sel:DWORD
	v_and_b32_sdwa v39, v6, v218 dst_sel:DWORD dst_unused:UNUSED_PAD src0_sel:WORD_1 src1_sel:DWORD
	v_add3_u32 v7, v7, v38, s91
	v_add3_u32 v6, v6, v39, s91
	v_and_b32_e32 v7, 0xffff0000, v7
	v_and_b32_e32 v6, 0xffff0000, v6
	v_or_b32_sdwa v7, v7, v15 dst_sel:DWORD dst_unused:UNUSED_PAD src0_sel:DWORD src1_sel:WORD_1
	v_or_b32_sdwa v6, v6, v14 dst_sel:DWORD dst_unused:UNUSED_PAD src0_sel:DWORD src1_sel:WORD_1
	global_store_dwordx2 v[2:3], v[6:7], off offset:96
	v_lshlrev_b32_e32 v14, 16, v36
	v_and_b32_e32 v2, 0xffff0000, v36
	v_lshlrev_b32_e32 v15, 16, v37
	v_and_b32_e32 v3, 0xffff0000, v37
	ds_read2_b64 v[36:39], v79 offset1:1
	v_lshlrev_b32_e32 v45, 16, v31
	v_and_b32_e32 v43, 0xffff0000, v31
	v_lshlrev_b32_e32 v41, 16, v35
	v_and_b32_e32 v35, 0xffff0000, v35
	s_waitcnt lgkmcnt(0)
	v_readfirstlane_b32 s48, v36
	v_readfirstlane_b32 s49, v37
	s_add_u32 s48, s48, s0
	s_addc_u32 s49, s49, s1
	s_nop 1
	v_lshl_add_u64 v[154:155], s[48:49], 0, v[0:1]
	global_load_dwordx4 v[156:159], v[154:155], off offset:144
	s_nop 1
	v_lshl_add_u64 v[148:149], s[48:49], 0, v[0:1]
	global_load_dwordx4 v[150:153], v[148:149], off offset:16
	v_mov_b32_e32 v46, v43
	v_mov_b32_e32 v47, v45
	v_lshlrev_b32_e32 v44, 16, v30
	v_and_b32_e32 v42, 0xffff0000, v30
	v_lshlrev_b32_e32 v30, 16, v32
	v_and_b32_e32 v6, 0xffff0000, v32
	v_lshlrev_b32_e32 v31, 16, v33
	v_and_b32_e32 v7, 0xffff0000, v33
	v_lshl_add_u64 v[32:33], s[48:49], 0, v[0:1]
	v_mov_b32_e32 v36, v35
	v_mov_b32_e32 v37, v41
	v_pk_mul_f32 v[46:47], v[46:47], v[46:47]
	global_load_dwordx4 v[50:53], v[32:33], off offset:128
	v_pk_fma_f32 v[36:37], v[36:37], v[36:37], v[46:47]
	global_load_dwordx4 v[46:49], v[32:33], off
	v_mov_b32_e32 v74, v7
	v_mov_b32_e32 v75, v31
	v_pk_mul_f32 v[74:75], v[74:75], v[74:75]
	v_lshlrev_b32_e32 v40, 16, v34
	v_and_b32_e32 v34, 0xffff0000, v34
	v_readlane_b32 s13, v255, 11
	v_readlane_b32 s16, v255, 12
	v_readlane_b32 s17, v255, 13
	v_readlane_b32 s76, v255, 16
	v_readlane_b32 s77, v255, 17
	v_readlane_b32 s78, v255, 18
	v_readlane_b32 s79, v255, 19
	s_mov_b64 s[42:43], s[4:5]
	v_readlane_b32 s4, v255, 20
	v_readlane_b32 s5, v255, 21
	v_readlane_b32 s7, v254, 62
	s_waitcnt vmcnt(0) lgkmcnt(0)
	v_mov_b32_e32 v118, v50
	v_mov_b32_e32 v119, v52
	v_mov_b32_e32 v52, v51
	v_mov_b32_e32 v50, v6
	v_mov_b32_e32 v51, v30
	v_mov_b32_e32 v116, v46
	v_mov_b32_e32 v117, v48
	v_mov_b32_e32 v48, v47
	v_mov_b32_e32 v46, v2
	v_mov_b32_e32 v47, v14
	v_pk_mul_f32 v[50:51], v[50:51], v[50:51]
	s_nop 0
	v_pk_fma_f32 v[46:47], v[46:47], v[46:47], v[50:51]
	v_mov_b32_e32 v50, v3
	v_mov_b32_e32 v51, v15
	v_pk_fma_f32 v[50:51], v[50:51], v[50:51], v[74:75]
	s_waitcnt vmcnt(2)
	s_nop 0
	v_mov_b32_e32 v74, v150
	v_mov_b32_e32 v75, v151
	v_mov_b32_e32 v76, v152
	v_mov_b32_e32 v77, v153
	s_nop 1
	s_waitcnt vmcnt(3)
	s_nop 0
	v_mov_b32_e32 v112, v156
	v_mov_b32_e32 v113, v157
	v_mov_b32_e32 v114, v158
	v_mov_b32_e32 v115, v159
	s_nop 1
	v_mul_f32_e32 v32, v34, v34
	v_mul_f32_e32 v33, v40, v40
	v_fmac_f32_e32 v32, v42, v42
	v_fmac_f32_e32 v33, v44, v44
	v_add_f32_e32 v32, v33, v32
	v_add_f32_e32 v32, v37, v32
	v_add_f32_e32 v32, v36, v32
	v_add_f32_e32 v32, v47, v32
	v_add_f32_e32 v32, v46, v32
	v_add_f32_e32 v32, v51, v32
	v_add_f32_e32 v32, v50, v32
	ds_bpermute_b32 v33, v109, v32
	s_waitcnt lgkmcnt(0)
	v_add_f32_e32 v32, v32, v33
	ds_bpermute_b32 v33, v110, v32
	s_waitcnt lgkmcnt(0)
	v_add_f32_e32 v32, v32, v33
	v_fmamk_f32 v32, v32, 0x3c800000, v219
	v_cmp_gt_f32_e32 vcc, s6, v32
	v_mul_f32_e32 v33, 0x4f800000, v32
	s_nop 0
	v_cndmask_b32_e32 v32, v32, v33, vcc
	v_sqrt_f32_e32 v33, v32
	s_nop 0
	v_add_u32_e32 v36, -1, v33
	v_fma_f32 v37, -v36, v33, v32
	v_cmp_ge_f32_e64 s[88:89], 0, v37
	v_add_u32_e32 v37, 1, v33
	s_nop 0
	v_cndmask_b32_e64 v36, v33, v36, s[88:89]
	v_fma_f32 v33, -v37, v33, v32
	v_cmp_lt_f32_e64 s[88:89], 0, v33
	s_nop 1
	v_cndmask_b32_e64 v33, v36, v37, s[88:89]
	v_mul_f32_e32 v36, 0x37800000, v33
	v_cndmask_b32_e32 v33, v33, v36, vcc
	v_cmp_class_f32_e32 vcc, v32, v221
	s_nop 1
	v_cndmask_b32_e32 v32, v33, v32, vcc
	v_div_scale_f32 v33, s[48:49], v32, v32, 1.0
	v_rcp_f32_e32 v36, v33
	v_readfirstlane_b32 s48, v38
	v_readfirstlane_b32 s49, v39
	s_add_u32 s48, s48, s2
	v_fma_f32 v37, -v33, v36, 1.0
	v_fmac_f32_e32 v36, v37, v36
	v_div_scale_f32 v37, vcc, 1.0, v32, 1.0
	v_mul_f32_e32 v46, v37, v36
	v_fma_f32 v47, -v33, v46, v37
	v_fmac_f32_e32 v46, v47, v36
	v_fma_f32 v33, -v33, v46, v37
	v_div_fmas_f32 v33, v33, v36, v46
	v_div_fixup_f32 v32, v33, v32, 1.0
	v_pk_mul_f32 v[34:35], v[32:33], v[34:35] op_sel_hi:[0,1]
	v_pk_mul_f32 v[34:35], v[34:35], v[48:49]
	v_pk_mul_f32 v[14:15], v[32:33], v[14:15] op_sel_hi:[0,1]
	v_pk_mul_f32 v[30:31], v[32:33], v[30:31] op_sel_hi:[0,1]
	v_pk_mul_f32 v[36:37], v[32:33], v[40:41] op_sel_hi:[0,1]
	v_pk_mul_f32 v[40:41], v[32:33], v[44:45] op_sel_hi:[0,1]
	v_pk_mul_f32 v[42:43], v[32:33], v[42:43] op_sel_hi:[0,1]
	v_pk_mul_f32 v[2:3], v[32:33], v[2:3] op_sel_hi:[0,1]
	v_pk_mul_f32 v[6:7], v[32:33], v[6:7] op_sel_hi:[0,1]
	v_pk_mul_f32 v[40:41], v[118:119], v[40:41]
	v_pk_mul_f32 v[36:37], v[116:117], v[36:37]
	v_pk_mul_f32 v[42:43], v[42:43], v[52:53]
	v_pk_mul_f32 v[44:45], v[102:103], v[40:41]
	s_waitcnt vmcnt(0)
	v_mov_b32_e32 v48, v74
	v_mov_b32_e32 v49, v76
	v_pk_mul_f32 v[14:15], v[14:15], v[48:49]
	v_mov_b32_e32 v48, v112
	v_mov_b32_e32 v49, v114
	v_pk_mul_f32 v[30:31], v[30:31], v[48:49]
	v_mov_b32_e32 v114, v113
	v_pk_mul_f32 v[32:33], v[10:11], v[30:31]
	v_mov_b32_e32 v76, v75
	v_pk_mul_f32 v[6:7], v[6:7], v[114:115]
	v_pk_fma_f32 v[32:33], v[18:19], v[14:15], v[32:33]
	v_pk_mul_f32 v[2:3], v[2:3], v[76:77]
	v_pk_mul_f32 v[48:49], v[32:33], s[86:87] op_sel_hi:[1,0]
	v_pk_mul_f32 v[32:33], v[8:9], v[6:7]
	v_pk_fma_f32 v[44:45], v[104:105], v[36:37], v[44:45]
	v_pk_fma_f32 v[32:33], v[16:17], v[2:3], v[32:33]
	v_pk_mul_f32 v[46:47], v[12:13], v[42:43]
	v_pk_mul_f32 v[50:51], v[32:33], s[86:87] op_sel_hi:[1,0]
	v_pk_mul_f32 v[32:33], v[104:105], v[40:41]
	v_pk_fma_f32 v[46:47], v[20:21], v[34:35], v[46:47]
	v_pk_fma_f32 v[32:33], v[102:103], v[36:37], v[32:33] neg_lo:[0,0,1] neg_hi:[0,0,1]
	v_pk_mul_f32 v[36:37], v[20:21], v[42:43]
	v_pk_mul_f32 v[30:31], v[18:19], v[30:31]
	v_pk_fma_f32 v[34:35], v[12:13], v[34:35], v[36:37] neg_lo:[0,0,1] neg_hi:[0,0,1]
	v_pk_fma_f32 v[14:15], v[10:11], v[14:15], v[30:31] neg_lo:[0,0,1] neg_hi:[0,0,1]
	v_pk_mul_f32 v[34:35], v[34:35], s[86:87] op_sel_hi:[1,0]
	v_pk_mul_f32 v[6:7], v[16:17], v[6:7]
	v_pk_mul_f32 v[14:15], v[14:15], s[86:87] op_sel_hi:[1,0]
	v_pk_fma_f32 v[2:3], v[8:9], v[2:3], v[6:7] neg_lo:[0,0,1] neg_hi:[0,0,1]
	v_bfe_u32 v30, v35, 16, 1
	v_bfe_u32 v31, v34, 16, 1
	v_pk_mul_f32 v[2:3], v[2:3], s[86:87] op_sel_hi:[1,0]
	v_add3_u32 v34, v34, v31, s91
	v_add3_u32 v30, v35, v30, s91
	v_bfe_u32 v31, v14, 16, 1
	v_bfe_u32 v35, v15, 16, 1
	ds_read_b128 v[38:41], v100
	v_pk_mul_f32 v[32:33], v[32:33], s[86:87] op_sel_hi:[1,0]
	v_bfe_u32 v6, v3, 16, 1
	v_bfe_u32 v7, v2, 16, 1
	v_add3_u32 v15, v15, v35, s91
	v_add3_u32 v14, v14, v31, s91
	v_pk_mul_f32 v[44:45], v[44:45], s[86:87] op_sel_hi:[1,0]
	v_add3_u32 v2, v2, v7, s91
	v_add3_u32 v3, v3, v6, s91
	v_bfe_u32 v6, v32, 16, 1
	v_bfe_u32 v7, v33, 16, 1
	v_lshrrev_b32_e32 v14, 16, v14
	v_lshrrev_b32_e32 v15, 16, v15
	v_add3_u32 v7, v33, v7, s91
	v_add3_u32 v6, v32, v6, s91
	v_and_or_b32 v33, v3, s33, v15
	v_and_or_b32 v32, v2, s33, v14
	v_bfe_u32 v14, v44, 16, 1
	v_bfe_u32 v15, v45, 16, 1
	v_add3_u32 v15, v45, v15, s91
	v_add3_u32 v14, v44, v14, s91
	ds_read_b128 v[42:45], v100 offset:64
	v_lshrrev_b32_e32 v6, 16, v6
	v_lshrrev_b32_e32 v7, 16, v7
	v_and_or_b32 v31, v30, s33, v7
	v_and_or_b32 v30, v34, s33, v6
	v_pk_mul_f32 v[46:47], v[46:47], s[86:87] op_sel_hi:[1,0]
	v_bfe_u32 v34, v48, 16, 1
	v_bfe_u32 v35, v49, 16, 1
	s_waitcnt lgkmcnt(1)
	v_mfma_f32_16x16x32_bf16 v[38:41], v[38:41], v[30:33], 0
	v_bfe_u32 v2, v51, 16, 1
	v_bfe_u32 v3, v50, 16, 1
	v_bfe_u32 v6, v47, 16, 1
	v_bfe_u32 v7, v46, 16, 1
	v_add3_u32 v35, v49, v35, s91
	v_add3_u32 v34, v48, v34, s91
	v_add3_u32 v7, v46, v7, s91
	v_add3_u32 v6, v47, v6, s91
	v_add3_u32 v3, v50, v3, s91
	v_add3_u32 v2, v51, v2, s91
	v_lshrrev_b32_e32 v14, 16, v14
	v_lshrrev_b32_e32 v15, 16, v15
	v_lshrrev_b32_e32 v34, 16, v34
	v_lshrrev_b32_e32 v35, 16, v35
	v_and_or_b32 v37, v2, s33, v35
	v_and_or_b32 v36, v3, s33, v34
	v_and_or_b32 v35, v6, s33, v15
	v_and_or_b32 v34, v7, s33, v14
	ds_read_b128 v[46:49], v98 offset:64
	s_addc_u32 s49, s49, s3
	s_nop 1
	v_mov_b64_e32 v[160:161], s[48:49]
	global_load_dword v162, v[160:161], off offset:4
	s_waitcnt lgkmcnt(1)
	v_mfma_f32_16x16x32_bf16 v[38:41], v[42:45], v[34:37], v[38:41]
	ds_read_b128 v[42:45], v98
	v_mov_b64_e32 v[2:3], s[48:49]
	s_waitcnt vmcnt(0)
	s_nop 0
	v_mov_b32_e32 v2, v162
	s_nop 1
	s_waitcnt lgkmcnt(0)
	v_mfma_f32_16x16x32_bf16 v[42:45], v[42:45], v[30:33], 0
	ds_read_b128 v[50:53], v96 offset:64
	ds_read_b128 v[74:77], v94 offset:64
	v_mfma_f32_16x16x32_bf16 v[42:45], v[46:49], v[34:37], v[42:45]
	ds_read_b128 v[46:49], v96
	v_mov_b32_e32 v6, s94
	v_cndmask_b32_e64 v3, v38, v6, s[8:9]
	s_waitcnt lgkmcnt(0)
	v_mfma_f32_16x16x32_bf16 v[46:49], v[46:49], v[30:33], 0
	v_cndmask_b32_e64 v7, v39, v227, s[40:41]
	s_mov_b64 s[40:41], s[80:81]
	v_max3_f32 v6, v3, s94, v7
	v_mfma_f32_16x16x32_bf16 v[46:49], v[50:53], v[34:37], v[46:49]
	ds_read_b128 v[50:53], v94
	ds_read_b128 v[112:115], v92 offset:64
	s_waitcnt lgkmcnt(0)
	v_mfma_f32_16x16x32_bf16 v[50:53], v[50:53], v[30:33], 0
	ds_read_b128 v[116:119], v90 offset:64
	v_cndmask_b32_e64 v14, v40, v227, s[40:41]
	v_cndmask_b32_e64 v15, v41, v227, s[92:93]
	v_mfma_f32_16x16x32_bf16 v[50:53], v[74:77], v[34:37], v[50:53]
	ds_read_b128 v[74:77], v92
	v_readlane_b32 s80, v255, 14
	v_readlane_b32 s81, v255, 15
	s_waitcnt lgkmcnt(0)
	v_mfma_f32_16x16x32_bf16 v[74:77], v[74:77], v[30:33], 0
	v_cndmask_b32_e64 v40, v47, v227, s[80:81]
	v_cndmask_b32_e64 v41, v49, v227, s[84:85]
	v_mfma_f32_16x16x32_bf16 v[74:77], v[112:115], v[34:37], v[74:77]
	ds_read_b128 v[112:115], v90
	ds_read_b128 v[120:123], v88 offset:64
	s_waitcnt lgkmcnt(0)
	v_mfma_f32_16x16x32_bf16 v[112:115], v[112:115], v[30:33], 0
	ds_read_b128 v[124:127], v86 offset:64
	s_nop 2
	v_cndmask_b32_e64 v49, v77, v227, s[26:27]
	v_mfma_f32_16x16x32_bf16 v[112:115], v[116:119], v[34:37], v[112:115]
	ds_read_b128 v[116:119], v88
	s_waitcnt lgkmcnt(0)
	v_mfma_f32_16x16x32_bf16 v[116:119], v[116:119], v[30:33], 0
	v_mfma_f32_16x16x32_bf16 v[116:119], v[120:123], v[34:37], v[116:119]
	ds_read_b128 v[120:123], v86
	ds_read_b128 v[128:131], v84 offset:64
	s_waitcnt lgkmcnt(0)
	v_mfma_f32_16x16x32_bf16 v[120:123], v[120:123], v[30:33], 0
	s_nop 3
	v_cndmask_b32_e64 v77, v119, v227, s[52:53]
	v_mfma_f32_16x16x32_bf16 v[120:123], v[124:127], v[34:37], v[120:123]
	ds_read_b128 v[124:127], v84
	s_waitcnt lgkmcnt(0)
	v_mfma_f32_16x16x32_bf16 v[124:127], v[124:127], v[30:33], 0
	s_nop 4
	v_cndmask_b32_e64 v87, v121, v227, s[56:57]
	v_cndmask_b32_e64 v89, v123, v227, s[60:61]
	v_mfma_f32_16x16x32_bf16 v[124:127], v[128:131], v[34:37], v[124:127]
	ds_read_b128 v[128:131], v82
	s_waitcnt lgkmcnt(0)
	v_mfma_f32_16x16x32_bf16 v[30:33], v[128:131], v[30:33], 0
	ds_read_b128 v[128:131], v82 offset:64
	s_nop 3
	v_cndmask_b32_e64 v95, v125, v227, s[64:65]
	v_cndmask_b32_e64 v97, v127, v227, s[68:69]
	s_waitcnt lgkmcnt(0)
	v_mfma_f32_16x16x32_bf16 v[30:33], v[128:131], v[34:37], v[30:33]
	v_max3_f32 v34, v6, v14, v15
	v_mov_b32_e32 v6, s94
	v_cndmask_b32_e64 v35, v42, v6, s[18:19]
	v_cndmask_b32_e64 v36, v43, v227, s[10:11]
	v_max3_f32 v6, v34, v35, v36
	v_cndmask_b32_e64 v34, v44, v227, s[12:13]
	v_cndmask_b32_e64 v37, v45, v227, s[44:45]
	v_max3_f32 v38, v6, v34, v37
	v_mov_b32_e32 v6, s94
	v_cndmask_b32_e64 v39, v46, v6, s[16:17]
	v_max3_f32 v6, v38, v39, v40
	v_cndmask_b32_e64 v38, v48, v227, s[82:83]
	v_max3_f32 v42, v6, v38, v41
	v_mov_b32_e32 v6, s94
	v_cndmask_b32_e64 v43, v50, v6, s[20:21]
	v_cndmask_b32_e64 v44, v51, v227, s[76:77]
	v_max3_f32 v6, v42, v43, v44
	v_cndmask_b32_e64 v42, v52, v227, s[78:79]
	v_cndmask_b32_e64 v45, v53, v227, s[14:15]
	v_max3_f32 v46, v6, v42, v45
	v_mov_b32_e32 v6, s94
	v_cndmask_b32_e64 v47, v74, v6, s[28:29]
	v_cndmask_b32_e64 v48, v75, v227, s[42:43]
	v_max3_f32 v6, v46, v47, v48
	v_cndmask_b32_e64 v46, v76, v227, s[22:23]
	v_max3_f32 v50, v6, v46, v49
	v_mov_b32_e32 v6, s94
	v_cndmask_b32_e64 v51, v112, v6, s[38:39]
	v_cndmask_b32_e64 v52, v113, v227, s[30:31]
	v_max3_f32 v6, v50, v51, v52
	v_cndmask_b32_e64 v50, v114, v227, s[34:35]
	v_cndmask_b32_e64 v53, v115, v227, s[36:37]
	v_max3_f32 v74, v6, v50, v53
	v_mov_b32_e32 v6, s94
	v_cndmask_b32_e64 v75, v116, v6, s[54:55]
	v_cndmask_b32_e64 v76, v117, v227, s[46:47]
	v_max3_f32 v6, v74, v75, v76
	v_cndmask_b32_e64 v74, v118, v227, s[50:51]
	v_max3_f32 v83, v6, v74, v77
	v_mov_b32_e32 v6, s94
	v_cndmask_b32_e64 v85, v120, v6, s[62:63]
	v_max3_f32 v6, v83, v85, v87
	v_cndmask_b32_e64 v83, v122, v227, s[58:59]
	v_max3_f32 v91, v6, v83, v89
	v_mov_b32_e32 v6, s94
	v_cndmask_b32_e64 v93, v124, v6, s[4:5]
	v_max3_f32 v6, v91, v93, v95
	v_cndmask_b32_e64 v91, v126, v227, s[66:67]
	v_max3_f32 v99, v6, v91, v97
	v_mov_b32_e32 v6, s94
	v_cndmask_b32_e64 v6, v30, v6, s[24:25]
	v_cndmask_b32_e64 v30, v31, v227, s[70:71]
	v_max3_f32 v31, v99, v6, v30
	v_cndmask_b32_e64 v32, v32, v227, s[72:73]
	v_cndmask_b32_e64 v33, v33, v227, s[74:75]
	v_max3_f32 v31, v31, v32, v33
	ds_bpermute_b32 v99, v109, v31
	s_lshl_b32 s94, s7, 1
	s_waitcnt lgkmcnt(0)
	v_max_f32_e32 v99, v99, v99
	v_max_f32_e32 v31, v31, v99
	ds_bpermute_b32 v99, v110, v31
	s_waitcnt vmcnt(0) lgkmcnt(0)
	v_max3_f32 v31, v31, v99, v2
	v_sub_f32_e32 v3, v3, v31
	v_mul_f32_e32 v3, 0x3fb8aa3b, v3
	v_sub_f32_e32 v7, v7, v31
	v_exp_f32_e32 v3, v3
	v_mul_f32_e32 v7, 0x3fb8aa3b, v7
	v_sub_f32_e32 v14, v14, v31
	v_exp_f32_e32 v7, v7
	v_mul_f32_e32 v14, 0x3fb8aa3b, v14
	v_sub_f32_e32 v15, v15, v31
	v_exp_f32_e32 v14, v14
	v_mul_f32_e32 v15, 0x3fb8aa3b, v15
	v_sub_f32_e32 v35, v35, v31
	v_exp_f32_e32 v15, v15
	v_mul_f32_e32 v35, 0x3fb8aa3b, v35
	v_sub_f32_e32 v36, v36, v31
	v_add_f32_e32 v99, 0, v3
	v_exp_f32_e32 v35, v35
	v_mul_f32_e32 v36, 0x3fb8aa3b, v36
	v_sub_f32_e32 v34, v34, v31
	v_add_f32_e32 v99, v7, v99
	v_exp_f32_e32 v36, v36
	v_mul_f32_e32 v34, 0x3fb8aa3b, v34
	v_sub_f32_e32 v37, v37, v31
	v_add_f32_e32 v99, v14, v99
	v_exp_f32_e32 v34, v34
	v_mul_f32_e32 v37, 0x3fb8aa3b, v37
	v_sub_f32_e32 v39, v39, v31
	v_add_f32_e32 v99, v15, v99
	v_exp_f32_e32 v37, v37
	v_mul_f32_e32 v39, 0x3fb8aa3b, v39
	v_add_f32_e32 v99, v35, v99
	v_exp_f32_e32 v101, v39
	v_add_f32_e32 v99, v36, v99
	v_add_f32_e32 v99, v34, v99
	v_sub_f32_e32 v40, v40, v31
	v_add_f32_e32 v99, v37, v99
	v_mul_f32_e32 v40, 0x3fb8aa3b, v40
	v_sub_f32_e32 v38, v38, v31
	v_add_f32_e32 v39, v101, v99
	v_exp_f32_e32 v99, v40
	v_mul_f32_e32 v38, 0x3fb8aa3b, v38
	v_exp_f32_e32 v111, v38
	v_sub_f32_e32 v6, v6, v31
	v_add_f32_e32 v39, v99, v39
	v_mul_f32_e32 v6, 0x3fb8aa3b, v6
	v_add_f32_e32 v38, v111, v39
	v_sub_f32_e32 v39, v41, v31
	v_mul_f32_e32 v39, 0x3fb8aa3b, v39
	v_exp_f32_e32 v112, v39
	v_sub_f32_e32 v39, v43, v31
	v_mul_f32_e32 v39, 0x3fb8aa3b, v39
	v_exp_f32_e32 v113, v39
	v_sub_f32_e32 v39, v44, v31
	v_mul_f32_e32 v39, 0x3fb8aa3b, v39
	v_exp_f32_e32 v114, v39
	v_sub_f32_e32 v39, v42, v31
	v_mul_f32_e32 v39, 0x3fb8aa3b, v39
	v_exp_f32_e32 v115, v39
	v_sub_f32_e32 v39, v45, v31
	v_mul_f32_e32 v39, 0x3fb8aa3b, v39
	v_exp_f32_e32 v116, v39
	v_sub_f32_e32 v39, v47, v31
	v_mul_f32_e32 v39, 0x3fb8aa3b, v39
	v_exp_f32_e32 v117, v39
	v_sub_f32_e32 v39, v48, v31
	v_mul_f32_e32 v39, 0x3fb8aa3b, v39
	v_exp_f32_e32 v118, v39
	v_sub_f32_e32 v39, v46, v31
	v_mul_f32_e32 v39, 0x3fb8aa3b, v39
	v_exp_f32_e32 v119, v39
	v_sub_f32_e32 v39, v49, v31
	v_mul_f32_e32 v39, 0x3fb8aa3b, v39
	v_exp_f32_e32 v120, v39
	v_sub_f32_e32 v39, v51, v31
	v_mul_f32_e32 v39, 0x3fb8aa3b, v39
	v_exp_f32_e32 v121, v39
	v_sub_f32_e32 v39, v52, v31
	v_mul_f32_e32 v39, 0x3fb8aa3b, v39
	v_exp_f32_e32 v122, v39
	v_sub_f32_e32 v39, v50, v31
	v_mul_f32_e32 v39, 0x3fb8aa3b, v39
	v_exp_f32_e32 v123, v39
	v_sub_f32_e32 v39, v53, v31
	v_mul_f32_e32 v39, 0x3fb8aa3b, v39
	v_exp_f32_e32 v124, v39
	v_sub_f32_e32 v39, v75, v31
	v_mul_f32_e32 v39, 0x3fb8aa3b, v39
	v_exp_f32_e32 v75, v39
	v_sub_f32_e32 v39, v76, v31
	v_mul_f32_e32 v39, 0x3fb8aa3b, v39
	v_add_f32_e32 v38, v112, v38
	v_exp_f32_e32 v76, v39
	v_sub_f32_e32 v39, v74, v31
	v_add_f32_e32 v38, v113, v38
	v_mul_f32_e32 v39, 0x3fb8aa3b, v39
	v_add_f32_e32 v38, v114, v38
	v_exp_f32_e32 v74, v39
	v_sub_f32_e32 v39, v77, v31
	v_add_f32_e32 v38, v115, v38
	v_mul_f32_e32 v39, 0x3fb8aa3b, v39
	v_add_f32_e32 v38, v116, v38
	v_exp_f32_e32 v77, v39
	v_sub_f32_e32 v39, v85, v31
	v_add_f32_e32 v38, v117, v38
	v_mul_f32_e32 v39, 0x3fb8aa3b, v39
	v_add_f32_e32 v38, v118, v38
	v_exp_f32_e32 v85, v39
	v_sub_f32_e32 v39, v87, v31
	v_add_f32_e32 v38, v119, v38
	v_mul_f32_e32 v39, 0x3fb8aa3b, v39
	v_add_f32_e32 v38, v120, v38
	v_exp_f32_e32 v87, v39
	v_sub_f32_e32 v39, v83, v31
	v_add_f32_e32 v38, v121, v38
	v_mul_f32_e32 v39, 0x3fb8aa3b, v39
	v_add_f32_e32 v38, v122, v38
	v_exp_f32_e32 v83, v39
	v_sub_f32_e32 v39, v89, v31
	v_add_f32_e32 v38, v123, v38
	v_mul_f32_e32 v39, 0x3fb8aa3b, v39
	v_add_f32_e32 v38, v124, v38
	v_exp_f32_e32 v89, v39
	v_sub_f32_e32 v39, v93, v31
	v_add_f32_e32 v38, v75, v38
	v_mul_f32_e32 v39, 0x3fb8aa3b, v39
	v_add_f32_e32 v38, v76, v38
	v_exp_f32_e32 v93, v39
	v_sub_f32_e32 v39, v95, v31
	v_add_f32_e32 v38, v74, v38
	v_mul_f32_e32 v39, 0x3fb8aa3b, v39
	v_add_f32_e32 v38, v77, v38
	v_exp_f32_e32 v95, v39
	v_sub_f32_e32 v39, v91, v31
	v_add_f32_e32 v38, v85, v38
	v_mul_f32_e32 v39, 0x3fb8aa3b, v39
	v_add_f32_e32 v38, v87, v38
	v_exp_f32_e32 v91, v39
	v_sub_f32_e32 v39, v97, v31
	v_add_f32_e32 v38, v83, v38
	v_mul_f32_e32 v39, 0x3fb8aa3b, v39
	v_add_f32_e32 v38, v89, v38
	v_exp_f32_e32 v97, v39
	v_sub_f32_e32 v30, v30, v31
	v_sub_f32_e32 v32, v32, v31
	v_add_f32_e32 v38, v93, v38
	v_exp_f32_e32 v6, v6
	v_mul_f32_e32 v30, 0x3fb8aa3b, v30
	v_mul_f32_e32 v32, 0x3fb8aa3b, v32
	v_add_f32_e32 v38, v95, v38
	v_exp_f32_e32 v125, v30
	v_exp_f32_e32 v126, v32
	v_sub_f32_e32 v32, v33, v31
	v_add_f32_e32 v38, v91, v38
	v_mul_f32_e32 v32, 0x3fb8aa3b, v32
	v_add_f32_e32 v38, v97, v38
	v_exp_f32_e32 v127, v32
	v_add_f32_e32 v38, v6, v38
	v_add_f32_e32 v30, v125, v38
	v_add_f32_e32 v30, v126, v30
	v_add_f32_e32 v30, v127, v30
	ds_bpermute_b32 v32, v109, v30
	v_sub_f32_e32 v2, v2, v31
	v_mul_f32_e32 v2, 0x3fb8aa3b, v2
	v_exp_f32_e32 v2, v2
	v_bfe_u32 v31, v36, 16, 1
	s_waitcnt lgkmcnt(0)
	v_add_f32_e32 v30, v30, v32
	ds_bpermute_b32 v32, v110, v30
	v_bfe_u32 v33, v7, 16, 1
	v_add3_u32 v31, v36, v31, s91
	v_bfe_u32 v36, v35, 16, 1
	v_add3_u32 v7, v7, v33, s91
	s_waitcnt lgkmcnt(0)
	v_add_f32_e32 v30, v30, v32
	v_add_f32_e32 v2, v2, v30
	v_bfe_u32 v30, v37, 16, 1
	v_bfe_u32 v32, v15, 16, 1
	v_add3_u32 v30, v37, v30, s91
	v_bfe_u32 v37, v34, 16, 1
	v_add3_u32 v15, v15, v32, s91
	v_bfe_u32 v32, v3, 16, 1
	v_bfe_u32 v33, v14, 16, 1
	v_add3_u32 v34, v34, v37, s91
	v_add3_u32 v35, v35, v36, s91
	v_add3_u32 v14, v14, v33, s91
	v_add3_u32 v3, v3, v32, s91
	v_lshrrev_b32_e32 v32, 16, v35
	v_lshrrev_b32_e32 v33, 16, v34
	ds_read2_b64 v[34:37], v73 offset1:4
	ds_read2_b64 v[38:41], v72 offset0:32 offset1:36
	ds_read2_b64 v[42:45], v71 offset0:64 offset1:68
	ds_read2_b64 v[46:49], v70 offset0:96 offset1:100
	ds_read2_b64 v[50:53], v69 offset1:4
	v_lshrrev_b32_e32 v3, 16, v3
	v_lshrrev_b32_e32 v14, 16, v14
	v_and_or_b32 v33, v30, s33, v33
	v_and_or_b32 v32, v31, s33, v32
	v_and_or_b32 v31, v15, s33, v14
	v_and_or_b32 v30, v7, s33, v3
	v_bfe_u32 v3, v116, 16, 1
	v_bfe_u32 v7, v114, 16, 1
	s_waitcnt lgkmcnt(4)
	v_mfma_f32_16x16x32_bf16 v[34:37], v[34:37], v[30:33], 0
	v_bfe_u32 v14, v112, 16, 1
	v_bfe_u32 v15, v99, 16, 1
	v_add3_u32 v15, v99, v15, s91
	s_waitcnt lgkmcnt(3)
	v_mfma_f32_16x16x32_bf16 v[38:41], v[38:41], v[30:33], 0
	v_add3_u32 v14, v112, v14, s91
	v_add3_u32 v7, v114, v7, s91
	v_add3_u32 v3, v116, v3, s91
	s_waitcnt lgkmcnt(2)
	v_mfma_f32_16x16x32_bf16 v[42:45], v[42:45], v[30:33], 0
	s_waitcnt lgkmcnt(1)
	v_mfma_f32_16x16x32_bf16 v[30:33], v[46:49], v[30:33], 0
	v_bfe_u32 v46, v101, 16, 1
	v_bfe_u32 v47, v111, 16, 1
	v_bfe_u32 v48, v113, 16, 1
	v_bfe_u32 v49, v115, 16, 1
	v_add3_u32 v49, v115, v49, s91
	v_add3_u32 v48, v113, v48, s91
	v_add3_u32 v47, v111, v47, s91
	v_add3_u32 v46, v101, v46, s91
	v_lshrrev_b32_e32 v46, 16, v46
	v_lshrrev_b32_e32 v47, 16, v47
	v_lshrrev_b32_e32 v48, 16, v48
	v_lshrrev_b32_e32 v49, 16, v49
	v_and_or_b32 v49, v3, s33, v49
	v_and_or_b32 v48, v7, s33, v48
	v_and_or_b32 v47, v14, s33, v47
	v_and_or_b32 v46, v15, s33, v46
	v_bfe_u32 v3, v124, 16, 1
	v_bfe_u32 v7, v122, 16, 1
	s_waitcnt lgkmcnt(0)
	v_mfma_f32_16x16x32_bf16 v[34:37], v[50:53], v[46:49], v[34:37]
	ds_read2_b64 v[50:53], v68 offset0:32 offset1:36
	v_bfe_u32 v14, v120, 16, 1
	v_bfe_u32 v15, v118, 16, 1
	s_waitcnt lgkmcnt(0)
	v_mfma_f32_16x16x32_bf16 v[38:41], v[50:53], v[46:49], v[38:41]
	ds_read2_b64 v[50:53], v67 offset0:64 offset1:68
	v_add3_u32 v15, v118, v15, s91
	v_add3_u32 v14, v120, v14, s91
	s_waitcnt lgkmcnt(0)
	v_mfma_f32_16x16x32_bf16 v[42:45], v[50:53], v[46:49], v[42:45]
	ds_read2_b64 v[50:53], v66 offset0:96 offset1:100
	v_add3_u32 v7, v122, v7, s91
	s_waitcnt lgkmcnt(0)
	v_mfma_f32_16x16x32_bf16 v[30:33], v[50:53], v[46:49], v[30:33]
	ds_read2_b64 v[50:53], v65 offset1:4
	v_bfe_u32 v46, v117, 16, 1
	v_bfe_u32 v47, v119, 16, 1
	v_bfe_u32 v48, v121, 16, 1
	v_bfe_u32 v49, v123, 16, 1
	v_add3_u32 v49, v123, v49, s91
	v_add3_u32 v48, v121, v48, s91
	v_add3_u32 v47, v119, v47, s91
	v_add3_u32 v46, v117, v46, s91
	v_add3_u32 v3, v124, v3, s91
	v_lshrrev_b32_e32 v46, 16, v46
	v_lshrrev_b32_e32 v47, 16, v47
	v_lshrrev_b32_e32 v48, 16, v48
	v_lshrrev_b32_e32 v49, 16, v49
	v_and_or_b32 v49, v3, s33, v49
	v_and_or_b32 v48, v7, s33, v48
	v_and_or_b32 v47, v14, s33, v47
	v_and_or_b32 v46, v15, s33, v46
	v_bfe_u32 v3, v89, 16, 1
	v_bfe_u32 v7, v87, 16, 1
	s_waitcnt lgkmcnt(0)
	v_mfma_f32_16x16x32_bf16 v[34:37], v[50:53], v[46:49], v[34:37]
	ds_read2_b64 v[50:53], v64 offset0:32 offset1:36
	v_bfe_u32 v14, v77, 16, 1
	v_bfe_u32 v15, v76, 16, 1
	s_waitcnt lgkmcnt(0)
	v_mfma_f32_16x16x32_bf16 v[38:41], v[50:53], v[46:49], v[38:41]
	ds_read2_b64 v[50:53], v63 offset0:64 offset1:68
	v_add3_u32 v15, v76, v15, s91
	v_add3_u32 v14, v77, v14, s91
	s_waitcnt lgkmcnt(0)
	v_mfma_f32_16x16x32_bf16 v[42:45], v[50:53], v[46:49], v[42:45]
	ds_read2_b64 v[50:53], v62 offset0:96 offset1:100
	v_add3_u32 v7, v87, v7, s91
	s_waitcnt lgkmcnt(0)
	v_mfma_f32_16x16x32_bf16 v[30:33], v[50:53], v[46:49], v[30:33]
	ds_read2_b64 v[50:53], v61 offset1:4
	v_bfe_u32 v46, v75, 16, 1
	v_bfe_u32 v47, v74, 16, 1
	v_bfe_u32 v48, v85, 16, 1
	v_bfe_u32 v49, v83, 16, 1
	v_add3_u32 v49, v83, v49, s91
	v_add3_u32 v48, v85, v48, s91
	v_add3_u32 v47, v74, v47, s91
	v_add3_u32 v46, v75, v46, s91
	v_add3_u32 v3, v89, v3, s91
	v_lshrrev_b32_e32 v46, 16, v46
	v_lshrrev_b32_e32 v47, 16, v47
	v_lshrrev_b32_e32 v48, 16, v48
	v_lshrrev_b32_e32 v49, 16, v49
	v_and_or_b32 v49, v3, s33, v49
	v_and_or_b32 v48, v7, s33, v48
	v_and_or_b32 v47, v14, s33, v47
	v_and_or_b32 v46, v15, s33, v46
	v_bfe_u32 v3, v127, 16, 1
	v_bfe_u32 v14, v97, 16, 1
	s_waitcnt lgkmcnt(0)
	v_mfma_f32_16x16x32_bf16 v[34:37], v[50:53], v[46:49], v[34:37]
	ds_read2_b64 v[50:53], v60 offset0:32 offset1:36
	v_bfe_u32 v15, v95, 16, 1
	v_add3_u32 v15, v95, v15, s91
	s_waitcnt lgkmcnt(0)
	v_mfma_f32_16x16x32_bf16 v[38:41], v[50:53], v[46:49], v[38:41]
	ds_read2_b64 v[50:53], v59 offset0:64 offset1:68
	v_add3_u32 v14, v97, v14, s91
	v_add3_u32 v3, v127, v3, s91
	s_waitcnt lgkmcnt(0)
	v_mfma_f32_16x16x32_bf16 v[50:53], v[50:53], v[46:49], v[42:45]
	s_nop 2
	ds_read2_b64 v[42:45], v58 offset0:96 offset1:100
	v_bfe_u32 v7, v125, 16, 1
	s_waitcnt lgkmcnt(0)
	v_mfma_f32_16x16x32_bf16 v[30:33], v[42:45], v[46:49], v[30:33]
	v_bfe_u32 v42, v93, 16, 1
	v_bfe_u32 v43, v91, 16, 1
	v_bfe_u32 v45, v126, 16, 1
	v_bfe_u32 v44, v6, 16, 1
	v_add3_u32 v45, v126, v45, s91
	v_add3_u32 v43, v91, v43, s91
	v_add3_u32 v42, v93, v42, s91
	v_add3_u32 v6, v6, v44, s91
	v_lshrrev_b32_e32 v42, 16, v42
	v_lshrrev_b32_e32 v43, 16, v43
	v_lshrrev_b32_e32 v44, 16, v45
	v_and_or_b32 v49, v3, s33, v44
	v_and_or_b32 v47, v14, s33, v43
	v_and_or_b32 v46, v15, s33, v42
	ds_read2_b64 v[42:45], v57 offset1:4
	v_add3_u32 v7, v125, v7, s91
	v_lshrrev_b32_e32 v6, 16, v6
	v_and_or_b32 v48, v7, s33, v6
	v_div_scale_f32 v3, s[48:49], v2, v2, 1.0
	s_waitcnt lgkmcnt(0)
	v_mfma_f32_16x16x32_bf16 v[42:45], v[42:45], v[46:49], v[34:37]
	s_nop 2
	ds_read2_b64 v[34:37], v56 offset0:32 offset1:36
	v_rcp_f32_e32 v6, v3
	s_waitcnt lgkmcnt(0)
	v_mfma_f32_16x16x32_bf16 v[38:41], v[34:37], v[46:49], v[38:41]
	v_fma_f32 v7, -v3, v6, 1.0
	v_fmac_f32_e32 v6, v7, v6
	v_div_scale_f32 v7, vcc, 1.0, v2, 1.0
	v_mul_f32_e32 v14, v7, v6
	v_fma_f32 v15, -v3, v14, v7
	v_fmac_f32_e32 v14, v15, v6
	ds_read2_b64 v[34:37], v55 offset0:64 offset1:68
	v_fma_f32 v3, -v3, v14, v7
	v_div_fmas_f32 v3, v3, v6, v14
	v_div_fixup_f32 v2, v3, v2, 1.0
	v_mov_b32_e32 v14, v42
	v_mov_b32_e32 v15, v44
	v_pk_mul_f32 v[14:15], v[2:3], v[14:15] op_sel_hi:[0,1]
	v_mov_b32_e32 v44, v43
	v_pk_mul_f32 v[42:43], v[2:3], v[44:45] op_sel_hi:[0,1]
	v_and_b32_sdwa v3, v15, v218 dst_sel:DWORD dst_unused:UNUSED_PAD src0_sel:WORD_1 src1_sel:DWORD
	v_and_b32_sdwa v44, v14, v218 dst_sel:DWORD dst_unused:UNUSED_PAD src0_sel:WORD_1 src1_sel:DWORD
	v_add3_u32 v14, v14, v44, s91
	v_add3_u32 v3, v15, v3, s91
	v_and_b32_sdwa v15, v43, v218 dst_sel:DWORD dst_unused:UNUSED_PAD src0_sel:WORD_1 src1_sel:DWORD
	v_and_b32_sdwa v44, v42, v218 dst_sel:DWORD dst_unused:UNUSED_PAD src0_sel:WORD_1 src1_sel:DWORD
	v_add3_u32 v15, v43, v15, s91
	v_add3_u32 v42, v42, v44, s91
	v_and_b32_e32 v15, 0xffff0000, v15
	v_and_b32_e32 v42, 0xffff0000, v42
	v_lshl_add_u64 v[6:7], v[80:81], 0, s[94:95]
	v_or_b32_sdwa v15, v15, v3 dst_sel:DWORD dst_unused:UNUSED_PAD src0_sel:DWORD src1_sel:WORD_1
	v_or_b32_sdwa v14, v42, v14 dst_sel:DWORD dst_unused:UNUSED_PAD src0_sel:DWORD src1_sel:WORD_1
	s_waitcnt lgkmcnt(0)
	v_mfma_f32_16x16x32_bf16 v[34:37], v[34:37], v[46:49], v[50:53]
	v_lshlrev_b32_e32 v44, 16, v22
	v_lshlrev_b32_e32 v45, 16, v23
	v_and_b32_e32 v42, 0xffff0000, v28
	ds_read2_b64 v[50:53], v54 offset0:96 offset1:100
	global_store_dwordx2 v[6:7], v[14:15], off
	v_mov_b32_e32 v14, v38
	v_mov_b32_e32 v15, v40
	v_pk_mul_f32 v[14:15], v[2:3], v[14:15] op_sel_hi:[0,1]
	v_mov_b32_e32 v40, v39
	v_pk_mul_f32 v[38:39], v[2:3], v[40:41] op_sel_hi:[0,1]
	v_and_b32_sdwa v3, v15, v218 dst_sel:DWORD dst_unused:UNUSED_PAD src0_sel:WORD_1 src1_sel:DWORD
	v_and_b32_sdwa v40, v14, v218 dst_sel:DWORD dst_unused:UNUSED_PAD src0_sel:WORD_1 src1_sel:DWORD
	v_add3_u32 v14, v14, v40, s91
	v_add3_u32 v3, v15, v3, s91
	v_and_b32_sdwa v15, v39, v218 dst_sel:DWORD dst_unused:UNUSED_PAD src0_sel:WORD_1 src1_sel:DWORD
	v_and_b32_sdwa v40, v38, v218 dst_sel:DWORD dst_unused:UNUSED_PAD src0_sel:WORD_1 src1_sel:DWORD
	v_add3_u32 v15, v39, v15, s91
	v_add3_u32 v38, v38, v40, s91
	v_and_b32_e32 v15, 0xffff0000, v15
	v_and_b32_e32 v38, 0xffff0000, v38
	v_or_b32_sdwa v15, v15, v3 dst_sel:DWORD dst_unused:UNUSED_PAD src0_sel:DWORD src1_sel:WORD_1
	v_or_b32_sdwa v14, v38, v14 dst_sel:DWORD dst_unused:UNUSED_PAD src0_sel:DWORD src1_sel:WORD_1
	global_store_dwordx2 v[6:7], v[14:15], off offset:32
	v_mov_b32_e32 v14, v34
	v_mov_b32_e32 v15, v36
	v_pk_mul_f32 v[14:15], v[2:3], v[14:15] op_sel_hi:[0,1]
	v_mov_b32_e32 v36, v35
	v_pk_mul_f32 v[34:35], v[2:3], v[36:37] op_sel_hi:[0,1]
	v_and_b32_sdwa v3, v15, v218 dst_sel:DWORD dst_unused:UNUSED_PAD src0_sel:WORD_1 src1_sel:DWORD
	v_and_b32_sdwa v36, v14, v218 dst_sel:DWORD dst_unused:UNUSED_PAD src0_sel:WORD_1 src1_sel:DWORD
	s_waitcnt lgkmcnt(0)
	v_mfma_f32_16x16x32_bf16 v[30:33], v[50:53], v[46:49], v[30:33]
	v_add3_u32 v14, v14, v36, s91
	v_add3_u32 v3, v15, v3, s91
	v_and_b32_sdwa v15, v35, v218 dst_sel:DWORD dst_unused:UNUSED_PAD src0_sel:WORD_1 src1_sel:DWORD
	v_and_b32_sdwa v36, v34, v218 dst_sel:DWORD dst_unused:UNUSED_PAD src0_sel:WORD_1 src1_sel:DWORD
	v_add3_u32 v15, v35, v15, s91
	v_add3_u32 v34, v34, v36, s91
	v_and_b32_e32 v15, 0xffff0000, v15
	v_and_b32_e32 v34, 0xffff0000, v34
	v_or_b32_sdwa v15, v15, v3 dst_sel:DWORD dst_unused:UNUSED_PAD src0_sel:DWORD src1_sel:WORD_1
	v_or_b32_sdwa v14, v34, v14 dst_sel:DWORD dst_unused:UNUSED_PAD src0_sel:DWORD src1_sel:WORD_1
	global_store_dwordx2 v[6:7], v[14:15], off offset:64
	v_mov_b32_e32 v14, v30
	v_mov_b32_e32 v15, v32
	v_pk_mul_f32 v[14:15], v[2:3], v[14:15] op_sel_hi:[0,1]
	v_mov_b32_e32 v32, v31
	v_pk_mul_f32 v[2:3], v[2:3], v[32:33] op_sel_hi:[0,1]
	v_and_b32_sdwa v30, v15, v218 dst_sel:DWORD dst_unused:UNUSED_PAD src0_sel:WORD_1 src1_sel:DWORD
	v_and_b32_sdwa v31, v14, v218 dst_sel:DWORD dst_unused:UNUSED_PAD src0_sel:WORD_1 src1_sel:DWORD
	v_add3_u32 v14, v14, v31, s91
	v_add3_u32 v15, v15, v30, s91
	v_and_b32_sdwa v30, v3, v218 dst_sel:DWORD dst_unused:UNUSED_PAD src0_sel:WORD_1 src1_sel:DWORD
	v_and_b32_sdwa v31, v2, v218 dst_sel:DWORD dst_unused:UNUSED_PAD src0_sel:WORD_1 src1_sel:DWORD
	v_add3_u32 v3, v3, v30, s91
	v_add3_u32 v2, v2, v31, s91
	v_and_b32_e32 v3, 0xffff0000, v3
	v_and_b32_e32 v2, 0xffff0000, v2
	v_or_b32_sdwa v3, v3, v15 dst_sel:DWORD dst_unused:UNUSED_PAD src0_sel:DWORD src1_sel:WORD_1
	v_or_b32_sdwa v2, v2, v14 dst_sel:DWORD dst_unused:UNUSED_PAD src0_sel:DWORD src1_sel:WORD_1
	global_store_dwordx2 v[6:7], v[2:3], off offset:96
	v_and_b32_e32 v46, 0xffff0000, v22
	v_and_b32_e32 v47, 0xffff0000, v23
	v_lshlrev_b32_e32 v48, 16, v24
	v_and_b32_e32 v50, 0xffff0000, v24
	v_lshlrev_b32_e32 v49, 16, v25
	v_and_b32_e32 v51, 0xffff0000, v25
	ds_read2_b64 v[22:25], v79 offset1:1
	v_lshlrev_b32_e32 v3, 16, v27
	v_and_b32_e32 v7, 0xffff0000, v27
	v_lshlrev_b32_e32 v14, 16, v28
	v_lshlrev_b32_e32 v15, 16, v29
	s_waitcnt lgkmcnt(0)
	v_readfirstlane_b32 s48, v22
	v_readfirstlane_b32 s49, v23
	s_add_u32 s0, s48, s0
	v_and_b32_e32 v43, 0xffff0000, v29
	s_addc_u32 s1, s49, s1
	s_nop 1
	v_lshl_add_u64 v[154:155], s[0:1], 0, v[0:1]
	global_load_dwordx4 v[156:159], v[154:155], off offset:144
	s_nop 1
	v_lshl_add_u64 v[148:149], s[0:1], 0, v[0:1]
	global_load_dwordx4 v[150:153], v[148:149], off offset:16
	v_mov_b32_e32 v28, v47
	v_mov_b32_e32 v29, v45
	v_lshlrev_b32_e32 v2, 16, v26
	v_and_b32_e32 v6, 0xffff0000, v26
	v_lshl_add_u64 v[22:23], s[0:1], 0, v[0:1]
	v_mov_b32_e32 v26, v7
	v_mov_b32_e32 v27, v3
	v_pk_mul_f32 v[28:29], v[28:29], v[28:29]
	global_load_dwordx4 v[30:33], v[22:23], off offset:128
	v_pk_fma_f32 v[52:53], v[26:27], v[26:27], v[28:29]
	global_load_dwordx4 v[26:29], v[22:23], off
	v_mov_b32_e32 v34, v51
	v_mov_b32_e32 v35, v49
	v_pk_mul_f32 v[34:35], v[34:35], v[34:35]
	v_mul_f32_e32 v0, v6, v6
	v_fmac_f32_e32 v0, v46, v46
	s_waitcnt vmcnt(0) lgkmcnt(0)
	v_mov_b32_e32 v76, v30
	v_mov_b32_e32 v77, v32
	v_mov_b32_e32 v32, v31
	v_mov_b32_e32 v30, v50
	v_mov_b32_e32 v31, v48
	v_mov_b32_e32 v74, v26
	v_mov_b32_e32 v75, v28
	v_mov_b32_e32 v28, v27
	v_mov_b32_e32 v26, v42
	v_mov_b32_e32 v27, v14
	v_pk_mul_f32 v[30:31], v[30:31], v[30:31]
	s_nop 0
	v_pk_fma_f32 v[26:27], v[26:27], v[26:27], v[30:31]
	v_mov_b32_e32 v30, v43
	v_mov_b32_e32 v31, v15
	v_pk_fma_f32 v[30:31], v[30:31], v[30:31], v[34:35]
	s_waitcnt vmcnt(2)
	s_nop 0
	v_mov_b32_e32 v34, v150
	v_mov_b32_e32 v35, v151
	v_mov_b32_e32 v36, v152
	v_mov_b32_e32 v37, v153
	s_nop 1
	s_waitcnt vmcnt(3)
	s_nop 0
	v_mov_b32_e32 v38, v156
	v_mov_b32_e32 v39, v157
	v_mov_b32_e32 v40, v158
	v_mov_b32_e32 v41, v159
	s_nop 1
	v_mul_f32_e32 v22, v2, v2
	v_fmac_f32_e32 v22, v44, v44
	v_add_f32_e32 v0, v22, v0
	v_add_f32_e32 v0, v53, v0
	v_add_f32_e32 v0, v52, v0
	v_add_f32_e32 v0, v27, v0
	v_add_f32_e32 v0, v26, v0
	v_add_f32_e32 v0, v31, v0
	v_add_f32_e32 v0, v30, v0
	ds_bpermute_b32 v22, v109, v0
	s_waitcnt lgkmcnt(0)
	v_add_f32_e32 v0, v0, v22
	ds_bpermute_b32 v22, v110, v0
	s_waitcnt lgkmcnt(0)
	v_add_f32_e32 v0, v0, v22
	v_fmamk_f32 v0, v0, 0x3c800000, v219
	v_cmp_gt_f32_e32 vcc, s6, v0
	v_mul_f32_e32 v22, 0x4f800000, v0
	s_nop 0
	v_cndmask_b32_e32 v0, v0, v22, vcc
	v_sqrt_f32_e32 v22, v0
	s_nop 0
	v_add_u32_e32 v23, -1, v22
	v_fma_f32 v26, -v23, v22, v0
	v_cmp_ge_f32_e64 s[88:89], 0, v26
	v_add_u32_e32 v26, 1, v22
	s_nop 0
	v_cndmask_b32_e64 v23, v22, v23, s[88:89]
	v_fma_f32 v22, -v26, v22, v0
	v_cmp_lt_f32_e64 s[88:89], 0, v22
	s_nop 1
	v_cndmask_b32_e64 v22, v23, v26, s[88:89]
	v_mul_f32_e32 v23, 0x37800000, v22
	v_cndmask_b32_e32 v22, v22, v23, vcc
	v_cmp_class_f32_e32 vcc, v0, v221
	s_mov_b32 s89, 0xf149f2ca
	s_movk_i32 s88, 0x90
	v_cndmask_b32_e32 v0, v22, v0, vcc
	v_div_scale_f32 v22, s[0:1], v0, v0, 1.0
	v_rcp_f32_e32 v23, v22
	v_readfirstlane_b32 s0, v24
	v_readfirstlane_b32 s1, v25
	s_add_u32 s0, s0, s2
	v_fma_f32 v26, -v22, v23, 1.0
	v_fmac_f32_e32 v23, v26, v23
	v_div_scale_f32 v26, vcc, 1.0, v0, 1.0
	v_mul_f32_e32 v27, v26, v23
	v_fma_f32 v30, -v22, v27, v26
	v_fmac_f32_e32 v27, v30, v23
	v_fma_f32 v22, -v22, v27, v26
	v_div_fmas_f32 v22, v22, v23, v27
	v_div_fixup_f32 v0, v22, v0, 1.0
	v_pk_mul_f32 v[26:27], v[0:1], v[46:47] op_sel_hi:[0,1]
	v_pk_mul_f32 v[6:7], v[0:1], v[6:7] op_sel_hi:[0,1]
	v_pk_mul_f32 v[26:27], v[26:27], v[32:33]
	v_pk_mul_f32 v[14:15], v[0:1], v[14:15] op_sel_hi:[0,1]
	v_pk_mul_f32 v[22:23], v[0:1], v[44:45] op_sel_hi:[0,1]
	v_pk_mul_f32 v[6:7], v[6:7], v[28:29]
	v_pk_mul_f32 v[30:31], v[12:13], v[26:27]
	v_pk_mul_f32 v[42:43], v[0:1], v[42:43] op_sel_hi:[0,1]
	v_pk_fma_f32 v[30:31], v[20:21], v[6:7], v[30:31]
	v_pk_mul_f32 v[20:21], v[20:21], v[26:27]
	v_pk_mul_f32 v[2:3], v[0:1], v[2:3] op_sel_hi:[0,1]
	v_pk_fma_f32 v[6:7], v[12:13], v[6:7], v[20:21] neg_lo:[0,0,1] neg_hi:[0,0,1]
	v_pk_mul_f32 v[22:23], v[76:77], v[22:23]
	v_pk_mul_f32 v[2:3], v[74:75], v[2:3]
	v_pk_mul_f32 v[28:29], v[102:103], v[22:23]
	s_waitcnt vmcnt(0)
	v_mov_b32_e32 v32, v34
	v_mov_b32_e32 v33, v36
	v_pk_mul_f32 v[14:15], v[14:15], v[32:33]
	v_pk_mul_f32 v[32:33], v[0:1], v[48:49] op_sel_hi:[0,1]
	v_mov_b32_e32 v44, v38
	v_mov_b32_e32 v45, v40
	v_mov_b32_e32 v36, v35
	v_pk_mul_f32 v[32:33], v[32:33], v[44:45]
	v_pk_mul_f32 v[34:35], v[42:43], v[36:37]
	v_pk_mul_f32 v[36:37], v[0:1], v[50:51] op_sel_hi:[0,1]
	v_mov_b32_e32 v40, v39
	v_pk_mul_f32 v[36:37], v[36:37], v[40:41]
	v_pk_mul_f32 v[12:13], v[18:19], v[32:33]
	v_pk_mul_f32 v[38:39], v[10:11], v[32:33]
	v_pk_fma_f32 v[10:11], v[10:11], v[14:15], v[12:13] neg_lo:[0,0,1] neg_hi:[0,0,1]
	v_pk_mul_f32 v[12:13], v[16:17], v[36:37]
	v_pk_mul_f32 v[40:41], v[8:9], v[36:37]
	v_pk_mul_f32 v[22:23], v[104:105], v[22:23]
	v_pk_mul_f32 v[6:7], v[6:7], s[86:87] op_sel_hi:[1,0]
	v_pk_fma_f32 v[8:9], v[8:9], v[34:35], v[12:13] neg_lo:[0,0,1] neg_hi:[0,0,1]
	v_pk_fma_f32 v[28:29], v[104:105], v[2:3], v[28:29]
	v_pk_fma_f32 v[38:39], v[18:19], v[14:15], v[38:39]
	v_pk_fma_f32 v[2:3], v[102:103], v[2:3], v[22:23] neg_lo:[0,0,1] neg_hi:[0,0,1]
	v_pk_mul_f32 v[10:11], v[10:11], s[86:87] op_sel_hi:[1,0]
	v_pk_mul_f32 v[8:9], v[8:9], s[86:87] op_sel_hi:[1,0]
	v_bfe_u32 v13, v7, 16, 1
	v_bfe_u32 v14, v6, 16, 1
	v_pk_mul_f32 v[2:3], v[2:3], s[86:87] op_sel_hi:[1,0]
	v_bfe_u32 v0, v9, 16, 1
	v_add3_u32 v6, v6, v14, s91
	v_add3_u32 v7, v7, v13, s91
	v_bfe_u32 v13, v10, 16, 1
	v_bfe_u32 v14, v11, 16, 1
	v_pk_mul_f32 v[28:29], v[28:29], s[86:87] op_sel_hi:[1,0]
	v_bfe_u32 v12, v8, 16, 1
	v_add3_u32 v0, v9, v0, s91
	v_bfe_u32 v9, v2, 16, 1
	v_add3_u32 v11, v11, v14, s91
	v_add3_u32 v10, v10, v13, s91
	v_pk_mul_f32 v[30:31], v[30:31], s[86:87] op_sel_hi:[1,0]
	v_pk_mul_f32 v[38:39], v[38:39], s[86:87] op_sel_hi:[1,0]
	v_add3_u32 v8, v8, v12, s91
	v_bfe_u32 v12, v3, 16, 1
	v_add3_u32 v2, v2, v9, s91
	v_lshrrev_b32_e32 v10, 16, v10
	v_lshrrev_b32_e32 v9, 16, v11
	v_bfe_u32 v11, v28, 16, 1
	v_add3_u32 v3, v3, v12, s91
	v_and_or_b32 v8, v8, s33, v10
	v_bfe_u32 v10, v30, 16, 1
	v_bfe_u32 v12, v29, 16, 1
	v_bfe_u32 v13, v38, 16, 1
	v_bfe_u32 v14, v39, 16, 1
	v_add3_u32 v11, v28, v11, s91
	v_add3_u32 v10, v30, v10, s91
	v_add3_u32 v14, v39, v14, s91
	v_add3_u32 v13, v38, v13, s91
	v_add3_u32 v12, v29, v12, s91
	v_lshrrev_b32_e32 v15, 16, v11
	v_pk_fma_f32 v[40:41], v[16:17], v[34:35], v[40:41]
	v_lshrrev_b32_e32 v11, 16, v12
	v_lshrrev_b32_e32 v12, 16, v13
	v_lshrrev_b32_e32 v13, 16, v14
	v_and_or_b32 v10, v10, s33, v15
	ds_read_b128 v[14:17], v100
	ds_read_b128 v[18:21], v100 offset:64
	v_lshrrev_b32_e32 v2, 16, v2
	v_lshrrev_b32_e32 v3, 16, v3
	v_and_or_b32 v9, v0, s33, v9
	v_and_or_b32 v7, v7, s33, v3
	v_and_or_b32 v6, v6, s33, v2
	v_pk_mul_f32 v[40:41], v[40:41], s[86:87] op_sel_hi:[1,0]
	v_bfe_u32 v3, v31, 16, 1
	s_waitcnt lgkmcnt(1)
	v_mfma_f32_16x16x32_bf16 v[14:17], v[14:17], v[6:9], 0
	v_bfe_u32 v0, v41, 16, 1
	v_bfe_u32 v2, v40, 16, 1
	v_add3_u32 v3, v31, v3, s91
	v_add3_u32 v2, v40, v2, s91
	v_add3_u32 v0, v41, v0, s91
	v_and_or_b32 v13, v0, s33, v13
	v_and_or_b32 v12, v2, s33, v12
	v_and_or_b32 v11, v3, s33, v11
	ds_read_b128 v[22:25], v98 offset:64
	s_addc_u32 s1, s1, s3
	s_nop 1
	v_mov_b64_e32 v[160:161], s[0:1]
	global_load_dword v162, v[160:161], off offset:8
	s_waitcnt lgkmcnt(1)
	v_mfma_f32_16x16x32_bf16 v[14:17], v[18:21], v[10:13], v[14:17]
	ds_read_b128 v[18:21], v98
	v_mov_b64_e32 v[2:3], s[0:1]
	s_waitcnt vmcnt(0)
	s_nop 0
	v_mov_b32_e32 v0, v162
	s_nop 1
	s_waitcnt lgkmcnt(0)
	v_mfma_f32_16x16x32_bf16 v[18:21], v[18:21], v[6:9], 0
	ds_read_b128 v[26:29], v96 offset:64
	ds_read_b128 v[30:33], v94 offset:64
	v_mfma_f32_16x16x32_bf16 v[18:21], v[22:25], v[10:13], v[18:21]
	ds_read_b128 v[22:25], v96
	v_readlane_b32 s0, v255, 22
	v_mov_b32_e32 v2, s89
	s_waitcnt lgkmcnt(0)
	v_mfma_f32_16x16x32_bf16 v[22:25], v[22:25], v[6:9], 0
	v_readlane_b32 s1, v255, 23
	v_cndmask_b32_e64 v3, v14, v2, s[8:9]
	v_mfma_f32_16x16x32_bf16 v[22:25], v[26:29], v[10:13], v[22:25]
	ds_read_b128 v[26:29], v94
	ds_read_b128 v[34:37], v92 offset:64
	s_waitcnt lgkmcnt(0)
	v_mfma_f32_16x16x32_bf16 v[26:29], v[26:29], v[6:9], 0
	ds_read_b128 v[38:41], v90 offset:64
	v_mfma_f32_16x16x32_bf16 v[26:29], v[30:33], v[10:13], v[26:29]
	ds_read_b128 v[30:33], v92
	s_waitcnt lgkmcnt(0)
	v_mfma_f32_16x16x32_bf16 v[30:33], v[30:33], v[6:9], 0
	v_mfma_f32_16x16x32_bf16 v[30:33], v[34:37], v[10:13], v[30:33]
	ds_read_b128 v[34:37], v90
	ds_read_b128 v[42:45], v88 offset:64
	s_waitcnt lgkmcnt(0)
	v_mfma_f32_16x16x32_bf16 v[34:37], v[34:37], v[6:9], 0
	ds_read_b128 v[46:49], v86 offset:64
	v_mfma_f32_16x16x32_bf16 v[34:37], v[38:41], v[10:13], v[34:37]
	ds_read_b128 v[38:41], v88
	s_waitcnt lgkmcnt(0)
	v_mfma_f32_16x16x32_bf16 v[38:41], v[38:41], v[6:9], 0
	s_nop 4
	v_cndmask_b32_e64 v37, v37, v227, s[36:37]
	v_mfma_f32_16x16x32_bf16 v[38:41], v[42:45], v[10:13], v[38:41]
	ds_read_b128 v[42:45], v86
	ds_read_b128 v[50:53], v84 offset:64
	s_waitcnt lgkmcnt(0)
	v_mfma_f32_16x16x32_bf16 v[42:45], v[42:45], v[6:9], 0
	s_nop 3
	v_cndmask_b32_e64 v39, v39, v227, s[46:47]
	v_cndmask_b32_e64 v40, v40, v227, s[50:51]
	v_cndmask_b32_e64 v41, v41, v227, s[52:53]
	v_mfma_f32_16x16x32_bf16 v[42:45], v[46:49], v[10:13], v[42:45]
	ds_read_b128 v[46:49], v84
	s_waitcnt lgkmcnt(0)
	v_mfma_f32_16x16x32_bf16 v[46:49], v[46:49], v[6:9], 0
	s_nop 4
	v_cndmask_b32_e64 v43, v43, v227, s[56:57]
	v_cndmask_b32_e64 v44, v44, v227, s[58:59]
	v_cndmask_b32_e64 v45, v45, v227, s[60:61]
	v_mfma_f32_16x16x32_bf16 v[46:49], v[50:53], v[10:13], v[46:49]
	ds_read_b128 v[50:53], v82
	s_waitcnt lgkmcnt(0)
	v_mfma_f32_16x16x32_bf16 v[6:9], v[50:53], v[6:9], 0
	ds_read_b128 v[50:53], v82 offset:64
	s_nop 3
	v_cndmask_b32_e64 v47, v47, v227, s[64:65]
	v_cndmask_b32_e64 v48, v48, v227, s[66:67]
	s_waitcnt lgkmcnt(0)
	v_mfma_f32_16x16x32_bf16 v[6:9], v[50:53], v[10:13], v[6:9]
	v_cndmask_b32_e64 v10, v15, v227, s[0:1]
	v_max3_f32 v2, v3, s89, v10
	v_cndmask_b32_e64 v11, v16, v227, s[40:41]
	v_cndmask_b32_e64 v12, v17, v227, s[92:93]
	v_max3_f32 v13, v2, v11, v12
	v_mov_b32_e32 v2, s89
	v_cndmask_b32_e64 v14, v18, v2, s[18:19]
	v_cndmask_b32_e64 v15, v19, v227, s[10:11]
	v_max3_f32 v2, v13, v14, v15
	v_cndmask_b32_e64 v13, v20, v227, s[12:13]
	v_cndmask_b32_e64 v16, v21, v227, s[44:45]
	v_max3_f32 v17, v2, v13, v16
	v_mov_b32_e32 v2, s89
	v_cndmask_b32_e64 v18, v22, v2, s[16:17]
	v_cndmask_b32_e64 v19, v23, v227, s[80:81]
	v_max3_f32 v2, v17, v18, v19
	v_cndmask_b32_e64 v17, v24, v227, s[82:83]
	v_cndmask_b32_e64 v20, v25, v227, s[84:85]
	v_max3_f32 v21, v2, v17, v20
	v_mov_b32_e32 v2, s89
	v_cndmask_b32_e64 v22, v26, v2, s[20:21]
	v_cndmask_b32_e64 v23, v27, v227, s[76:77]
	v_max3_f32 v2, v21, v22, v23
	v_cndmask_b32_e64 v21, v28, v227, s[78:79]
	v_cndmask_b32_e64 v24, v29, v227, s[14:15]
	v_max3_f32 v25, v2, v21, v24
	v_mov_b32_e32 v2, s89
	v_cndmask_b32_e64 v26, v30, v2, s[28:29]
	v_cndmask_b32_e64 v27, v31, v227, s[42:43]
	v_max3_f32 v2, v25, v26, v27
	v_cndmask_b32_e64 v25, v32, v227, s[22:23]
	v_cndmask_b32_e64 v50, v33, v227, s[26:27]
	v_max3_f32 v28, v2, v25, v50
	v_mov_b32_e32 v2, s89
	v_cndmask_b32_e64 v51, v34, v2, s[38:39]
	v_cndmask_b32_e64 v52, v35, v227, s[30:31]
	v_max3_f32 v2, v28, v51, v52
	v_cndmask_b32_e64 v53, v36, v227, s[34:35]
	v_max3_f32 v28, v2, v53, v37
	v_mov_b32_e32 v2, s89
	v_cndmask_b32_e64 v38, v38, v2, s[54:55]
	v_max3_f32 v2, v28, v38, v39
	v_max3_f32 v28, v2, v40, v41
	v_mov_b32_e32 v2, s89
	v_cndmask_b32_e64 v42, v42, v2, s[62:63]
	v_max3_f32 v2, v28, v42, v43
	v_max3_f32 v28, v2, v44, v45
	v_mov_b32_e32 v2, s89
	v_cndmask_b32_e64 v46, v46, v2, s[4:5]
	v_max3_f32 v2, v28, v46, v47
	v_cndmask_b32_e64 v49, v49, v227, s[68:69]
	v_max3_f32 v28, v2, v48, v49
	v_mov_b32_e32 v2, s89
	v_cndmask_b32_e64 v74, v6, v2, s[24:25]
	v_cndmask_b32_e64 v75, v7, v227, s[70:71]
	v_max3_f32 v2, v28, v74, v75
	v_cndmask_b32_e64 v76, v8, v227, s[72:73]
	v_cndmask_b32_e64 v77, v9, v227, s[74:75]
	v_max3_f32 v2, v2, v76, v77
	ds_bpermute_b32 v6, v109, v2
	v_readlane_b32 s40, v254, 60
	s_mov_b32 s85, 0xf800000
	s_waitcnt lgkmcnt(0)
	v_max_f32_e32 v6, v6, v6
	v_max_f32_e32 v2, v2, v6
	ds_bpermute_b32 v6, v110, v2
	s_waitcnt vmcnt(0) lgkmcnt(0)
	v_max3_f32 v79, v2, v6, v0
	v_sub_f32_e32 v2, v3, v79
	v_sub_f32_e32 v3, v10, v79
	v_mul_f32_e32 v3, 0x3fb8aa3b, v3
	v_exp_f32_e32 v82, v3
	v_sub_f32_e32 v3, v11, v79
	v_mul_f32_e32 v3, 0x3fb8aa3b, v3
	v_exp_f32_e32 v83, v3
	v_sub_f32_e32 v3, v12, v79
	v_mul_f32_e32 v3, 0x3fb8aa3b, v3
	v_exp_f32_e32 v84, v3
	v_sub_f32_e32 v3, v14, v79
	v_mul_f32_e32 v3, 0x3fb8aa3b, v3
	v_exp_f32_e32 v85, v3
	v_sub_f32_e32 v3, v15, v79
	v_mul_f32_e32 v3, 0x3fb8aa3b, v3
	v_exp_f32_e32 v86, v3
	v_sub_f32_e32 v3, v13, v79
	v_mul_f32_e32 v3, 0x3fb8aa3b, v3
	v_exp_f32_e32 v87, v3
	v_sub_f32_e32 v3, v16, v79
	v_mul_f32_e32 v3, 0x3fb8aa3b, v3
	v_exp_f32_e32 v88, v3
	v_sub_f32_e32 v3, v18, v79
	v_mul_f32_e32 v3, 0x3fb8aa3b, v3
	v_exp_f32_e32 v28, v3
	v_sub_f32_e32 v3, v19, v79
	v_mul_f32_e32 v3, 0x3fb8aa3b, v3
	v_exp_f32_e32 v30, v3
	v_sub_f32_e32 v3, v17, v79
	v_mul_f32_e32 v3, 0x3fb8aa3b, v3
	v_exp_f32_e32 v29, v3
	v_sub_f32_e32 v3, v20, v79
	v_mul_f32_e32 v3, 0x3fb8aa3b, v3
	v_exp_f32_e32 v31, v3
	v_sub_f32_e32 v3, v22, v79
	v_mul_f32_e32 v3, 0x3fb8aa3b, v3
	v_exp_f32_e32 v32, v3
	v_sub_f32_e32 v3, v23, v79
	v_mul_f32_e32 v3, 0x3fb8aa3b, v3
	v_exp_f32_e32 v33, v3
	v_sub_f32_e32 v3, v21, v79
	v_mul_f32_e32 v3, 0x3fb8aa3b, v3
	v_exp_f32_e32 v34, v3
	v_sub_f32_e32 v3, v24, v79
	v_mul_f32_e32 v3, 0x3fb8aa3b, v3
	v_mul_f32_e32 v2, 0x3fb8aa3b, v2
	v_exp_f32_e32 v35, v3
	v_sub_f32_e32 v3, v26, v79
	v_exp_f32_e32 v36, v2
	v_mul_f32_e32 v3, 0x3fb8aa3b, v3
	v_exp_f32_e32 v20, v3
	v_sub_f32_e32 v3, v27, v79
	v_mul_f32_e32 v3, 0x3fb8aa3b, v3
	v_exp_f32_e32 v22, v3
	v_sub_f32_e32 v3, v25, v79
	v_add_f32_e32 v2, 0, v36
	v_mul_f32_e32 v3, 0x3fb8aa3b, v3
	v_add_f32_e32 v2, v82, v2
	v_exp_f32_e32 v21, v3
	v_sub_f32_e32 v3, v50, v79
	v_add_f32_e32 v2, v83, v2
	v_mul_f32_e32 v3, 0x3fb8aa3b, v3
	v_add_f32_e32 v2, v84, v2
	v_exp_f32_e32 v23, v3
	v_sub_f32_e32 v3, v51, v79
	v_add_f32_e32 v2, v85, v2
	v_mul_f32_e32 v3, 0x3fb8aa3b, v3
	v_add_f32_e32 v2, v86, v2
	v_exp_f32_e32 v24, v3
	v_sub_f32_e32 v3, v52, v79
	v_add_f32_e32 v2, v87, v2
	v_mul_f32_e32 v3, 0x3fb8aa3b, v3
	v_add_f32_e32 v2, v88, v2
	v_exp_f32_e32 v25, v3
	v_sub_f32_e32 v3, v53, v79
	v_add_f32_e32 v2, v28, v2
	v_mul_f32_e32 v3, 0x3fb8aa3b, v3
	v_add_f32_e32 v2, v30, v2
	v_exp_f32_e32 v26, v3
	v_sub_f32_e32 v3, v37, v79
	v_add_f32_e32 v2, v29, v2
	v_mul_f32_e32 v3, 0x3fb8aa3b, v3
	v_add_f32_e32 v2, v31, v2
	v_exp_f32_e32 v27, v3
	v_sub_f32_e32 v3, v38, v79
	v_add_f32_e32 v2, v32, v2
	v_mul_f32_e32 v3, 0x3fb8aa3b, v3
	v_add_f32_e32 v2, v33, v2
	v_exp_f32_e32 v12, v3
	v_sub_f32_e32 v3, v39, v79
	v_add_f32_e32 v2, v34, v2
	v_mul_f32_e32 v3, 0x3fb8aa3b, v3
	v_add_f32_e32 v2, v35, v2
	v_exp_f32_e32 v14, v3
	v_sub_f32_e32 v3, v40, v79
	v_add_f32_e32 v2, v20, v2
	v_mul_f32_e32 v3, 0x3fb8aa3b, v3
	v_add_f32_e32 v2, v22, v2
	v_exp_f32_e32 v13, v3
	v_sub_f32_e32 v3, v41, v79
	v_add_f32_e32 v2, v21, v2
	v_mul_f32_e32 v3, 0x3fb8aa3b, v3
	v_add_f32_e32 v2, v23, v2
	v_exp_f32_e32 v15, v3
	v_sub_f32_e32 v3, v42, v79
	v_add_f32_e32 v2, v24, v2
	v_mul_f32_e32 v3, 0x3fb8aa3b, v3
	v_add_f32_e32 v2, v25, v2
	v_exp_f32_e32 v16, v3
	v_sub_f32_e32 v3, v43, v79
	v_add_f32_e32 v2, v26, v2
	v_mul_f32_e32 v3, 0x3fb8aa3b, v3
	v_add_f32_e32 v2, v27, v2
	v_exp_f32_e32 v17, v3
	v_sub_f32_e32 v3, v44, v79
	v_add_f32_e32 v2, v12, v2
	v_mul_f32_e32 v3, 0x3fb8aa3b, v3
	v_add_f32_e32 v2, v14, v2
	v_exp_f32_e32 v18, v3
	v_sub_f32_e32 v3, v45, v79
	v_add_f32_e32 v2, v13, v2
	v_mul_f32_e32 v3, 0x3fb8aa3b, v3
	v_add_f32_e32 v2, v15, v2
	v_exp_f32_e32 v19, v3
	v_add_f32_e32 v2, v16, v2
	v_add_f32_e32 v2, v17, v2
	v_add_f32_e32 v2, v18, v2
	v_add_f32_e32 v3, v19, v2
	v_sub_f32_e32 v2, v46, v79
	v_mul_f32_e32 v2, 0x3fb8aa3b, v2
	v_sub_f32_e32 v6, v47, v79
	v_exp_f32_e32 v2, v2
	v_mul_f32_e32 v6, 0x3fb8aa3b, v6
	v_exp_f32_e32 v6, v6
	v_sub_f32_e32 v8, v49, v79
	v_add_f32_e32 v3, v2, v3
	v_mul_f32_e32 v8, 0x3fb8aa3b, v8
	v_add_f32_e32 v7, v6, v3
	v_sub_f32_e32 v3, v48, v79
	v_mul_f32_e32 v3, 0x3fb8aa3b, v3
	v_exp_f32_e32 v3, v3
	v_exp_f32_e32 v8, v8
	v_sub_f32_e32 v10, v75, v79
	v_mul_f32_e32 v10, 0x3fb8aa3b, v10
	v_add_f32_e32 v7, v3, v7
	v_add_f32_e32 v9, v8, v7
	v_sub_f32_e32 v7, v74, v79
	v_mul_f32_e32 v7, 0x3fb8aa3b, v7
	v_exp_f32_e32 v7, v7
	v_exp_f32_e32 v10, v10
	v_sub_f32_e32 v0, v0, v79
	v_mul_f32_e32 v0, 0x3fb8aa3b, v0
	v_add_f32_e32 v9, v7, v9
	v_add_f32_e32 v11, v10, v9
	v_sub_f32_e32 v9, v76, v79
	v_mul_f32_e32 v9, 0x3fb8aa3b, v9
	v_exp_f32_e32 v9, v9
	v_exp_f32_e32 v0, v0
	v_bfe_u32 v39, v84, 16, 1
	v_add3_u32 v41, v84, v39, s91
	v_add_f32_e32 v37, v9, v11
	v_sub_f32_e32 v11, v77, v79
	v_mul_f32_e32 v11, 0x3fb8aa3b, v11
	v_exp_f32_e32 v11, v11
	v_bfe_u32 v39, v36, 16, 1
	v_bfe_u32 v42, v83, 16, 1
	v_bfe_u32 v43, v85, 16, 1
	v_add_f32_e32 v37, v11, v37
	ds_bpermute_b32 v38, v109, v37
	v_bfe_u32 v44, v87, 16, 1
	v_bfe_u32 v40, v82, 16, 1
	v_add3_u32 v44, v87, v44, s91
	v_add3_u32 v43, v85, v43, s91
	s_waitcnt lgkmcnt(0)
	v_add_f32_e32 v37, v37, v38
	ds_bpermute_b32 v38, v110, v37
	v_add3_u32 v42, v83, v42, s91
	v_add3_u32 v36, v36, v39, s91
	v_add3_u32 v40, v82, v40, s91
	v_lshrrev_b32_e32 v36, 16, v36
	s_waitcnt lgkmcnt(0)
	v_add_f32_e32 v37, v37, v38
	v_add_f32_e32 v0, v0, v37
	v_bfe_u32 v37, v88, 16, 1
	v_bfe_u32 v38, v86, 16, 1
	v_add3_u32 v38, v86, v38, s91
	v_add3_u32 v37, v88, v37, s91
	v_lshrrev_b32_e32 v42, 16, v42
	v_lshrrev_b32_e32 v43, 16, v43
	v_lshrrev_b32_e32 v39, 16, v44
	v_and_or_b32 v39, v37, s33, v39
	v_and_or_b32 v38, v38, s33, v43
	v_and_or_b32 v37, v41, s33, v42
	v_and_or_b32 v36, v40, s33, v36
	ds_read2_b64 v[40:43], v73 offset1:4
	ds_read2_b64 v[44:47], v72 offset0:32 offset1:36
	ds_read2_b64 v[48:51], v71 offset0:64 offset1:68
	ds_read2_b64 v[70:73], v70 offset0:96 offset1:100
	s_waitcnt lgkmcnt(3)
	v_mfma_f32_16x16x32_bf16 v[40:43], v[40:43], v[36:39], 0
	v_bfe_u32 v52, v35, 16, 1
	v_bfe_u32 v53, v33, 16, 1
	s_waitcnt lgkmcnt(2)
	v_mfma_f32_16x16x32_bf16 v[44:47], v[44:47], v[36:39], 0
	s_waitcnt lgkmcnt(1)
	v_mfma_f32_16x16x32_bf16 v[48:51], v[48:51], v[36:39], 0
	s_waitcnt lgkmcnt(0)
	v_mfma_f32_16x16x32_bf16 v[36:39], v[70:73], v[36:39], 0
	v_bfe_u32 v70, v31, 16, 1
	v_bfe_u32 v71, v30, 16, 1
	v_add3_u32 v71, v30, v71, s91
	v_add3_u32 v70, v31, v70, s91
	v_add3_u32 v30, v33, v53, s91
	v_add3_u32 v31, v35, v52, s91
	v_bfe_u32 v52, v32, 16, 1
	v_bfe_u32 v53, v34, 16, 1
	v_bfe_u32 v33, v28, 16, 1
	v_add3_u32 v34, v34, v53, s91
	v_add3_u32 v32, v32, v52, s91
	v_bfe_u32 v35, v29, 16, 1
	v_add3_u32 v28, v28, v33, s91
	v_lshrrev_b32_e32 v32, 16, v32
	v_lshrrev_b32_e32 v33, 16, v34
	v_add3_u32 v29, v29, v35, s91
	v_and_or_b32 v31, v31, s33, v33
	v_and_or_b32 v30, v30, s33, v32
	ds_read2_b64 v[32:35], v69 offset1:4
	v_lshrrev_b32_e32 v28, 16, v28
	v_lshrrev_b32_e32 v29, 16, v29
	v_and_or_b32 v29, v70, s33, v29
	v_and_or_b32 v28, v71, s33, v28
	s_waitcnt lgkmcnt(0)
	s_nop 0
	v_mfma_f32_16x16x32_bf16 v[32:35], v[32:35], v[28:31], v[40:43]
	s_nop 2
	ds_read2_b64 v[40:43], v68 offset0:32 offset1:36
	s_waitcnt lgkmcnt(0)
	v_mfma_f32_16x16x32_bf16 v[40:43], v[40:43], v[28:31], v[44:47]
	s_nop 2
	ds_read2_b64 v[44:47], v67 offset0:64 offset1:68
	s_waitcnt lgkmcnt(0)
	v_mfma_f32_16x16x32_bf16 v[44:47], v[44:47], v[28:31], v[48:51]
	s_nop 2
	ds_read2_b64 v[48:51], v66 offset0:96 offset1:100
	s_waitcnt lgkmcnt(0)
	v_mfma_f32_16x16x32_bf16 v[28:31], v[48:51], v[28:31], v[36:39]
	s_nop 2
	v_bfe_u32 v36, v27, 16, 1
	v_bfe_u32 v37, v25, 16, 1
	v_bfe_u32 v38, v23, 16, 1
	v_bfe_u32 v39, v22, 16, 1
	v_add3_u32 v39, v22, v39, s91
	v_add3_u32 v38, v23, v38, s91
	v_add3_u32 v22, v25, v37, s91
	v_add3_u32 v23, v27, v36, s91
	v_bfe_u32 v36, v24, 16, 1
	v_bfe_u32 v37, v26, 16, 1
	v_bfe_u32 v25, v20, 16, 1
	v_add3_u32 v26, v26, v37, s91
	v_add3_u32 v24, v24, v36, s91
	v_bfe_u32 v27, v21, 16, 1
	v_add3_u32 v20, v20, v25, s91
	v_lshrrev_b32_e32 v24, 16, v24
	v_lshrrev_b32_e32 v25, 16, v26
	v_add3_u32 v21, v21, v27, s91
	v_and_or_b32 v23, v23, s33, v25
	v_and_or_b32 v22, v22, s33, v24
	ds_read2_b64 v[24:27], v65 offset1:4
	v_lshrrev_b32_e32 v20, 16, v20
	v_lshrrev_b32_e32 v21, 16, v21
	v_and_or_b32 v21, v38, s33, v21
	v_and_or_b32 v20, v39, s33, v20
	ds_read2_b64 v[36:39], v63 offset0:64 offset1:68
	s_waitcnt lgkmcnt(1)
	v_mfma_f32_16x16x32_bf16 v[24:27], v[24:27], v[20:23], v[32:35]
	s_nop 2
	ds_read2_b64 v[32:35], v64 offset0:32 offset1:36
	s_waitcnt lgkmcnt(0)
	v_mfma_f32_16x16x32_bf16 v[32:35], v[32:35], v[20:23], v[40:43]
	s_nop 2
	ds_read2_b64 v[40:43], v62 offset0:96 offset1:100
	v_mfma_f32_16x16x32_bf16 v[36:39], v[36:39], v[20:23], v[44:47]
	s_waitcnt lgkmcnt(0)
	v_mfma_f32_16x16x32_bf16 v[20:23], v[40:43], v[20:23], v[28:31]
	s_nop 2
	v_bfe_u32 v28, v19, 16, 1
	v_bfe_u32 v29, v17, 16, 1
	v_bfe_u32 v30, v15, 16, 1
	v_bfe_u32 v31, v14, 16, 1
	v_add3_u32 v31, v14, v31, s91
	v_add3_u32 v30, v15, v30, s91
	v_add3_u32 v14, v17, v29, s91
	v_add3_u32 v15, v19, v28, s91
	v_bfe_u32 v28, v16, 16, 1
	v_bfe_u32 v29, v18, 16, 1
	v_bfe_u32 v17, v12, 16, 1
	v_add3_u32 v18, v18, v29, s91
	v_add3_u32 v16, v16, v28, s91
	v_bfe_u32 v19, v13, 16, 1
	v_add3_u32 v12, v12, v17, s91
	v_lshrrev_b32_e32 v16, 16, v16
	v_lshrrev_b32_e32 v17, 16, v18
	v_add3_u32 v13, v13, v19, s91
	v_and_or_b32 v15, v15, s33, v17
	v_and_or_b32 v14, v14, s33, v16
	ds_read2_b64 v[16:19], v61 offset1:4
	v_lshrrev_b32_e32 v12, 16, v12
	v_lshrrev_b32_e32 v13, 16, v13
	v_and_or_b32 v13, v30, s33, v13
	v_and_or_b32 v12, v31, s33, v12
	ds_read2_b64 v[28:31], v59 offset0:64 offset1:68
	s_waitcnt lgkmcnt(1)
	v_mfma_f32_16x16x32_bf16 v[16:19], v[16:19], v[12:15], v[24:27]
	s_nop 2
	ds_read2_b64 v[24:27], v60 offset0:32 offset1:36
	s_waitcnt lgkmcnt(0)
	v_mfma_f32_16x16x32_bf16 v[24:27], v[24:27], v[12:15], v[32:35]
	s_nop 2
	ds_read2_b64 v[32:35], v58 offset0:96 offset1:100
	v_mfma_f32_16x16x32_bf16 v[28:31], v[28:31], v[12:15], v[36:39]
	s_waitcnt lgkmcnt(0)
	v_mfma_f32_16x16x32_bf16 v[12:15], v[32:35], v[12:15], v[20:23]
	s_nop 2
	v_bfe_u32 v20, v11, 16, 1
	v_bfe_u32 v21, v10, 16, 1
	v_bfe_u32 v22, v8, 16, 1
	v_add3_u32 v22, v8, v22, s91
	v_add3_u32 v8, v10, v21, s91
	v_add3_u32 v10, v11, v20, s91
	v_bfe_u32 v20, v3, 16, 1
	v_bfe_u32 v21, v7, 16, 1
	v_bfe_u32 v23, v6, 16, 1
	v_add3_u32 v7, v7, v21, s91
	v_add3_u32 v3, v3, v20, s91
	v_add3_u32 v6, v6, v23, s91
	v_bfe_u32 v23, v9, 16, 1
	v_lshrrev_b32_e32 v3, 16, v3
	v_lshrrev_b32_e32 v7, 16, v7
	v_add3_u32 v9, v9, v23, s91
	v_and_or_b32 v8, v8, s33, v7
	v_and_or_b32 v7, v22, s33, v3
	ds_read2_b64 v[20:23], v57 offset1:4
	v_bfe_u32 v11, v2, 16, 1
	v_add3_u32 v2, v2, v11, s91
	v_lshrrev_b32_e32 v2, 16, v2
	v_lshrrev_b32_e32 v9, 16, v9
	v_and_or_b32 v9, v10, s33, v9
	v_and_or_b32 v6, v6, s33, v2
	v_div_scale_f32 v2, s[0:1], v0, v0, 1.0
	s_waitcnt lgkmcnt(0)
	v_mfma_f32_16x16x32_bf16 v[16:19], v[20:23], v[6:9], v[16:19]
	ds_read2_b64 v[20:23], v56 offset0:32 offset1:36
	v_rcp_f32_e32 v3, v2
	v_readlane_b32 s0, v254, 63
	s_waitcnt lgkmcnt(0)
	v_mfma_f32_16x16x32_bf16 v[20:23], v[20:23], v[6:9], v[24:27]
	s_nop 2
	ds_read2_b64 v[24:27], v55 offset0:64 offset1:68
	v_fma_f32 v10, -v2, v3, 1.0
	v_fmac_f32_e32 v3, v10, v3
	s_waitcnt lgkmcnt(0)
	v_mfma_f32_16x16x32_bf16 v[24:27], v[24:27], v[6:9], v[28:31]
	s_nop 2
	ds_read2_b64 v[28:31], v54 offset0:96 offset1:100
	v_div_scale_f32 v10, vcc, 1.0, v0, 1.0
	v_mul_f32_e32 v11, v10, v3
	s_waitcnt lgkmcnt(0)
	v_mfma_f32_16x16x32_bf16 v[6:9], v[28:31], v[6:9], v[12:15]
	s_nop 2
	v_fma_f32 v12, -v2, v11, v10
	v_fmac_f32_e32 v11, v12, v3
	v_fma_f32 v2, -v2, v11, v10
	v_div_fmas_f32 v2, v2, v3, v11
	v_div_fixup_f32 v0, v2, v0, 1.0
	v_mov_b32_e32 v10, v16
	v_mov_b32_e32 v11, v18
	v_pk_mul_f32 v[10:11], v[0:1], v[10:11] op_sel_hi:[0,1]
	v_mov_b32_e32 v18, v17
	v_pk_mul_f32 v[12:13], v[0:1], v[18:19] op_sel_hi:[0,1]
	v_and_b32_sdwa v14, v11, v218 dst_sel:DWORD dst_unused:UNUSED_PAD src0_sel:WORD_1 src1_sel:DWORD
	v_and_b32_sdwa v15, v10, v218 dst_sel:DWORD dst_unused:UNUSED_PAD src0_sel:WORD_1 src1_sel:DWORD
	v_add3_u32 v10, v10, v15, s91
	v_add3_u32 v11, v11, v14, s91
	v_and_b32_sdwa v14, v13, v218 dst_sel:DWORD dst_unused:UNUSED_PAD src0_sel:WORD_1 src1_sel:DWORD
	v_and_b32_sdwa v15, v12, v218 dst_sel:DWORD dst_unused:UNUSED_PAD src0_sel:WORD_1 src1_sel:DWORD
	v_add3_u32 v13, v13, v14, s91
	v_add3_u32 v12, v12, v15, s91
	s_lshl_b32 s94, s0, 1
	v_and_b32_e32 v13, 0xffff0000, v13
	v_and_b32_e32 v12, 0xffff0000, v12
	v_lshl_add_u64 v[2:3], v[80:81], 0, s[94:95]
	v_or_b32_sdwa v11, v13, v11 dst_sel:DWORD dst_unused:UNUSED_PAD src0_sel:DWORD src1_sel:WORD_1
	v_or_b32_sdwa v10, v12, v10 dst_sel:DWORD dst_unused:UNUSED_PAD src0_sel:DWORD src1_sel:WORD_1
	global_store_dwordx2 v[2:3], v[10:11], off
	v_mov_b32_e32 v10, v20
	v_mov_b32_e32 v11, v22
	v_pk_mul_f32 v[10:11], v[0:1], v[10:11] op_sel_hi:[0,1]
	v_mov_b32_e32 v22, v21
	v_pk_mul_f32 v[12:13], v[0:1], v[22:23] op_sel_hi:[0,1]
	v_and_b32_sdwa v14, v11, v218 dst_sel:DWORD dst_unused:UNUSED_PAD src0_sel:WORD_1 src1_sel:DWORD
	v_and_b32_sdwa v15, v10, v218 dst_sel:DWORD dst_unused:UNUSED_PAD src0_sel:WORD_1 src1_sel:DWORD
	v_add3_u32 v10, v10, v15, s91
	v_add3_u32 v11, v11, v14, s91
	v_and_b32_sdwa v14, v13, v218 dst_sel:DWORD dst_unused:UNUSED_PAD src0_sel:WORD_1 src1_sel:DWORD
	v_and_b32_sdwa v15, v12, v218 dst_sel:DWORD dst_unused:UNUSED_PAD src0_sel:WORD_1 src1_sel:DWORD
	v_add3_u32 v13, v13, v14, s91
	v_add3_u32 v12, v12, v15, s91
	v_and_b32_e32 v13, 0xffff0000, v13
	v_and_b32_e32 v12, 0xffff0000, v12
	v_or_b32_sdwa v11, v13, v11 dst_sel:DWORD dst_unused:UNUSED_PAD src0_sel:DWORD src1_sel:WORD_1
	v_or_b32_sdwa v10, v12, v10 dst_sel:DWORD dst_unused:UNUSED_PAD src0_sel:DWORD src1_sel:WORD_1
	global_store_dwordx2 v[2:3], v[10:11], off offset:32
	v_mov_b32_e32 v10, v24
	v_mov_b32_e32 v11, v26
	v_pk_mul_f32 v[10:11], v[0:1], v[10:11] op_sel_hi:[0,1]
	v_mov_b32_e32 v26, v25
	v_pk_mul_f32 v[12:13], v[0:1], v[26:27] op_sel_hi:[0,1]
	v_and_b32_sdwa v14, v11, v218 dst_sel:DWORD dst_unused:UNUSED_PAD src0_sel:WORD_1 src1_sel:DWORD
	v_and_b32_sdwa v15, v10, v218 dst_sel:DWORD dst_unused:UNUSED_PAD src0_sel:WORD_1 src1_sel:DWORD
	v_add3_u32 v10, v10, v15, s91
	v_add3_u32 v11, v11, v14, s91
	v_and_b32_sdwa v14, v13, v218 dst_sel:DWORD dst_unused:UNUSED_PAD src0_sel:WORD_1 src1_sel:DWORD
	v_and_b32_sdwa v15, v12, v218 dst_sel:DWORD dst_unused:UNUSED_PAD src0_sel:WORD_1 src1_sel:DWORD
	v_add3_u32 v13, v13, v14, s91
	v_add3_u32 v12, v12, v15, s91
	v_and_b32_e32 v13, 0xffff0000, v13
	v_and_b32_e32 v12, 0xffff0000, v12
	v_or_b32_sdwa v11, v13, v11 dst_sel:DWORD dst_unused:UNUSED_PAD src0_sel:DWORD src1_sel:WORD_1
	v_or_b32_sdwa v10, v12, v10 dst_sel:DWORD dst_unused:UNUSED_PAD src0_sel:DWORD src1_sel:WORD_1
	global_store_dwordx2 v[2:3], v[10:11], off offset:64
	v_mov_b32_e32 v10, v6
	v_mov_b32_e32 v11, v8
	v_pk_mul_f32 v[10:11], v[0:1], v[10:11] op_sel_hi:[0,1]
	v_mov_b32_e32 v8, v7
	v_pk_mul_f32 v[6:7], v[0:1], v[8:9] op_sel_hi:[0,1]
	v_and_b32_sdwa v8, v10, v218 dst_sel:DWORD dst_unused:UNUSED_PAD src0_sel:WORD_1 src1_sel:DWORD
	v_add3_u32 v8, v10, v8, s91
	v_and_b32_sdwa v9, v7, v218 dst_sel:DWORD dst_unused:UNUSED_PAD src0_sel:WORD_1 src1_sel:DWORD
	v_and_b32_sdwa v10, v6, v218 dst_sel:DWORD dst_unused:UNUSED_PAD src0_sel:WORD_1 src1_sel:DWORD
	v_and_b32_sdwa v0, v11, v218 dst_sel:DWORD dst_unused:UNUSED_PAD src0_sel:WORD_1 src1_sel:DWORD
	v_add3_u32 v7, v7, v9, s91
	v_add3_u32 v6, v6, v10, s91
	v_add3_u32 v0, v11, v0, s91
	v_and_b32_e32 v7, 0xffff0000, v7
	v_and_b32_e32 v6, 0xffff0000, v6
	v_or_b32_sdwa v7, v7, v0 dst_sel:DWORD dst_unused:UNUSED_PAD src0_sel:DWORD src1_sel:WORD_1
	v_or_b32_sdwa v6, v6, v8 dst_sel:DWORD dst_unused:UNUSED_PAD src0_sel:DWORD src1_sel:WORD_1
	global_store_dwordx2 v[2:3], v[6:7], off offset:96
	s_waitcnt lgkmcnt(0)
	s_barrier

.LBB0_406:
	s_nop 1
	global_load_dword v148, v[8:9], off
	global_load_dword v13, v[10:11], off
	v_add_u32_e32 v7, 8, v7
	s_waitcnt vmcnt(0) lgkmcnt(0)
	v_mul_f32_e32 v14, v13, v13
	ds_bpermute_b32 v14, v5, v14
	s_waitcnt lgkmcnt(0)
	v_fmac_f32_e32 v14, v13, v13
	ds_bpermute_b32 v15, v106, v14
	s_waitcnt lgkmcnt(0)
	v_add_f32_e32 v14, v14, v15
	ds_bpermute_b32 v15, v107, v14
	s_waitcnt lgkmcnt(0)
	v_add_f32_e32 v14, v14, v15
	ds_bpermute_b32 v15, v108, v14
	s_waitcnt lgkmcnt(0)
	v_add_f32_e32 v14, v14, v15
	ds_bpermute_b32 v15, v109, v14
	s_waitcnt lgkmcnt(0)
	v_add_f32_e32 v14, v14, v15
	ds_bpermute_b32 v15, v110, v14
	s_waitcnt lgkmcnt(0)
	v_add_f32_e32 v14, v14, v15
	v_fmamk_f32 v14, v14, 0x3c800000, v219
	v_cmp_gt_f32_e32 vcc, s85, v14
	v_mul_f32_e32 v15, 0x4f800000, v14
	s_nop 0
	v_cndmask_b32_e32 v14, v14, v15, vcc
	v_sqrt_f32_e32 v15, v14
	s_nop 0
	v_add_u32_e32 v16, -1, v15
	v_fma_f32 v17, -v16, v15, v14
	v_cmp_ge_f32_e64 s[6:7], 0, v17
	v_add_u32_e32 v17, 1, v15
	s_nop 0
	v_cndmask_b32_e64 v16, v15, v16, s[6:7]
	v_fma_f32 v15, -v17, v15, v14
	v_cmp_lt_f32_e64 s[6:7], 0, v15
	s_nop 1
	v_cndmask_b32_e64 v15, v16, v17, s[6:7]
	v_mul_f32_e32 v16, 0x37800000, v15
	v_cndmask_b32_e32 v15, v15, v16, vcc
	v_cmp_class_f32_e32 vcc, v14, v221
	s_nop 1
	v_cndmask_b32_e32 v14, v15, v14, vcc
	v_div_scale_f32 v15, s[6:7], v14, v14, 1.0
	v_rcp_f32_e32 v16, v15
	s_mov_b64 s[6:7], 0x800
	v_lshl_add_u64 v[10:11], v[10:11], 0, s[6:7]
	v_fma_f32 v17, -v15, v16, 1.0
	v_fmac_f32_e32 v16, v17, v16
	v_div_scale_f32 v17, vcc, 1.0, v14, 1.0
	v_mul_f32_e32 v18, v17, v16
	v_fma_f32 v19, -v15, v18, v17
	v_fmac_f32_e32 v18, v19, v16
	v_fma_f32 v15, -v15, v18, v17
	v_div_fmas_f32 v15, v15, v16, v18
	v_div_fixup_f32 v14, v15, v14, 1.0
	v_mul_f32_e32 v13, v13, v14
	s_waitcnt vmcnt(1)
	s_nop 0
	v_mov_b32_e32 v14, v148
	s_nop 1
	v_cmp_lt_i32_e32 vcc, -5, v7
	s_or_b64 s[2:3], vcc, s[2:3]
	s_waitcnt vmcnt(0) lgkmcnt(0)
	v_mul_f32_e32 v13, v14, v13
	v_mul_f32_e32 v13, 0x3e000000, v13
	ds_write_b32 v12, v13
	v_add_u32_e32 v12, 0x800, v12
	s_andn2_b64 exec, exec, s[2:3]
	s_cbranch_execnz .LBB0_406

.LBB0_443:
	s_nop 1
	global_load_dword v150, v[12:13], off
	s_nop 1
	global_load_dword v149, v[10:11], off
	s_nop 1
	global_load_dword v148, v[8:9], off
	v_ashrrev_i32_e32 v15, 31, v14
	v_lshl_add_u64 v[18:19], v[14:15], 2, s[10:11]
	global_load_dword v15, v[18:19], off
	v_add_u32_e32 v3, 8, v3
	v_add_u32_e32 v14, 0x200, v14
	s_waitcnt vmcnt(0) lgkmcnt(0)
	v_mul_f32_e32 v17, v15, v15
	ds_bpermute_b32 v17, v5, v17
	s_waitcnt lgkmcnt(0)
	v_fmac_f32_e32 v17, v15, v15
	ds_bpermute_b32 v18, v106, v17
	s_waitcnt lgkmcnt(0)
	v_add_f32_e32 v17, v17, v18
	ds_bpermute_b32 v18, v107, v17
	s_waitcnt lgkmcnt(0)
	v_add_f32_e32 v17, v17, v18
	ds_bpermute_b32 v18, v108, v17
	s_waitcnt lgkmcnt(0)
	v_add_f32_e32 v17, v17, v18
	ds_bpermute_b32 v18, v109, v17
	s_waitcnt lgkmcnt(0)
	v_add_f32_e32 v17, v17, v18
	ds_bpermute_b32 v18, v110, v17
	s_waitcnt lgkmcnt(0)
	v_add_f32_e32 v17, v17, v18
	v_fmamk_f32 v17, v17, 0x3c800000, v219
	v_cmp_gt_f32_e32 vcc, s85, v17
	v_mul_f32_e32 v18, 0x4f800000, v17
	s_nop 0
	v_cndmask_b32_e32 v17, v17, v18, vcc
	v_sqrt_f32_e32 v18, v17
	s_nop 0
	v_add_u32_e32 v19, -1, v18
	v_fma_f32 v20, -v19, v18, v17
	v_cmp_ge_f32_e64 s[8:9], 0, v20
	v_add_u32_e32 v20, 1, v18
	s_nop 0
	v_cndmask_b32_e64 v19, v18, v19, s[8:9]
	v_fma_f32 v18, -v20, v18, v17
	v_cmp_lt_f32_e64 s[8:9], 0, v18
	s_nop 1
	v_cndmask_b32_e64 v18, v19, v20, s[8:9]
	v_mul_f32_e32 v19, 0x37800000, v18
	v_cndmask_b32_e32 v18, v18, v19, vcc
	v_cmp_class_f32_e32 vcc, v17, v221
	s_nop 1
	v_cndmask_b32_e32 v17, v18, v17, vcc
	v_div_scale_f32 v18, s[8:9], v17, v17, 1.0
	v_rcp_f32_e32 v19, v18
	s_nop 0
	v_fma_f32 v20, -v18, v19, 1.0
	v_fmac_f32_e32 v19, v20, v19
	v_div_scale_f32 v20, vcc, 1.0, v17, 1.0
	v_mul_f32_e32 v21, v20, v19
	v_fma_f32 v23, -v18, v21, v20
	v_fmac_f32_e32 v21, v23, v19
	v_fma_f32 v18, -v18, v21, v20
	v_div_fmas_f32 v18, v18, v19, v21
	v_div_fixup_f32 v17, v18, v17, 1.0
	v_mul_f32_e32 v15, v15, v17
	s_waitcnt vmcnt(1)
	s_nop 0
	v_mov_b32_e32 v17, v148
	s_nop 1
	s_waitcnt vmcnt(2)
	s_nop 0
	v_mov_b32_e32 v18, v149
	s_nop 1
	s_waitcnt vmcnt(3)
	s_nop 0
	v_mov_b32_e32 v19, v150
	s_nop 1
	v_cmp_lt_i32_e32 vcc, 3, v3
	s_or_b64 s[18:19], vcc, s[18:19]
	s_waitcnt vmcnt(0) lgkmcnt(0)
	v_mul_f32_e32 v15, v17, v15
	ds_bpermute_b32 v17, v110, v15
	s_waitcnt lgkmcnt(0)
	v_mul_f32_e32 v17, v19, v17
	v_cndmask_b32_e64 v17, v17, -v17, s[6:7]
	v_fmac_f32_e32 v17, v18, v15
	v_mul_f32_e32 v15, 0x3e000000, v17
	ds_write_b32 v7, v15
	v_add_u32_e32 v7, 0x800, v7
	s_andn2_b64 exec, exec, s[18:19]
	s_cbranch_execnz .LBB0_443
.LBB0_444:
	s_or_b64 exec, exec, s[16:17]
	v_cmp_gt_i32_e32 vcc, 4, v2
	s_and_saveexec_b64 s[8:9], vcc
	s_cbranch_execz .LBB0_447
	s_nop 1
	v_and_b32_e32 v152, 0xffffffc0, v78
	v_or_b32_e32 v148, v152, v22
	v_add_u32_e32 v150, 0x500, v148
	v_ashrrev_i32_e32 v151, 31, v150
	v_lshl_add_u64 v[150:151], v[150:151], 2, s[10:11]
	global_load_dword v149, v[150:151], off
	v_and_b32_e32 v8, 0xffffffc0, v78
	v_or_b32_e32 v3, v8, v22
	v_add_u32_e32 v10, 0x400, v3
	v_ashrrev_i32_e32 v11, 31, v10
	v_lshl_add_u64 v[10:11], v[10:11], 2, s[10:11]
	global_load_dword v9, v[10:11], off
	v_readlane_b32 s6, v254, 15
	s_nop 1
	v_mov_b32_e32 v7, s6
	ds_read_b64 v[10:11], v7
	v_mov_b32_e32 v7, v1
	s_waitcnt lgkmcnt(0)
	v_readfirstlane_b32 s6, v10
	v_readfirstlane_b32 s7, v11
	s_nop 1
	v_lshl_add_u64 v[10:11], s[6:7], 0, v[0:1]
	global_load_dword v12, v[10:11], off
	v_lshl_add_u64 v[10:11], s[12:13], 0, v[6:7]
	v_lshl_add_u64 v[6:7], s[14:15], 0, v[6:7]
	global_load_dword v10, v[10:11], off
	s_nop 0
	global_load_dword v11, v[6:7], off
	v_add_u32_e32 v6, 0x500, v3
	v_ashrrev_i32_e32 v7, 31, v6
	v_lshl_add_u64 v[6:7], v[6:7], 2, s[10:11]
	s_waitcnt vmcnt(0)
	v_mul_f32_e32 v3, v9, v9
	ds_bpermute_b32 v13, v5, v3
	s_waitcnt vmcnt(4)
	s_nop 0
	v_mov_b32_e32 v3, v149
	s_nop 1
	s_waitcnt lgkmcnt(0)
	v_fmac_f32_e32 v13, v9, v9
	ds_bpermute_b32 v6, v106, v13
	s_waitcnt lgkmcnt(0)
	v_add_f32_e32 v6, v13, v6
	ds_bpermute_b32 v7, v107, v6
	s_waitcnt lgkmcnt(0)
	v_add_f32_e32 v6, v6, v7
	ds_bpermute_b32 v7, v108, v6
	s_waitcnt lgkmcnt(0)
	v_add_f32_e32 v6, v6, v7
	ds_bpermute_b32 v7, v109, v6
	s_waitcnt lgkmcnt(0)
	v_add_f32_e32 v6, v6, v7
	ds_bpermute_b32 v7, v110, v6
	s_waitcnt lgkmcnt(0)
	v_add_f32_e32 v6, v6, v7
	v_fmamk_f32 v6, v6, 0x3c800000, v219
	v_mul_f32_e32 v7, 0x4f800000, v6
	v_cmp_gt_f32_e32 vcc, s85, v6
	s_nop 1
	v_cndmask_b32_e32 v6, v6, v7, vcc
	v_sqrt_f32_e32 v7, v6
	s_nop 0
	v_add_u32_e32 v13, -1, v7
	v_add_u32_e32 v14, 1, v7
	v_fma_f32 v15, -v13, v7, v6
	v_fma_f32 v17, -v14, v7, v6
	v_cmp_ge_f32_e64 s[6:7], 0, v15
	s_nop 1
	v_cndmask_b32_e64 v7, v7, v13, s[6:7]
	v_cmp_lt_f32_e64 s[6:7], 0, v17
	s_nop 1
	v_cndmask_b32_e64 v7, v7, v14, s[6:7]
	v_mul_f32_e32 v13, 0x37800000, v7
	v_cndmask_b32_e32 v7, v7, v13, vcc
	v_cmp_class_f32_e32 vcc, v6, v221
	s_nop 1
	v_cndmask_b32_e32 v6, v7, v6, vcc
	v_div_scale_f32 v7, s[6:7], v6, v6, 1.0
	v_rcp_f32_e32 v13, v7
	v_div_scale_f32 v14, vcc, 1.0, v6, 1.0
	v_readlane_b32 s6, v254, 49
	v_fma_f32 v15, -v7, v13, 1.0
	v_fmac_f32_e32 v13, v15, v13
	v_mul_f32_e32 v15, v14, v13
	v_fma_f32 v17, -v7, v15, v14
	v_fmac_f32_e32 v15, v17, v13
	v_fma_f32 v7, -v7, v15, v14
	v_div_fmas_f32 v7, v7, v13, v15
	v_div_fixup_f32 v6, v7, v6, 1.0
	v_mul_f32_e32 v6, v9, v6
	v_mul_f32_e32 v7, v12, v6
	ds_bpermute_b32 v6, v110, v7
	v_cmp_gt_u32_e32 vcc, 32, v22
	v_lshl_add_u32 v9, v78, 2, 0
	v_readlane_b32 s7, v254, 50
	v_add_u32_e32 v9, 0xc0, v9
	s_waitcnt lgkmcnt(0)
	v_mul_f32_e32 v6, v11, v6
	v_cndmask_b32_e64 v6, v6, -v6, vcc
	v_fmac_f32_e32 v6, v10, v7
	s_andn2_b64 vcc, exec, s[6:7]
	s_waitcnt vmcnt(0)
	ds_write2st64_b32 v9, v6, v3 offset0:60 offset1:64
	s_cbranch_vccnz .LBB0_447
	v_readlane_b32 s6, v254, 8
	v_ashrrev_i32_e32 v9, 31, v8
	s_nop 0
	v_mov_b32_e32 v7, s6
	ds_read_b64 v[10:11], v7
	s_lshl_b64 s[6:7], s[94:95], 10
	s_waitcnt lgkmcnt(0)
	v_readfirstlane_b32 s10, v10
	v_readfirstlane_b32 s11, v11
	s_add_u32 s6, s10, s6
	s_addc_u32 s7, s11, s7
	v_lshl_add_u64 v[8:9], v[8:9], 2, s[6:7]
	v_lshl_add_u64 v[8:9], v[8:9], 0, v[0:1]
	v_add_co_u32_e32 v10, vcc, 0x6558000, v8
	s_nop 1
	v_addc_co_u32_e32 v11, vcc, 0, v9, vcc
	global_store_dword v[10:11], v6, off
	v_add_co_u32_e32 v6, vcc, 0x6578000, v8
	s_nop 1
	v_addc_co_u32_e32 v7, vcc, 0, v9, vcc
	global_store_dword v[6:7], v3, off

.LBB0_459:
	v_add_u32_e32 v28, s4, v30
	v_mad_i64_i32 v[6:7], s[4:5], s14, v28, 0
	v_lshl_add_u64 v[10:11], v[6:7], 1, v[2:3]
	v_mov_b32_e32 v14, s9
	global_load_dwordx4 v[6:9], v[10:11], off nt
	s_nop 0
	global_load_dwordx4 v[10:13], v[10:11], off offset:64 nt
	ds_read_b64 v[14:15], v14
	s_lshl_b64 s[4:5], s[12:13], 2
	v_ashrrev_i32_e32 v29, 31, v28
	s_waitcnt lgkmcnt(0)
	v_readfirstlane_b32 s6, v14
	v_readfirstlane_b32 s7, v15
	s_add_u32 s4, s6, s4
	s_addc_u32 s5, s7, s5
	s_nop 1
	v_lshl_add_u64 v[160:161], s[4:5], 0, v[0:1]
	global_load_dwordx4 v[162:165], v[160:161], off offset:144
	s_nop 1
	v_lshl_add_u64 v[154:155], s[4:5], 0, v[0:1]
	global_load_dwordx4 v[156:159], v[154:155], off offset:16
	s_nop 1
	v_lshl_add_u64 v[148:149], s[4:5], 0, v[0:1]
	global_load_dwordx4 v[150:153], v[148:149], off
	v_lshl_add_u64 v[18:19], s[4:5], 0, v[0:1]
	global_load_dwordx4 v[14:17], v[18:19], off offset:128
	s_waitcnt vmcnt(0)
	v_lshlrev_b32_e32 v37, 16, v7
	v_lshlrev_b32_e32 v21, 16, v11
	v_lshlrev_b32_e32 v20, 16, v10
	v_and_b32_e32 v23, 0xffff0000, v11
	v_and_b32_e32 v22, 0xffff0000, v10
	v_and_b32_e32 v35, 0xffff0000, v13
	v_and_b32_e32 v34, 0xffff0000, v12
	v_lshlrev_b32_e32 v36, 16, v6
	v_and_b32_e32 v39, 0xffff0000, v7
	v_and_b32_e32 v38, 0xffff0000, v6
	v_mov_b32_e32 v6, v23
	v_mov_b32_e32 v7, v21
	s_waitcnt lgkmcnt(0)
	v_mov_b32_e32 v24, v14
	v_mov_b32_e32 v25, v16
	v_mov_b32_e32 v16, v15
	v_lshlrev_b32_e32 v15, 16, v13
	v_lshlrev_b32_e32 v14, 16, v12
	s_waitcnt vmcnt(1)
	s_nop 0
	v_mov_b32_e32 v10, v150
	v_mov_b32_e32 v11, v151
	v_mov_b32_e32 v12, v152
	v_mov_b32_e32 v13, v153
	s_nop 1
	v_pk_mul_f32 v[6:7], v[6:7], v[6:7]
	v_mov_b32_e32 v40, v39
	v_mov_b32_e32 v41, v37
	v_pk_fma_f32 v[40:41], v[40:41], v[40:41], v[6:7]
	v_and_b32_e32 v45, 0xffff0000, v9
	v_and_b32_e32 v44, 0xffff0000, v8
	v_mul_f32_e32 v27, v38, v38
	v_mul_f32_e32 v33, v36, v36
	v_fmac_f32_e32 v27, v22, v22
	v_fmac_f32_e32 v33, v20, v20
	v_mov_b32_e32 v46, v34
	v_mov_b32_e32 v47, v14
	v_add_f32_e32 v27, v33, v27
	v_pk_mul_f32 v[46:47], v[46:47], v[46:47]
	v_mov_b32_e32 v48, v44
	v_add_f32_e32 v27, v41, v27
	v_add_f32_e32 v27, v40, v27
	v_mov_b32_e32 v50, v45
	s_waitcnt vmcnt(0) lgkmcnt(0)
	v_mov_b32_e32 v42, v10
	v_mov_b32_e32 v43, v12
	v_mov_b32_e32 v12, v11
	v_lshlrev_b32_e32 v11, 16, v9
	v_lshlrev_b32_e32 v10, 16, v8
	s_waitcnt vmcnt(2)
	s_nop 0
	v_mov_b32_e32 v6, v156
	v_mov_b32_e32 v7, v157
	v_mov_b32_e32 v8, v158
	v_mov_b32_e32 v9, v159
	s_nop 1
	v_mov_b32_e32 v49, v10
	v_pk_fma_f32 v[46:47], v[48:49], v[48:49], v[46:47]
	v_mov_b32_e32 v48, v35
	v_mov_b32_e32 v49, v15
	v_pk_mul_f32 v[48:49], v[48:49], v[48:49]
	v_mov_b32_e32 v51, v11
	v_add_f32_e32 v27, v47, v27
	v_pk_fma_f32 v[48:49], v[50:51], v[50:51], v[48:49]
	v_add_f32_e32 v27, v46, v27
	v_add_f32_e32 v27, v49, v27
	v_add_f32_e32 v27, v48, v27
	ds_bpermute_b32 v33, v109, v27
	s_waitcnt lgkmcnt(0)
	v_add_f32_e32 v27, v27, v33
	ds_bpermute_b32 v33, v110, v27
	s_waitcnt lgkmcnt(0)
	v_add_f32_e32 v27, v27, v33
	v_fmamk_f32 v27, v27, 0x3c800000, v219
	v_cmp_gt_f32_e32 vcc, s85, v27
	v_mul_f32_e32 v33, 0x4f800000, v27
	s_nop 0
	v_cndmask_b32_e32 v27, v27, v33, vcc
	v_sqrt_f32_e32 v33, v27
	s_nop 0
	v_add_u32_e32 v40, -1, v33
	v_fma_f32 v41, -v40, v33, v27
	v_cmp_ge_f32_e64 s[4:5], 0, v41
	v_add_u32_e32 v41, 1, v33
	s_nop 0
	v_cndmask_b32_e64 v40, v33, v40, s[4:5]
	v_fma_f32 v33, -v41, v33, v27
	v_cmp_lt_f32_e64 s[4:5], 0, v33
	s_nop 1
	v_cndmask_b32_e64 v33, v40, v41, s[4:5]
	v_mul_f32_e32 v40, 0x37800000, v33
	v_cndmask_b32_e32 v33, v33, v40, vcc
	v_cmp_class_f32_e32 vcc, v27, v221
	s_nop 1
	v_cndmask_b32_e32 v27, v33, v27, vcc
	v_div_scale_f32 v33, s[4:5], v27, v27, s86
	v_rcp_f32_e32 v40, v33
	s_nop 0
	v_fma_f32 v41, -v33, v40, 1.0
	v_fmac_f32_e32 v40, v41, v40
	v_div_scale_f32 v41, vcc, s86, v27, s86
	v_mul_f32_e32 v46, v41, v40
	v_fma_f32 v47, -v33, v46, v41
	v_fmac_f32_e32 v46, v47, v40
	v_fma_f32 v33, -v33, v46, v41
	v_div_fmas_f32 v33, v33, v40, v46
	v_div_fixup_f32 v40, v33, v27, s86
	v_pk_mul_f32 v[38:39], v[40:41], v[38:39] op_sel_hi:[0,1]
	v_pk_mul_f32 v[12:13], v[12:13], v[38:39]
	v_pk_mul_f32 v[10:11], v[40:41], v[10:11] op_sel_hi:[0,1]
	v_pk_mul_f32 v[36:37], v[40:41], v[36:37] op_sel_hi:[0,1]
	v_pk_mul_f32 v[36:37], v[42:43], v[36:37]
	v_bfe_u32 v27, v13, 16, 1
	v_bfe_u32 v33, v12, 16, 1
	v_add3_u32 v12, v12, v33, s91
	v_add3_u32 v13, v13, v27, s91
	v_pk_mul_f32 v[14:15], v[40:41], v[14:15] op_sel_hi:[0,1]
	s_waitcnt vmcnt(0)
	v_mov_b32_e32 v38, v6
	v_mov_b32_e32 v39, v8
	v_pk_mul_f32 v[10:11], v[38:39], v[10:11]
	v_pk_mul_f32 v[38:39], v[40:41], v[44:45] op_sel_hi:[0,1]
	v_mov_b32_e32 v8, v7
	v_pk_mul_f32 v[6:7], v[8:9], v[38:39]
	v_bfe_u32 v27, v10, 16, 1
	v_bfe_u32 v8, v7, 16, 1
	v_bfe_u32 v9, v6, 16, 1
	v_add3_u32 v6, v6, v9, s91
	v_add3_u32 v7, v7, v8, s91
	v_bfe_u32 v8, v36, 16, 1
	v_bfe_u32 v9, v37, 16, 1
	v_bfe_u32 v33, v11, 16, 1
	v_add3_u32 v11, v11, v33, s91
	v_add3_u32 v10, v10, v27, s91
	v_add3_u32 v9, v37, v9, s91
	v_add3_u32 v8, v36, v8, s91
	v_lshrrev_b32_e32 v27, 16, v8
	v_lshrrev_b32_e32 v33, 16, v9
	v_lshrrev_b32_e32 v8, 16, v10
	v_lshrrev_b32_e32 v9, 16, v11
	v_pk_mul_f32 v[10:11], v[40:41], v[20:21] op_sel_hi:[0,1]
	v_pk_mul_f32 v[20:21], v[24:25], v[10:11]
	v_pk_mul_f32 v[10:11], v[40:41], v[22:23] op_sel_hi:[0,1]
	v_and_or_b32 v9, v7, s33, v9
	v_and_or_b32 v8, v6, s33, v8
	v_and_or_b32 v7, v13, s33, v33
	v_and_or_b32 v6, v12, s33, v27
	v_pk_mul_f32 v[16:17], v[16:17], v[10:11]
	s_waitcnt vmcnt(3)
	s_nop 0
	v_mov_b32_e32 v10, v162
	v_mov_b32_e32 v11, v163
	v_mov_b32_e32 v12, v164
	v_mov_b32_e32 v13, v165
	s_nop 1
	s_waitcnt vmcnt(0) lgkmcnt(0)
	v_mov_b32_e32 v18, v10
	v_mov_b32_e32 v19, v12
	v_pk_mul_f32 v[14:15], v[18:19], v[14:15]
	v_pk_mul_f32 v[18:19], v[40:41], v[34:35] op_sel_hi:[0,1]
	v_mov_b32_e32 v12, v11
	v_pk_mul_f32 v[10:11], v[18:19], v[12:13]
	v_bfe_u32 v18, v17, 16, 1
	v_bfe_u32 v12, v11, 16, 1
	v_bfe_u32 v13, v10, 16, 1
	v_bfe_u32 v19, v16, 16, 1
	v_add3_u32 v16, v16, v19, s91
	v_add3_u32 v17, v17, v18, s91
	v_add3_u32 v10, v10, v13, s91
	v_add3_u32 v11, v11, v12, s91
	v_bfe_u32 v12, v20, 16, 1
	v_bfe_u32 v13, v21, 16, 1
	v_bfe_u32 v18, v14, 16, 1
	v_bfe_u32 v19, v15, 16, 1
	v_add3_u32 v15, v15, v19, s91
	v_add3_u32 v14, v14, v18, s91
	v_add3_u32 v13, v21, v13, s91
	v_add3_u32 v12, v20, v12, s91
	v_lshrrev_b32_e32 v18, 16, v12
	v_lshrrev_b32_e32 v19, 16, v13
	v_lshrrev_b32_e32 v12, 16, v14
	v_lshrrev_b32_e32 v13, 16, v15
	v_and_or_b32 v13, v11, s33, v13
	v_and_or_b32 v12, v10, s33, v12
	v_and_or_b32 v11, v17, s33, v19
	v_and_or_b32 v10, v16, s33, v18
	ds_read_b128 v[14:17], v31
	ds_read_b128 v[18:21], v31 offset:64
	s_waitcnt lgkmcnt(1)
	v_mfma_f32_16x16x32_bf16 v[14:17], v[14:17], v[6:9], 0
	s_waitcnt lgkmcnt(0)
	v_mfma_f32_16x16x32_bf16 v[34:37], v[18:21], v[10:13], v[14:17]
	ds_read_b128 v[18:21], v31 offset:2368
	s_nop 4
	ds_read_b128 v[14:17], v31 offset:2304
	s_waitcnt lgkmcnt(0)
	v_mfma_f32_16x16x32_bf16 v[14:17], v[14:17], v[6:9], 0
	v_mfma_f32_16x16x32_bf16 v[38:41], v[18:21], v[10:13], v[14:17]
	ds_read_b128 v[18:21], v31 offset:4672
	s_nop 5
	ds_read_b128 v[14:17], v31 offset:4608
	s_waitcnt lgkmcnt(0)
	v_mfma_f32_16x16x32_bf16 v[14:17], v[14:17], v[6:9], 0
	v_mfma_f32_16x16x32_bf16 v[42:45], v[18:21], v[10:13], v[14:17]
	ds_read_b128 v[18:21], v31 offset:6976
	s_nop 5
	ds_read_b128 v[14:17], v31 offset:6912
	s_waitcnt lgkmcnt(0)
	v_mfma_f32_16x16x32_bf16 v[14:17], v[14:17], v[6:9], 0
	v_mfma_f32_16x16x32_bf16 v[50:53], v[18:21], v[10:13], v[14:17]
	ds_read_b128 v[18:21], v31 offset:9280
	s_nop 5
	ds_read_b128 v[14:17], v31 offset:9216
	s_waitcnt lgkmcnt(0)
	v_mfma_f32_16x16x32_bf16 v[14:17], v[14:17], v[6:9], 0
	v_mfma_f32_16x16x32_bf16 v[56:59], v[18:21], v[10:13], v[14:17]
	ds_read_b128 v[18:21], v31 offset:11584
	s_nop 5
	ds_read_b128 v[14:17], v31 offset:11520
	s_waitcnt lgkmcnt(0)
	v_mfma_f32_16x16x32_bf16 v[14:17], v[14:17], v[6:9], 0
	v_mfma_f32_16x16x32_bf16 v[66:69], v[18:21], v[10:13], v[14:17]
	ds_read_b128 v[18:21], v31 offset:13888
	s_nop 5
	ds_read_b128 v[14:17], v31 offset:13824
	s_waitcnt lgkmcnt(0)
	v_mfma_f32_16x16x32_bf16 v[14:17], v[14:17], v[6:9], 0
	v_mfma_f32_16x16x32_bf16 v[74:77], v[18:21], v[10:13], v[14:17]
	ds_read_b128 v[18:21], v31 offset:16192
	s_nop 5
	ds_read_b128 v[14:17], v31 offset:16128
	s_waitcnt lgkmcnt(0)
	v_mfma_f32_16x16x32_bf16 v[14:17], v[14:17], v[6:9], 0
	v_mfma_f32_16x16x32_bf16 v[80:83], v[18:21], v[10:13], v[14:17]
	ds_read_b128 v[18:21], v31 offset:18496
	s_nop 5
	ds_read_b128 v[14:17], v31 offset:18432
	s_waitcnt lgkmcnt(0)
	v_mfma_f32_16x16x32_bf16 v[14:17], v[14:17], v[6:9], 0
	v_mfma_f32_16x16x32_bf16 v[84:87], v[18:21], v[10:13], v[14:17]
	ds_read_b128 v[18:21], v31 offset:20800
	s_nop 5
	ds_read_b128 v[14:17], v31 offset:20736
	s_waitcnt lgkmcnt(0)
	v_mfma_f32_16x16x32_bf16 v[14:17], v[14:17], v[6:9], 0
	v_mfma_f32_16x16x32_bf16 v[88:91], v[18:21], v[10:13], v[14:17]
	ds_read_b128 v[18:21], v31 offset:23104
	s_nop 5
	ds_read_b128 v[14:17], v31 offset:23040
	s_waitcnt lgkmcnt(0)
	v_mfma_f32_16x16x32_bf16 v[14:17], v[14:17], v[6:9], 0
	v_mfma_f32_16x16x32_bf16 v[92:95], v[18:21], v[10:13], v[14:17]
	ds_read_b128 v[18:21], v31 offset:25408
	s_nop 5
	ds_read_b128 v[14:17], v31 offset:25344
	s_waitcnt lgkmcnt(0)
	v_mfma_f32_16x16x32_bf16 v[14:17], v[14:17], v[6:9], 0
	v_mfma_f32_16x16x32_bf16 v[96:99], v[18:21], v[10:13], v[14:17]
	ds_read_b128 v[18:21], v31 offset:27712
	s_nop 5
	ds_read_b128 v[14:17], v31 offset:27648
	s_waitcnt lgkmcnt(0)
	v_mfma_f32_16x16x32_bf16 v[14:17], v[14:17], v[6:9], 0
	v_mfma_f32_16x16x32_bf16 v[22:25], v[18:21], v[10:13], v[14:17]
	ds_read_b128 v[18:21], v31 offset:30016
	s_nop 5
	ds_read_b128 v[14:17], v31 offset:29952
	s_waitcnt lgkmcnt(0)
	v_mfma_f32_16x16x32_bf16 v[14:17], v[14:17], v[6:9], 0
	ds_read_b128 v[46:49], v31 offset:32320
	v_mfma_f32_16x16x32_bf16 v[18:21], v[18:21], v[10:13], v[14:17]
	s_nop 5
	ds_read_b128 v[14:17], v31 offset:32256
	s_waitcnt lgkmcnt(0)
	v_mfma_f32_16x16x32_bf16 v[14:17], v[14:17], v[6:9], 0
	v_mfma_f32_16x16x32_bf16 v[14:17], v[46:49], v[10:13], v[14:17]
	ds_read_b128 v[46:49], v31 offset:34560
	s_waitcnt lgkmcnt(0)
	v_mfma_f32_16x16x32_bf16 v[6:9], v[46:49], v[6:9], 0
	ds_read_b128 v[46:49], v31 offset:34624
	s_waitcnt lgkmcnt(0)
	v_mfma_f32_16x16x32_bf16 v[6:9], v[46:49], v[10:13], v[6:9]
	v_max3_f32 v10, v34, s89, v35
	v_max3_f32 v10, v10, v36, v37
	v_max3_f32 v10, v10, v38, v39
	v_max3_f32 v10, v10, v40, v41
	v_max3_f32 v10, v10, v42, v43
	v_max3_f32 v10, v10, v44, v45
	v_max3_f32 v10, v10, v50, v51
	v_max3_f32 v10, v10, v52, v53
	v_max3_f32 v10, v10, v56, v57
	v_max3_f32 v10, v10, v58, v59
	v_max3_f32 v10, v10, v66, v67
	v_max3_f32 v10, v10, v68, v69
	v_max3_f32 v10, v10, v74, v75
	v_max3_f32 v10, v10, v76, v77
	v_max3_f32 v10, v10, v80, v81
	v_max3_f32 v10, v10, v82, v83
	v_max3_f32 v10, v10, v84, v85
	v_max3_f32 v10, v10, v86, v87
	v_max3_f32 v10, v10, v88, v89
	v_max3_f32 v10, v10, v90, v91
	v_max3_f32 v10, v10, v92, v93
	v_max3_f32 v10, v10, v94, v95
	v_max3_f32 v10, v10, v96, v97
	v_max3_f32 v10, v10, v98, v99
	v_max3_f32 v10, v10, v22, v23
	v_max3_f32 v10, v10, v24, v25
	v_max3_f32 v10, v10, v18, v19
	v_max3_f32 v10, v10, v20, v21
	v_max3_f32 v10, v10, v14, v15
	v_max3_f32 v10, v10, v16, v17
	v_max3_f32 v10, v10, v6, v7
	v_max3_f32 v10, v10, v8, v9
	ds_bpermute_b32 v11, v109, v10
	s_waitcnt lgkmcnt(0)
	v_max_f32_e32 v11, v11, v11
	v_max_f32_e32 v10, v10, v11
	ds_bpermute_b32 v11, v110, v10
	s_waitcnt lgkmcnt(0)
	v_max_f32_e32 v11, v11, v11
	v_max_f32_e32 v73, v10, v11
	v_sub_f32_e32 v11, v35, v73
	v_mul_f32_e32 v11, 0x3fb8aa3b, v11
	v_exp_f32_e32 v100, v11
	v_sub_f32_e32 v11, v36, v73
	v_mul_f32_e32 v11, 0x3fb8aa3b, v11
	v_exp_f32_e32 v101, v11
	v_sub_f32_e32 v11, v37, v73
	v_mul_f32_e32 v11, 0x3fb8aa3b, v11
	v_exp_f32_e32 v102, v11
	v_sub_f32_e32 v11, v38, v73
	v_mul_f32_e32 v11, 0x3fb8aa3b, v11
	v_exp_f32_e32 v103, v11
	v_sub_f32_e32 v11, v39, v73
	v_mul_f32_e32 v11, 0x3fb8aa3b, v11
	v_exp_f32_e32 v104, v11
	v_sub_f32_e32 v11, v40, v73
	v_mul_f32_e32 v11, 0x3fb8aa3b, v11
	v_exp_f32_e32 v105, v11
	v_sub_f32_e32 v11, v41, v73
	v_mul_f32_e32 v11, 0x3fb8aa3b, v11
	v_exp_f32_e32 v111, v11
	v_sub_f32_e32 v11, v42, v73
	v_mul_f32_e32 v11, 0x3fb8aa3b, v11
	v_sub_f32_e32 v10, v34, v73
	v_exp_f32_e32 v34, v11
	v_sub_f32_e32 v11, v43, v73
	v_mul_f32_e32 v11, 0x3fb8aa3b, v11
	v_exp_f32_e32 v46, v11
	v_sub_f32_e32 v11, v44, v73
	v_mul_f32_e32 v11, 0x3fb8aa3b, v11
	v_exp_f32_e32 v39, v11
	v_sub_f32_e32 v11, v45, v73
	v_mul_f32_e32 v11, 0x3fb8aa3b, v11
	v_exp_f32_e32 v55, v11
	v_sub_f32_e32 v11, v50, v73
	v_mul_f32_e32 v11, 0x3fb8aa3b, v11
	v_exp_f32_e32 v50, v11
	v_sub_f32_e32 v11, v51, v73
	v_mul_f32_e32 v11, 0x3fb8aa3b, v11
	v_exp_f32_e32 v65, v11
	v_sub_f32_e32 v11, v52, v73
	v_mul_f32_e32 v11, 0x3fb8aa3b, v11
	v_exp_f32_e32 v62, v11
	v_sub_f32_e32 v11, v53, v73
	v_mul_f32_e32 v11, 0x3fb8aa3b, v11
	v_exp_f32_e32 v72, v11
	v_sub_f32_e32 v11, v56, v73
	v_mul_f32_e32 v11, 0x3fb8aa3b, v11
	v_exp_f32_e32 v33, v11
	v_sub_f32_e32 v11, v57, v73
	v_mul_f32_e32 v11, 0x3fb8aa3b, v11
	v_exp_f32_e32 v44, v11
	v_sub_f32_e32 v11, v58, v73
	v_mul_f32_e32 v11, 0x3fb8aa3b, v11
	v_exp_f32_e32 v38, v11
	v_sub_f32_e32 v11, v59, v73
	v_mul_f32_e32 v11, 0x3fb8aa3b, v11
	v_exp_f32_e32 v54, v11
	v_sub_f32_e32 v11, v66, v73
	v_mul_f32_e32 v11, 0x3fb8aa3b, v11
	v_exp_f32_e32 v49, v11
	v_sub_f32_e32 v11, v67, v73
	v_mul_f32_e32 v11, 0x3fb8aa3b, v11
	v_exp_f32_e32 v64, v11
	v_sub_f32_e32 v11, v68, v73
	v_mul_f32_e32 v11, 0x3fb8aa3b, v11
	v_exp_f32_e32 v60, v11
	v_sub_f32_e32 v11, v69, v73
	v_mul_f32_e32 v11, 0x3fb8aa3b, v11
	v_exp_f32_e32 v71, v11
	v_sub_f32_e32 v11, v74, v73
	v_mul_f32_e32 v11, 0x3fb8aa3b, v11
	v_mul_f32_e32 v10, 0x3fb8aa3b, v10
	v_exp_f32_e32 v27, v11
	v_sub_f32_e32 v11, v75, v73
	v_exp_f32_e32 v79, v10
	v_mul_f32_e32 v11, 0x3fb8aa3b, v11
	v_exp_f32_e32 v43, v11
	v_sub_f32_e32 v11, v76, v73
	v_mul_f32_e32 v11, 0x3fb8aa3b, v11
	v_exp_f32_e32 v37, v11
	v_sub_f32_e32 v11, v77, v73
	v_add_f32_e32 v10, 0, v79
	v_mul_f32_e32 v11, 0x3fb8aa3b, v11
	v_add_f32_e32 v10, v100, v10
	v_exp_f32_e32 v53, v11
	v_sub_f32_e32 v11, v80, v73
	v_add_f32_e32 v10, v101, v10
	v_mul_f32_e32 v11, 0x3fb8aa3b, v11
	v_add_f32_e32 v10, v102, v10
	v_exp_f32_e32 v48, v11
	v_sub_f32_e32 v11, v81, v73
	v_add_f32_e32 v10, v103, v10
	v_mul_f32_e32 v11, 0x3fb8aa3b, v11
	v_add_f32_e32 v10, v104, v10
	v_exp_f32_e32 v63, v11
	v_sub_f32_e32 v11, v82, v73
	v_add_f32_e32 v10, v105, v10
	v_mul_f32_e32 v11, 0x3fb8aa3b, v11
	v_add_f32_e32 v10, v111, v10
	v_exp_f32_e32 v58, v11
	v_sub_f32_e32 v11, v83, v73
	v_add_f32_e32 v10, v34, v10
	v_mul_f32_e32 v11, 0x3fb8aa3b, v11
	v_add_f32_e32 v10, v46, v10
	v_exp_f32_e32 v70, v11
	v_sub_f32_e32 v11, v84, v73
	v_add_f32_e32 v10, v39, v10
	v_mul_f32_e32 v11, 0x3fb8aa3b, v11
	v_add_f32_e32 v10, v55, v10
	v_exp_f32_e32 v13, v11
	v_sub_f32_e32 v11, v85, v73
	v_add_f32_e32 v10, v50, v10
	v_mul_f32_e32 v11, 0x3fb8aa3b, v11
	v_add_f32_e32 v10, v65, v10
	v_exp_f32_e32 v42, v11
	v_sub_f32_e32 v11, v86, v73
	v_add_f32_e32 v10, v62, v10
	v_mul_f32_e32 v11, 0x3fb8aa3b, v11
	v_add_f32_e32 v10, v72, v10
	v_exp_f32_e32 v36, v11
	v_sub_f32_e32 v11, v87, v73
	v_add_f32_e32 v10, v33, v10
	v_mul_f32_e32 v11, 0x3fb8aa3b, v11
	v_add_f32_e32 v10, v44, v10
	v_exp_f32_e32 v52, v11
	v_sub_f32_e32 v11, v88, v73
	v_add_f32_e32 v10, v38, v10
	v_mul_f32_e32 v11, 0x3fb8aa3b, v11
	v_add_f32_e32 v10, v54, v10
	v_exp_f32_e32 v47, v11
	v_sub_f32_e32 v11, v89, v73
	v_add_f32_e32 v10, v49, v10
	v_mul_f32_e32 v11, 0x3fb8aa3b, v11
	v_add_f32_e32 v10, v64, v10
	v_exp_f32_e32 v61, v11
	v_sub_f32_e32 v11, v90, v73
	v_add_f32_e32 v10, v60, v10
	v_mul_f32_e32 v11, 0x3fb8aa3b, v11
	v_add_f32_e32 v10, v71, v10
	v_exp_f32_e32 v57, v11
	v_sub_f32_e32 v11, v91, v73
	v_add_f32_e32 v10, v27, v10
	v_mul_f32_e32 v11, 0x3fb8aa3b, v11
	v_add_f32_e32 v10, v43, v10
	v_exp_f32_e32 v69, v11
	v_sub_f32_e32 v11, v92, v73
	v_add_f32_e32 v10, v37, v10
	v_mul_f32_e32 v11, 0x3fb8aa3b, v11
	v_add_f32_e32 v10, v53, v10
	v_exp_f32_e32 v12, v11
	v_sub_f32_e32 v11, v93, v73
	v_add_f32_e32 v10, v48, v10
	v_mul_f32_e32 v11, 0x3fb8aa3b, v11
	v_add_f32_e32 v10, v63, v10
	v_exp_f32_e32 v41, v11
	v_sub_f32_e32 v11, v94, v73
	v_add_f32_e32 v10, v58, v10
	v_mul_f32_e32 v11, 0x3fb8aa3b, v11
	v_add_f32_e32 v10, v70, v10
	v_exp_f32_e32 v35, v11
	v_sub_f32_e32 v11, v95, v73
	v_add_f32_e32 v10, v13, v10
	v_mul_f32_e32 v11, 0x3fb8aa3b, v11
	v_add_f32_e32 v10, v42, v10
	v_exp_f32_e32 v51, v11
	v_sub_f32_e32 v11, v96, v73
	v_add_f32_e32 v10, v36, v10
	v_mul_f32_e32 v11, 0x3fb8aa3b, v11
	v_add_f32_e32 v10, v52, v10
	v_exp_f32_e32 v45, v11
	v_sub_f32_e32 v11, v97, v73
	v_add_f32_e32 v10, v47, v10
	v_mul_f32_e32 v11, 0x3fb8aa3b, v11
	v_add_f32_e32 v10, v61, v10
	v_exp_f32_e32 v59, v11
	v_sub_f32_e32 v11, v98, v73
	v_add_f32_e32 v10, v57, v10
	v_mul_f32_e32 v11, 0x3fb8aa3b, v11
	v_add_f32_e32 v10, v69, v10
	v_exp_f32_e32 v56, v11
	v_sub_f32_e32 v11, v99, v73
	v_add_f32_e32 v10, v12, v10
	v_mul_f32_e32 v11, 0x3fb8aa3b, v11
	v_add_f32_e32 v10, v41, v10
	v_exp_f32_e32 v68, v11
	v_sub_f32_e32 v11, v22, v73
	v_sub_f32_e32 v22, v23, v73
	v_add_f32_e32 v10, v35, v10
	v_mul_f32_e32 v22, 0x3fb8aa3b, v22
	v_add_f32_e32 v10, v51, v10
	v_mul_f32_e32 v11, 0x3fb8aa3b, v11
	v_exp_f32_e32 v40, v22
	v_sub_f32_e32 v22, v24, v73
	v_add_f32_e32 v10, v45, v10
	v_exp_f32_e32 v11, v11
	v_mul_f32_e32 v22, 0x3fb8aa3b, v22
	v_add_f32_e32 v10, v59, v10
	v_exp_f32_e32 v23, v22
	v_sub_f32_e32 v22, v25, v73
	v_sub_f32_e32 v19, v19, v73
	v_add_f32_e32 v10, v56, v10
	v_mul_f32_e32 v22, 0x3fb8aa3b, v22
	v_sub_f32_e32 v18, v18, v73
	v_mul_f32_e32 v19, 0x3fb8aa3b, v19
	v_add_f32_e32 v10, v68, v10
	v_exp_f32_e32 v24, v22
	v_mul_f32_e32 v18, 0x3fb8aa3b, v18
	v_exp_f32_e32 v25, v19
	v_sub_f32_e32 v19, v20, v73
	v_add_f32_e32 v10, v11, v10
	v_exp_f32_e32 v18, v18
	v_mul_f32_e32 v19, 0x3fb8aa3b, v19
	v_add_f32_e32 v10, v40, v10
	v_exp_f32_e32 v20, v19
	v_sub_f32_e32 v19, v21, v73
	v_add_f32_e32 v10, v23, v10
	v_mul_f32_e32 v19, 0x3fb8aa3b, v19
	v_add_f32_e32 v10, v24, v10
	v_exp_f32_e32 v67, v19
	v_add_f32_e32 v10, v18, v10
	v_add_f32_e32 v10, v25, v10
	v_add_f32_e32 v10, v20, v10
	v_add_f32_e32 v19, v67, v10
	v_sub_f32_e32 v10, v14, v73
	v_mul_f32_e32 v10, 0x3fb8aa3b, v10
	v_sub_f32_e32 v15, v15, v73
	v_exp_f32_e32 v10, v10
	v_mul_f32_e32 v15, 0x3fb8aa3b, v15
	v_exp_f32_e32 v15, v15
	v_sub_f32_e32 v17, v17, v73
	v_add_f32_e32 v14, v10, v19
	v_mul_f32_e32 v17, 0x3fb8aa3b, v17
	v_add_f32_e32 v19, v15, v14
	v_sub_f32_e32 v14, v16, v73
	v_mul_f32_e32 v14, 0x3fb8aa3b, v14
	v_exp_f32_e32 v14, v14
	v_exp_f32_e32 v17, v17
	v_sub_f32_e32 v6, v6, v73
	v_mul_f32_e32 v6, 0x3fb8aa3b, v6
	v_add_f32_e32 v16, v14, v19
	v_add_f32_e32 v19, v17, v16
	v_exp_f32_e32 v16, v6
	v_sub_f32_e32 v7, v7, v73
	v_mul_f32_e32 v7, 0x3fb8aa3b, v7
	v_exp_f32_e32 v21, v7
	v_sub_f32_e32 v7, v8, v73
	v_mul_f32_e32 v7, 0x3fb8aa3b, v7
	v_add_f32_e32 v6, v16, v19
	v_exp_f32_e32 v19, v7
	v_sub_f32_e32 v7, v9, v73
	v_mul_f32_e32 v7, 0x3fb8aa3b, v7
	v_exp_f32_e32 v66, v7
	v_add_f32_e32 v6, v21, v6
	v_add_f32_e32 v6, v19, v6
	v_bfe_u32 v8, v102, 16, 1
	v_add_f32_e32 v6, v66, v6
	ds_bpermute_b32 v7, v109, v6
	v_bfe_u32 v9, v100, 16, 1
	v_add3_u32 v73, v100, v9, s91
	v_add3_u32 v74, v102, v8, s91
	v_bfe_u32 v8, v79, 16, 1
	s_waitcnt lgkmcnt(0)
	v_add_f32_e32 v6, v6, v7
	ds_bpermute_b32 v7, v110, v6
	v_bfe_u32 v9, v101, 16, 1
	v_bfe_u32 v75, v103, 16, 1
	v_bfe_u32 v76, v105, 16, 1
	v_add3_u32 v75, v103, v75, s91
	s_waitcnt lgkmcnt(0)
	v_add_f32_e32 v22, v6, v7
	v_bfe_u32 v7, v104, 16, 1
	v_add3_u32 v9, v101, v9, s91
	v_add3_u32 v8, v79, v8, s91
	v_bfe_u32 v6, v111, 16, 1
	v_add3_u32 v7, v104, v7, s91
	v_add3_u32 v76, v105, v76, s91
	v_lshrrev_b32_e32 v77, 16, v8
	v_lshrrev_b32_e32 v79, 16, v9
	v_lshrrev_b32_e32 v8, 16, v75
	v_add3_u32 v6, v111, v6, s91
	v_lshrrev_b32_e32 v9, 16, v76
	v_and_or_b32 v8, v7, s33, v8
	v_and_or_b32 v7, v74, s33, v79
	v_add_u32_e32 v79, 0x9000, v32
	v_add_u32_e32 v96, 0xb000, v32
	v_add_u32_e32 v97, 0xd000, v32
	v_add_u32_e32 v98, 0xf000, v32
	v_and_or_b32 v9, v6, s33, v9
	v_and_or_b32 v6, v73, s33, v77
	ds_read2_b64 v[74:77], v79 offset1:4
	ds_read2_b64 v[80:83], v96 offset0:32 offset1:36
	ds_read2_b64 v[84:87], v97 offset0:64 offset1:68
	ds_read2_b64 v[88:91], v98 offset0:96 offset1:100
	ds_read2_b64 v[92:95], v79 offset0:8 offset1:12
	s_waitcnt lgkmcnt(4)
	v_mfma_f32_16x16x32_bf16 v[74:77], v[74:77], v[6:9], 0
	v_bfe_u32 v73, v72, 16, 1
	v_add3_u32 v72, v72, v73, s91
	v_bfe_u32 v73, v34, 16, 1
	s_waitcnt lgkmcnt(3)
	v_mfma_f32_16x16x32_bf16 v[80:83], v[80:83], v[6:9], 0
	v_add3_u32 v34, v34, v73, s91
	v_lshrrev_b32_e32 v34, 16, v34
	s_waitcnt lgkmcnt(2)
	v_mfma_f32_16x16x32_bf16 v[84:87], v[84:87], v[6:9], 0
	s_waitcnt lgkmcnt(1)
	v_mfma_f32_16x16x32_bf16 v[6:9], v[88:91], v[6:9], 0
	v_bfe_u32 v88, v65, 16, 1
	v_bfe_u32 v89, v55, 16, 1
	v_bfe_u32 v90, v46, 16, 1
	v_add3_u32 v46, v46, v90, s91
	v_add3_u32 v55, v55, v89, s91
	v_add3_u32 v65, v65, v88, s91
	v_bfe_u32 v88, v39, 16, 1
	v_bfe_u32 v89, v50, 16, 1
	v_bfe_u32 v90, v62, 16, 1
	v_add3_u32 v62, v62, v90, s91
	v_add3_u32 v50, v50, v89, s91
	v_add3_u32 v39, v39, v88, s91
	v_lshrrev_b32_e32 v39, 16, v39
	v_lshrrev_b32_e32 v50, 16, v50
	v_lshrrev_b32_e32 v62, 16, v62
	v_and_or_b32 v91, v72, s33, v62
	v_and_or_b32 v90, v65, s33, v50
	v_and_or_b32 v89, v55, s33, v39
	v_and_or_b32 v88, v46, s33, v34
	v_bfe_u32 v46, v54, 16, 1
	v_bfe_u32 v50, v44, 16, 1
	s_waitcnt lgkmcnt(0)
	v_mfma_f32_16x16x32_bf16 v[72:75], v[92:95], v[88:91], v[74:77]
	ds_read2_b64 v[92:95], v96 offset0:40 offset1:44
	v_add3_u32 v44, v44, v50, s91
	v_add3_u32 v46, v54, v46, s91
	s_waitcnt lgkmcnt(0)
	v_mfma_f32_16x16x32_bf16 v[80:83], v[92:95], v[88:91], v[80:83]
	ds_read2_b64 v[92:95], v97 offset0:72 offset1:76
	v_bfe_u32 v50, v33, 16, 1
	v_bfe_u32 v54, v38, 16, 1
	s_waitcnt lgkmcnt(0)
	v_mfma_f32_16x16x32_bf16 v[84:87], v[92:95], v[88:91], v[84:87]
	ds_read2_b64 v[92:95], v98 offset0:104 offset1:108
	v_bfe_u32 v55, v49, 16, 1
	s_waitcnt lgkmcnt(0)
	v_mfma_f32_16x16x32_bf16 v[6:9], v[92:95], v[88:91], v[6:9]
	ds_read2_b64 v[92:95], v79 offset0:16 offset1:20
	v_bfe_u32 v62, v60, 16, 1
	v_bfe_u32 v34, v71, 16, 1
	v_bfe_u32 v39, v64, 16, 1
	v_add3_u32 v60, v60, v62, s91
	v_add3_u32 v49, v49, v55, s91
	v_add3_u32 v38, v38, v54, s91
	v_add3_u32 v33, v33, v50, s91
	v_add3_u32 v39, v64, v39, s91
	v_add3_u32 v34, v71, v34, s91
	v_lshrrev_b32_e32 v33, 16, v33
	v_lshrrev_b32_e32 v38, 16, v38
	v_lshrrev_b32_e32 v49, 16, v49
	v_lshrrev_b32_e32 v50, 16, v60
	v_and_or_b32 v91, v34, s33, v50
	v_and_or_b32 v90, v39, s33, v49
	v_and_or_b32 v89, v46, s33, v38
	v_and_or_b32 v88, v44, s33, v33
	v_bfe_u32 v39, v43, 16, 1
	v_add3_u32 v39, v43, v39, s91
	s_waitcnt lgkmcnt(0)
	v_mfma_f32_16x16x32_bf16 v[72:75], v[92:95], v[88:91], v[72:75]
	ds_read2_b64 v[92:95], v96 offset0:48 offset1:52
	v_bfe_u32 v43, v27, 16, 1
	v_bfe_u32 v44, v37, 16, 1
	s_waitcnt lgkmcnt(0)
	v_mfma_f32_16x16x32_bf16 v[80:83], v[92:95], v[88:91], v[80:83]
	ds_read2_b64 v[92:95], v97 offset0:80 offset1:84
	v_bfe_u32 v46, v48, 16, 1
	v_bfe_u32 v49, v58, 16, 1
	s_waitcnt lgkmcnt(0)
	v_mfma_f32_16x16x32_bf16 v[84:87], v[92:95], v[88:91], v[84:87]
	ds_read2_b64 v[92:95], v98 offset0:112 offset1:116
	v_bfe_u32 v33, v70, 16, 1
	s_waitcnt lgkmcnt(0)
	v_mfma_f32_16x16x32_bf16 v[6:9], v[92:95], v[88:91], v[6:9]
	ds_read2_b64 v[88:91], v79 offset0:24 offset1:28
	v_bfe_u32 v34, v63, 16, 1
	v_bfe_u32 v38, v53, 16, 1
	v_add3_u32 v49, v58, v49, s91
	v_add3_u32 v46, v48, v46, s91
	v_add3_u32 v37, v37, v44, s91
	v_add3_u32 v27, v27, v43, s91
	v_add3_u32 v38, v53, v38, s91
	v_add3_u32 v34, v63, v34, s91
	v_add3_u32 v33, v70, v33, s91
	v_lshrrev_b32_e32 v27, 16, v27
	v_lshrrev_b32_e32 v37, 16, v37
	v_lshrrev_b32_e32 v43, 16, v46
	v_lshrrev_b32_e32 v44, 16, v49
	v_and_or_b32 v65, v33, s33, v44
	v_and_or_b32 v64, v34, s33, v43
	v_and_or_b32 v63, v38, s33, v37
	v_and_or_b32 v62, v39, s33, v27
	v_bfe_u32 v39, v47, 16, 1
	v_add3_u32 v39, v47, v39, s91
	s_waitcnt lgkmcnt(0)
	v_mfma_f32_16x16x32_bf16 v[70:73], v[88:91], v[62:65], v[72:75]
	v_bfe_u32 v37, v42, 16, 1
	v_add3_u32 v42, v42, v37, s91
	v_bfe_u32 v37, v13, 16, 1
	ds_read2_b64 v[74:77], v96 offset0:56 offset1:60
	s_waitcnt lgkmcnt(0)
	v_mfma_f32_16x16x32_bf16 v[74:77], v[74:77], v[62:65], v[80:83]
	s_nop 2
	ds_read2_b64 v[80:83], v97 offset0:88 offset1:92
	v_bfe_u32 v38, v36, 16, 1
	v_bfe_u32 v43, v57, 16, 1
	s_waitcnt lgkmcnt(0)
	v_mfma_f32_16x16x32_bf16 v[80:83], v[80:83], v[62:65], v[84:87]
	s_nop 2
	ds_read2_b64 v[84:87], v98 offset0:120 offset1:124
	ds_read2_b64 v[46:49], v79 offset0:32 offset1:36
	v_bfe_u32 v27, v69, 16, 1
	v_bfe_u32 v33, v61, 16, 1
	v_bfe_u32 v34, v52, 16, 1
	v_add3_u32 v43, v57, v43, s91
	v_add3_u32 v36, v36, v38, s91
	v_add3_u32 v13, v13, v37, s91
	v_add3_u32 v34, v52, v34, s91
	v_add3_u32 v33, v61, v33, s91
	v_add3_u32 v27, v69, v27, s91
	v_lshrrev_b32_e32 v13, 16, v13
	v_lshrrev_b32_e32 v36, 16, v36
	v_lshrrev_b32_e32 v37, 16, v39
	v_lshrrev_b32_e32 v38, 16, v43
	v_and_or_b32 v39, v27, s33, v38
	v_and_or_b32 v38, v33, s33, v37
	v_and_or_b32 v37, v34, s33, v36
	v_and_or_b32 v36, v42, s33, v13
	s_waitcnt lgkmcnt(1)
	v_mfma_f32_16x16x32_bf16 v[6:9], v[84:87], v[62:65], v[6:9]
	ds_read2_b64 v[52:55], v96 offset0:64 offset1:68
	ds_read2_b64 v[60:63], v97 offset0:96 offset1:100
	v_bfe_u32 v13, v68, 16, 1
	s_waitcnt lgkmcnt(2)
	v_mfma_f32_16x16x32_bf16 v[46:49], v[46:49], v[36:39], v[70:73]
	v_bfe_u32 v27, v59, 16, 1
	v_bfe_u32 v33, v51, 16, 1
	v_bfe_u32 v34, v41, 16, 1
	ds_read2_b64 v[70:73], v98 offset0:128 offset1:132
	s_waitcnt lgkmcnt(2)
	v_mfma_f32_16x16x32_bf16 v[52:55], v[52:55], v[36:39], v[74:77]
	v_add3_u32 v34, v41, v34, s91
	v_add3_u32 v33, v51, v33, s91
	s_waitcnt lgkmcnt(1)
	v_mfma_f32_16x16x32_bf16 v[60:63], v[60:63], v[36:39], v[80:83]
	v_add3_u32 v27, v59, v27, s91
	v_add3_u32 v13, v68, v13, s91
	s_waitcnt lgkmcnt(0)
	v_mfma_f32_16x16x32_bf16 v[6:9], v[70:73], v[36:39], v[6:9]
	v_bfe_u32 v38, v45, 16, 1
	v_add3_u32 v38, v45, v38, s91
	ds_read2_b64 v[42:45], v79 offset0:40 offset1:44
	v_bfe_u32 v36, v12, 16, 1
	v_bfe_u32 v37, v35, 16, 1
	v_bfe_u32 v39, v56, 16, 1
	v_add3_u32 v39, v56, v39, s91
	v_add3_u32 v35, v35, v37, s91
	v_add3_u32 v12, v12, v36, s91
	v_lshrrev_b32_e32 v12, 16, v12
	v_lshrrev_b32_e32 v35, 16, v35
	v_lshrrev_b32_e32 v36, 16, v38
	v_lshrrev_b32_e32 v37, 16, v39
	v_and_or_b32 v37, v13, s33, v37
	v_and_or_b32 v36, v27, s33, v36
	v_and_or_b32 v35, v33, s33, v35
	v_and_or_b32 v34, v34, s33, v12
	v_bfe_u32 v33, v40, 16, 1
	v_add3_u32 v33, v40, v33, s91
	s_waitcnt lgkmcnt(0)
	v_mfma_f32_16x16x32_bf16 v[42:45], v[42:45], v[34:37], v[46:49]
	v_bfe_u32 v13, v25, 16, 1
	v_bfe_u32 v27, v24, 16, 1
	v_add3_u32 v24, v24, v27, s91
	ds_read2_b64 v[46:49], v96 offset0:72 offset1:76
	s_waitcnt lgkmcnt(0)
	v_mfma_f32_16x16x32_bf16 v[46:49], v[46:49], v[34:37], v[52:55]
	s_nop 2
	ds_read2_b64 v[50:53], v97 offset0:104 offset1:108
	ds_read2_b64 v[54:57], v98 offset0:136 offset1:140
	ds_read2_b64 v[38:41], v79 offset0:48 offset1:52
	s_waitcnt lgkmcnt(2)
	v_mfma_f32_16x16x32_bf16 v[50:53], v[50:53], v[34:37], v[60:63]
	v_add3_u32 v13, v25, v13, s91
	v_bfe_u32 v25, v11, 16, 1
	v_bfe_u32 v27, v23, 16, 1
	s_waitcnt lgkmcnt(1)
	v_mfma_f32_16x16x32_bf16 v[6:9], v[54:57], v[34:37], v[6:9]
	v_bfe_u32 v34, v18, 16, 1
	v_bfe_u32 v35, v20, 16, 1
	v_bfe_u32 v12, v67, 16, 1
	v_add3_u32 v20, v20, v35, s91
	v_add3_u32 v18, v18, v34, s91
	v_add3_u32 v23, v23, v27, s91
	v_add3_u32 v11, v11, v25, s91
	v_add3_u32 v12, v67, v12, s91
	v_lshrrev_b32_e32 v11, 16, v11
	v_lshrrev_b32_e32 v23, 16, v23
	v_lshrrev_b32_e32 v18, 16, v18
	v_lshrrev_b32_e32 v20, 16, v20
	v_and_or_b32 v37, v12, s33, v20
	v_and_or_b32 v36, v13, s33, v18
	v_and_or_b32 v35, v24, s33, v23
	v_and_or_b32 v34, v33, s33, v11
	v_bfe_u32 v12, v21, 16, 1
	v_bfe_u32 v13, v17, 16, 1
	s_waitcnt lgkmcnt(0)
	v_mfma_f32_16x16x32_bf16 v[38:41], v[38:41], v[34:37], v[42:45]
	v_bfe_u32 v18, v15, 16, 1
	v_add3_u32 v15, v15, v18, s91
	v_add3_u32 v13, v17, v13, s91
	ds_read2_b64 v[42:45], v96 offset0:80 offset1:84
	s_waitcnt lgkmcnt(0)
	v_mfma_f32_16x16x32_bf16 v[42:45], v[42:45], v[34:37], v[46:49]
	s_nop 2
	ds_read2_b64 v[46:49], v97 offset0:112 offset1:116
	v_add3_u32 v12, v21, v12, s91
	v_bfe_u32 v17, v10, 16, 1
	s_waitcnt lgkmcnt(0)
	v_mfma_f32_16x16x32_bf16 v[46:49], v[46:49], v[34:37], v[50:53]
	s_nop 2
	ds_read2_b64 v[50:53], v98 offset0:144 offset1:148
	v_bfe_u32 v18, v14, 16, 1
	v_bfe_u32 v20, v16, 16, 1
	v_bfe_u32 v21, v19, 16, 1
	v_bfe_u32 v11, v66, 16, 1
	v_add3_u32 v19, v19, v21, s91
	v_add3_u32 v16, v16, v20, s91
	v_add3_u32 v14, v14, v18, s91
	v_add3_u32 v10, v10, v17, s91
	v_add3_u32 v11, v66, v11, s91
	v_lshrrev_b32_e32 v10, 16, v10
	v_lshrrev_b32_e32 v14, 16, v14
	v_lshrrev_b32_e32 v16, 16, v16
	v_lshrrev_b32_e32 v17, 16, v19
	s_waitcnt lgkmcnt(0)
	v_mfma_f32_16x16x32_bf16 v[6:9], v[50:53], v[34:37], v[6:9]
	v_and_or_b32 v37, v11, s33, v17
	v_and_or_b32 v36, v12, s33, v16
	v_and_or_b32 v35, v13, s33, v14
	v_and_or_b32 v34, v15, s33, v10
	ds_read2_b64 v[10:13], v79 offset0:56 offset1:60
	v_div_scale_f32 v23, s[4:5], v22, v22, 1.0
	s_waitcnt lgkmcnt(0)
	v_mfma_f32_16x16x32_bf16 v[18:21], v[10:13], v[34:37], v[38:41]
	ds_read2_b64 v[10:13], v96 offset0:88 offset1:92
	v_rcp_f32_e32 v27, v23
	s_nop 0
	ds_read2_b64 v[38:41], v98 offset0:152 offset1:156
	s_waitcnt lgkmcnt(1)
	v_mfma_f32_16x16x32_bf16 v[14:17], v[10:13], v[34:37], v[42:45]
	ds_read2_b64 v[10:13], v97 offset0:120 offset1:124
	v_lshlrev_b64 v[24:25], 11, v[28:29]
	v_fma_f32 v28, -v23, v27, 1.0
	v_fmac_f32_e32 v27, v28, v27
	v_div_scale_f32 v28, vcc, 1.0, v22, 1.0
	v_mul_f32_e32 v29, v28, v27
	v_fma_f32 v33, -v23, v29, v28
	v_fmac_f32_e32 v29, v33, v27
	v_fma_f32 v23, -v23, v29, v28
	v_div_fmas_f32 v23, v23, v27, v29
	s_waitcnt lgkmcnt(0)
	v_mfma_f32_16x16x32_bf16 v[10:13], v[10:13], v[34:37], v[46:49]
	v_div_fixup_f32 v22, v23, v22, 1.0
	v_lshl_add_u64 v[24:25], s[0:1], 0, v[24:25]
	v_lshl_add_u64 v[24:25], v[24:25], 0, s[94:95]
	v_mfma_f32_16x16x32_bf16 v[6:9], v[38:41], v[34:37], v[6:9]
	v_mov_b32_e32 v35, v20
	v_mov_b32_e32 v20, v19
	v_mov_b32_e32 v34, v18
	v_pk_mul_f32 v[18:19], v[22:23], v[20:21] op_sel_hi:[0,1]
	v_mov_b32_e32 v27, v1
	v_pk_mul_f32 v[34:35], v[22:23], v[34:35] op_sel_hi:[0,1]
	v_and_b32_sdwa v23, v19, v218 dst_sel:DWORD dst_unused:UNUSED_PAD src0_sel:WORD_1 src1_sel:DWORD
	v_lshl_add_u64 v[24:25], v[24:25], 0, v[26:27]
	v_and_b32_sdwa v20, v35, v218 dst_sel:DWORD dst_unused:UNUSED_PAD src0_sel:WORD_1 src1_sel:DWORD
	v_and_b32_sdwa v27, v18, v218 dst_sel:DWORD dst_unused:UNUSED_PAD src0_sel:WORD_1 src1_sel:DWORD
	v_add3_u32 v19, v19, v23, s91
	v_and_b32_sdwa v21, v34, v218 dst_sel:DWORD dst_unused:UNUSED_PAD src0_sel:WORD_1 src1_sel:DWORD
	v_add3_u32 v20, v35, v20, s91
	v_add3_u32 v18, v18, v27, s91
	v_and_b32_e32 v19, 0xffff0000, v19
	v_add3_u32 v21, v34, v21, s91
	v_and_b32_e32 v18, 0xffff0000, v18
	v_or_b32_sdwa v19, v19, v20 dst_sel:DWORD dst_unused:UNUSED_PAD src0_sel:DWORD src1_sel:WORD_1
	v_add_co_u32_e32 v20, vcc, s8, v24
	v_or_b32_sdwa v18, v18, v21 dst_sel:DWORD dst_unused:UNUSED_PAD src0_sel:DWORD src1_sel:WORD_1
	s_nop 0
	v_addc_co_u32_e32 v21, vcc, 0, v25, vcc
	global_store_dwordx2 v[20:21], v[18:19], off offset:1536
	v_mov_b32_e32 v18, v14
	v_mov_b32_e32 v19, v16
	v_pk_mul_f32 v[18:19], v[22:23], v[18:19] op_sel_hi:[0,1]
	v_mov_b32_e32 v16, v15
	v_pk_mul_f32 v[14:15], v[22:23], v[16:17] op_sel_hi:[0,1]
	v_and_b32_sdwa v16, v19, v218 dst_sel:DWORD dst_unused:UNUSED_PAD src0_sel:WORD_1 src1_sel:DWORD
	v_and_b32_sdwa v17, v18, v218 dst_sel:DWORD dst_unused:UNUSED_PAD src0_sel:WORD_1 src1_sel:DWORD
	v_add3_u32 v17, v18, v17, s91
	v_add3_u32 v16, v19, v16, s91
	v_and_b32_sdwa v18, v15, v218 dst_sel:DWORD dst_unused:UNUSED_PAD src0_sel:WORD_1 src1_sel:DWORD
	v_and_b32_sdwa v19, v14, v218 dst_sel:DWORD dst_unused:UNUSED_PAD src0_sel:WORD_1 src1_sel:DWORD
	v_add3_u32 v15, v15, v18, s91
	v_add3_u32 v14, v14, v19, s91
	v_and_b32_e32 v15, 0xffff0000, v15
	v_and_b32_e32 v14, 0xffff0000, v14
	v_lshl_add_u64 v[28:29], v[24:25], 0, s[10:11]
	v_or_b32_sdwa v15, v15, v16 dst_sel:DWORD dst_unused:UNUSED_PAD src0_sel:DWORD src1_sel:WORD_1
	v_or_b32_sdwa v14, v14, v17 dst_sel:DWORD dst_unused:UNUSED_PAD src0_sel:DWORD src1_sel:WORD_1
	global_store_dwordx2 v[28:29], v[14:15], off offset:32
	v_mov_b32_e32 v14, v10
	v_mov_b32_e32 v15, v12
	v_pk_mul_f32 v[14:15], v[22:23], v[14:15] op_sel_hi:[0,1]
	v_mov_b32_e32 v12, v11
	v_pk_mul_f32 v[10:11], v[22:23], v[12:13] op_sel_hi:[0,1]
	v_and_b32_sdwa v12, v15, v218 dst_sel:DWORD dst_unused:UNUSED_PAD src0_sel:WORD_1 src1_sel:DWORD
	v_and_b32_sdwa v13, v14, v218 dst_sel:DWORD dst_unused:UNUSED_PAD src0_sel:WORD_1 src1_sel:DWORD
	v_add3_u32 v13, v14, v13, s91
	v_add3_u32 v12, v15, v12, s91
	v_and_b32_sdwa v14, v11, v218 dst_sel:DWORD dst_unused:UNUSED_PAD src0_sel:WORD_1 src1_sel:DWORD
	v_and_b32_sdwa v15, v10, v218 dst_sel:DWORD dst_unused:UNUSED_PAD src0_sel:WORD_1 src1_sel:DWORD
	v_add3_u32 v11, v11, v14, s91
	v_add3_u32 v10, v10, v15, s91
	v_and_b32_e32 v11, 0xffff0000, v11
	v_and_b32_e32 v10, 0xffff0000, v10
	v_or_b32_sdwa v11, v11, v12 dst_sel:DWORD dst_unused:UNUSED_PAD src0_sel:DWORD src1_sel:WORD_1
	v_or_b32_sdwa v10, v10, v13 dst_sel:DWORD dst_unused:UNUSED_PAD src0_sel:DWORD src1_sel:WORD_1
	global_store_dwordx2 v[28:29], v[10:11], off offset:64
	v_mov_b32_e32 v10, v6
	v_mov_b32_e32 v11, v8
	v_pk_mul_f32 v[10:11], v[22:23], v[10:11] op_sel_hi:[0,1]
	v_mov_b32_e32 v8, v7
	v_pk_mul_f32 v[6:7], v[22:23], v[8:9] op_sel_hi:[0,1]
	v_and_b32_sdwa v8, v11, v218 dst_sel:DWORD dst_unused:UNUSED_PAD src0_sel:WORD_1 src1_sel:DWORD
	v_and_b32_sdwa v9, v10, v218 dst_sel:DWORD dst_unused:UNUSED_PAD src0_sel:WORD_1 src1_sel:DWORD
	v_add3_u32 v9, v10, v9, s91
	v_add3_u32 v8, v11, v8, s91
	v_and_b32_sdwa v10, v7, v218 dst_sel:DWORD dst_unused:UNUSED_PAD src0_sel:WORD_1 src1_sel:DWORD
	v_and_b32_sdwa v11, v6, v218 dst_sel:DWORD dst_unused:UNUSED_PAD src0_sel:WORD_1 src1_sel:DWORD
	v_add3_u32 v7, v7, v10, s91
	v_add3_u32 v6, v6, v11, s91
	v_and_b32_e32 v7, 0xffff0000, v7
	v_and_b32_e32 v6, 0xffff0000, v6
	v_or_b32_sdwa v7, v7, v8 dst_sel:DWORD dst_unused:UNUSED_PAD src0_sel:DWORD src1_sel:WORD_1
	v_or_b32_sdwa v6, v6, v9 dst_sel:DWORD dst_unused:UNUSED_PAD src0_sel:DWORD src1_sel:WORD_1
	s_movk_i32 s4, 0x80
	s_and_b64 vcc, exec, s[2:3]
	s_mov_b64 s[2:3], 0
	global_store_dwordx2 v[28:29], v[6:7], off offset:96
	s_cbranch_vccnz .LBB0_459
	s_waitcnt lgkmcnt(0)
	s_barrier

.LBB0_465:
	s_or_b64 exec, exec, s[4:5]
	v_pk_mul_f32 v[56:57], v[50:51], v[50:51]
	v_pk_mul_f32 v[60:61], v[52:53], v[52:53]
	v_pk_fma_f32 v[56:57], v[46:47], v[46:47], v[56:57]
	v_pk_fma_f32 v[60:61], v[48:49], v[48:49], v[60:61]
	v_add_f32_e32 v0, v57, v56
	v_pk_mul_f32 v[62:63], v[58:59], v[58:59]
	v_add_f32_e32 v0, v60, v0
	v_pk_fma_f32 v[62:63], v[64:65], v[64:65], v[62:63]
	v_add_f32_e32 v0, v61, v0
	v_pk_mul_f32 v[66:67], v[72:73], v[72:73]
	v_add_f32_e32 v0, v62, v0
	v_pk_fma_f32 v[66:67], v[70:71], v[70:71], v[66:67]
	v_add_f32_e32 v0, v63, v0
	v_add_f32_e32 v0, v66, v0
	v_add_f32_e32 v0, v67, v0
	ds_bpermute_b32 v55, v5, v0
	s_cmp_eq_u32 s13, 31
	v_readlane_b32 s6, v254, 49
	s_cselect_b64 s[4:5], -1, 0
	v_readlane_b32 s7, v254, 50
	s_waitcnt lgkmcnt(0)
	v_add_f32_e32 v0, v0, v55
	ds_bpermute_b32 v55, v106, v0
	s_and_b64 s[6:7], s[6:7], s[4:5]
	v_max_i32_e32 v54, 0, v54
	s_nop 1
	v_lshl_or_b32 v191, v54, 5, v3
	v_or_b32_e32 v196, 4, v191
	v_ashrrev_i32_e32 v197, 31, v196
	v_lshlrev_b64 v[196:197], 2, v[196:197]
	v_lshl_add_u64 v[200:201], s[10:11], 0, v[196:197]
	global_load_dwordx4 v[202:205], v[200:201], off
	s_nop 1
	v_lshl_or_b32 v190, v54, 5, v3
	v_or_b32_e32 v186, 4, v190
	v_ashrrev_i32_e32 v187, 31, v186
	v_lshlrev_b64 v[186:187], 2, v[186:187]
	v_lshl_add_u64 v[188:189], s[8:9], 0, v[186:187]
	global_load_dwordx4 v[192:195], v[188:189], off
	s_nop 1
	v_lshl_or_b32 v162, v54, 5, v3
	v_ashrrev_i32_e32 v163, 31, v162
	v_lshlrev_b64 v[158:159], 2, v[162:163]
	v_lshl_add_u64 v[160:161], s[8:9], 0, v[158:159]
	global_load_dwordx4 v[164:167], v[160:161], off
	s_nop 1
	v_lshl_or_b32 v150, v54, 5, v3
	v_ashrrev_i32_e32 v151, 31, v150
	v_lshlrev_b64 v[148:149], 2, v[150:151]
	v_lshl_add_u64 v[152:153], s[10:11], 0, v[148:149]
	global_load_dwordx4 v[154:157], v[152:153], off
	v_lshl_or_b32 v76, v54, 5, v3
	v_ashrrev_i32_e32 v77, 31, v76
	s_waitcnt lgkmcnt(0)
	v_add_f32_e32 v0, v0, v55
	v_fmamk_f32 v0, v0, 0x3c800000, v219
	v_cmp_gt_f32_e32 vcc, s85, v0
	v_mul_f32_e32 v55, 0x4f800000, v0
	s_and_b32 s20, s20, 0xffffff80
	v_cndmask_b32_e32 v0, v0, v55, vcc
	v_sqrt_f32_e32 v55, v0
	s_addk_i32 s20, 0xff80
	v_add_u32_e32 v56, -1, v55
	v_fma_f32 v57, -v56, v55, v0
	v_cmp_ge_f32_e64 s[4:5], 0, v57
	v_add_u32_e32 v57, 1, v55
	s_nop 0
	v_cndmask_b32_e64 v56, v55, v56, s[4:5]
	v_fma_f32 v55, -v57, v55, v0
	v_cmp_lt_f32_e64 s[4:5], 0, v55
	s_nop 1
	v_cndmask_b32_e64 v55, v56, v57, s[4:5]
	v_mul_f32_e32 v56, 0x37800000, v55
	v_cndmask_b32_e32 v55, v55, v56, vcc
	v_cmp_class_f32_e32 vcc, v0, v221
	s_nop 1
	v_cndmask_b32_e32 v0, v55, v0, vcc
	v_div_scale_f32 v55, s[4:5], v0, v0, 1.0
	v_rcp_f32_e32 v56, v55
	v_readlane_b32 s4, v254, 15
	v_fma_f32 v57, -v55, v56, 1.0
	v_fmac_f32_e32 v56, v57, v56
	v_div_scale_f32 v57, vcc, 1.0, v0, 1.0
	v_mul_f32_e32 v60, v57, v56
	v_fma_f32 v61, -v55, v60, v57
	v_fmac_f32_e32 v60, v61, v56
	v_fma_f32 v55, -v55, v60, v57
	v_div_fmas_f32 v55, v55, v56, v60
	v_div_fixup_f32 v74, v55, v0, 1.0
	v_mov_b32_e32 v0, s4
	ds_read_b64 v[56:57], v0
	v_lshlrev_b32_e32 v0, 2, v3
	v_lshlrev_b64 v[54:55], 2, v[76:77]
	v_lshl_add_u64 v[80:81], s[10:11], 0, v[54:55]
	s_waitcnt vmcnt(0)
	s_nop 0
	v_mov_b32_e32 v84, v154
	v_mov_b32_e32 v85, v155
	v_mov_b32_e32 v86, v156
	v_mov_b32_e32 v87, v157
	s_nop 1
	s_waitcnt lgkmcnt(0)
	v_readfirstlane_b32 s4, v56
	v_readfirstlane_b32 s5, v57
	s_nop 1
	v_lshl_add_u64 v[206:207], s[4:5], 0, v[0:1]
	global_load_dwordx4 v[208:211], v[206:207], off offset:16
	s_nop 1
	v_lshl_add_u64 v[180:181], s[4:5], 0, v[0:1]
	global_load_dwordx4 v[182:185], v[180:181], off offset:144
	s_nop 1
	v_lshl_add_u64 v[174:175], s[4:5], 0, v[0:1]
	global_load_dwordx4 v[176:179], v[174:175], off
	s_nop 1
	v_lshl_add_u64 v[168:169], s[4:5], 0, v[0:1]
	global_load_dwordx4 v[170:173], v[168:169], off offset:128
	v_lshl_add_u64 v[56:57], s[8:9], 0, v[54:55]
	s_waitcnt vmcnt(1)
	s_nop 0
	v_mov_b32_e32 v54, v164
	v_mov_b32_e32 v55, v165
	v_mov_b32_e32 v56, v166
	v_mov_b32_e32 v57, v167
	s_nop 1
	v_lshl_add_u64 v[66:67], s[4:5], 0, v[0:1]
	s_waitcnt vmcnt(0)
	s_nop 0
	v_mov_b32_e32 v60, v170
	v_mov_b32_e32 v61, v171
	v_mov_b32_e32 v62, v172
	v_mov_b32_e32 v63, v173
	s_nop 1
	s_waitcnt vmcnt(1)
	s_nop 0
	v_mov_b32_e32 v88, v176
	v_mov_b32_e32 v89, v177
	v_mov_b32_e32 v90, v178
	v_mov_b32_e32 v91, v179
	s_nop 1
	v_pk_mul_f32 v[50:51], v[50:51], v[74:75] op_sel_hi:[1,0]
	v_pk_mul_f32 v[46:47], v[46:47], v[74:75] op_sel_hi:[1,0]
	v_pk_mul_f32 v[52:53], v[52:53], v[74:75] op_sel_hi:[1,0]
	v_pk_mul_f32 v[48:49], v[48:49], v[74:75] op_sel_hi:[1,0]
	v_pk_mul_f32 v[58:59], v[58:59], v[74:75] op_sel_hi:[1,0]
	s_movk_i32 s4, 0x7f
	v_cmp_lt_i32_e32 vcc, s4, v82
	s_and_b64 s[22:23], s[6:7], vcc
	s_waitcnt vmcnt(1) lgkmcnt(0)
	v_pk_mul_f32 v[60:61], v[60:61], v[50:51]
	v_pk_mul_f32 v[46:47], v[88:89], v[46:47]
	v_pk_mul_f32 v[50:51], v[84:85], v[60:61]
	v_pk_mul_f32 v[48:49], v[48:49], v[90:91]
	v_pk_fma_f32 v[50:51], v[54:55], v[46:47], v[50:51] neg_lo:[0,0,1] neg_hi:[0,0,1]
	v_pk_mul_f32 v[54:55], v[54:55], v[60:61]
	v_bfe_u32 v69, v50, 16, 1
	v_pk_fma_f32 v[46:47], v[84:85], v[46:47], v[54:55]
	v_pk_mul_f32 v[54:55], v[52:53], v[62:63]
	s_waitcnt vmcnt(2)
	s_nop 0
	v_mov_b32_e32 v60, v182
	v_mov_b32_e32 v61, v183
	v_mov_b32_e32 v62, v184
	v_mov_b32_e32 v63, v185
	s_nop 1
	v_pk_mul_f32 v[52:53], v[86:87], v[54:55]
	v_pk_mul_f32 v[54:55], v[56:57], v[54:55]
	v_pk_fma_f32 v[52:53], v[56:57], v[48:49], v[52:53] neg_lo:[0,0,1] neg_hi:[0,0,1]
	v_pk_fma_f32 v[48:49], v[86:87], v[48:49], v[54:55]
	v_or_b32_e32 v54, 4, v76
	v_ashrrev_i32_e32 v55, 31, v54
	v_lshlrev_b64 v[54:55], 2, v[54:55]
	v_lshl_add_u64 v[80:81], s[10:11], 0, v[54:55]
	v_lshl_add_u64 v[56:57], s[8:9], 0, v[54:55]
	s_waitcnt vmcnt(5)
	s_nop 0
	v_mov_b32_e32 v54, v192
	v_mov_b32_e32 v55, v193
	v_mov_b32_e32 v56, v194
	v_mov_b32_e32 v57, v195
	s_nop 1
	v_add3_u32 v69, v50, v69, s91
	v_lshrrev_b32_e32 v69, 16, v69
	s_waitcnt vmcnt(5) lgkmcnt(0)
	v_pk_mul_f32 v[76:77], v[58:59], v[60:61]
	s_waitcnt vmcnt(6)
	s_nop 0
	v_mov_b32_e32 v58, v202
	v_mov_b32_e32 v59, v203
	v_mov_b32_e32 v60, v204
	v_mov_b32_e32 v61, v205
	s_nop 1
	v_pk_mul_f32 v[80:81], v[64:65], v[74:75] op_sel_hi:[1,0]
	s_waitcnt vmcnt(3)
	s_nop 0
	v_mov_b32_e32 v64, v208
	v_mov_b32_e32 v65, v209
	v_mov_b32_e32 v66, v210
	v_mov_b32_e32 v67, v211
	s_nop 1
	s_waitcnt vmcnt(3) lgkmcnt(0)
	v_pk_mul_f32 v[80:81], v[80:81], v[64:65]
	v_pk_mul_f32 v[64:65], v[58:59], v[76:77]
	s_nop 0
	v_pk_fma_f32 v[64:65], v[54:55], v[80:81], v[64:65] neg_lo:[0,0,1] neg_hi:[0,0,1]
	v_pk_mul_f32 v[54:55], v[54:55], v[76:77]
	s_nop 0
	v_pk_fma_f32 v[54:55], v[58:59], v[80:81], v[54:55]
	v_pk_mul_f32 v[58:59], v[72:73], v[74:75] op_sel_hi:[1,0]
	s_nop 0
	v_pk_mul_f32 v[58:59], v[58:59], v[62:63]
	v_pk_mul_f32 v[62:63], v[70:71], v[74:75] op_sel_hi:[1,0]
	v_bfe_u32 v70, v64, 16, 1
	v_pk_mul_f32 v[62:63], v[62:63], v[66:67]
	v_pk_mul_f32 v[66:67], v[60:61], v[58:59]
	v_add3_u32 v70, v64, v70, s91
	v_pk_fma_f32 v[66:67], v[56:57], v[62:63], v[66:67] neg_lo:[0,0,1] neg_hi:[0,0,1]
	v_pk_mul_f32 v[56:57], v[56:57], v[58:59]
	v_bfe_u32 v58, v65, 16, 1
	v_pk_fma_f32 v[56:57], v[60:61], v[62:63], v[56:57]
	v_bfe_u32 v60, v67, 16, 1
	v_bfe_u32 v61, v53, 16, 1
	v_add3_u32 v62, v53, v61, s91
	v_add3_u32 v61, v67, v60, s91
	v_bfe_u32 v60, v52, 16, 1
	v_bfe_u32 v59, v51, 16, 1
	v_bfe_u32 v63, v66, 16, 1
	v_add3_u32 v60, v52, v60, s91
	v_add3_u32 v59, v51, v59, s91
	v_add3_u32 v58, v65, v58, s91
	v_add3_u32 v63, v66, v63, s91
	v_lshrrev_b32_e32 v71, 16, v60
	v_lshrrev_b32_e32 v60, 16, v70
	v_lshrrev_b32_e32 v63, 16, v63
	v_and_or_b32 v60, v58, s33, v60
	v_and_or_b32 v58, v59, s33, v69
	v_and_or_b32 v59, v62, s33, v71
	v_mul_lo_u32 v62, v82, s88
	v_and_or_b32 v61, v61, s33, v63
	v_add3_u32 v62, 0, v62, v68
	ds_write_b128 v62, v[58:61]
	v_bfe_u32 v60, v57, 16, 1
	v_bfe_u32 v61, v49, 16, 1
	v_add3_u32 v63, v49, v61, s91
	v_add3_u32 v61, v57, v60, s91
	v_bfe_u32 v60, v48, 16, 1
	v_bfe_u32 v69, v56, 16, 1
	v_bfe_u32 v70, v46, 16, 1
	v_bfe_u32 v71, v54, 16, 1
	v_bfe_u32 v58, v55, 16, 1
	v_bfe_u32 v59, v47, 16, 1
	v_add3_u32 v71, v54, v71, s91
	v_add3_u32 v70, v46, v70, s91
	v_add3_u32 v69, v56, v69, s91
	v_add3_u32 v60, v48, v60, s91
	v_add3_u32 v59, v47, v59, s91
	v_add3_u32 v58, v55, v58, s91
	v_lshrrev_b32_e32 v72, 16, v60
	v_lshrrev_b32_e32 v69, 16, v69
	v_lshrrev_b32_e32 v70, 16, v70
	v_lshrrev_b32_e32 v60, 16, v71
	v_and_or_b32 v60, v58, s33, v60
	v_and_or_b32 v58, v59, s33, v70
	v_and_or_b32 v61, v61, s33, v69
	v_and_or_b32 v59, v63, s33, v72
	ds_write_b128 v62, v[58:61] offset:64
	s_and_saveexec_b64 s[4:5], s[22:23]
	s_cbranch_execz .LBB0_467
	v_readlane_b32 s21, v254, 8
	s_lshl_b32 s94, s15, 2
	s_nop 0
	v_mov_b32_e32 v58, s21
	ds_read_b64 v[58:59], v58
	s_mov_b32 s21, 0x4158000
	s_waitcnt lgkmcnt(0)
	v_readfirstlane_b32 s22, v58
	v_add_u32_e32 v58, s20, v82
	v_readfirstlane_b32 s23, v59
	v_ashrrev_i32_e32 v59, 31, v58
	v_lshlrev_b64 v[58:59], 10, v[58:59]
	v_lshl_add_u64 v[58:59], s[22:23], 0, v[58:59]
	v_lshl_add_u64 v[58:59], v[58:59], 0, s[94:95]
	v_lshl_add_u64 v[58:59], v[58:59], 0, v[0:1]
	s_mov_b64 s[22:23], 0x4158000
	v_lshl_add_u64 v[60:61], v[58:59], 0, s[22:23]
	v_add_co_u32_e32 v58, vcc, s21, v58
	s_nop 1
	v_addc_co_u32_e32 v59, vcc, 0, v59, vcc
	global_store_dwordx4 v[58:59], v[50:53], off
	global_store_dwordx4 v[60:61], v[64:67], off offset:16
	global_store_dwordx4 v[60:61], v[46:49], off offset:128
	global_store_dwordx4 v[60:61], v[54:57], off offset:144

.LBB0_469:
	s_or_b64 exec, exec, s[4:5]
	v_pk_mul_f32 v[56:57], v[50:51], v[50:51]
	v_pk_mul_f32 v[60:61], v[52:53], v[52:53]
	v_pk_fma_f32 v[56:57], v[46:47], v[46:47], v[56:57]
	v_pk_fma_f32 v[60:61], v[48:49], v[48:49], v[60:61]
	v_add_f32_e32 v55, v57, v56
	v_pk_mul_f32 v[62:63], v[58:59], v[58:59]
	v_add_f32_e32 v55, v60, v55
	v_pk_fma_f32 v[62:63], v[64:65], v[64:65], v[62:63]
	v_add_f32_e32 v55, v61, v55
	v_pk_mul_f32 v[66:67], v[72:73], v[72:73]
	v_add_f32_e32 v55, v62, v55
	v_pk_fma_f32 v[66:67], v[70:71], v[70:71], v[66:67]
	v_add_f32_e32 v55, v63, v55
	v_add_f32_e32 v55, v66, v55
	v_add_f32_e32 v55, v67, v55
	ds_bpermute_b32 v56, v5, v55
	v_max_i32_e32 v54, 0, v54
	s_nop 1
	v_lshl_or_b32 v191, v54, 5, v3
	v_or_b32_e32 v196, 4, v191
	v_ashrrev_i32_e32 v197, 31, v196
	v_lshlrev_b64 v[196:197], 2, v[196:197]
	v_lshl_add_u64 v[200:201], s[10:11], 0, v[196:197]
	global_load_dwordx4 v[202:205], v[200:201], off
	s_nop 1
	v_lshl_or_b32 v190, v54, 5, v3
	v_or_b32_e32 v186, 4, v190
	v_ashrrev_i32_e32 v187, 31, v186
	v_lshlrev_b64 v[186:187], 2, v[186:187]
	v_lshl_add_u64 v[188:189], s[8:9], 0, v[186:187]
	global_load_dwordx4 v[192:195], v[188:189], off
	s_nop 1
	v_lshl_or_b32 v162, v54, 5, v3
	v_ashrrev_i32_e32 v163, 31, v162
	v_lshlrev_b64 v[158:159], 2, v[162:163]
	v_lshl_add_u64 v[160:161], s[8:9], 0, v[158:159]
	global_load_dwordx4 v[164:167], v[160:161], off
	s_nop 1
	v_lshl_or_b32 v150, v54, 5, v3
	v_ashrrev_i32_e32 v151, 31, v150
	v_lshlrev_b64 v[148:149], 2, v[150:151]
	v_lshl_add_u64 v[152:153], s[10:11], 0, v[148:149]
	global_load_dwordx4 v[154:157], v[152:153], off
	v_lshl_or_b32 v76, v54, 5, v3
	v_ashrrev_i32_e32 v77, 31, v76
	s_waitcnt lgkmcnt(0)
	v_add_f32_e32 v55, v55, v56
	ds_bpermute_b32 v56, v106, v55
	s_waitcnt lgkmcnt(0)
	v_add_f32_e32 v55, v55, v56
	v_fmamk_f32 v55, v55, 0x3c800000, v219
	v_cmp_gt_f32_e32 vcc, s85, v55
	v_mul_f32_e32 v56, 0x4f800000, v55
	s_nop 0
	v_cndmask_b32_e32 v55, v55, v56, vcc
	v_sqrt_f32_e32 v56, v55
	s_nop 0
	v_add_u32_e32 v57, -1, v56
	v_fma_f32 v60, -v57, v56, v55
	v_cmp_ge_f32_e64 s[4:5], 0, v60
	v_add_u32_e32 v60, 1, v56
	s_nop 0
	v_cndmask_b32_e64 v57, v56, v57, s[4:5]
	v_fma_f32 v56, -v60, v56, v55
	v_cmp_lt_f32_e64 s[4:5], 0, v56
	s_nop 1
	v_cndmask_b32_e64 v56, v57, v60, s[4:5]
	v_mul_f32_e32 v57, 0x37800000, v56
	v_cndmask_b32_e32 v56, v56, v57, vcc
	v_cmp_class_f32_e32 vcc, v55, v221
	s_nop 1
	v_cndmask_b32_e32 v55, v56, v55, vcc
	v_div_scale_f32 v56, s[4:5], v55, v55, 1.0
	v_rcp_f32_e32 v57, v56
	v_readlane_b32 s4, v254, 15
	v_fma_f32 v60, -v56, v57, 1.0
	v_fmac_f32_e32 v57, v60, v57
	v_div_scale_f32 v60, vcc, 1.0, v55, 1.0
	v_mul_f32_e32 v61, v60, v57
	v_fma_f32 v62, -v56, v61, v60
	v_fmac_f32_e32 v61, v62, v57
	v_fma_f32 v56, -v56, v61, v60
	v_div_fmas_f32 v56, v56, v57, v61
	v_div_fixup_f32 v74, v56, v55, 1.0
	v_mov_b32_e32 v55, s4
	ds_read_b64 v[56:57], v55
	v_lshlrev_b64 v[54:55], 2, v[76:77]
	v_lshl_add_u64 v[80:81], s[10:11], 0, v[54:55]
	s_waitcnt vmcnt(0)
	s_nop 0
	v_mov_b32_e32 v84, v154
	v_mov_b32_e32 v85, v155
	v_mov_b32_e32 v86, v156
	v_mov_b32_e32 v87, v157
	s_nop 1
	v_pk_mul_f32 v[50:51], v[50:51], v[74:75] op_sel_hi:[1,0]
	s_waitcnt lgkmcnt(0)
	v_readfirstlane_b32 s4, v56
	v_readfirstlane_b32 s5, v57
	s_nop 1
	v_lshl_add_u64 v[206:207], s[4:5], 0, v[0:1]
	global_load_dwordx4 v[208:211], v[206:207], off offset:16
	s_nop 1
	v_lshl_add_u64 v[180:181], s[4:5], 0, v[0:1]
	global_load_dwordx4 v[182:185], v[180:181], off offset:144
	s_nop 1
	v_lshl_add_u64 v[174:175], s[4:5], 0, v[0:1]
	global_load_dwordx4 v[176:179], v[174:175], off
	s_nop 1
	v_lshl_add_u64 v[168:169], s[4:5], 0, v[0:1]
	global_load_dwordx4 v[170:173], v[168:169], off offset:128
	v_lshl_add_u64 v[56:57], s[8:9], 0, v[54:55]
	s_waitcnt vmcnt(1)
	s_nop 0
	v_mov_b32_e32 v54, v164
	v_mov_b32_e32 v55, v165
	v_mov_b32_e32 v56, v166
	v_mov_b32_e32 v57, v167
	s_nop 1
	v_lshl_add_u64 v[66:67], s[4:5], 0, v[0:1]
	s_waitcnt vmcnt(0)
	s_nop 0
	v_mov_b32_e32 v60, v170
	v_mov_b32_e32 v61, v171
	v_mov_b32_e32 v62, v172
	v_mov_b32_e32 v63, v173
	s_nop 1
	s_waitcnt vmcnt(1)
	s_nop 0
	v_mov_b32_e32 v88, v176
	v_mov_b32_e32 v89, v177
	v_mov_b32_e32 v90, v178
	v_mov_b32_e32 v91, v179
	s_nop 1
	v_pk_mul_f32 v[46:47], v[46:47], v[74:75] op_sel_hi:[1,0]
	v_pk_mul_f32 v[52:53], v[52:53], v[74:75] op_sel_hi:[1,0]
	v_pk_mul_f32 v[48:49], v[48:49], v[74:75] op_sel_hi:[1,0]
	v_pk_mul_f32 v[58:59], v[58:59], v[74:75] op_sel_hi:[1,0]
	s_movk_i32 s4, 0x7f
	v_cmp_lt_i32_e32 vcc, s4, v82
	s_waitcnt vmcnt(1) lgkmcnt(0)
	v_pk_mul_f32 v[60:61], v[60:61], v[50:51]
	v_pk_mul_f32 v[46:47], v[88:89], v[46:47]
	v_pk_mul_f32 v[50:51], v[84:85], v[60:61]
	v_pk_mul_f32 v[48:49], v[48:49], v[90:91]
	v_pk_fma_f32 v[50:51], v[54:55], v[46:47], v[50:51] neg_lo:[0,0,1] neg_hi:[0,0,1]
	v_pk_mul_f32 v[54:55], v[54:55], v[60:61]
	s_nop 0
	v_pk_fma_f32 v[46:47], v[84:85], v[46:47], v[54:55]
	v_pk_mul_f32 v[54:55], v[52:53], v[62:63]
	s_waitcnt vmcnt(2)
	s_nop 0
	v_mov_b32_e32 v60, v182
	v_mov_b32_e32 v61, v183
	v_mov_b32_e32 v62, v184
	v_mov_b32_e32 v63, v185
	s_nop 1
	v_pk_mul_f32 v[52:53], v[86:87], v[54:55]
	v_pk_mul_f32 v[54:55], v[56:57], v[54:55]
	v_pk_fma_f32 v[52:53], v[56:57], v[48:49], v[52:53] neg_lo:[0,0,1] neg_hi:[0,0,1]
	v_pk_fma_f32 v[48:49], v[86:87], v[48:49], v[54:55]
	v_or_b32_e32 v54, 4, v76
	v_ashrrev_i32_e32 v55, 31, v54
	v_lshlrev_b64 v[54:55], 2, v[54:55]
	v_lshl_add_u64 v[80:81], s[10:11], 0, v[54:55]
	v_lshl_add_u64 v[56:57], s[8:9], 0, v[54:55]
	s_waitcnt vmcnt(5)
	s_nop 0
	v_mov_b32_e32 v54, v192
	v_mov_b32_e32 v55, v193
	v_mov_b32_e32 v56, v194
	v_mov_b32_e32 v57, v195
	s_nop 1
	s_and_b64 s[8:9], s[6:7], vcc
	s_waitcnt vmcnt(5) lgkmcnt(0)
	v_pk_mul_f32 v[76:77], v[58:59], v[60:61]
	s_waitcnt vmcnt(6)
	s_nop 0
	v_mov_b32_e32 v58, v202
	v_mov_b32_e32 v59, v203
	v_mov_b32_e32 v60, v204
	v_mov_b32_e32 v61, v205
	s_nop 1
	v_pk_mul_f32 v[80:81], v[64:65], v[74:75] op_sel_hi:[1,0]
	s_waitcnt vmcnt(3)
	s_nop 0
	v_mov_b32_e32 v64, v208
	v_mov_b32_e32 v65, v209
	v_mov_b32_e32 v66, v210
	v_mov_b32_e32 v67, v211
	s_nop 1
	s_waitcnt vmcnt(3) lgkmcnt(0)
	v_pk_mul_f32 v[80:81], v[80:81], v[64:65]
	v_pk_mul_f32 v[64:65], v[58:59], v[76:77]
	s_nop 0
	v_pk_fma_f32 v[64:65], v[54:55], v[80:81], v[64:65] neg_lo:[0,0,1] neg_hi:[0,0,1]
	v_pk_mul_f32 v[54:55], v[54:55], v[76:77]
	v_bfe_u32 v69, v64, 16, 1
	v_pk_fma_f32 v[54:55], v[58:59], v[80:81], v[54:55]
	v_pk_mul_f32 v[58:59], v[72:73], v[74:75] op_sel_hi:[1,0]
	v_bfe_u32 v3, v65, 16, 1
	v_pk_mul_f32 v[58:59], v[58:59], v[62:63]
	v_pk_mul_f32 v[62:63], v[70:71], v[74:75] op_sel_hi:[1,0]
	v_add3_u32 v69, v64, v69, s91
	v_pk_mul_f32 v[62:63], v[62:63], v[66:67]
	v_pk_mul_f32 v[66:67], v[60:61], v[58:59]
	v_add3_u32 v3, v65, v3, s91
	v_pk_fma_f32 v[66:67], v[56:57], v[62:63], v[66:67] neg_lo:[0,0,1] neg_hi:[0,0,1]
	v_pk_mul_f32 v[56:57], v[56:57], v[58:59]
	v_bfe_u32 v58, v51, 16, 1
	v_pk_fma_f32 v[56:57], v[60:61], v[62:63], v[56:57]
	v_bfe_u32 v60, v53, 16, 1
	v_add3_u32 v62, v53, v60, s91
	v_bfe_u32 v60, v52, 16, 1
	v_bfe_u32 v61, v66, 16, 1
	v_bfe_u32 v63, v50, 16, 1
	v_add3_u32 v60, v52, v60, s91
	v_bfe_u32 v59, v67, 16, 1
	v_add3_u32 v63, v50, v63, s91
	v_add3_u32 v61, v66, v61, s91
	v_lshrrev_b32_e32 v70, 16, v60
	v_lshrrev_b32_e32 v60, 16, v69
	v_add3_u32 v59, v67, v59, s91
	v_add3_u32 v58, v51, v58, s91
	v_lshrrev_b32_e32 v61, 16, v61
	v_lshrrev_b32_e32 v63, 16, v63
	v_and_or_b32 v60, v3, s33, v60
	v_mul_lo_u32 v3, v82, s88
	v_and_or_b32 v58, v58, s33, v63
	v_and_or_b32 v61, v59, s33, v61
	v_and_or_b32 v59, v62, s33, v70
	v_add3_u32 v3, 0, v3, v68
	ds_write_b128 v3, v[58:61]
	v_bfe_u32 v60, v57, 16, 1
	v_bfe_u32 v61, v49, 16, 1
	v_add3_u32 v62, v49, v61, s91
	v_add3_u32 v61, v57, v60, s91
	v_bfe_u32 v60, v48, 16, 1
	v_bfe_u32 v63, v56, 16, 1
	v_bfe_u32 v68, v46, 16, 1
	v_bfe_u32 v69, v54, 16, 1
	v_bfe_u32 v58, v55, 16, 1
	v_bfe_u32 v59, v47, 16, 1
	v_add3_u32 v69, v54, v69, s91
	v_add3_u32 v68, v46, v68, s91
	v_add3_u32 v63, v56, v63, s91
	v_add3_u32 v60, v48, v60, s91
	v_add3_u32 v59, v47, v59, s91
	v_add3_u32 v58, v55, v58, s91
	v_lshrrev_b32_e32 v70, 16, v60
	v_lshrrev_b32_e32 v63, 16, v63
	v_lshrrev_b32_e32 v68, 16, v68
	v_lshrrev_b32_e32 v60, 16, v69
	v_and_or_b32 v60, v58, s33, v60
	v_and_or_b32 v58, v59, s33, v68
	v_and_or_b32 v61, v61, s33, v63
	v_and_or_b32 v59, v62, s33, v70
	ds_write_b128 v3, v[58:61] offset:64
	s_and_saveexec_b64 s[4:5], s[8:9]
	s_cbranch_execz .LBB0_471
	v_readlane_b32 s8, v254, 8
	s_lshl_b32 s94, s15, 2
	s_nop 0
	v_mov_b32_e32 v3, s8
	ds_read_b64 v[58:59], v3
	s_waitcnt lgkmcnt(0)
	v_readfirstlane_b32 s8, v58
	v_add_u32_e32 v58, s20, v82
	v_readfirstlane_b32 s9, v59
	v_ashrrev_i32_e32 v59, 31, v58
	v_lshlrev_b64 v[58:59], 10, v[58:59]
	v_lshl_add_u64 v[58:59], s[8:9], 0, v[58:59]
	v_lshl_add_u64 v[58:59], v[58:59], 0, s[94:95]
	v_lshl_add_u64 v[58:59], v[58:59], 0, v[0:1]
	s_mov_b64 s[8:9], 0x4158000
	v_lshl_add_u64 v[60:61], v[58:59], 0, s[8:9]
	s_mov_b32 s8, 0x4158000
	v_add_co_u32_e32 v58, vcc, s8, v58
	s_nop 1
	v_addc_co_u32_e32 v59, vcc, 0, v59, vcc
	global_store_dwordx4 v[58:59], v[50:53], off
	global_store_dwordx4 v[60:61], v[64:67], off offset:16
	global_store_dwordx4 v[60:61], v[46:49], off offset:128
	global_store_dwordx4 v[60:61], v[54:57], off offset:144

.LBB0_536:
	v_add_u32_e32 v28, s4, v5
	v_mad_i64_i32 v[6:7], s[4:5], s11, v28, 0
	v_lshl_add_u64 v[10:11], v[6:7], 1, v[2:3]
	v_mov_b32_e32 v14, s9
	global_load_dwordx4 v[6:9], v[10:11], off nt
	s_nop 0
	global_load_dwordx4 v[10:13], v[10:11], off offset:64 nt
	ds_read_b64 v[14:15], v14
	v_ashrrev_i32_e32 v29, 31, v28
	s_waitcnt lgkmcnt(0)
	v_readfirstlane_b32 s4, v14
	v_readfirstlane_b32 s5, v15
	s_add_u32 s4, s4, s6
	s_addc_u32 s5, s5, s7
	s_nop 1
	v_lshl_add_u64 v[126:127], s[4:5], 0, v[0:1]
	global_load_dwordx4 v[128:131], v[126:127], off offset:144
	s_nop 1
	v_lshl_add_u64 v[120:121], s[4:5], 0, v[0:1]
	global_load_dwordx4 v[122:125], v[120:121], off offset:16
	s_nop 1
	v_lshl_add_u64 v[114:115], s[4:5], 0, v[0:1]
	global_load_dwordx4 v[116:119], v[114:115], off
	v_lshl_add_u64 v[18:19], s[4:5], 0, v[0:1]
	global_load_dwordx4 v[14:17], v[18:19], off offset:128
	s_waitcnt vmcnt(0)
	v_lshlrev_b32_e32 v35, 16, v7
	v_lshlrev_b32_e32 v21, 16, v11
	v_lshlrev_b32_e32 v20, 16, v10
	v_and_b32_e32 v23, 0xffff0000, v11
	v_and_b32_e32 v22, 0xffff0000, v10
	v_and_b32_e32 v33, 0xffff0000, v13
	v_and_b32_e32 v32, 0xffff0000, v12
	v_lshlrev_b32_e32 v34, 16, v6
	v_and_b32_e32 v37, 0xffff0000, v7
	v_and_b32_e32 v36, 0xffff0000, v6
	v_mov_b32_e32 v6, v23
	v_mov_b32_e32 v7, v21
	s_waitcnt lgkmcnt(0)
	v_mov_b32_e32 v24, v14
	v_mov_b32_e32 v25, v16
	v_mov_b32_e32 v16, v15
	v_lshlrev_b32_e32 v15, 16, v13
	v_lshlrev_b32_e32 v14, 16, v12
	s_waitcnt vmcnt(1)
	s_nop 0
	v_mov_b32_e32 v10, v116
	v_mov_b32_e32 v11, v117
	v_mov_b32_e32 v12, v118
	v_mov_b32_e32 v13, v119
	s_nop 1
	v_pk_mul_f32 v[6:7], v[6:7], v[6:7]
	v_mov_b32_e32 v38, v37
	v_mov_b32_e32 v39, v35
	v_pk_fma_f32 v[38:39], v[38:39], v[38:39], v[6:7]
	v_and_b32_e32 v43, 0xffff0000, v9
	v_and_b32_e32 v42, 0xffff0000, v8
	v_mov_b32_e32 v44, v32
	v_mov_b32_e32 v45, v14
	v_pk_mul_f32 v[44:45], v[44:45], v[44:45]
	v_mov_b32_e32 v46, v42
	v_mov_b32_e32 v48, v43
	v_mul_f32_e32 v27, v36, v36
	v_fmac_f32_e32 v27, v22, v22
	s_waitcnt vmcnt(0) lgkmcnt(0)
	v_mov_b32_e32 v40, v10
	v_mov_b32_e32 v41, v12
	v_mov_b32_e32 v12, v11
	v_lshlrev_b32_e32 v11, 16, v9
	v_lshlrev_b32_e32 v10, 16, v8
	s_waitcnt vmcnt(2)
	s_nop 0
	v_mov_b32_e32 v6, v122
	v_mov_b32_e32 v7, v123
	v_mov_b32_e32 v8, v124
	v_mov_b32_e32 v9, v125
	s_nop 1
	v_mov_b32_e32 v47, v10
	v_pk_fma_f32 v[44:45], v[46:47], v[46:47], v[44:45]
	v_mov_b32_e32 v46, v33
	v_mov_b32_e32 v47, v15
	v_pk_mul_f32 v[46:47], v[46:47], v[46:47]
	v_mov_b32_e32 v49, v11
	v_pk_fma_f32 v[46:47], v[48:49], v[48:49], v[46:47]
	v_mul_f32_e32 v48, v34, v34
	v_fmac_f32_e32 v48, v20, v20
	v_add_f32_e32 v27, v48, v27
	v_add_f32_e32 v27, v39, v27
	v_add_f32_e32 v27, v38, v27
	v_add_f32_e32 v27, v45, v27
	v_add_f32_e32 v27, v44, v27
	v_add_f32_e32 v27, v47, v27
	v_add_f32_e32 v27, v46, v27
	ds_bpermute_b32 v38, v98, v27
	s_waitcnt lgkmcnt(0)
	v_add_f32_e32 v27, v27, v38
	ds_bpermute_b32 v38, v99, v27
	s_waitcnt lgkmcnt(0)
	v_add_f32_e32 v27, v27, v38
	v_fmamk_f32 v27, v27, 0x3c800000, v219
	v_cmp_gt_f32_e32 vcc, s85, v27
	v_mul_f32_e32 v38, 0x4f800000, v27
	s_nop 0
	v_cndmask_b32_e32 v27, v27, v38, vcc
	v_sqrt_f32_e32 v38, v27
	s_nop 0
	v_add_u32_e32 v39, -1, v38
	v_fma_f32 v44, -v39, v38, v27
	v_cmp_ge_f32_e64 s[4:5], 0, v44
	v_add_u32_e32 v44, 1, v38
	s_nop 0
	v_cndmask_b32_e64 v39, v38, v39, s[4:5]
	v_fma_f32 v38, -v44, v38, v27
	v_cmp_lt_f32_e64 s[4:5], 0, v38
	s_nop 1
	v_cndmask_b32_e64 v38, v39, v44, s[4:5]
	v_mul_f32_e32 v39, 0x37800000, v38
	v_cndmask_b32_e32 v38, v38, v39, vcc
	v_cmp_class_f32_e32 vcc, v27, v221
	s_nop 1
	v_cndmask_b32_e32 v27, v38, v27, vcc
	v_div_scale_f32 v38, s[4:5], v27, v27, s86
	v_rcp_f32_e32 v39, v38
	s_nop 0
	v_fma_f32 v44, -v38, v39, 1.0
	v_fmac_f32_e32 v39, v44, v39
	v_div_scale_f32 v44, vcc, s86, v27, s86
	v_mul_f32_e32 v45, v44, v39
	v_fma_f32 v46, -v38, v45, v44
	v_fmac_f32_e32 v45, v46, v39
	v_fma_f32 v38, -v38, v45, v44
	v_div_fmas_f32 v38, v38, v39, v45
	v_div_fixup_f32 v38, v38, v27, s86
	v_pk_mul_f32 v[36:37], v[38:39], v[36:37] op_sel_hi:[0,1]
	v_pk_mul_f32 v[12:13], v[12:13], v[36:37]
	v_pk_mul_f32 v[10:11], v[38:39], v[10:11] op_sel_hi:[0,1]
	v_pk_mul_f32 v[34:35], v[38:39], v[34:35] op_sel_hi:[0,1]
	v_pk_mul_f32 v[34:35], v[40:41], v[34:35]
	v_bfe_u32 v27, v13, 16, 1
	v_add3_u32 v13, v13, v27, s91
	v_pk_mul_f32 v[14:15], v[38:39], v[14:15] op_sel_hi:[0,1]
	s_waitcnt vmcnt(0)
	v_mov_b32_e32 v36, v6
	v_mov_b32_e32 v37, v8
	v_pk_mul_f32 v[10:11], v[36:37], v[10:11]
	v_pk_mul_f32 v[36:37], v[38:39], v[42:43] op_sel_hi:[0,1]
	v_mov_b32_e32 v8, v7
	v_pk_mul_f32 v[6:7], v[8:9], v[36:37]
	v_bfe_u32 v36, v12, 16, 1
	v_bfe_u32 v8, v7, 16, 1
	v_bfe_u32 v9, v6, 16, 1
	v_add3_u32 v12, v12, v36, s91
	v_add3_u32 v6, v6, v9, s91
	v_add3_u32 v7, v7, v8, s91
	v_bfe_u32 v8, v34, 16, 1
	v_bfe_u32 v9, v35, 16, 1
	v_bfe_u32 v27, v10, 16, 1
	v_bfe_u32 v36, v11, 16, 1
	v_add3_u32 v11, v11, v36, s91
	v_add3_u32 v10, v10, v27, s91
	v_add3_u32 v9, v35, v9, s91
	v_add3_u32 v8, v34, v8, s91
	v_lshrrev_b32_e32 v27, 16, v8
	v_lshrrev_b32_e32 v34, 16, v9
	v_lshrrev_b32_e32 v8, 16, v10
	v_lshrrev_b32_e32 v9, 16, v11
	v_pk_mul_f32 v[10:11], v[38:39], v[20:21] op_sel_hi:[0,1]
	v_pk_mul_f32 v[20:21], v[24:25], v[10:11]
	v_pk_mul_f32 v[10:11], v[38:39], v[22:23] op_sel_hi:[0,1]
	v_and_or_b32 v9, v7, s33, v9
	v_and_or_b32 v8, v6, s33, v8
	v_and_or_b32 v7, v13, s33, v34
	v_and_or_b32 v6, v12, s33, v27
	v_pk_mul_f32 v[16:17], v[16:17], v[10:11]
	s_waitcnt vmcnt(3)
	s_nop 0
	v_mov_b32_e32 v10, v128
	v_mov_b32_e32 v11, v129
	v_mov_b32_e32 v12, v130
	v_mov_b32_e32 v13, v131
	s_nop 1
	s_waitcnt vmcnt(0) lgkmcnt(0)
	v_mov_b32_e32 v18, v10
	v_mov_b32_e32 v19, v12
	v_pk_mul_f32 v[14:15], v[18:19], v[14:15]
	v_pk_mul_f32 v[18:19], v[38:39], v[32:33] op_sel_hi:[0,1]
	v_mov_b32_e32 v12, v11
	v_pk_mul_f32 v[10:11], v[18:19], v[12:13]
	v_bfe_u32 v18, v17, 16, 1
	v_bfe_u32 v12, v11, 16, 1
	v_bfe_u32 v13, v10, 16, 1
	v_bfe_u32 v19, v16, 16, 1
	v_add3_u32 v16, v16, v19, s91
	v_add3_u32 v17, v17, v18, s91
	v_add3_u32 v10, v10, v13, s91
	v_add3_u32 v11, v11, v12, s91
	v_bfe_u32 v12, v20, 16, 1
	v_bfe_u32 v13, v21, 16, 1
	v_bfe_u32 v18, v14, 16, 1
	v_bfe_u32 v19, v15, 16, 1
	v_add3_u32 v15, v15, v19, s91
	v_add3_u32 v14, v14, v18, s91
	v_add3_u32 v13, v21, v13, s91
	v_add3_u32 v12, v20, v12, s91
	v_lshrrev_b32_e32 v18, 16, v12
	v_lshrrev_b32_e32 v19, 16, v13
	v_lshrrev_b32_e32 v12, 16, v14
	v_lshrrev_b32_e32 v13, 16, v15
	v_and_or_b32 v13, v11, s33, v13
	v_and_or_b32 v12, v10, s33, v12
	v_and_or_b32 v11, v17, s33, v19
	v_and_or_b32 v10, v16, s33, v18
	ds_read_b128 v[14:17], v30
	ds_read_b128 v[18:21], v30 offset:64
	s_waitcnt lgkmcnt(1)
	v_mfma_f32_16x16x32_bf16 v[14:17], v[14:17], v[6:9], 0
	s_waitcnt lgkmcnt(0)
	v_mfma_f32_16x16x32_bf16 v[32:35], v[18:21], v[10:13], v[14:17]
	ds_read_b128 v[18:21], v30 offset:2368
	s_nop 4
	ds_read_b128 v[14:17], v30 offset:2304
	s_waitcnt lgkmcnt(0)
	v_mfma_f32_16x16x32_bf16 v[14:17], v[14:17], v[6:9], 0
	v_mfma_f32_16x16x32_bf16 v[36:39], v[18:21], v[10:13], v[14:17]
	ds_read_b128 v[18:21], v30 offset:4672
	s_nop 5
	ds_read_b128 v[14:17], v30 offset:4608
	s_waitcnt lgkmcnt(0)
	v_mfma_f32_16x16x32_bf16 v[14:17], v[14:17], v[6:9], 0
	v_mfma_f32_16x16x32_bf16 v[40:43], v[18:21], v[10:13], v[14:17]
	ds_read_b128 v[18:21], v30 offset:6976
	s_nop 5
	ds_read_b128 v[14:17], v30 offset:6912
	s_waitcnt lgkmcnt(0)
	v_mfma_f32_16x16x32_bf16 v[14:17], v[14:17], v[6:9], 0
	v_mfma_f32_16x16x32_bf16 v[50:53], v[18:21], v[10:13], v[14:17]
	ds_read_b128 v[18:21], v30 offset:9280
	s_nop 5
	ds_read_b128 v[14:17], v30 offset:9216
	s_waitcnt lgkmcnt(0)
	v_mfma_f32_16x16x32_bf16 v[14:17], v[14:17], v[6:9], 0
	v_mfma_f32_16x16x32_bf16 v[56:59], v[18:21], v[10:13], v[14:17]
	ds_read_b128 v[18:21], v30 offset:11584
	s_nop 5
	ds_read_b128 v[14:17], v30 offset:11520
	s_waitcnt lgkmcnt(0)
	v_mfma_f32_16x16x32_bf16 v[14:17], v[14:17], v[6:9], 0
	v_mfma_f32_16x16x32_bf16 v[66:69], v[18:21], v[10:13], v[14:17]
	ds_read_b128 v[18:21], v30 offset:13888
	s_nop 5
	ds_read_b128 v[14:17], v30 offset:13824
	s_waitcnt lgkmcnt(0)
	v_mfma_f32_16x16x32_bf16 v[14:17], v[14:17], v[6:9], 0
	v_mfma_f32_16x16x32_bf16 v[72:75], v[18:21], v[10:13], v[14:17]
	ds_read_b128 v[18:21], v30 offset:16192
	s_nop 5
	ds_read_b128 v[14:17], v30 offset:16128
	s_waitcnt lgkmcnt(0)
	v_mfma_f32_16x16x32_bf16 v[14:17], v[14:17], v[6:9], 0
	v_mfma_f32_16x16x32_bf16 v[76:79], v[18:21], v[10:13], v[14:17]
	ds_read_b128 v[18:21], v30 offset:18496
	s_nop 5
	ds_read_b128 v[14:17], v30 offset:18432
	s_waitcnt lgkmcnt(0)
	v_mfma_f32_16x16x32_bf16 v[14:17], v[14:17], v[6:9], 0
	v_mfma_f32_16x16x32_bf16 v[84:87], v[18:21], v[10:13], v[14:17]
	ds_read_b128 v[18:21], v30 offset:20800
	s_nop 5
	ds_read_b128 v[14:17], v30 offset:20736
	s_waitcnt lgkmcnt(0)
	v_mfma_f32_16x16x32_bf16 v[14:17], v[14:17], v[6:9], 0
	v_mfma_f32_16x16x32_bf16 v[88:91], v[18:21], v[10:13], v[14:17]
	ds_read_b128 v[18:21], v30 offset:23104
	s_nop 5
	ds_read_b128 v[14:17], v30 offset:23040
	s_waitcnt lgkmcnt(0)
	v_mfma_f32_16x16x32_bf16 v[14:17], v[14:17], v[6:9], 0
	v_mfma_f32_16x16x32_bf16 v[92:95], v[18:21], v[10:13], v[14:17]
	ds_read_b128 v[18:21], v30 offset:25408
	s_nop 5
	ds_read_b128 v[14:17], v30 offset:25344
	s_waitcnt lgkmcnt(0)
	v_mfma_f32_16x16x32_bf16 v[14:17], v[14:17], v[6:9], 0
	v_mfma_f32_16x16x32_bf16 v[102:105], v[18:21], v[10:13], v[14:17]
	ds_read_b128 v[18:21], v30 offset:27712
	s_nop 5
	ds_read_b128 v[14:17], v30 offset:27648
	s_waitcnt lgkmcnt(0)
	v_mfma_f32_16x16x32_bf16 v[14:17], v[14:17], v[6:9], 0
	v_mfma_f32_16x16x32_bf16 v[22:25], v[18:21], v[10:13], v[14:17]
	ds_read_b128 v[18:21], v30 offset:30016
	s_nop 5
	ds_read_b128 v[14:17], v30 offset:29952
	s_waitcnt lgkmcnt(0)
	v_mfma_f32_16x16x32_bf16 v[14:17], v[14:17], v[6:9], 0
	ds_read_b128 v[44:47], v30 offset:32320
	v_mfma_f32_16x16x32_bf16 v[18:21], v[18:21], v[10:13], v[14:17]
	s_nop 5
	ds_read_b128 v[14:17], v30 offset:32256
	s_waitcnt lgkmcnt(0)
	v_mfma_f32_16x16x32_bf16 v[14:17], v[14:17], v[6:9], 0
	v_mfma_f32_16x16x32_bf16 v[14:17], v[44:47], v[10:13], v[14:17]
	ds_read_b128 v[44:47], v30 offset:34560
	s_waitcnt lgkmcnt(0)
	v_mfma_f32_16x16x32_bf16 v[6:9], v[44:47], v[6:9], 0
	ds_read_b128 v[44:47], v30 offset:34624
	s_waitcnt lgkmcnt(0)
	v_mfma_f32_16x16x32_bf16 v[6:9], v[44:47], v[10:13], v[6:9]
	v_max3_f32 v10, v32, s89, v33
	v_max3_f32 v10, v10, v34, v35
	v_max3_f32 v10, v10, v36, v37
	v_max3_f32 v10, v10, v38, v39
	v_max3_f32 v10, v10, v40, v41
	v_max3_f32 v10, v10, v42, v43
	v_max3_f32 v10, v10, v50, v51
	v_max3_f32 v10, v10, v52, v53
	v_max3_f32 v10, v10, v56, v57
	v_max3_f32 v10, v10, v58, v59
	v_max3_f32 v10, v10, v66, v67
	v_max3_f32 v10, v10, v68, v69
	v_max3_f32 v10, v10, v72, v73
	v_max3_f32 v10, v10, v74, v75
	v_max3_f32 v10, v10, v76, v77
	v_max3_f32 v10, v10, v78, v79
	v_max3_f32 v10, v10, v84, v85
	v_max3_f32 v10, v10, v86, v87
	v_max3_f32 v10, v10, v88, v89
	v_max3_f32 v10, v10, v90, v91
	v_max3_f32 v10, v10, v92, v93
	v_max3_f32 v10, v10, v94, v95
	v_max3_f32 v10, v10, v102, v103
	v_max3_f32 v10, v10, v104, v105
	v_max3_f32 v10, v10, v22, v23
	v_max3_f32 v10, v10, v24, v25
	v_max3_f32 v10, v10, v18, v19
	v_max3_f32 v10, v10, v20, v21
	v_max3_f32 v10, v10, v14, v15
	v_max3_f32 v10, v10, v16, v17
	v_max3_f32 v10, v10, v6, v7
	v_max3_f32 v10, v10, v8, v9
	ds_bpermute_b32 v11, v98, v10
	s_waitcnt lgkmcnt(0)
	v_max_f32_e32 v11, v11, v11
	v_max_f32_e32 v10, v10, v11
	ds_bpermute_b32 v11, v99, v10
	s_waitcnt lgkmcnt(0)
	v_max_f32_e32 v11, v11, v11
	v_max_f32_e32 v65, v10, v11
	v_sub_f32_e32 v11, v33, v65
	v_mul_f32_e32 v11, 0x3fb8aa3b, v11
	v_exp_f32_e32 v81, v11
	v_sub_f32_e32 v11, v34, v65
	v_mul_f32_e32 v11, 0x3fb8aa3b, v11
	v_exp_f32_e32 v82, v11
	v_sub_f32_e32 v11, v35, v65
	v_mul_f32_e32 v11, 0x3fb8aa3b, v11
	v_exp_f32_e32 v96, v11
	v_sub_f32_e32 v11, v36, v65
	v_mul_f32_e32 v11, 0x3fb8aa3b, v11
	v_exp_f32_e32 v97, v11
	v_sub_f32_e32 v11, v37, v65
	v_mul_f32_e32 v11, 0x3fb8aa3b, v11
	v_exp_f32_e32 v101, v11
	v_sub_f32_e32 v11, v38, v65
	v_mul_f32_e32 v11, 0x3fb8aa3b, v11
	v_exp_f32_e32 v106, v11
	v_sub_f32_e32 v11, v39, v65
	v_mul_f32_e32 v11, 0x3fb8aa3b, v11
	v_exp_f32_e32 v107, v11
	v_sub_f32_e32 v11, v40, v65
	v_mul_f32_e32 v11, 0x3fb8aa3b, v11
	v_exp_f32_e32 v33, v11
	v_sub_f32_e32 v11, v41, v65
	v_mul_f32_e32 v11, 0x3fb8aa3b, v11
	v_exp_f32_e32 v45, v11
	v_sub_f32_e32 v11, v42, v65
	v_mul_f32_e32 v11, 0x3fb8aa3b, v11
	v_exp_f32_e32 v38, v11
	v_sub_f32_e32 v11, v43, v65
	v_mul_f32_e32 v11, 0x3fb8aa3b, v11
	v_exp_f32_e32 v54, v11
	v_sub_f32_e32 v11, v50, v65
	v_mul_f32_e32 v11, 0x3fb8aa3b, v11
	v_exp_f32_e32 v49, v11
	v_sub_f32_e32 v11, v51, v65
	v_mul_f32_e32 v11, 0x3fb8aa3b, v11
	v_exp_f32_e32 v64, v11
	v_sub_f32_e32 v11, v52, v65
	v_mul_f32_e32 v11, 0x3fb8aa3b, v11
	v_exp_f32_e32 v61, v11
	v_sub_f32_e32 v11, v53, v65
	v_mul_f32_e32 v11, 0x3fb8aa3b, v11
	v_exp_f32_e32 v71, v11
	v_sub_f32_e32 v11, v56, v65
	v_mul_f32_e32 v11, 0x3fb8aa3b, v11
	v_sub_f32_e32 v10, v32, v65
	v_exp_f32_e32 v32, v11
	v_sub_f32_e32 v11, v57, v65
	v_mul_f32_e32 v11, 0x3fb8aa3b, v11
	v_exp_f32_e32 v43, v11
	v_sub_f32_e32 v11, v58, v65
	v_mul_f32_e32 v11, 0x3fb8aa3b, v11
	v_exp_f32_e32 v37, v11
	v_sub_f32_e32 v11, v59, v65
	v_mul_f32_e32 v11, 0x3fb8aa3b, v11
	v_exp_f32_e32 v53, v11
	v_sub_f32_e32 v11, v66, v65
	v_mul_f32_e32 v11, 0x3fb8aa3b, v11
	v_exp_f32_e32 v48, v11
	v_sub_f32_e32 v11, v67, v65
	v_mul_f32_e32 v11, 0x3fb8aa3b, v11
	v_exp_f32_e32 v63, v11
	v_sub_f32_e32 v11, v68, v65
	v_mul_f32_e32 v11, 0x3fb8aa3b, v11
	v_exp_f32_e32 v59, v11
	v_sub_f32_e32 v11, v69, v65
	v_mul_f32_e32 v11, 0x3fb8aa3b, v11
	v_exp_f32_e32 v70, v11
	v_sub_f32_e32 v11, v72, v65
	v_mul_f32_e32 v11, 0x3fb8aa3b, v11
	v_mul_f32_e32 v10, 0x3fb8aa3b, v10
	v_exp_f32_e32 v27, v11
	v_sub_f32_e32 v11, v73, v65
	v_exp_f32_e32 v80, v10
	v_mul_f32_e32 v11, 0x3fb8aa3b, v11
	v_exp_f32_e32 v42, v11
	v_sub_f32_e32 v11, v74, v65
	v_mul_f32_e32 v11, 0x3fb8aa3b, v11
	v_exp_f32_e32 v36, v11
	v_sub_f32_e32 v11, v75, v65
	v_add_f32_e32 v10, 0, v80
	v_mul_f32_e32 v11, 0x3fb8aa3b, v11
	v_add_f32_e32 v10, v81, v10
	v_exp_f32_e32 v52, v11
	v_sub_f32_e32 v11, v76, v65
	v_add_f32_e32 v10, v82, v10
	v_mul_f32_e32 v11, 0x3fb8aa3b, v11
	v_add_f32_e32 v10, v96, v10
	v_exp_f32_e32 v47, v11
	v_sub_f32_e32 v11, v77, v65
	v_add_f32_e32 v10, v97, v10
	v_mul_f32_e32 v11, 0x3fb8aa3b, v11
	v_add_f32_e32 v10, v101, v10
	v_exp_f32_e32 v62, v11
	v_sub_f32_e32 v11, v78, v65
	v_add_f32_e32 v10, v106, v10
	v_mul_f32_e32 v11, 0x3fb8aa3b, v11
	v_add_f32_e32 v10, v107, v10
	v_exp_f32_e32 v57, v11
	v_sub_f32_e32 v11, v79, v65
	v_add_f32_e32 v10, v33, v10
	v_mul_f32_e32 v11, 0x3fb8aa3b, v11
	v_add_f32_e32 v10, v45, v10
	v_exp_f32_e32 v69, v11
	v_sub_f32_e32 v11, v84, v65
	v_add_f32_e32 v10, v38, v10
	v_mul_f32_e32 v11, 0x3fb8aa3b, v11
	v_add_f32_e32 v10, v54, v10
	v_exp_f32_e32 v13, v11
	v_sub_f32_e32 v11, v85, v65
	v_add_f32_e32 v10, v49, v10
	v_mul_f32_e32 v11, 0x3fb8aa3b, v11
	v_add_f32_e32 v10, v64, v10
	v_exp_f32_e32 v41, v11
	v_sub_f32_e32 v11, v86, v65
	v_add_f32_e32 v10, v61, v10
	v_mul_f32_e32 v11, 0x3fb8aa3b, v11
	v_add_f32_e32 v10, v71, v10
	v_exp_f32_e32 v35, v11
	v_sub_f32_e32 v11, v87, v65
	v_add_f32_e32 v10, v32, v10
	v_mul_f32_e32 v11, 0x3fb8aa3b, v11
	v_add_f32_e32 v10, v43, v10
	v_exp_f32_e32 v51, v11
	v_sub_f32_e32 v11, v88, v65
	v_add_f32_e32 v10, v37, v10
	v_mul_f32_e32 v11, 0x3fb8aa3b, v11
	v_add_f32_e32 v10, v53, v10
	v_exp_f32_e32 v46, v11
	v_sub_f32_e32 v11, v89, v65
	v_add_f32_e32 v10, v48, v10
	v_mul_f32_e32 v11, 0x3fb8aa3b, v11
	v_add_f32_e32 v10, v63, v10
	v_exp_f32_e32 v60, v11
	v_sub_f32_e32 v11, v90, v65
	v_add_f32_e32 v10, v59, v10
	v_mul_f32_e32 v11, 0x3fb8aa3b, v11
	v_add_f32_e32 v10, v70, v10
	v_exp_f32_e32 v56, v11
	v_sub_f32_e32 v11, v91, v65
	v_add_f32_e32 v10, v27, v10
	v_mul_f32_e32 v11, 0x3fb8aa3b, v11
	v_add_f32_e32 v10, v42, v10
	v_exp_f32_e32 v68, v11
	v_sub_f32_e32 v11, v92, v65
	v_add_f32_e32 v10, v36, v10
	v_mul_f32_e32 v11, 0x3fb8aa3b, v11
	v_add_f32_e32 v10, v52, v10
	v_exp_f32_e32 v12, v11
	v_sub_f32_e32 v11, v93, v65
	v_add_f32_e32 v10, v47, v10
	v_mul_f32_e32 v11, 0x3fb8aa3b, v11
	v_add_f32_e32 v10, v62, v10
	v_exp_f32_e32 v40, v11
	v_sub_f32_e32 v11, v94, v65
	v_add_f32_e32 v10, v57, v10
	v_mul_f32_e32 v11, 0x3fb8aa3b, v11
	v_add_f32_e32 v10, v69, v10
	v_exp_f32_e32 v34, v11
	v_sub_f32_e32 v11, v95, v65
	v_add_f32_e32 v10, v13, v10
	v_mul_f32_e32 v11, 0x3fb8aa3b, v11
	v_add_f32_e32 v10, v41, v10
	v_exp_f32_e32 v50, v11
	v_sub_f32_e32 v11, v102, v65
	v_add_f32_e32 v10, v35, v10
	v_mul_f32_e32 v11, 0x3fb8aa3b, v11
	v_add_f32_e32 v10, v51, v10
	v_exp_f32_e32 v44, v11
	v_sub_f32_e32 v11, v103, v65
	v_add_f32_e32 v10, v46, v10
	v_mul_f32_e32 v11, 0x3fb8aa3b, v11
	v_add_f32_e32 v10, v60, v10
	v_exp_f32_e32 v58, v11
	v_sub_f32_e32 v11, v104, v65
	v_add_f32_e32 v10, v56, v10
	v_mul_f32_e32 v11, 0x3fb8aa3b, v11
	v_add_f32_e32 v10, v68, v10
	v_exp_f32_e32 v55, v11
	v_sub_f32_e32 v11, v105, v65
	v_add_f32_e32 v10, v12, v10
	v_mul_f32_e32 v11, 0x3fb8aa3b, v11
	v_add_f32_e32 v10, v40, v10
	v_exp_f32_e32 v67, v11
	v_sub_f32_e32 v11, v22, v65
	v_sub_f32_e32 v22, v23, v65
	v_add_f32_e32 v10, v34, v10
	v_mul_f32_e32 v22, 0x3fb8aa3b, v22
	v_add_f32_e32 v10, v50, v10
	v_mul_f32_e32 v11, 0x3fb8aa3b, v11
	v_exp_f32_e32 v39, v22
	v_sub_f32_e32 v22, v24, v65
	v_add_f32_e32 v10, v44, v10
	v_exp_f32_e32 v11, v11
	v_mul_f32_e32 v22, 0x3fb8aa3b, v22
	v_add_f32_e32 v10, v58, v10
	v_exp_f32_e32 v23, v22
	v_sub_f32_e32 v22, v25, v65
	v_sub_f32_e32 v19, v19, v65
	v_add_f32_e32 v10, v55, v10
	v_mul_f32_e32 v22, 0x3fb8aa3b, v22
	v_sub_f32_e32 v18, v18, v65
	v_mul_f32_e32 v19, 0x3fb8aa3b, v19
	v_add_f32_e32 v10, v67, v10
	v_exp_f32_e32 v24, v22
	v_mul_f32_e32 v18, 0x3fb8aa3b, v18
	v_exp_f32_e32 v25, v19
	v_sub_f32_e32 v19, v20, v65
	v_add_f32_e32 v10, v11, v10
	v_exp_f32_e32 v18, v18
	v_mul_f32_e32 v19, 0x3fb8aa3b, v19
	v_add_f32_e32 v10, v39, v10
	v_exp_f32_e32 v20, v19
	v_sub_f32_e32 v19, v21, v65
	v_add_f32_e32 v10, v23, v10
	v_mul_f32_e32 v19, 0x3fb8aa3b, v19
	v_add_f32_e32 v10, v24, v10
	v_exp_f32_e32 v66, v19
	v_add_f32_e32 v10, v18, v10
	v_add_f32_e32 v10, v25, v10
	v_add_f32_e32 v10, v20, v10
	v_add_f32_e32 v19, v66, v10
	v_sub_f32_e32 v10, v14, v65
	v_mul_f32_e32 v10, 0x3fb8aa3b, v10
	v_sub_f32_e32 v15, v15, v65
	v_exp_f32_e32 v10, v10
	v_mul_f32_e32 v15, 0x3fb8aa3b, v15
	v_exp_f32_e32 v15, v15
	v_sub_f32_e32 v17, v17, v65
	v_add_f32_e32 v14, v10, v19
	v_mul_f32_e32 v17, 0x3fb8aa3b, v17
	v_add_f32_e32 v19, v15, v14
	v_sub_f32_e32 v14, v16, v65
	v_mul_f32_e32 v14, 0x3fb8aa3b, v14
	v_exp_f32_e32 v14, v14
	v_exp_f32_e32 v17, v17
	v_sub_f32_e32 v6, v6, v65
	v_mul_f32_e32 v6, 0x3fb8aa3b, v6
	v_add_f32_e32 v16, v14, v19
	v_add_f32_e32 v19, v17, v16
	v_exp_f32_e32 v16, v6
	v_sub_f32_e32 v7, v7, v65
	v_mul_f32_e32 v7, 0x3fb8aa3b, v7
	v_exp_f32_e32 v21, v7
	v_sub_f32_e32 v7, v8, v65
	v_mul_f32_e32 v7, 0x3fb8aa3b, v7
	v_add_f32_e32 v6, v16, v19
	v_exp_f32_e32 v19, v7
	v_sub_f32_e32 v7, v9, v65
	v_mul_f32_e32 v7, 0x3fb8aa3b, v7
	v_exp_f32_e32 v65, v7
	v_add_f32_e32 v6, v21, v6
	v_add_f32_e32 v6, v19, v6
	v_bfe_u32 v8, v96, 16, 1
	v_add_f32_e32 v6, v65, v6
	ds_bpermute_b32 v7, v98, v6
	v_bfe_u32 v9, v81, 16, 1
	v_add3_u32 v72, v81, v9, s91
	v_add3_u32 v73, v96, v8, s91
	v_bfe_u32 v8, v80, 16, 1
	s_waitcnt lgkmcnt(0)
	v_add_f32_e32 v6, v6, v7
	ds_bpermute_b32 v7, v99, v6
	v_bfe_u32 v9, v82, 16, 1
	v_bfe_u32 v74, v97, 16, 1
	v_bfe_u32 v75, v106, 16, 1
	v_add3_u32 v75, v106, v75, s91
	s_waitcnt lgkmcnt(0)
	v_add_f32_e32 v22, v6, v7
	v_bfe_u32 v6, v107, 16, 1
	v_bfe_u32 v7, v101, 16, 1
	v_add3_u32 v74, v97, v74, s91
	v_add3_u32 v9, v82, v9, s91
	v_add3_u32 v8, v80, v8, s91
	v_add3_u32 v7, v101, v7, s91
	v_add3_u32 v6, v107, v6, s91
	v_lshrrev_b32_e32 v76, 16, v8
	v_lshrrev_b32_e32 v77, 16, v9
	v_lshrrev_b32_e32 v8, 16, v74
	v_lshrrev_b32_e32 v9, 16, v75
	v_add_u32_e32 v82, 0x9000, v31
	v_add_u32_e32 v96, 0xb000, v31
	v_add_u32_e32 v97, 0xd000, v31
	v_add_u32_e32 v101, 0xf000, v31
	v_and_or_b32 v9, v6, s33, v9
	v_and_or_b32 v8, v7, s33, v8
	v_and_or_b32 v7, v73, s33, v77
	v_and_or_b32 v6, v72, s33, v76
	ds_read2_b64 v[72:75], v82 offset1:4
	ds_read2_b64 v[76:79], v96 offset0:32 offset1:36
	ds_read2_b64 v[84:87], v97 offset0:64 offset1:68
	ds_read2_b64 v[88:91], v101 offset0:96 offset1:100
	ds_read2_b64 v[92:95], v82 offset0:8 offset1:12
	s_waitcnt lgkmcnt(4)
	v_mfma_f32_16x16x32_bf16 v[72:75], v[72:75], v[6:9], 0
	v_bfe_u32 v80, v71, 16, 1
	v_bfe_u32 v81, v64, 16, 1
	v_add3_u32 v64, v64, v81, s91
	s_waitcnt lgkmcnt(3)
	v_mfma_f32_16x16x32_bf16 v[76:79], v[76:79], v[6:9], 0
	v_add3_u32 v71, v71, v80, s91
	v_bfe_u32 v80, v33, 16, 1
	v_bfe_u32 v81, v38, 16, 1
	s_waitcnt lgkmcnt(2)
	v_mfma_f32_16x16x32_bf16 v[84:87], v[84:87], v[6:9], 0
	v_add3_u32 v38, v38, v81, s91
	v_add3_u32 v33, v33, v80, s91
	v_lshrrev_b32_e32 v33, 16, v33
	s_waitcnt lgkmcnt(1)
	v_mfma_f32_16x16x32_bf16 v[6:9], v[88:91], v[6:9], 0
	v_bfe_u32 v88, v54, 16, 1
	v_bfe_u32 v89, v45, 16, 1
	v_add3_u32 v45, v45, v89, s91
	v_add3_u32 v54, v54, v88, s91
	v_bfe_u32 v88, v49, 16, 1
	v_bfe_u32 v89, v61, 16, 1
	v_add3_u32 v61, v61, v89, s91
	v_add3_u32 v49, v49, v88, s91
	v_lshrrev_b32_e32 v38, 16, v38
	v_lshrrev_b32_e32 v49, 16, v49
	v_lshrrev_b32_e32 v61, 16, v61
	v_and_or_b32 v91, v71, s33, v61
	v_and_or_b32 v90, v64, s33, v49
	v_and_or_b32 v89, v54, s33, v38
	v_and_or_b32 v88, v45, s33, v33
	v_bfe_u32 v45, v53, 16, 1
	v_bfe_u32 v49, v43, 16, 1
	s_waitcnt lgkmcnt(0)
	v_mfma_f32_16x16x32_bf16 v[72:75], v[92:95], v[88:91], v[72:75]
	ds_read2_b64 v[92:95], v96 offset0:40 offset1:44
	v_add3_u32 v43, v43, v49, s91
	v_add3_u32 v45, v53, v45, s91
	s_waitcnt lgkmcnt(0)
	v_mfma_f32_16x16x32_bf16 v[76:79], v[92:95], v[88:91], v[76:79]
	ds_read2_b64 v[92:95], v97 offset0:72 offset1:76
	v_bfe_u32 v49, v32, 16, 1
	v_bfe_u32 v53, v37, 16, 1
	s_waitcnt lgkmcnt(0)
	v_mfma_f32_16x16x32_bf16 v[84:87], v[92:95], v[88:91], v[84:87]
	ds_read2_b64 v[92:95], v101 offset0:104 offset1:108
	v_bfe_u32 v54, v48, 16, 1
	s_waitcnt lgkmcnt(0)
	v_mfma_f32_16x16x32_bf16 v[6:9], v[92:95], v[88:91], v[6:9]
	ds_read2_b64 v[92:95], v82 offset0:16 offset1:20
	v_bfe_u32 v61, v59, 16, 1
	v_bfe_u32 v33, v70, 16, 1
	v_bfe_u32 v38, v63, 16, 1
	v_add3_u32 v59, v59, v61, s91
	v_add3_u32 v48, v48, v54, s91
	v_add3_u32 v37, v37, v53, s91
	v_add3_u32 v32, v32, v49, s91
	v_add3_u32 v38, v63, v38, s91
	v_add3_u32 v33, v70, v33, s91
	v_lshrrev_b32_e32 v32, 16, v32
	v_lshrrev_b32_e32 v37, 16, v37
	v_lshrrev_b32_e32 v48, 16, v48
	v_lshrrev_b32_e32 v49, 16, v59
	v_and_or_b32 v91, v33, s33, v49
	v_and_or_b32 v90, v38, s33, v48
	v_and_or_b32 v89, v45, s33, v37
	v_and_or_b32 v88, v43, s33, v32
	v_bfe_u32 v38, v42, 16, 1
	v_add3_u32 v38, v42, v38, s91
	s_waitcnt lgkmcnt(0)
	v_mfma_f32_16x16x32_bf16 v[70:73], v[92:95], v[88:91], v[72:75]
	ds_read2_b64 v[92:95], v96 offset0:48 offset1:52
	v_bfe_u32 v42, v27, 16, 1
	v_bfe_u32 v43, v36, 16, 1
	s_waitcnt lgkmcnt(0)
	v_mfma_f32_16x16x32_bf16 v[74:77], v[92:95], v[88:91], v[76:79]
	s_nop 2
	ds_read2_b64 v[78:81], v97 offset0:80 offset1:84
	v_bfe_u32 v45, v47, 16, 1
	v_bfe_u32 v48, v57, 16, 1
	s_waitcnt lgkmcnt(0)
	v_mfma_f32_16x16x32_bf16 v[78:81], v[78:81], v[88:91], v[84:87]
	s_nop 2
	ds_read2_b64 v[84:87], v101 offset0:112 offset1:116
	v_bfe_u32 v32, v69, 16, 1
	s_waitcnt lgkmcnt(0)
	v_mfma_f32_16x16x32_bf16 v[6:9], v[84:87], v[88:91], v[6:9]
	ds_read2_b64 v[88:91], v82 offset0:24 offset1:28
	v_bfe_u32 v33, v62, 16, 1
	v_bfe_u32 v37, v52, 16, 1
	v_add3_u32 v48, v57, v48, s91
	v_add3_u32 v45, v47, v45, s91
	v_add3_u32 v36, v36, v43, s91
	v_add3_u32 v27, v27, v42, s91
	v_add3_u32 v37, v52, v37, s91
	v_add3_u32 v33, v62, v33, s91
	v_add3_u32 v32, v69, v32, s91
	v_lshrrev_b32_e32 v27, 16, v27
	v_lshrrev_b32_e32 v36, 16, v36
	v_lshrrev_b32_e32 v42, 16, v45
	v_lshrrev_b32_e32 v43, 16, v48
	v_and_or_b32 v87, v32, s33, v43
	v_and_or_b32 v86, v33, s33, v42
	v_and_or_b32 v85, v37, s33, v36
	v_and_or_b32 v84, v38, s33, v27
	v_bfe_u32 v32, v60, 16, 1
	v_add3_u32 v32, v60, v32, s91
	s_waitcnt lgkmcnt(0)
	v_mfma_f32_16x16x32_bf16 v[70:73], v[88:91], v[84:87], v[70:73]
	ds_read2_b64 v[88:91], v96 offset0:56 offset1:60
	v_bfe_u32 v36, v41, 16, 1
	v_add3_u32 v36, v41, v36, s91
	s_waitcnt lgkmcnt(0)
	v_mfma_f32_16x16x32_bf16 v[74:77], v[88:91], v[84:87], v[74:77]
	ds_read2_b64 v[88:91], v97 offset0:88 offset1:92
	v_bfe_u32 v37, v13, 16, 1
	v_bfe_u32 v38, v35, 16, 1
	s_waitcnt lgkmcnt(0)
	v_mfma_f32_16x16x32_bf16 v[78:81], v[88:91], v[84:87], v[78:81]
	ds_read2_b64 v[88:91], v101 offset0:120 offset1:124
	ds_read2_b64 v[60:63], v82 offset0:32 offset1:36
	v_bfe_u32 v41, v46, 16, 1
	v_bfe_u32 v42, v56, 16, 1
	v_bfe_u32 v27, v68, 16, 1
	v_bfe_u32 v33, v51, 16, 1
	v_add3_u32 v42, v56, v42, s91
	v_add3_u32 v41, v46, v41, s91
	v_add3_u32 v35, v35, v38, s91
	v_add3_u32 v13, v13, v37, s91
	v_add3_u32 v33, v51, v33, s91
	v_add3_u32 v27, v68, v27, s91
	v_lshrrev_b32_e32 v13, 16, v13
	v_lshrrev_b32_e32 v35, 16, v35
	v_lshrrev_b32_e32 v37, 16, v41
	v_lshrrev_b32_e32 v38, 16, v42
	v_and_or_b32 v49, v27, s33, v38
	v_and_or_b32 v48, v32, s33, v37
	v_and_or_b32 v47, v33, s33, v35
	v_and_or_b32 v46, v36, s33, v13
	s_waitcnt lgkmcnt(1)
	v_mfma_f32_16x16x32_bf16 v[6:9], v[88:91], v[84:87], v[6:9]
	v_bfe_u32 v32, v50, 16, 1
	v_bfe_u32 v33, v40, 16, 1
	v_bfe_u32 v37, v44, 16, 1
	s_waitcnt lgkmcnt(0)
	v_mfma_f32_16x16x32_bf16 v[60:63], v[60:63], v[46:49], v[70:73]
	v_bfe_u32 v38, v55, 16, 1
	v_add3_u32 v36, v40, v33, s91
	v_add3_u32 v32, v50, v32, s91
	ds_read2_b64 v[68:71], v96 offset0:64 offset1:68
	s_waitcnt lgkmcnt(0)
	v_mfma_f32_16x16x32_bf16 v[68:71], v[68:71], v[46:49], v[74:77]
	s_nop 2
	ds_read2_b64 v[72:75], v97 offset0:96 offset1:100
	v_add3_u32 v38, v55, v38, s91
	v_add3_u32 v37, v44, v37, s91
	s_waitcnt lgkmcnt(0)
	v_mfma_f32_16x16x32_bf16 v[72:75], v[72:75], v[46:49], v[78:81]
	s_nop 2
	ds_read2_b64 v[76:79], v101 offset0:128 offset1:132
	ds_read2_b64 v[40:43], v82 offset0:40 offset1:44
	s_waitcnt lgkmcnt(1)
	v_mfma_f32_16x16x32_bf16 v[6:9], v[76:79], v[46:49], v[6:9]
	ds_read2_b64 v[44:47], v96 offset0:72 offset1:76
	ds_read2_b64 v[48:51], v97 offset0:104 offset1:108
	ds_read2_b64 v[52:55], v101 offset0:136 offset1:140
	v_bfe_u32 v33, v12, 16, 1
	v_bfe_u32 v35, v34, 16, 1
	v_bfe_u32 v13, v67, 16, 1
	v_bfe_u32 v27, v58, 16, 1
	v_add3_u32 v34, v34, v35, s91
	v_add3_u32 v12, v12, v33, s91
	v_add3_u32 v27, v58, v27, s91
	v_add3_u32 v13, v67, v13, s91
	v_lshrrev_b32_e32 v12, 16, v12
	v_lshrrev_b32_e32 v33, 16, v34
	v_lshrrev_b32_e32 v34, 16, v37
	v_lshrrev_b32_e32 v35, 16, v38
	v_and_or_b32 v35, v13, s33, v35
	v_and_or_b32 v34, v27, s33, v34
	v_and_or_b32 v33, v32, s33, v33
	v_and_or_b32 v32, v36, s33, v12
	v_bfe_u32 v13, v25, 16, 1
	v_bfe_u32 v27, v24, 16, 1
	s_waitcnt lgkmcnt(3)
	v_mfma_f32_16x16x32_bf16 v[40:43], v[40:43], v[32:35], v[60:63]
	v_add3_u32 v24, v24, v27, s91
	v_add3_u32 v13, v25, v13, s91
	v_bfe_u32 v25, v11, 16, 1
	s_waitcnt lgkmcnt(2)
	v_mfma_f32_16x16x32_bf16 v[44:47], v[44:47], v[32:35], v[68:71]
	v_bfe_u32 v27, v23, 16, 1
	v_bfe_u32 v12, v66, 16, 1
	v_add3_u32 v23, v23, v27, s91
	s_waitcnt lgkmcnt(1)
	v_mfma_f32_16x16x32_bf16 v[48:51], v[48:51], v[32:35], v[72:75]
	v_add3_u32 v11, v11, v25, s91
	v_add3_u32 v12, v66, v12, s91
	v_lshrrev_b32_e32 v11, 16, v11
	s_waitcnt lgkmcnt(0)
	v_mfma_f32_16x16x32_bf16 v[6:9], v[52:55], v[32:35], v[6:9]
	v_bfe_u32 v32, v39, 16, 1
	v_add3_u32 v32, v39, v32, s91
	ds_read2_b64 v[36:39], v82 offset0:48 offset1:52
	v_bfe_u32 v33, v18, 16, 1
	v_bfe_u32 v34, v20, 16, 1
	v_add3_u32 v20, v20, v34, s91
	v_add3_u32 v18, v18, v33, s91
	v_lshrrev_b32_e32 v23, 16, v23
	v_lshrrev_b32_e32 v18, 16, v18
	v_lshrrev_b32_e32 v20, 16, v20
	v_and_or_b32 v35, v12, s33, v20
	v_and_or_b32 v34, v13, s33, v18
	v_and_or_b32 v33, v24, s33, v23
	v_and_or_b32 v32, v32, s33, v11
	v_bfe_u32 v12, v21, 16, 1
	v_bfe_u32 v13, v17, 16, 1
	s_waitcnt lgkmcnt(0)
	v_mfma_f32_16x16x32_bf16 v[36:39], v[36:39], v[32:35], v[40:43]
	v_bfe_u32 v18, v15, 16, 1
	v_add3_u32 v15, v15, v18, s91
	v_add3_u32 v13, v17, v13, s91
	ds_read2_b64 v[40:43], v96 offset0:80 offset1:84
	s_waitcnt lgkmcnt(0)
	v_mfma_f32_16x16x32_bf16 v[40:43], v[40:43], v[32:35], v[44:47]
	s_nop 2
	ds_read2_b64 v[44:47], v97 offset0:112 offset1:116
	v_add3_u32 v12, v21, v12, s91
	v_bfe_u32 v17, v10, 16, 1
	s_waitcnt lgkmcnt(0)
	v_mfma_f32_16x16x32_bf16 v[44:47], v[44:47], v[32:35], v[48:51]
	s_nop 2
	ds_read2_b64 v[48:51], v101 offset0:144 offset1:148
	v_bfe_u32 v18, v14, 16, 1
	v_bfe_u32 v20, v16, 16, 1
	v_bfe_u32 v21, v19, 16, 1
	v_bfe_u32 v11, v65, 16, 1
	v_add3_u32 v19, v19, v21, s91
	v_add3_u32 v16, v16, v20, s91
	v_add3_u32 v14, v14, v18, s91
	v_add3_u32 v10, v10, v17, s91
	v_add3_u32 v11, v65, v11, s91
	v_lshrrev_b32_e32 v10, 16, v10
	v_lshrrev_b32_e32 v14, 16, v14
	v_lshrrev_b32_e32 v16, 16, v16
	v_lshrrev_b32_e32 v17, 16, v19
	s_waitcnt lgkmcnt(0)
	v_mfma_f32_16x16x32_bf16 v[6:9], v[48:51], v[32:35], v[6:9]
	v_and_or_b32 v35, v11, s33, v17
	v_and_or_b32 v34, v12, s33, v16
	v_and_or_b32 v33, v13, s33, v14
	v_and_or_b32 v32, v15, s33, v10
	ds_read2_b64 v[10:13], v82 offset0:56 offset1:60
	v_div_scale_f32 v23, s[4:5], v22, v22, 1.0
	s_waitcnt lgkmcnt(0)
	v_mfma_f32_16x16x32_bf16 v[18:21], v[10:13], v[32:35], v[36:39]
	ds_read2_b64 v[10:13], v96 offset0:88 offset1:92
	s_nop 1
	ds_read2_b64 v[36:39], v101 offset0:152 offset1:156
	v_rcp_f32_e32 v27, v23
	s_waitcnt lgkmcnt(1)
	v_mfma_f32_16x16x32_bf16 v[14:17], v[10:13], v[32:35], v[40:43]
	ds_read2_b64 v[10:13], v97 offset0:120 offset1:124
	v_lshlrev_b64 v[24:25], 11, v[28:29]
	v_fma_f32 v28, -v23, v27, 1.0
	v_fmac_f32_e32 v27, v28, v27
	v_div_scale_f32 v28, vcc, 1.0, v22, 1.0
	v_mul_f32_e32 v29, v28, v27
	s_waitcnt lgkmcnt(0)
	v_mfma_f32_16x16x32_bf16 v[10:13], v[10:13], v[32:35], v[44:47]
	v_lshl_add_u64 v[24:25], s[0:1], 0, v[24:25]
	v_lshl_add_u64 v[24:25], v[24:25], 0, s[94:95]
	v_mfma_f32_16x16x32_bf16 v[6:9], v[36:39], v[32:35], v[6:9]
	v_fma_f32 v32, -v23, v29, v28
	v_fmac_f32_e32 v29, v32, v27
	v_fma_f32 v23, -v23, v29, v28
	v_div_fmas_f32 v23, v23, v27, v29
	v_div_fixup_f32 v22, v23, v22, 1.0
	v_mov_b32_e32 v33, v20
	v_mov_b32_e32 v20, v19
	v_mov_b32_e32 v32, v18
	v_pk_mul_f32 v[18:19], v[22:23], v[20:21] op_sel_hi:[0,1]
	v_mov_b32_e32 v27, v1
	v_pk_mul_f32 v[32:33], v[22:23], v[32:33] op_sel_hi:[0,1]
	v_and_b32_sdwa v23, v19, v218 dst_sel:DWORD dst_unused:UNUSED_PAD src0_sel:WORD_1 src1_sel:DWORD
	v_lshl_add_u64 v[24:25], v[24:25], 0, v[26:27]
	v_and_b32_sdwa v20, v33, v218 dst_sel:DWORD dst_unused:UNUSED_PAD src0_sel:WORD_1 src1_sel:DWORD
	v_and_b32_sdwa v27, v18, v218 dst_sel:DWORD dst_unused:UNUSED_PAD src0_sel:WORD_1 src1_sel:DWORD
	v_add3_u32 v19, v19, v23, s91
	v_and_b32_sdwa v21, v32, v218 dst_sel:DWORD dst_unused:UNUSED_PAD src0_sel:WORD_1 src1_sel:DWORD
	v_add3_u32 v20, v33, v20, s91
	v_add3_u32 v18, v18, v27, s91
	v_and_b32_e32 v19, 0xffff0000, v19
	v_add3_u32 v21, v32, v21, s91
	v_and_b32_e32 v18, 0xffff0000, v18
	v_or_b32_sdwa v19, v19, v20 dst_sel:DWORD dst_unused:UNUSED_PAD src0_sel:DWORD src1_sel:WORD_1
	v_add_co_u32_e32 v20, vcc, s8, v24
	v_or_b32_sdwa v18, v18, v21 dst_sel:DWORD dst_unused:UNUSED_PAD src0_sel:DWORD src1_sel:WORD_1
	s_nop 0
	v_addc_co_u32_e32 v21, vcc, 0, v25, vcc
	global_store_dwordx2 v[20:21], v[18:19], off offset:1536
	v_mov_b32_e32 v18, v14
	v_mov_b32_e32 v19, v16
	v_pk_mul_f32 v[18:19], v[22:23], v[18:19] op_sel_hi:[0,1]
	v_mov_b32_e32 v16, v15
	v_pk_mul_f32 v[14:15], v[22:23], v[16:17] op_sel_hi:[0,1]
	v_and_b32_sdwa v16, v19, v218 dst_sel:DWORD dst_unused:UNUSED_PAD src0_sel:WORD_1 src1_sel:DWORD
	v_and_b32_sdwa v17, v18, v218 dst_sel:DWORD dst_unused:UNUSED_PAD src0_sel:WORD_1 src1_sel:DWORD
	v_add3_u32 v17, v18, v17, s91
	v_add3_u32 v16, v19, v16, s91
	v_and_b32_sdwa v18, v15, v218 dst_sel:DWORD dst_unused:UNUSED_PAD src0_sel:WORD_1 src1_sel:DWORD
	v_and_b32_sdwa v19, v14, v218 dst_sel:DWORD dst_unused:UNUSED_PAD src0_sel:WORD_1 src1_sel:DWORD
	v_add3_u32 v15, v15, v18, s91
	v_add3_u32 v14, v14, v19, s91
	v_and_b32_e32 v15, 0xffff0000, v15
	v_and_b32_e32 v14, 0xffff0000, v14
	v_lshl_add_u64 v[28:29], v[24:25], 0, s[16:17]
	v_or_b32_sdwa v15, v15, v16 dst_sel:DWORD dst_unused:UNUSED_PAD src0_sel:DWORD src1_sel:WORD_1
	v_or_b32_sdwa v14, v14, v17 dst_sel:DWORD dst_unused:UNUSED_PAD src0_sel:DWORD src1_sel:WORD_1
	global_store_dwordx2 v[28:29], v[14:15], off offset:32
	v_mov_b32_e32 v14, v10
	v_mov_b32_e32 v15, v12
	v_pk_mul_f32 v[14:15], v[22:23], v[14:15] op_sel_hi:[0,1]
	v_mov_b32_e32 v12, v11
	v_pk_mul_f32 v[10:11], v[22:23], v[12:13] op_sel_hi:[0,1]
	v_and_b32_sdwa v12, v15, v218 dst_sel:DWORD dst_unused:UNUSED_PAD src0_sel:WORD_1 src1_sel:DWORD
	v_and_b32_sdwa v13, v14, v218 dst_sel:DWORD dst_unused:UNUSED_PAD src0_sel:WORD_1 src1_sel:DWORD
	v_add3_u32 v13, v14, v13, s91
	v_add3_u32 v12, v15, v12, s91
	v_and_b32_sdwa v14, v11, v218 dst_sel:DWORD dst_unused:UNUSED_PAD src0_sel:WORD_1 src1_sel:DWORD
	v_and_b32_sdwa v15, v10, v218 dst_sel:DWORD dst_unused:UNUSED_PAD src0_sel:WORD_1 src1_sel:DWORD
	v_add3_u32 v11, v11, v14, s91
	v_add3_u32 v10, v10, v15, s91
	v_and_b32_e32 v11, 0xffff0000, v11
	v_and_b32_e32 v10, 0xffff0000, v10
	v_or_b32_sdwa v11, v11, v12 dst_sel:DWORD dst_unused:UNUSED_PAD src0_sel:DWORD src1_sel:WORD_1
	v_or_b32_sdwa v10, v10, v13 dst_sel:DWORD dst_unused:UNUSED_PAD src0_sel:DWORD src1_sel:WORD_1
	global_store_dwordx2 v[28:29], v[10:11], off offset:64
	v_mov_b32_e32 v10, v6
	v_mov_b32_e32 v11, v8
	v_pk_mul_f32 v[10:11], v[22:23], v[10:11] op_sel_hi:[0,1]
	v_mov_b32_e32 v8, v7
	v_pk_mul_f32 v[6:7], v[22:23], v[8:9] op_sel_hi:[0,1]
	v_and_b32_sdwa v8, v11, v218 dst_sel:DWORD dst_unused:UNUSED_PAD src0_sel:WORD_1 src1_sel:DWORD
	v_and_b32_sdwa v9, v10, v218 dst_sel:DWORD dst_unused:UNUSED_PAD src0_sel:WORD_1 src1_sel:DWORD
	v_add3_u32 v9, v10, v9, s91
	v_add3_u32 v8, v11, v8, s91
	v_and_b32_sdwa v10, v7, v218 dst_sel:DWORD dst_unused:UNUSED_PAD src0_sel:WORD_1 src1_sel:DWORD
	v_and_b32_sdwa v11, v6, v218 dst_sel:DWORD dst_unused:UNUSED_PAD src0_sel:WORD_1 src1_sel:DWORD
	v_add3_u32 v7, v7, v10, s91
	v_add3_u32 v6, v6, v11, s91
	v_and_b32_e32 v7, 0xffff0000, v7
	v_and_b32_e32 v6, 0xffff0000, v6
	v_or_b32_sdwa v7, v7, v8 dst_sel:DWORD dst_unused:UNUSED_PAD src0_sel:DWORD src1_sel:WORD_1
	v_or_b32_sdwa v6, v6, v9 dst_sel:DWORD dst_unused:UNUSED_PAD src0_sel:DWORD src1_sel:WORD_1
	s_movk_i32 s4, 0x80
	s_and_b64 vcc, exec, s[2:3]
	s_mov_b64 s[2:3], 0
	global_store_dwordx2 v[28:29], v[6:7], off offset:96
	s_cbranch_vccnz .LBB0_536
	s_waitcnt lgkmcnt(0)
	s_barrier
	s_branch .LBB0_533

.LBB0_547:
	s_or_b64 exec, exec, s[2:3]
	v_lshl_add_u64 v[2:3], v[80:81], 1, s[0:1]
	s_mov_b64 s[0:1], 0xc400000
	v_lshl_add_u64 v[6:7], v[2:3], 0, s[0:1]
	s_mov_b64 s[0:1], 0xa000000
	s_movk_i32 s2, 0xe00
	v_lshl_add_u64 v[2:3], v[2:3], 0, s[0:1]
	v_pk_fma_f32 v[64:65], v[64:65], v[72:73], v[68:69]
	v_mad_i64_i32 v[68:69], s[0:1], v96, s2, v[6:7]
	global_load_dwordx2 v[68:69], v[68:69], off nt
	v_pk_fma_f32 v[66:67], v[66:67], v[74:75], v[70:71]
	v_ashrrev_i32_e32 v97, 31, v96
	v_pk_fma_f32 v[56:57], v[56:57], v[64:65], v[60:61]
	v_mad_i64_i32 v[60:61], s[0:1], v94, s2, v[6:7]
	s_nop 1
	global_load_dwordx2 v[114:115], v[60:61], off nt
	v_pk_fma_f32 v[58:59], v[58:59], v[66:67], v[62:63]
	v_ashrrev_i32_e32 v95, 31, v94
	v_pk_fma_f32 v[48:49], v[48:49], v[56:57], v[52:53]
	v_mad_i64_i32 v[52:53], s[0:1], v92, s2, v[6:7]
	s_nop 1
	global_load_dwordx2 v[116:117], v[52:53], off nt
	v_pk_fma_f32 v[50:51], v[50:51], v[58:59], v[54:55]
	v_ashrrev_i32_e32 v93, 31, v92
	v_pk_fma_f32 v[40:41], v[40:41], v[48:49], v[44:45]
	v_mad_i64_i32 v[44:45], s[0:1], v90, s2, v[6:7]
	s_nop 1
	global_load_dwordx2 v[118:119], v[44:45], off nt
	v_pk_fma_f32 v[42:43], v[42:43], v[50:51], v[46:47]
	v_ashrrev_i32_e32 v91, 31, v90
	v_pk_fma_f32 v[32:33], v[32:33], v[40:41], v[36:37]
	v_mad_i64_i32 v[36:37], s[0:1], v88, s2, v[6:7]
	s_nop 1
	global_load_dwordx2 v[120:121], v[36:37], off nt
	v_pk_fma_f32 v[34:35], v[34:35], v[42:43], v[38:39]
	v_ashrrev_i32_e32 v89, 31, v88
	v_pk_fma_f32 v[24:25], v[24:25], v[32:33], v[28:29]
	v_mad_i64_i32 v[28:29], s[0:1], v86, s2, v[6:7]
	s_nop 1
	global_load_dwordx2 v[122:123], v[28:29], off nt
	v_pk_fma_f32 v[26:27], v[26:27], v[34:35], v[30:31]
	v_ashrrev_i32_e32 v87, 31, v86
	v_pk_fma_f32 v[16:17], v[16:17], v[24:25], v[20:21]
	v_mad_i64_i32 v[20:21], s[0:1], v84, s2, v[6:7]
	s_nop 1
	global_load_dwordx2 v[124:125], v[20:21], off nt
	v_pk_fma_f32 v[18:19], v[18:19], v[26:27], v[22:23]
	v_ashrrev_i32_e32 v85, 31, v84
	v_mad_i64_i32 v[6:7], s[0:1], v82, s2, v[6:7]
	s_nop 1
	global_load_dwordx2 v[126:127], v[6:7], off nt
	v_pk_fma_f32 v[8:9], v[8:9], v[16:17], v[12:13]
	v_pk_fma_f32 v[10:11], v[10:11], v[18:19], v[14:15]
	v_ashrrev_i32_e32 v83, 31, v82
	v_cmp_eq_u32_e32 vcc, 31, v103
	v_cmp_eq_u32_e64 s[4:5], 15, v102
	s_and_b64 s[2:3], s[4:5], vcc
	s_waitcnt vmcnt(0) lgkmcnt(0)
	v_lshlrev_b32_e32 v71, 16, v69
	v_lshlrev_b32_e32 v70, 16, v68
	v_pk_mul_f32 v[72:73], v[70:71], v[70:71]
	v_and_b32_e32 v69, 0xffff0000, v69
	v_fmamk_f32 v0, v72, 0xbdd2d3e2, v220
	v_mul_f32_e32 v0, v0, v70
	v_exp_f32_e32 v0, v0
	v_and_b32_e32 v68, 0xffff0000, v68
	v_pk_mul_f32 v[74:75], v[68:69], v[68:69]
	v_add_f32_e32 v0, 1.0, v0
	v_rcp_f32_e32 v72, v0
	v_fmamk_f32 v0, v74, 0xbdd2d3e2, v220
	v_mul_f32_e32 v0, v0, v68
	v_exp_f32_e32 v0, v0
	s_nop 0
	v_add_f32_e32 v0, 1.0, v0
	v_rcp_f32_e32 v74, v0
	v_fmamk_f32 v0, v73, 0xbdd2d3e2, v220
	v_mul_f32_e32 v0, v0, v71
	v_exp_f32_e32 v0, v0
	s_nop 0
	v_add_f32_e32 v0, 1.0, v0
	v_rcp_f32_e32 v73, v0
	v_fmamk_f32 v0, v75, 0xbdd2d3e2, v220
	v_mul_f32_e32 v0, v0, v69
	v_exp_f32_e32 v0, v0
	v_pk_mul_f32 v[70:71], v[72:73], v[70:71]
	v_mov_b32_e32 v72, v64
	v_mov_b32_e32 v73, v66
	v_add_f32_e32 v0, 1.0, v0
	v_rcp_f32_e32 v75, v0
	v_pk_mul_f32 v[70:71], v[72:73], v[70:71]
	v_mov_b32_e32 v72, v65
	v_mov_b32_e32 v73, v67
	v_pk_mul_f32 v[68:69], v[74:75], v[68:69]
	v_and_b32_sdwa v0, v71, v218 dst_sel:DWORD dst_unused:UNUSED_PAD src0_sel:WORD_1 src1_sel:DWORD
	v_pk_mul_f32 v[68:69], v[72:73], v[68:69]
	v_and_b32_sdwa v5, v70, v218 dst_sel:DWORD dst_unused:UNUSED_PAD src0_sel:WORD_1 src1_sel:DWORD
	v_add3_u32 v5, v70, v5, s91
	v_add3_u32 v0, v71, v0, s91
	v_and_b32_sdwa v70, v69, v218 dst_sel:DWORD dst_unused:UNUSED_PAD src0_sel:WORD_1 src1_sel:DWORD
	v_and_b32_sdwa v71, v68, v218 dst_sel:DWORD dst_unused:UNUSED_PAD src0_sel:WORD_1 src1_sel:DWORD
	v_add3_u32 v69, v69, v70, s91
	v_add3_u32 v68, v68, v71, s91
	v_and_b32_e32 v69, 0xffff0000, v69
	v_and_b32_e32 v68, 0xffff0000, v68
	v_lshlrev_b64 v[70:71], 11, v[96:97]
	v_or_b32_sdwa v69, v69, v0 dst_sel:DWORD dst_unused:UNUSED_PAD src0_sel:DWORD src1_sel:WORD_1
	v_or_b32_sdwa v68, v68, v5 dst_sel:DWORD dst_unused:UNUSED_PAD src0_sel:DWORD src1_sel:WORD_1
	v_lshl_add_u64 v[70:71], v[2:3], 0, v[70:71]
	global_store_dwordx2 v[70:71], v[68:69], off
	s_waitcnt vmcnt(1)
	s_nop 0
	v_mov_b32_e32 v60, v114
	v_mov_b32_e32 v61, v115
	s_nop 1
	s_waitcnt vmcnt(1) lgkmcnt(0)
	v_lshlrev_b32_e32 v63, 16, v61
	v_lshlrev_b32_e32 v62, 16, v60
	v_pk_mul_f32 v[64:65], v[62:63], v[62:63]
	v_and_b32_e32 v61, 0xffff0000, v61
	v_fmamk_f32 v0, v64, 0xbdd2d3e2, v220
	v_mul_f32_e32 v0, v0, v62
	v_exp_f32_e32 v0, v0
	v_and_b32_e32 v60, 0xffff0000, v60
	v_pk_mul_f32 v[66:67], v[60:61], v[60:61]
	v_add_f32_e32 v0, 1.0, v0
	v_rcp_f32_e32 v64, v0
	v_fmamk_f32 v0, v66, 0xbdd2d3e2, v220
	v_mul_f32_e32 v0, v0, v60
	v_exp_f32_e32 v0, v0
	s_nop 0
	v_add_f32_e32 v0, 1.0, v0
	v_rcp_f32_e32 v66, v0
	v_fmamk_f32 v0, v65, 0xbdd2d3e2, v220
	v_mul_f32_e32 v0, v0, v63
	v_exp_f32_e32 v0, v0
	s_nop 0
	v_add_f32_e32 v0, 1.0, v0
	v_rcp_f32_e32 v65, v0
	v_fmamk_f32 v0, v67, 0xbdd2d3e2, v220
	v_mul_f32_e32 v0, v0, v61
	v_exp_f32_e32 v0, v0
	v_pk_mul_f32 v[62:63], v[64:65], v[62:63]
	v_mov_b32_e32 v64, v56
	v_mov_b32_e32 v65, v58
	v_add_f32_e32 v0, 1.0, v0
	v_rcp_f32_e32 v67, v0
	v_pk_mul_f32 v[62:63], v[64:65], v[62:63]
	v_mov_b32_e32 v64, v57
	v_mov_b32_e32 v65, v59
	v_pk_mul_f32 v[60:61], v[66:67], v[60:61]
	v_and_b32_sdwa v0, v63, v218 dst_sel:DWORD dst_unused:UNUSED_PAD src0_sel:WORD_1 src1_sel:DWORD
	v_pk_mul_f32 v[60:61], v[64:65], v[60:61]
	v_and_b32_sdwa v5, v62, v218 dst_sel:DWORD dst_unused:UNUSED_PAD src0_sel:WORD_1 src1_sel:DWORD
	v_add3_u32 v5, v62, v5, s91
	v_add3_u32 v0, v63, v0, s91
	v_and_b32_sdwa v62, v61, v218 dst_sel:DWORD dst_unused:UNUSED_PAD src0_sel:WORD_1 src1_sel:DWORD
	v_and_b32_sdwa v63, v60, v218 dst_sel:DWORD dst_unused:UNUSED_PAD src0_sel:WORD_1 src1_sel:DWORD
	v_add3_u32 v61, v61, v62, s91
	v_add3_u32 v60, v60, v63, s91
	v_and_b32_e32 v61, 0xffff0000, v61
	v_and_b32_e32 v60, 0xffff0000, v60
	v_lshlrev_b64 v[62:63], 11, v[94:95]
	v_or_b32_sdwa v61, v61, v0 dst_sel:DWORD dst_unused:UNUSED_PAD src0_sel:DWORD src1_sel:WORD_1
	v_or_b32_sdwa v60, v60, v5 dst_sel:DWORD dst_unused:UNUSED_PAD src0_sel:DWORD src1_sel:WORD_1
	v_lshl_add_u64 v[62:63], v[2:3], 0, v[62:63]
	global_store_dwordx2 v[62:63], v[60:61], off
	s_waitcnt vmcnt(2)
	s_nop 0
	v_mov_b32_e32 v52, v116
	v_mov_b32_e32 v53, v117
	s_nop 1
	s_waitcnt vmcnt(2) lgkmcnt(0)
	v_lshlrev_b32_e32 v55, 16, v53
	v_lshlrev_b32_e32 v54, 16, v52
	v_pk_mul_f32 v[56:57], v[54:55], v[54:55]
	v_and_b32_e32 v53, 0xffff0000, v53
	v_fmamk_f32 v0, v56, 0xbdd2d3e2, v220
	v_mul_f32_e32 v0, v0, v54
	v_exp_f32_e32 v0, v0
	v_and_b32_e32 v52, 0xffff0000, v52
	v_pk_mul_f32 v[58:59], v[52:53], v[52:53]
	v_add_f32_e32 v0, 1.0, v0
	v_rcp_f32_e32 v56, v0
	v_fmamk_f32 v0, v58, 0xbdd2d3e2, v220
	v_mul_f32_e32 v0, v0, v52
	v_exp_f32_e32 v0, v0
	s_nop 0
	v_add_f32_e32 v0, 1.0, v0
	v_rcp_f32_e32 v58, v0
	v_fmamk_f32 v0, v57, 0xbdd2d3e2, v220
	v_mul_f32_e32 v0, v0, v55
	v_exp_f32_e32 v0, v0
	s_nop 0
	v_add_f32_e32 v0, 1.0, v0
	v_rcp_f32_e32 v57, v0
	v_fmamk_f32 v0, v59, 0xbdd2d3e2, v220
	v_mul_f32_e32 v0, v0, v53
	v_exp_f32_e32 v0, v0
	v_pk_mul_f32 v[54:55], v[56:57], v[54:55]
	v_mov_b32_e32 v56, v48
	v_mov_b32_e32 v57, v50
	v_add_f32_e32 v0, 1.0, v0
	v_rcp_f32_e32 v59, v0
	v_pk_mul_f32 v[54:55], v[56:57], v[54:55]
	v_mov_b32_e32 v56, v49
	v_mov_b32_e32 v57, v51
	v_pk_mul_f32 v[52:53], v[58:59], v[52:53]
	v_and_b32_sdwa v0, v55, v218 dst_sel:DWORD dst_unused:UNUSED_PAD src0_sel:WORD_1 src1_sel:DWORD
	v_pk_mul_f32 v[52:53], v[56:57], v[52:53]
	v_and_b32_sdwa v5, v54, v218 dst_sel:DWORD dst_unused:UNUSED_PAD src0_sel:WORD_1 src1_sel:DWORD
	v_add3_u32 v5, v54, v5, s91
	v_add3_u32 v0, v55, v0, s91
	v_and_b32_sdwa v54, v53, v218 dst_sel:DWORD dst_unused:UNUSED_PAD src0_sel:WORD_1 src1_sel:DWORD
	v_and_b32_sdwa v55, v52, v218 dst_sel:DWORD dst_unused:UNUSED_PAD src0_sel:WORD_1 src1_sel:DWORD
	v_add3_u32 v53, v53, v54, s91
	v_add3_u32 v52, v52, v55, s91
	v_and_b32_e32 v53, 0xffff0000, v53
	v_and_b32_e32 v52, 0xffff0000, v52
	v_lshlrev_b64 v[54:55], 11, v[92:93]
	v_or_b32_sdwa v53, v53, v0 dst_sel:DWORD dst_unused:UNUSED_PAD src0_sel:DWORD src1_sel:WORD_1
	v_or_b32_sdwa v52, v52, v5 dst_sel:DWORD dst_unused:UNUSED_PAD src0_sel:DWORD src1_sel:WORD_1
	v_lshl_add_u64 v[54:55], v[2:3], 0, v[54:55]
	global_store_dwordx2 v[54:55], v[52:53], off
	s_waitcnt vmcnt(3)
	s_nop 0
	v_mov_b32_e32 v44, v118
	v_mov_b32_e32 v45, v119
	s_nop 1
	s_waitcnt vmcnt(3) lgkmcnt(0)
	v_lshlrev_b32_e32 v47, 16, v45
	v_lshlrev_b32_e32 v46, 16, v44
	v_pk_mul_f32 v[48:49], v[46:47], v[46:47]
	v_and_b32_e32 v45, 0xffff0000, v45
	v_fmamk_f32 v0, v48, 0xbdd2d3e2, v220
	v_mul_f32_e32 v0, v0, v46
	v_exp_f32_e32 v0, v0
	v_and_b32_e32 v44, 0xffff0000, v44
	v_pk_mul_f32 v[50:51], v[44:45], v[44:45]
	v_add_f32_e32 v0, 1.0, v0
	v_rcp_f32_e32 v48, v0
	v_fmamk_f32 v0, v50, 0xbdd2d3e2, v220
	v_mul_f32_e32 v0, v0, v44
	v_exp_f32_e32 v0, v0
	s_nop 0
	v_add_f32_e32 v0, 1.0, v0
	v_rcp_f32_e32 v50, v0
	v_fmamk_f32 v0, v49, 0xbdd2d3e2, v220
	v_mul_f32_e32 v0, v0, v47
	v_exp_f32_e32 v0, v0
	s_nop 0
	v_add_f32_e32 v0, 1.0, v0
	v_rcp_f32_e32 v49, v0
	v_fmamk_f32 v0, v51, 0xbdd2d3e2, v220
	v_mul_f32_e32 v0, v0, v45
	v_exp_f32_e32 v0, v0
	v_pk_mul_f32 v[46:47], v[48:49], v[46:47]
	v_mov_b32_e32 v48, v40
	v_mov_b32_e32 v49, v42
	v_add_f32_e32 v0, 1.0, v0
	v_rcp_f32_e32 v51, v0
	v_pk_mul_f32 v[46:47], v[48:49], v[46:47]
	v_mov_b32_e32 v48, v41
	v_mov_b32_e32 v49, v43
	v_pk_mul_f32 v[44:45], v[50:51], v[44:45]
	v_and_b32_sdwa v0, v47, v218 dst_sel:DWORD dst_unused:UNUSED_PAD src0_sel:WORD_1 src1_sel:DWORD
	v_pk_mul_f32 v[44:45], v[48:49], v[44:45]
	v_and_b32_sdwa v5, v46, v218 dst_sel:DWORD dst_unused:UNUSED_PAD src0_sel:WORD_1 src1_sel:DWORD
	v_add3_u32 v5, v46, v5, s91
	v_add3_u32 v0, v47, v0, s91
	v_and_b32_sdwa v46, v45, v218 dst_sel:DWORD dst_unused:UNUSED_PAD src0_sel:WORD_1 src1_sel:DWORD
	v_and_b32_sdwa v47, v44, v218 dst_sel:DWORD dst_unused:UNUSED_PAD src0_sel:WORD_1 src1_sel:DWORD
	v_add3_u32 v45, v45, v46, s91
	v_add3_u32 v44, v44, v47, s91
	v_and_b32_e32 v45, 0xffff0000, v45
	v_and_b32_e32 v44, 0xffff0000, v44
	v_lshlrev_b64 v[46:47], 11, v[90:91]
	v_or_b32_sdwa v45, v45, v0 dst_sel:DWORD dst_unused:UNUSED_PAD src0_sel:DWORD src1_sel:WORD_1
	v_or_b32_sdwa v44, v44, v5 dst_sel:DWORD dst_unused:UNUSED_PAD src0_sel:DWORD src1_sel:WORD_1
	v_lshl_add_u64 v[46:47], v[2:3], 0, v[46:47]
	global_store_dwordx2 v[46:47], v[44:45], off
	s_waitcnt vmcnt(4)
	s_nop 0
	v_mov_b32_e32 v36, v120
	v_mov_b32_e32 v37, v121
	s_nop 1
	s_waitcnt vmcnt(4) lgkmcnt(0)
	v_lshlrev_b32_e32 v39, 16, v37
	v_lshlrev_b32_e32 v38, 16, v36
	v_pk_mul_f32 v[40:41], v[38:39], v[38:39]
	v_and_b32_e32 v37, 0xffff0000, v37
	v_fmamk_f32 v0, v40, 0xbdd2d3e2, v220
	v_mul_f32_e32 v0, v0, v38
	v_exp_f32_e32 v0, v0
	v_and_b32_e32 v36, 0xffff0000, v36
	v_pk_mul_f32 v[42:43], v[36:37], v[36:37]
	v_add_f32_e32 v0, 1.0, v0
	v_rcp_f32_e32 v40, v0
	v_fmamk_f32 v0, v42, 0xbdd2d3e2, v220
	v_mul_f32_e32 v0, v0, v36
	v_exp_f32_e32 v0, v0
	s_nop 0
	v_add_f32_e32 v0, 1.0, v0
	v_rcp_f32_e32 v42, v0
	v_fmamk_f32 v0, v41, 0xbdd2d3e2, v220
	v_mul_f32_e32 v0, v0, v39
	v_exp_f32_e32 v0, v0
	s_nop 0
	v_add_f32_e32 v0, 1.0, v0
	v_rcp_f32_e32 v41, v0
	v_fmamk_f32 v0, v43, 0xbdd2d3e2, v220
	v_mul_f32_e32 v0, v0, v37
	v_exp_f32_e32 v0, v0
	v_pk_mul_f32 v[38:39], v[40:41], v[38:39]
	v_mov_b32_e32 v40, v32
	v_mov_b32_e32 v41, v34
	v_add_f32_e32 v0, 1.0, v0
	v_rcp_f32_e32 v43, v0
	v_pk_mul_f32 v[38:39], v[40:41], v[38:39]
	v_mov_b32_e32 v40, v33
	v_mov_b32_e32 v41, v35
	v_pk_mul_f32 v[36:37], v[42:43], v[36:37]
	v_and_b32_sdwa v0, v39, v218 dst_sel:DWORD dst_unused:UNUSED_PAD src0_sel:WORD_1 src1_sel:DWORD
	v_pk_mul_f32 v[36:37], v[40:41], v[36:37]
	v_and_b32_sdwa v5, v38, v218 dst_sel:DWORD dst_unused:UNUSED_PAD src0_sel:WORD_1 src1_sel:DWORD
	v_add3_u32 v5, v38, v5, s91
	v_add3_u32 v0, v39, v0, s91
	v_and_b32_sdwa v38, v37, v218 dst_sel:DWORD dst_unused:UNUSED_PAD src0_sel:WORD_1 src1_sel:DWORD
	v_and_b32_sdwa v39, v36, v218 dst_sel:DWORD dst_unused:UNUSED_PAD src0_sel:WORD_1 src1_sel:DWORD
	v_add3_u32 v37, v37, v38, s91
	v_add3_u32 v36, v36, v39, s91
	v_and_b32_e32 v37, 0xffff0000, v37
	v_and_b32_e32 v36, 0xffff0000, v36
	v_lshlrev_b64 v[38:39], 11, v[88:89]
	v_or_b32_sdwa v37, v37, v0 dst_sel:DWORD dst_unused:UNUSED_PAD src0_sel:DWORD src1_sel:WORD_1
	v_or_b32_sdwa v36, v36, v5 dst_sel:DWORD dst_unused:UNUSED_PAD src0_sel:DWORD src1_sel:WORD_1
	v_lshl_add_u64 v[38:39], v[2:3], 0, v[38:39]
	global_store_dwordx2 v[38:39], v[36:37], off
	s_waitcnt vmcnt(5)
	s_nop 0
	v_mov_b32_e32 v28, v122
	v_mov_b32_e32 v29, v123
	s_nop 1
	s_waitcnt vmcnt(5) lgkmcnt(0)
	v_lshlrev_b32_e32 v31, 16, v29
	v_lshlrev_b32_e32 v30, 16, v28
	v_pk_mul_f32 v[32:33], v[30:31], v[30:31]
	v_and_b32_e32 v29, 0xffff0000, v29
	v_fmamk_f32 v0, v32, 0xbdd2d3e2, v220
	v_mul_f32_e32 v0, v0, v30
	v_exp_f32_e32 v0, v0
	v_and_b32_e32 v28, 0xffff0000, v28
	v_pk_mul_f32 v[34:35], v[28:29], v[28:29]
	v_add_f32_e32 v0, 1.0, v0
	v_rcp_f32_e32 v32, v0
	v_fmamk_f32 v0, v34, 0xbdd2d3e2, v220
	v_mul_f32_e32 v0, v0, v28
	v_exp_f32_e32 v0, v0
	s_nop 0
	v_add_f32_e32 v0, 1.0, v0
	v_rcp_f32_e32 v34, v0
	v_fmamk_f32 v0, v33, 0xbdd2d3e2, v220
	v_mul_f32_e32 v0, v0, v31
	v_exp_f32_e32 v0, v0
	s_nop 0
	v_add_f32_e32 v0, 1.0, v0
	v_rcp_f32_e32 v33, v0
	v_fmamk_f32 v0, v35, 0xbdd2d3e2, v220
	v_mul_f32_e32 v0, v0, v29
	v_exp_f32_e32 v0, v0
	v_pk_mul_f32 v[30:31], v[32:33], v[30:31]
	v_mov_b32_e32 v32, v24
	v_mov_b32_e32 v33, v26
	v_add_f32_e32 v0, 1.0, v0
	v_rcp_f32_e32 v35, v0
	v_pk_mul_f32 v[30:31], v[32:33], v[30:31]
	v_mov_b32_e32 v32, v25
	v_mov_b32_e32 v33, v27
	v_pk_mul_f32 v[28:29], v[34:35], v[28:29]
	v_and_b32_sdwa v0, v31, v218 dst_sel:DWORD dst_unused:UNUSED_PAD src0_sel:WORD_1 src1_sel:DWORD
	v_pk_mul_f32 v[28:29], v[32:33], v[28:29]
	v_and_b32_sdwa v5, v30, v218 dst_sel:DWORD dst_unused:UNUSED_PAD src0_sel:WORD_1 src1_sel:DWORD
	v_add3_u32 v5, v30, v5, s91
	v_add3_u32 v0, v31, v0, s91
	v_and_b32_sdwa v30, v29, v218 dst_sel:DWORD dst_unused:UNUSED_PAD src0_sel:WORD_1 src1_sel:DWORD
	v_and_b32_sdwa v31, v28, v218 dst_sel:DWORD dst_unused:UNUSED_PAD src0_sel:WORD_1 src1_sel:DWORD
	v_add3_u32 v29, v29, v30, s91
	v_add3_u32 v28, v28, v31, s91
	v_and_b32_e32 v29, 0xffff0000, v29
	v_and_b32_e32 v28, 0xffff0000, v28
	v_lshlrev_b64 v[30:31], 11, v[86:87]
	v_or_b32_sdwa v29, v29, v0 dst_sel:DWORD dst_unused:UNUSED_PAD src0_sel:DWORD src1_sel:WORD_1
	v_or_b32_sdwa v28, v28, v5 dst_sel:DWORD dst_unused:UNUSED_PAD src0_sel:DWORD src1_sel:WORD_1
	v_lshl_add_u64 v[30:31], v[2:3], 0, v[30:31]
	global_store_dwordx2 v[30:31], v[28:29], off
	s_waitcnt vmcnt(6)
	s_nop 0
	v_mov_b32_e32 v20, v124
	v_mov_b32_e32 v21, v125
	s_nop 1
	s_waitcnt vmcnt(6) lgkmcnt(0)
	v_lshlrev_b32_e32 v23, 16, v21
	v_lshlrev_b32_e32 v22, 16, v20
	v_pk_mul_f32 v[24:25], v[22:23], v[22:23]
	v_and_b32_e32 v21, 0xffff0000, v21
	v_fmamk_f32 v0, v24, 0xbdd2d3e2, v220
	v_mul_f32_e32 v0, v0, v22
	v_exp_f32_e32 v0, v0
	v_and_b32_e32 v20, 0xffff0000, v20
	v_pk_mul_f32 v[26:27], v[20:21], v[20:21]
	v_add_f32_e32 v0, 1.0, v0
	v_rcp_f32_e32 v24, v0
	v_fmamk_f32 v0, v26, 0xbdd2d3e2, v220
	v_mul_f32_e32 v0, v0, v20
	v_exp_f32_e32 v0, v0
	s_nop 0
	v_add_f32_e32 v0, 1.0, v0
	v_rcp_f32_e32 v26, v0
	v_fmamk_f32 v0, v25, 0xbdd2d3e2, v220
	v_mul_f32_e32 v0, v0, v23
	v_exp_f32_e32 v0, v0
	s_nop 0
	v_add_f32_e32 v0, 1.0, v0
	v_rcp_f32_e32 v25, v0
	v_fmamk_f32 v0, v27, 0xbdd2d3e2, v220
	v_mul_f32_e32 v0, v0, v21
	v_exp_f32_e32 v0, v0
	v_pk_mul_f32 v[22:23], v[24:25], v[22:23]
	v_mov_b32_e32 v24, v16
	v_mov_b32_e32 v25, v18
	v_add_f32_e32 v0, 1.0, v0
	v_rcp_f32_e32 v27, v0
	v_pk_mul_f32 v[22:23], v[24:25], v[22:23]
	v_mov_b32_e32 v24, v17
	v_mov_b32_e32 v25, v19
	v_pk_mul_f32 v[20:21], v[26:27], v[20:21]
	v_and_b32_sdwa v0, v23, v218 dst_sel:DWORD dst_unused:UNUSED_PAD src0_sel:WORD_1 src1_sel:DWORD
	v_pk_mul_f32 v[20:21], v[24:25], v[20:21]
	v_and_b32_sdwa v5, v22, v218 dst_sel:DWORD dst_unused:UNUSED_PAD src0_sel:WORD_1 src1_sel:DWORD
	v_add3_u32 v5, v22, v5, s91
	v_add3_u32 v0, v23, v0, s91
	v_and_b32_sdwa v22, v21, v218 dst_sel:DWORD dst_unused:UNUSED_PAD src0_sel:WORD_1 src1_sel:DWORD
	v_and_b32_sdwa v23, v20, v218 dst_sel:DWORD dst_unused:UNUSED_PAD src0_sel:WORD_1 src1_sel:DWORD
	v_add3_u32 v21, v21, v22, s91
	v_add3_u32 v20, v20, v23, s91
	v_and_b32_e32 v21, 0xffff0000, v21
	v_and_b32_e32 v20, 0xffff0000, v20
	v_lshlrev_b64 v[22:23], 11, v[84:85]
	v_or_b32_sdwa v21, v21, v0 dst_sel:DWORD dst_unused:UNUSED_PAD src0_sel:DWORD src1_sel:WORD_1
	v_or_b32_sdwa v20, v20, v5 dst_sel:DWORD dst_unused:UNUSED_PAD src0_sel:DWORD src1_sel:WORD_1
	v_lshl_add_u64 v[22:23], v[2:3], 0, v[22:23]
	global_store_dwordx2 v[22:23], v[20:21], off
	s_waitcnt vmcnt(7)
	s_nop 0
	v_mov_b32_e32 v6, v126
	v_mov_b32_e32 v7, v127
	s_nop 1
	s_waitcnt vmcnt(7) lgkmcnt(0)
	v_lshlrev_b32_e32 v13, 16, v7
	v_lshlrev_b32_e32 v12, 16, v6
	v_pk_mul_f32 v[14:15], v[12:13], v[12:13]
	v_and_b32_e32 v7, 0xffff0000, v7
	v_fmamk_f32 v0, v14, 0xbdd2d3e2, v220
	v_mul_f32_e32 v0, v0, v12
	v_exp_f32_e32 v0, v0
	v_and_b32_e32 v6, 0xffff0000, v6
	v_pk_mul_f32 v[16:17], v[6:7], v[6:7]
	v_add_f32_e32 v0, 1.0, v0
	v_rcp_f32_e32 v14, v0
	v_fmamk_f32 v0, v16, 0xbdd2d3e2, v220
	v_mul_f32_e32 v0, v0, v6
	v_exp_f32_e32 v0, v0
	s_nop 0
	v_add_f32_e32 v0, 1.0, v0
	v_rcp_f32_e32 v16, v0
	v_fmamk_f32 v0, v15, 0xbdd2d3e2, v220
	v_mul_f32_e32 v0, v0, v13
	v_exp_f32_e32 v0, v0
	s_nop 0
	v_add_f32_e32 v0, 1.0, v0
	v_rcp_f32_e32 v15, v0
	v_fmamk_f32 v0, v17, 0xbdd2d3e2, v220
	v_mul_f32_e32 v0, v0, v7
	v_exp_f32_e32 v0, v0
	v_pk_mul_f32 v[12:13], v[14:15], v[12:13]
	v_mov_b32_e32 v14, v8
	v_mov_b32_e32 v15, v10
	v_add_f32_e32 v0, 1.0, v0
	v_rcp_f32_e32 v17, v0
	v_pk_mul_f32 v[12:13], v[14:15], v[12:13]
	v_mov_b32_e32 v14, v9
	v_mov_b32_e32 v15, v11
	v_pk_mul_f32 v[6:7], v[16:17], v[6:7]
	v_and_b32_sdwa v0, v13, v218 dst_sel:DWORD dst_unused:UNUSED_PAD src0_sel:WORD_1 src1_sel:DWORD
	v_pk_mul_f32 v[6:7], v[14:15], v[6:7]
	v_and_b32_sdwa v5, v12, v218 dst_sel:DWORD dst_unused:UNUSED_PAD src0_sel:WORD_1 src1_sel:DWORD
	v_add3_u32 v5, v12, v5, s91
	v_add3_u32 v0, v13, v0, s91
	v_and_b32_sdwa v12, v7, v218 dst_sel:DWORD dst_unused:UNUSED_PAD src0_sel:WORD_1 src1_sel:DWORD
	v_and_b32_sdwa v13, v6, v218 dst_sel:DWORD dst_unused:UNUSED_PAD src0_sel:WORD_1 src1_sel:DWORD
	v_add3_u32 v7, v7, v12, s91
	v_add3_u32 v6, v6, v13, s91
	v_and_b32_e32 v7, 0xffff0000, v7
	v_and_b32_e32 v6, 0xffff0000, v6
	v_lshlrev_b64 v[12:13], 11, v[82:83]
	v_or_b32_sdwa v7, v7, v0 dst_sel:DWORD dst_unused:UNUSED_PAD src0_sel:DWORD src1_sel:WORD_1
	v_or_b32_sdwa v6, v6, v5 dst_sel:DWORD dst_unused:UNUSED_PAD src0_sel:DWORD src1_sel:WORD_1
	v_lshl_add_u64 v[2:3], v[2:3], 0, v[12:13]
	global_store_dwordx2 v[2:3], v[6:7], off
	s_and_saveexec_b64 s[0:1], s[2:3]
	s_cbranch_execz .LBB0_532
	v_readlane_b32 s2, v254, 8
	s_nop 1
	v_mov_b32_e32 v0, s2
	ds_read_b64 v[2:3], v0
	v_add_u32_e32 v0, s12, v101
	s_waitcnt lgkmcnt(0)
	v_readfirstlane_b32 s2, v2
	v_readfirstlane_b32 s3, v3
	s_nop 0
	v_mov_b32_e32 v2, s2
	s_movk_i32 s2, 0xc00
	v_mov_b32_e32 v3, s3
	v_mad_i64_i32 v[2:3], s[2:3], v0, s2, v[2:3]
	v_lshl_add_u64 v[2:3], v[80:81], 2, v[2:3]
	v_add_co_u32_e32 v2, vcc, 0x4080000, v2
	s_nop 1
	v_addc_co_u32_e32 v3, vcc, 0, v3, vcc
	global_store_dwordx4 v[2:3], v[8:11], off
	s_branch .LBB0_532

.LBB0_558:
	s_andn2_saveexec_b64 s[14:15], s[6:7]
	s_cbranch_execz .LBB0_555
	s_waitcnt lgkmcnt(0)
	v_add_f32_e32 v14, v23, v25
	v_fmamk_f32 v14, v14, 0x3c800000, v219
	v_cmp_gt_f32_e32 vcc, s85, v14
	v_mul_f32_e32 v15, 0x4f800000, v14
	s_nop 0
	v_cndmask_b32_e32 v14, v14, v15, vcc
	v_sqrt_f32_e32 v15, v14
	s_nop 0
	v_add_u32_e32 v16, -1, v15
	v_fma_f32 v17, -v16, v15, v14
	v_cmp_ge_f32_e64 s[6:7], 0, v17
	v_add_u32_e32 v17, 1, v15
	s_nop 0
	v_cndmask_b32_e64 v16, v15, v16, s[6:7]
	v_fma_f32 v15, -v17, v15, v14
	v_cmp_lt_f32_e64 s[6:7], 0, v15
	s_nop 1
	v_cndmask_b32_e64 v15, v16, v17, s[6:7]
	v_mul_f32_e32 v16, 0x37800000, v15
	v_cndmask_b32_e32 v15, v15, v16, vcc
	v_cmp_class_f32_e32 vcc, v14, v221
	s_nop 1
	v_cndmask_b32_e32 v14, v15, v14, vcc
	v_div_scale_f32 v15, s[6:7], v14, v14, 1.0
	v_rcp_f32_e32 v16, v15
	v_readlane_b32 s6, v254, 18
	v_fma_f32 v17, -v15, v16, 1.0
	v_fmac_f32_e32 v16, v17, v16
	v_div_scale_f32 v17, vcc, 1.0, v14, 1.0
	v_mul_f32_e32 v23, v17, v16
	v_fma_f32 v25, -v15, v23, v17
	v_fmac_f32_e32 v23, v25, v16
	v_fma_f32 v15, -v15, v23, v17
	v_div_fmas_f32 v15, v15, v16, v23
	v_div_fixup_f32 v30, v15, v14, 1.0
	v_mov_b32_e32 v14, s6
	ds_read_b64 v[14:15], v14
	s_lshl_b32 s6, s9, 6
	s_ashr_i32 s7, s6, 31
	s_lshl_b64 s[6:7], s[6:7], 2
	v_pk_mul_f32 v[6:7], v[30:31], v[6:7] op_sel_hi:[0,1]
	s_waitcnt lgkmcnt(0)
	v_readfirstlane_b32 s16, v14
	v_readfirstlane_b32 s17, v15
	s_add_u32 s6, s16, s6
	s_addc_u32 s7, s17, s7
	s_nop 1
	v_lshl_add_u64 v[102:103], s[6:7], 0, v[0:1]
	global_load_dwordx4 v[104:107], v[102:103], off offset:16
	v_lshl_add_u64 v[32:33], s[6:7], 0, v[0:1]
	global_load_dwordx4 v[14:17], v[32:33], off
	v_pk_mul_f32 v[8:9], v[30:31], v[8:9] op_sel_hi:[0,1]
	v_pk_mul_f32 v[10:11], v[30:31], v[10:11] op_sel_hi:[0,1]
	v_readlane_b32 s6, v254, 8
	v_mov_b32_e32 v25, v1
	v_pk_mul_f32 v[12:13], v[30:31], v[12:13] op_sel_hi:[0,1]
	s_waitcnt vmcnt(0) lgkmcnt(0)
	v_pk_mul_f32 v[6:7], v[6:7], v[14:15]
	v_pk_mul_f32 v[8:9], v[8:9], v[16:17]
	s_waitcnt vmcnt(1)
	s_nop 0
	v_mov_b32_e32 v14, v104
	v_mov_b32_e32 v15, v105
	v_mov_b32_e32 v16, v106
	v_mov_b32_e32 v17, v107
	s_nop 1
	s_waitcnt vmcnt(0) lgkmcnt(0)
	v_pk_mul_f32 v[10:11], v[10:11], v[14:15]
	v_mov_b32_e32 v14, s6
	ds_read_b64 v[14:15], v14
	s_lshl_b32 s6, s9, 2
	s_or_b32 s6, s6, s3
	s_ashr_i32 s7, s6, 31
	s_lshl_b64 s[16:17], s[6:7], 18
	s_waitcnt lgkmcnt(0)
	v_readfirstlane_b32 s18, v14
	v_readfirstlane_b32 s19, v15
	s_add_u32 s3, s18, s16
	s_addc_u32 s7, s19, s17
	s_lshl_b32 s9, s1, 10
	s_add_u32 s16, s3, s9
	s_addc_u32 s17, s7, 0
	v_lshl_add_u64 v[14:15], s[16:17], 0, v[24:25]
	v_lshl_add_u64 v[14:15], v[14:15], 0, v[0:1]
	s_mov_b64 s[16:17], 0x4258000
	s_mov_b32 s3, 0x4258000
	v_pk_mul_f32 v[12:13], v[12:13], v[16:17]
	v_lshl_add_u64 v[16:17], v[14:15], 0, s[16:17]
	v_add_co_u32_e32 v14, vcc, s3, v14
	v_bfe_u32 v0, v11, 16, 1
	s_nop 0
	v_addc_co_u32_e32 v15, vcc, 0, v15, vcc
	global_store_dwordx4 v[14:15], v[6:9], off
	global_store_dwordx4 v[16:17], v[10:13], off offset:16
	v_bfe_u32 v14, v7, 16, 1
	v_bfe_u32 v15, v13, 16, 1
	v_bfe_u32 v16, v9, 16, 1
	v_add3_u32 v16, v9, v16, s91
	v_add3_u32 v9, v13, v15, s91
	v_add3_u32 v7, v7, v14, s91
	v_add3_u32 v0, v11, v0, s91
	v_bfe_u32 v11, v8, 16, 1
	v_bfe_u32 v14, v6, 16, 1
	v_bfe_u32 v15, v10, 16, 1
	v_add3_u32 v10, v10, v15, s91
	v_add3_u32 v6, v6, v14, s91
	v_add3_u32 v8, v8, v11, s91
	v_lshrrev_b32_e32 v11, 16, v8
	v_lshrrev_b32_e32 v6, 16, v6
	v_lshrrev_b32_e32 v8, 16, v10
	v_lshl_or_b32 v10, s6, 2, v27
	v_and_or_b32 v6, v7, s33, v6
	v_and_or_b32 v7, v16, s33, v11
	v_ashrrev_i32_e32 v11, 31, v10
	v_bfe_u32 v13, v12, 16, 1
	v_lshlrev_b64 v[10:11], 15, v[10:11]
	v_add3_u32 v12, v12, v13, s91
	v_lshl_add_u64 v[10:11], s[10:11], 0, v[10:11]
	s_lshl_b32 s94, s1, 7
	v_lshrrev_b32_e32 v12, 16, v12
	v_and_or_b32 v8, v0, s33, v8
	v_lshl_add_u64 v[10:11], v[10:11], 0, s[94:95]
	v_lshlrev_b32_e32 v0, 1, v2
	v_and_or_b32 v9, v9, s33, v12
	v_lshl_add_u64 v[10:11], v[10:11], 0, v[0:1]
	global_store_dwordx4 v[10:11], v[6:9], off
	s_branch .LBB0_555

.LBB0_568:
	s_nop 1
	global_load_dword v102, v[8:9], off
	v_ashrrev_i32_e32 v11, 31, v10
	v_lshl_add_u64 v[14:15], v[10:11], 2, s[2:3]
	global_load_dword v11, v[14:15], off
	v_add_u32_e32 v7, 8, v7
	v_add_u32_e32 v10, 0x200, v10
	s_waitcnt vmcnt(0) lgkmcnt(0)
	v_mul_f32_e32 v14, v11, v11
	ds_bpermute_b32 v14, v5, v14
	s_waitcnt lgkmcnt(0)
	v_fmac_f32_e32 v14, v11, v11
	ds_bpermute_b32 v15, v88, v14
	s_waitcnt lgkmcnt(0)
	v_add_f32_e32 v14, v14, v15
	ds_bpermute_b32 v15, v89, v14
	s_waitcnt lgkmcnt(0)
	v_add_f32_e32 v14, v14, v15
	ds_bpermute_b32 v15, v90, v14
	s_waitcnt lgkmcnt(0)
	v_add_f32_e32 v14, v14, v15
	ds_bpermute_b32 v15, v91, v14
	s_waitcnt lgkmcnt(0)
	v_add_f32_e32 v14, v14, v15
	ds_bpermute_b32 v15, v92, v14
	s_waitcnt lgkmcnt(0)
	v_add_f32_e32 v14, v14, v15
	v_fmamk_f32 v14, v14, 0x3c800000, v219
	v_cmp_gt_f32_e32 vcc, s85, v14
	v_mul_f32_e32 v15, 0x4f800000, v14
	s_nop 0
	v_cndmask_b32_e32 v14, v14, v15, vcc
	v_sqrt_f32_e32 v15, v14
	s_nop 0
	v_add_u32_e32 v16, -1, v15
	v_fma_f32 v17, -v16, v15, v14
	v_cmp_ge_f32_e64 s[6:7], 0, v17
	v_add_u32_e32 v17, 1, v15
	s_nop 0
	v_cndmask_b32_e64 v16, v15, v16, s[6:7]
	v_fma_f32 v15, -v17, v15, v14
	v_cmp_lt_f32_e64 s[6:7], 0, v15
	s_nop 1
	v_cndmask_b32_e64 v15, v16, v17, s[6:7]
	v_mul_f32_e32 v16, 0x37800000, v15
	v_cndmask_b32_e32 v15, v15, v16, vcc
	v_cmp_class_f32_e32 vcc, v14, v221
	s_nop 1
	v_cndmask_b32_e32 v14, v15, v14, vcc
	v_div_scale_f32 v15, s[6:7], v14, v14, 1.0
	v_rcp_f32_e32 v16, v15
	s_nop 0
	v_fma_f32 v17, -v15, v16, 1.0
	v_fmac_f32_e32 v16, v17, v16
	v_div_scale_f32 v17, vcc, 1.0, v14, 1.0
	v_mul_f32_e32 v18, v17, v16
	v_fma_f32 v19, -v15, v18, v17
	v_fmac_f32_e32 v18, v19, v16
	v_fma_f32 v15, -v15, v18, v17
	v_div_fmas_f32 v15, v15, v16, v18
	v_div_fixup_f32 v14, v15, v14, 1.0
	v_mul_f32_e32 v11, v11, v14
	s_waitcnt vmcnt(1)
	s_nop 0
	v_mov_b32_e32 v14, v102
	s_nop 1
	v_cmp_lt_i32_e32 vcc, -5, v7
	s_or_b64 s[20:21], vcc, s[20:21]
	s_waitcnt vmcnt(0) lgkmcnt(0)
	v_mul_f32_e32 v11, v14, v11
	v_mul_f32_e32 v11, 0x3e000000, v11
	ds_write_b32 v13, v11
	v_add_u32_e32 v13, 0x800, v13
	s_andn2_b64 exec, exec, s[20:21]
	s_cbranch_execnz .LBB0_568

.LBB0_602:
	s_and_b64 vcc, exec, s[0:1]
	s_cbranch_vccz .LBB0_633
	v_readlane_b32 s0, v254, 4
	v_readlane_b32 s1, v254, 19
	v_bfe_u32 v3, v2, 3, 6
	v_mov_b32_e32 v0, s0
	ds_read_b64 v[10:11], v0
	s_add_i32 s0, s28, 0xfffffa00
	s_lshl_b32 s94, s0, 6
	s_add_i32 s0, s0, s24
	v_mov_b32_e32 v0, s1
	s_ashr_i32 s1, s0, 31
	s_waitcnt lgkmcnt(0)
	v_readfirstlane_b32 s15, v10
	s_lshl_b64 s[0:1], s[0:1], 14
	v_readfirstlane_b32 s17, v11
	s_add_u32 s0, s15, s0
	ds_read2_b64 v[6:9], v0 offset1:1
	s_addc_u32 s1, s17, s1
	v_lshlrev_b32_e32 v0, 7, v3
	v_lshl_add_u64 v[10:11], s[0:1], 0, v[0:1]
	v_lshlrev_b32_e32 v0, 4, v2
	v_and_b32_e32 v0, 0x70, v0
	v_lshl_add_u64 v[10:11], v[10:11], 0, v[0:1]
	s_mov_b64 s[0:1], 0x9d00000
	s_nop 1
	v_lshl_add_u64 v[102:103], v[10:11], 0, s[0:1]
	v_add_u32_e32 v104, 0x200, v2
	v_ashrrev_i32_e32 v106, 9, v104
	v_lshlrev_b32_e32 v104, 12, v106
	v_ashrrev_i32_e32 v105, 31, v104
	v_lshl_add_u64 v[102:103], v[104:105], 1, v[102:103]
	global_load_dwordx4 v[108:111], v[102:103], off
	v_ashrrev_i32_e32 v18, 9, v2
	v_lshl_add_u64 v[14:15], v[10:11], 0, s[0:1]
	v_lshlrev_b32_e32 v10, 12, v18
	v_ashrrev_i32_e32 v11, 31, v10
	v_lshl_add_u64 v[10:11], v[10:11], 1, v[14:15]
	global_load_dwordx4 v[10:13], v[10:11], off
	v_add_u32_e32 v16, 0x200, v2
	v_mul_u32_u24_e32 v3, 0x90, v3
	v_ashrrev_i32_e32 v19, 9, v16
	v_readlane_b32 s0, v254, 20
	v_lshlrev_b32_e32 v16, 12, v19
	v_ashrrev_i32_e32 v17, 31, v16
	v_add3_u32 v0, s0, v3, v0
	s_movk_i32 s0, 0x2400
	v_mad_i32_i24 v3, v18, s0, v0
	v_lshl_add_u64 v[14:15], v[16:17], 1, v[14:15]
	s_waitcnt lgkmcnt(0)
	v_readfirstlane_b32 s2, v6
	v_readfirstlane_b32 s3, v7
	v_readfirstlane_b32 s6, v8
	v_readfirstlane_b32 s7, v9
	v_mad_i32_i24 v0, v19, s0, v0
	v_cmp_gt_i32_e32 vcc, 64, v2
	s_waitcnt vmcnt(0)
	ds_write_b128 v3, v[10:13]
	s_waitcnt vmcnt(1)
	s_nop 0
	v_mov_b32_e32 v10, v108
	v_mov_b32_e32 v11, v109
	v_mov_b32_e32 v12, v110
	v_mov_b32_e32 v13, v111
	s_nop 1
	s_waitcnt vmcnt(0) lgkmcnt(0)
	ds_write_b128 v0, v[10:13]
	s_and_saveexec_b64 s[0:1], vcc
	s_cbranch_execz .LBB0_605
	v_readlane_b32 s4, v254, 21
	s_add_i32 s20, s94, s10
	s_nop 0
	v_mov_b32_e32 v0, s4
	ds_read_b128 v[6:9], v0
	s_waitcnt lgkmcnt(0)
	v_readfirstlane_b32 s4, v8
	v_add_u32_e32 v8, s20, v2
	v_readfirstlane_b32 s5, v9
	v_ashrrev_i32_e32 v9, 31, v8
	v_lshlrev_b64 v[8:9], 2, v[8:9]
	v_lshl_add_u64 v[10:11], s[4:5], 0, v[8:9]
	global_load_dword v0, v[10:11], off
	s_mov_b32 s4, 0xbfb8aa3b
	s_waitcnt vmcnt(0) lgkmcnt(0)
	v_mul_f32_e32 v3, 0xbfb8aa3b, v0
	v_fma_f32 v10, v0, s4, -v3
	v_rndne_f32_e32 v11, v3
	v_fmac_f32_e32 v10, 0xb2a5705f, v0
	v_sub_f32_e32 v3, v3, v11
	v_add_f32_e32 v3, v3, v10
	v_exp_f32_e32 v3, v3
	v_cvt_i32_f32_e32 v10, v11
	s_mov_b32 s4, 0x42ce8ed0
	v_cmp_nlt_f32_e32 vcc, s4, v0
	s_mov_b32 s4, 0xc2b17218
	v_ldexp_f32 v3, v3, v10
	v_cndmask_b32_e32 v3, 0, v3, vcc
	v_cmp_ngt_f32_e32 vcc, s4, v0
	s_mov_b32 s4, 0x3f2aaaab
	s_nop 0
	v_cndmask_b32_e32 v0, v228, v3, vcc
	v_add_f32_e32 v3, 1.0, v0
	v_add_f32_e32 v10, -1.0, v3
	v_sub_f32_e32 v11, v10, v3
	v_add_f32_e32 v11, 1.0, v11
	v_sub_f32_e32 v10, v0, v10
	v_add_f32_e32 v12, v10, v11
	v_frexp_mant_f32_e32 v10, v3
	v_cmp_gt_f32_e32 vcc, s4, v10
	v_cvt_f64_f32_e32 v[10:11], v3
	v_frexp_exp_i32_f64_e32 v10, v[10:11]
	v_subbrev_co_u32_e32 v10, vcc, 0, v10, vcc
	v_sub_u32_e32 v11, 0, v10
	v_ldexp_f32 v3, v3, v11
	v_ldexp_f32 v11, v12, v11
	v_add_f32_e32 v12, -1.0, v3
	v_add_f32_e32 v13, 1.0, v12
	v_sub_f32_e32 v13, v3, v13
	v_add_f32_e32 v13, v11, v13
	v_add_f32_e32 v14, v12, v13
	v_sub_f32_e32 v12, v12, v14
	v_add_f32_e32 v12, v13, v12
	v_add_f32_e32 v13, 1.0, v3
	v_add_f32_e32 v15, -1.0, v13
	v_sub_f32_e32 v3, v3, v15
	v_add_f32_e32 v3, v11, v3
	v_add_f32_e32 v11, v13, v3
	v_sub_f32_e32 v13, v13, v11
	v_add_f32_e32 v3, v3, v13
	v_rcp_f32_e32 v13, v11
	v_cvt_f32_i32_e32 v10, v10
	s_mov_b32 s4, 0x3f317218
	v_mul_f32_e32 v15, v14, v13
	v_mul_f32_e32 v16, v11, v15
	v_fma_f32 v17, v15, v11, -v16
	v_fmac_f32_e32 v17, v15, v3
	v_add_f32_e32 v18, v16, v17
	v_sub_f32_e32 v19, v14, v18
	v_sub_f32_e32 v14, v14, v19
	v_sub_f32_e32 v16, v18, v16
	v_sub_f32_e32 v14, v14, v18
	v_add_f32_e32 v12, v12, v14
	v_sub_f32_e32 v14, v16, v17
	v_add_f32_e32 v12, v14, v12
	v_add_f32_e32 v14, v19, v12
	v_mul_f32_e32 v16, v13, v14
	v_mul_f32_e32 v17, v11, v16
	v_fma_f32 v11, v16, v11, -v17
	v_fmac_f32_e32 v11, v16, v3
	v_sub_f32_e32 v3, v19, v14
	v_add_f32_e32 v3, v12, v3
	v_add_f32_e32 v12, v17, v11
	v_sub_f32_e32 v18, v14, v12
	v_sub_f32_e32 v14, v14, v18
	v_sub_f32_e32 v17, v12, v17
	v_sub_f32_e32 v12, v14, v12
	v_add_f32_e32 v3, v3, v12
	v_sub_f32_e32 v11, v17, v11
	v_add_f32_e32 v3, v11, v3
	v_add_f32_e32 v11, v15, v16
	v_add_f32_e32 v3, v18, v3
	v_sub_f32_e32 v12, v11, v15
	v_mul_f32_e32 v3, v13, v3
	v_sub_f32_e32 v12, v16, v12
	v_add_f32_e32 v3, v12, v3
	v_mul_f32_e32 v15, 0x3f317218, v10
	v_add_f32_e32 v12, v11, v3
	v_fma_f32 v16, v10, s4, -v15
	v_mul_f32_e32 v13, v12, v12
	v_fmac_f32_e32 v16, 0xb102e308, v10
	v_sub_f32_e32 v10, v12, v11
	v_fmamk_f32 v14, v13, 0x3e9b6dac, v222
	v_sub_f32_e32 v3, v3, v10
	v_add_f32_e32 v10, v15, v16
	v_fmaak_f32 v14, v13, v14, 0x3f2aaada
	v_sub_f32_e32 v11, v10, v15
	v_ldexp_f32 v15, v12, 1
	v_mul_f32_e32 v12, v12, v13
	v_mul_f32_e32 v12, v12, v14
	v_add_f32_e32 v13, v15, v12
	v_sub_f32_e32 v14, v13, v15
	v_ldexp_f32 v3, v3, 1
	v_sub_f32_e32 v12, v12, v14
	v_add_f32_e32 v3, v3, v12
	v_add_f32_e32 v12, v13, v3
	v_sub_f32_e32 v13, v12, v13
	v_sub_f32_e32 v3, v3, v13
	v_add_f32_e32 v13, v10, v12
	v_sub_f32_e32 v14, v13, v10
	v_sub_f32_e32 v15, v13, v14
	v_sub_f32_e32 v11, v16, v11
	v_sub_f32_e32 v10, v10, v15
	v_sub_f32_e32 v12, v12, v14
	v_add_f32_e32 v10, v12, v10
	v_add_f32_e32 v12, v11, v3
	v_sub_f32_e32 v14, v12, v11
	v_sub_f32_e32 v15, v12, v14
	v_sub_f32_e32 v11, v11, v15
	v_sub_f32_e32 v3, v3, v14
	v_add_f32_e32 v10, v12, v10
	v_add_f32_e32 v3, v3, v11
	v_add_f32_e32 v11, v13, v10
	v_sub_f32_e32 v12, v11, v13
	v_sub_f32_e32 v10, v10, v12
	v_add_f32_e32 v3, v3, v10
	s_mov_b32 s4, 0x7f800000
	v_add_f32_e32 v3, v11, v3
	v_cmp_neq_f32_e32 vcc, s4, v0
	s_mov_b32 s4, 0x33800000
	s_nop 0
	v_cndmask_b32_e32 v3, v228, v3, vcc
	v_cmp_lt_f32_e64 vcc, |v0|, s4
	v_readlane_b32 s4, v254, 22
	s_nop 0
	v_cndmask_b32_e32 v0, v3, v0, vcc
	v_xor_b32_e32 v3, 0x80000000, v0
	v_lshl_add_u32 v0, v2, 2, 0
	v_add_u32_e32 v0, 0x22500, v0
	ds_write_b32 v0, v3
	v_mov_b32_e32 v3, s4
	ds_read_b64 v[10:11], v3
	s_waitcnt lgkmcnt(0)
	v_readfirstlane_b32 s4, v10
	v_readfirstlane_b32 s5, v11
	s_nop 1
	v_lshl_add_u64 v[10:11], s[4:5], 0, v[8:9]
	global_load_dword v3, v[10:11], off
	v_readfirstlane_b32 s4, v6
	v_readfirstlane_b32 s5, v7
	s_nop 1
	v_lshl_add_u64 v[102:103], s[4:5], 0, v[8:9]
	global_load_dword v104, v[102:103], off
	s_waitcnt vmcnt(0) lgkmcnt(0)
	ds_write_b32 v0, v3 offset:256
	v_lshl_add_u64 v[6:7], s[4:5], 0, v[8:9]
	s_waitcnt vmcnt(0)
	s_nop 0
	v_mov_b32_e32 v3, v104
	s_nop 1
	s_waitcnt vmcnt(0) lgkmcnt(0)
	ds_write_b32 v0, v3 offset:512

.LBB0_607:
	s_nop 1
	global_load_dword v106, v[16:17], off
	s_nop 1
	global_load_dword v105, v[14:15], off
	s_nop 1
	global_load_dword v104, v[12:13], off offset:3072
	s_nop 1
	global_load_dword v103, v[12:13], off
	s_nop 1
	global_load_dword v102, v[10:11], off
	v_ashrrev_i32_e32 v24, 6, v19
	s_waitcnt lgkmcnt(0)
	v_readfirstlane_b32 s29, v6
	v_readfirstlane_b32 s30, v7
	v_add_u32_e32 v25, s25, v24
	v_mov_b32_e32 v22, s29
	v_mov_b32_e32 v23, s30
	v_mad_i64_i32 v[22:23], s[30:31], v25, s35, v[22:23]
	v_lshl_add_u64 v[22:23], v[22:23], 0, s[2:3]
	v_lshl_add_u64 v[22:23], v[22:23], 0, v[0:1]
	s_movk_i32 s29, 0x1000
	global_load_dword v26, v[22:23], off
	global_load_dword v28, v[22:23], off offset:3072
	v_add_co_u32_e32 v22, vcc, s29, v22
	s_waitcnt lgkmcnt(0)
	v_readfirstlane_b32 s29, v8
	v_addc_co_u32_e32 v23, vcc, 0, v23, vcc
	global_load_dword v29, v[22:23], off offset:2048
	v_mad_i64_i32 v[22:23], s[30:31], v24, s34, v[20:21]
	global_load_dword v30, v[22:23], off offset:3072
	s_nop 0
	s_waitcnt vmcnt(4)
	s_nop 0
	v_mov_b32_e32 v22, v102
	s_nop 1
	s_waitcnt vmcnt(5)
	s_nop 0
	v_mov_b32_e32 v23, v103
	s_nop 1
	s_waitcnt vmcnt(0) lgkmcnt(0)
	v_fmac_f32_e32 v22, v26, v23
	s_waitcnt vmcnt(6)
	s_nop 0
	v_mov_b32_e32 v23, v104
	s_nop 1
	s_waitcnt vmcnt(0) lgkmcnt(0)
	v_fmac_f32_e32 v22, v28, v23
	s_waitcnt vmcnt(7)
	s_nop 0
	v_mov_b32_e32 v23, v105
	s_nop 1
	s_waitcnt vmcnt(0) lgkmcnt(0)
	v_fmac_f32_e32 v22, v29, v23
	s_waitcnt vmcnt(8)
	s_nop 0
	v_mov_b32_e32 v23, v106
	s_nop 1
	s_waitcnt vmcnt(0) lgkmcnt(0)
	v_fmac_f32_e32 v22, v30, v23
	v_bfe_u32 v23, v22, 16, 1
	ds_write_b32 v3, v22
	v_add3_u32 v26, v22, v23, s91
	v_mad_u64_u32 v[22:23], s[30:31], v24, s88, v[18:19]
	v_readfirstlane_b32 s30, v9
	ds_write_b16_d16_hi v22, v26
	v_mov_b32_e32 v22, s29
	v_mov_b32_e32 v23, s30
	v_mad_i64_i32 v[22:23], s[30:31], v25, s35, v[22:23]
	v_lshl_add_u64 v[22:23], v[22:23], 0, s[2:3]
	v_lshl_add_u64 v[22:23], v[22:23], 0, v[0:1]
	v_add_co_u32_e32 v26, vcc, 0x4b18000, v22
	s_mov_b64 s[30:31], 0x4b18000
	s_nop 0
	v_addc_co_u32_e32 v27, vcc, 0, v23, vcc
	v_lshl_add_u64 v[24:25], v[22:23], 0, s[30:31]
	v_add_co_u32_e32 v22, vcc, 0x4b19000, v22
	global_store_dword v[26:27], v28, off
	global_store_dword v[24:25], v29, off offset:3072
	v_addc_co_u32_e32 v23, vcc, 0, v23, vcc
	global_store_dword v[22:23], v30, off offset:2048
	v_add_u32_e32 v22, 0x200, v19
	v_cmp_lt_i32_e32 vcc, s36, v19
	v_add_u32_e32 v3, 0x800, v3
	s_or_b64 s[6:7], vcc, s[6:7]
	v_mov_b32_e32 v19, v22
	s_andn2_b64 exec, exec, s[6:7]
	s_cbranch_execnz .LBB0_607

.LBB0_613:
	v_readlane_b32 s0, v254, 4
	s_mul_hi_i32 s2, s28, 0x2aaaaaab
	s_lshr_b32 s3, s2, 31
	v_mov_b32_e32 v0, s0
	s_ashr_i32 s15, s2, 1
	ds_read_b64 v[10:11], v0
	s_add_i32 s15, s15, s3
	s_mul_i32 s2, s15, 12
	s_sub_i32 s4, s28, s2
	s_lshl_b32 s2, s4, 6
	s_add_i32 s4, s4, s24
	v_readlane_b32 s0, v254, 19
	s_ashr_i32 s5, s4, 31
	s_ashr_i32 s3, s2, 31
	v_mov_b32_e32 v0, s0
	s_waitcnt lgkmcnt(0)
	v_readfirstlane_b32 s0, v10
	s_lshl_b64 s[4:5], s[4:5], 14
	v_readfirstlane_b32 s1, v11
	s_add_u32 s4, s0, s4
	v_bfe_u32 v16, v2, 3, 6
	ds_read2_b64 v[6:9], v0 offset1:1
	s_addc_u32 s5, s1, s5
	v_lshlrev_b32_e32 v0, 7, v16
	v_lshl_add_u64 v[10:11], s[4:5], 0, v[0:1]
	v_lshlrev_b32_e32 v0, 3, v2
	v_and_b32_e32 v3, 56, v0
	v_lshlrev_b32_e32 v62, 1, v3
	v_mov_b32_e32 v63, v1
	v_lshl_add_u64 v[10:11], v[10:11], 0, v[62:63]
	s_mov_b64 s[4:5], 0x9d00000
	s_nop 1
	v_lshl_add_u64 v[102:103], v[10:11], 0, s[4:5]
	v_add_u32_e32 v105, 0x200, v2
	v_ashrrev_i32_e32 v106, 9, v105
	v_lshlrev_b32_e32 v104, 12, v106
	v_ashrrev_i32_e32 v105, 31, v104
	v_lshl_add_u64 v[102:103], v[104:105], 1, v[102:103]
	global_load_dwordx4 v[108:111], v[102:103], off
	v_ashrrev_i32_e32 v0, 9, v2
	v_lshl_add_u64 v[14:15], v[10:11], 0, s[4:5]
	v_lshlrev_b32_e32 v10, 12, v0
	v_ashrrev_i32_e32 v11, 31, v10
	v_lshl_add_u64 v[10:11], v[10:11], 1, v[14:15]
	global_load_dwordx4 v[10:13], v[10:11], off
	v_add_u32_e32 v17, 0x200, v2
	v_mul_u32_u24_e32 v18, 0x90, v16
	v_ashrrev_i32_e32 v19, 9, v17
	v_readlane_b32 s4, v254, 20
	v_lshlrev_b32_e32 v16, 12, v19
	v_ashrrev_i32_e32 v17, 31, v16
	v_add3_u32 v18, s4, v18, v62
	s_movk_i32 s4, 0x2400
	v_mad_i32_i24 v0, v0, s4, v18
	v_lshl_add_u64 v[14:15], v[16:17], 1, v[14:15]
	s_waitcnt lgkmcnt(0)
	v_readfirstlane_b32 s17, v6
	v_readfirstlane_b32 s20, v7
	v_readfirstlane_b32 s21, v8
	v_readfirstlane_b32 s29, v9
	v_cmp_gt_i32_e32 vcc, 64, v2
	s_waitcnt vmcnt(0)
	ds_write_b128 v0, v[10:13]
	s_waitcnt vmcnt(1)
	s_nop 0
	v_mov_b32_e32 v10, v108
	v_mov_b32_e32 v11, v109
	v_mov_b32_e32 v12, v110
	v_mov_b32_e32 v13, v111
	s_nop 1
	v_mad_i32_i24 v0, v19, s4, v18
	s_waitcnt vmcnt(0) lgkmcnt(0)
	ds_write_b128 v0, v[10:13]
	s_and_saveexec_b64 s[4:5], vcc
	s_cbranch_execz .LBB0_615
	v_readlane_b32 s6, v254, 21
	s_add_i32 s30, s2, s10
	s_nop 0
	v_mov_b32_e32 v0, s6
	ds_read_b128 v[6:9], v0
	s_waitcnt lgkmcnt(0)
	v_readfirstlane_b32 s6, v8
	v_add_u32_e32 v8, s30, v2
	v_readfirstlane_b32 s7, v9
	v_ashrrev_i32_e32 v9, 31, v8
	v_lshlrev_b64 v[8:9], 2, v[8:9]
	v_lshl_add_u64 v[10:11], s[6:7], 0, v[8:9]
	global_load_dword v0, v[10:11], off
	s_mov_b32 s6, 0xbfb8aa3b
	s_waitcnt vmcnt(0) lgkmcnt(0)
	v_mul_f32_e32 v10, 0xbfb8aa3b, v0
	v_fma_f32 v11, v0, s6, -v10
	v_rndne_f32_e32 v12, v10
	v_fmac_f32_e32 v11, 0xb2a5705f, v0
	v_sub_f32_e32 v10, v10, v12
	v_add_f32_e32 v10, v10, v11
	v_exp_f32_e32 v10, v10
	v_cvt_i32_f32_e32 v11, v12
	s_mov_b32 s6, 0x42ce8ed0
	v_cmp_nlt_f32_e32 vcc, s6, v0
	s_mov_b32 s6, 0xc2b17218
	v_ldexp_f32 v10, v10, v11
	v_cndmask_b32_e32 v10, 0, v10, vcc
	v_cmp_ngt_f32_e32 vcc, s6, v0
	s_mov_b32 s6, 0x3f2aaaab
	s_nop 0
	v_cndmask_b32_e32 v0, v228, v10, vcc
	v_add_f32_e32 v12, 1.0, v0
	v_add_f32_e32 v10, -1.0, v12
	v_sub_f32_e32 v11, v10, v12
	v_add_f32_e32 v11, 1.0, v11
	v_sub_f32_e32 v10, v0, v10
	v_add_f32_e32 v13, v10, v11
	v_frexp_mant_f32_e32 v10, v12
	v_cmp_gt_f32_e32 vcc, s6, v10
	v_cvt_f64_f32_e32 v[10:11], v12
	v_frexp_exp_i32_f64_e32 v10, v[10:11]
	v_subbrev_co_u32_e32 v10, vcc, 0, v10, vcc
	v_sub_u32_e32 v11, 0, v10
	v_ldexp_f32 v12, v12, v11
	v_ldexp_f32 v11, v13, v11
	v_add_f32_e32 v13, -1.0, v12
	v_add_f32_e32 v14, 1.0, v13
	v_sub_f32_e32 v14, v12, v14
	v_add_f32_e32 v14, v11, v14
	v_add_f32_e32 v15, v13, v14
	v_sub_f32_e32 v13, v13, v15
	v_add_f32_e32 v13, v14, v13
	v_add_f32_e32 v14, 1.0, v12
	v_add_f32_e32 v16, -1.0, v14
	v_sub_f32_e32 v12, v12, v16
	v_add_f32_e32 v11, v11, v12
	v_add_f32_e32 v12, v14, v11
	v_sub_f32_e32 v14, v14, v12
	v_add_f32_e32 v11, v11, v14
	v_rcp_f32_e32 v14, v12
	v_cvt_f32_i32_e32 v10, v10
	s_mov_b32 s6, 0x3f317218
	v_mul_f32_e32 v16, v15, v14
	v_mul_f32_e32 v17, v12, v16
	v_fma_f32 v18, v16, v12, -v17
	v_fmac_f32_e32 v18, v16, v11
	v_add_f32_e32 v19, v17, v18
	v_sub_f32_e32 v20, v15, v19
	v_sub_f32_e32 v15, v15, v20
	v_sub_f32_e32 v17, v19, v17
	v_sub_f32_e32 v15, v15, v19
	v_add_f32_e32 v13, v13, v15
	v_sub_f32_e32 v15, v17, v18
	v_add_f32_e32 v13, v15, v13
	v_add_f32_e32 v15, v20, v13
	v_mul_f32_e32 v17, v14, v15
	v_mul_f32_e32 v18, v12, v17
	v_fma_f32 v12, v17, v12, -v18
	v_fmac_f32_e32 v12, v17, v11
	v_sub_f32_e32 v11, v20, v15
	v_add_f32_e32 v11, v13, v11
	v_add_f32_e32 v13, v18, v12
	v_sub_f32_e32 v19, v15, v13
	v_sub_f32_e32 v15, v15, v19
	v_sub_f32_e32 v18, v13, v18
	v_sub_f32_e32 v13, v15, v13
	v_add_f32_e32 v11, v11, v13
	v_sub_f32_e32 v12, v18, v12
	v_add_f32_e32 v11, v12, v11
	v_add_f32_e32 v12, v16, v17
	v_add_f32_e32 v11, v19, v11
	v_sub_f32_e32 v13, v12, v16
	v_mul_f32_e32 v11, v14, v11
	v_sub_f32_e32 v13, v17, v13
	v_add_f32_e32 v11, v13, v11
	v_mul_f32_e32 v16, 0x3f317218, v10
	v_add_f32_e32 v13, v12, v11
	v_fma_f32 v17, v10, s6, -v16
	v_mul_f32_e32 v14, v13, v13
	v_fmac_f32_e32 v17, 0xb102e308, v10
	v_sub_f32_e32 v10, v13, v12
	v_fmamk_f32 v15, v14, 0x3e9b6dac, v222
	v_sub_f32_e32 v10, v11, v10
	v_add_f32_e32 v11, v16, v17
	v_fmaak_f32 v15, v14, v15, 0x3f2aaada
	v_sub_f32_e32 v12, v11, v16
	v_ldexp_f32 v16, v13, 1
	v_mul_f32_e32 v13, v13, v14
	v_mul_f32_e32 v13, v13, v15
	v_add_f32_e32 v14, v16, v13
	v_sub_f32_e32 v15, v14, v16
	v_ldexp_f32 v10, v10, 1
	v_sub_f32_e32 v13, v13, v15
	v_add_f32_e32 v10, v10, v13
	v_add_f32_e32 v13, v14, v10
	v_sub_f32_e32 v14, v13, v14
	v_sub_f32_e32 v10, v10, v14
	v_add_f32_e32 v14, v11, v13
	v_sub_f32_e32 v15, v14, v11
	v_sub_f32_e32 v16, v14, v15
	v_sub_f32_e32 v12, v17, v12
	v_sub_f32_e32 v11, v11, v16
	v_sub_f32_e32 v13, v13, v15
	v_add_f32_e32 v11, v13, v11
	v_add_f32_e32 v13, v12, v10
	v_sub_f32_e32 v15, v13, v12
	v_sub_f32_e32 v16, v13, v15
	v_sub_f32_e32 v12, v12, v16
	v_sub_f32_e32 v10, v10, v15
	v_add_f32_e32 v11, v13, v11
	v_add_f32_e32 v10, v10, v12
	v_add_f32_e32 v12, v14, v11
	v_sub_f32_e32 v13, v12, v14
	v_sub_f32_e32 v11, v11, v13
	v_add_f32_e32 v10, v10, v11
	s_mov_b32 s6, 0x7f800000
	v_add_f32_e32 v10, v12, v10
	v_cmp_neq_f32_e32 vcc, s6, v0
	s_mov_b32 s6, 0x33800000
	s_nop 0
	v_cndmask_b32_e32 v10, v228, v10, vcc
	v_cmp_lt_f32_e64 vcc, |v0|, s6
	v_readlane_b32 s6, v254, 22
	s_nop 0
	v_cndmask_b32_e32 v0, v10, v0, vcc
	v_xor_b32_e32 v10, 0x80000000, v0
	v_lshl_add_u32 v0, v2, 2, 0
	v_add_u32_e32 v0, 0x22500, v0
	ds_write_b32 v0, v10
	v_mov_b32_e32 v10, s6
	ds_read_b64 v[10:11], v10
	s_waitcnt lgkmcnt(0)
	v_readfirstlane_b32 s6, v10
	v_readfirstlane_b32 s7, v11
	s_nop 1
	v_lshl_add_u64 v[10:11], s[6:7], 0, v[8:9]
	global_load_dword v10, v[10:11], off
	v_readfirstlane_b32 s6, v6
	v_readfirstlane_b32 s7, v7
	s_nop 1
	v_lshl_add_u64 v[102:103], s[6:7], 0, v[8:9]
	global_load_dword v104, v[102:103], off
	s_waitcnt vmcnt(0) lgkmcnt(0)
	ds_write_b32 v0, v10 offset:256
	v_lshl_add_u64 v[6:7], s[6:7], 0, v[8:9]
	s_waitcnt vmcnt(0)
	s_nop 0
	v_mov_b32_e32 v6, v104
	s_nop 1
	s_waitcnt vmcnt(0) lgkmcnt(0)
	ds_write_b32 v0, v6 offset:512
